# GEMM K-loops: per-phase s_setprio flips removed (timing only)
# speedup vs baseline: 1.0074x; 1.0074x over previous
; #define PG8_STAGE(bufoff, gbase, voff) do { _Pragma("unroll") for (int _i = 0; _i < 2; ++_i) \
;         __builtin_amdgcn_global_load_lds((const unsigned*)((const char*)(gbase) + (voff)[_i]), (LAS unsigned*)(lds + (bufoff) + ldsw + _i * 8192), 16, 0, 0); } while (0)
; #define PG8_LDA(dst, b, h) do { _Pragma("unroll") for (int m = 0; m < 4; ++m) _Pragma("unroll") for (int k = 0; k < 2; ++k) dst[m][k] = *(const LAS bf16x8*)(lds + PG8_SA(b, h) + aoff + m * 2048 + k * 1024); } while (0)
; #define PG8_LDB(dst, b, h) do { _Pragma("unroll") for (int n = 0; n < 2; ++n) _Pragma("unroll") for (int k = 0; k < 2; ++k) dst[n][k] = *(const LAS bf16x8*)(lds + PG8_SB(b, h) + boff + n * 2048 + k * 1024); } while (0)
; #define PG8_MMA(ai, bj, At, Bt) do { __builtin_amdgcn_s_setprio(1); _Pragma("unroll") for (int m = 0; m < 4; ++m) _Pragma("unroll") for (int n = 0; n < 2; ++n) _Pragma("unroll") for (int k = 0; k < 2; ++k) \
;         acc[ai][bj][m][n] = __builtin_amdgcn_mfma_f32_16x16x32_bf16(Bt[n][k], At[m][k], acc[ai][bj][m][n], 0, 0, 0); __builtin_amdgcn_s_setprio(0); } while (0)
; #define PG8_WAIT_L(n) asm volatile("s_waitcnt lgkmcnt(" #n ")" ::: "memory")
; #define PG8_BAR __builtin_amdgcn_s_barrier()
; #define PG8_SCHED __builtin_amdgcn_sched_barrier(0)
; template <class Epi>
; __device__ __forceinline__ void gemm_phase(LAS unsigned char* lds, const Gemm g, const StaticOrder& S, const Epi& E) {
;     ...
;             const char* a2 = last ? nA : cA + (size_t)(t + 2) * kstep; const char* b2 = last ? nB : cB + (size_t)(t + 2) * kstep;
;             const char* a3 = a2 + kstep; const char* b3 = b2 + kstep;
;             PG8_LDB(B0, 0, 0); PG8_SCHED; PG8_LDA(At, 0, 0); PG8_STAGE(PG8_SA(1, 1), a1 + hstep, voffA);
;             PG8_WAIT_L(8); PG8_BAR; PG8_WAIT_L(0); PG8_MMA(0, 0, At, B0); PG8_BAR; PG8_SCHED;
;             PG8_LDB(B1, 0, 1); PG8_STAGE(PG8_SB(0, 0), b2, voffB);
;             PG8_BAR; PG8_WAIT_L(0); PG8_MMA(0, 1, At, B1); PG8_BAR;
;             PG8_LDA(At, 0, 1); PG8_STAGE(PG8_SA(0, 0), a2, voffA);
;             PG8_BAR; PG8_WAIT_L(0); PG8_MMA(1, 0, At, B0); PG8_BAR; PG8_SCHED;
.LBB0_136:
	ds_read_b128 v[144:147], v154
	ds_read_b128 v[158:161], v154 offset:1024
	ds_read_b128 v[162:165], v154 offset:2048
	ds_read_b128 v[166:169], v154 offset:3072
	s_add_u32 s24, s22, 0xfff80080
	s_addc_u32 s25, s23, -1
	s_cmp_eq_u32 s77, 28
	s_cselect_b32 s27, s11, s25
	s_cselect_b32 s26, s73, s24
	s_cselect_b32 s25, s9, s76
	s_cselect_b32 s24, s74, s75
	v_lshl_add_u64 v[202:203], s[22:23], 0, v[136:137]
	s_add_i32 m0, s17, 0xc000
	ds_read_b128 v[170:173], v155
	ds_read_b128 v[174:177], v155 offset:1024
	ds_read_b128 v[178:181], v155 offset:2048
	ds_read_b128 v[182:185], v155 offset:3072
	ds_read_b128 v[186:189], v155 offset:4096
	ds_read_b128 v[190:193], v155 offset:5120
	ds_read_b128 v[194:197], v155 offset:6144
	ds_read_b128 v[198:201], v155 offset:7168
	global_load_lds_dwordx4 v[202:203], off
	v_lshl_add_u64 v[202:203], s[22:23], 0, v[138:139]
	s_add_i32 m0, s17, 0xe000
	s_nop 0
	global_load_lds_dwordx4 v[202:203], off
	s_waitcnt lgkmcnt(8)
	s_barrier
	s_waitcnt lgkmcnt(0)
	s_waitcnt lgkmcnt(0)
	v_mfma_f32_16x16x32_bf16 v[124:127], v[144:147], v[170:173], v[124:127]
	v_mfma_f32_16x16x32_bf16 v[120:123], v[162:165], v[170:173], v[120:123]
	v_mfma_f32_16x16x32_bf16 v[116:119], v[144:147], v[178:181], v[116:119]
	v_mfma_f32_16x16x32_bf16 v[108:111], v[162:165], v[178:181], v[108:111]
	v_mfma_f32_16x16x32_bf16 v[100:103], v[144:147], v[186:189], v[100:103]
	v_mfma_f32_16x16x32_bf16 v[92:95], v[162:165], v[186:189], v[92:95]
	v_mfma_f32_16x16x32_bf16 v[84:87], v[144:147], v[194:197], v[84:87]
	v_mfma_f32_16x16x32_bf16 v[76:79], v[162:165], v[194:197], v[76:79]
	v_mfma_f32_16x16x32_bf16 v[124:127], v[158:161], v[174:177], v[124:127]
	v_mfma_f32_16x16x32_bf16 v[120:123], v[166:169], v[174:177], v[120:123]
	v_mfma_f32_16x16x32_bf16 v[116:119], v[158:161], v[182:185], v[116:119]
	v_mfma_f32_16x16x32_bf16 v[108:111], v[166:169], v[182:185], v[108:111]
	v_mfma_f32_16x16x32_bf16 v[100:103], v[158:161], v[190:193], v[100:103]
	v_mfma_f32_16x16x32_bf16 v[92:95], v[166:169], v[190:193], v[92:95]
	v_mfma_f32_16x16x32_bf16 v[84:87], v[158:161], v[198:201], v[84:87]
	v_mfma_f32_16x16x32_bf16 v[76:79], v[166:169], v[198:201], v[76:79]
	s_barrier
	s_add_i32 s78, s69, s29
	v_lshl_add_u64 v[220:221], s[24:25], 0, v[130:131]
	s_mov_b32 m0, s78
	ds_read_b128 v[202:205], v156
	ds_read_b128 v[206:209], v156 offset:1024
	ds_read_b128 v[210:213], v156 offset:2048
	ds_read_b128 v[216:219], v156 offset:3072
	global_load_lds_dwordx4 v[220:221], off
	v_lshl_add_u64 v[222:223], s[24:25], 0, v[134:135]
	s_add_i32 m0, s78, 0x2000
	s_nop 0
	global_load_lds_dwordx4 v[222:223], off
	s_barrier
	s_waitcnt lgkmcnt(0)
	s_waitcnt lgkmcnt(0)
	v_mfma_f32_16x16x32_bf16 v[112:115], v[202:205], v[170:173], v[112:115]
	v_mfma_f32_16x16x32_bf16 v[104:107], v[210:213], v[170:173], v[104:107]
	v_mfma_f32_16x16x32_bf16 v[96:99], v[202:205], v[178:181], v[96:99]
	v_mfma_f32_16x16x32_bf16 v[88:91], v[210:213], v[178:181], v[88:91]
	v_mfma_f32_16x16x32_bf16 v[80:83], v[202:205], v[186:189], v[80:83]
	v_mfma_f32_16x16x32_bf16 v[72:75], v[210:213], v[186:189], v[72:75]
	v_mfma_f32_16x16x32_bf16 v[68:71], v[202:205], v[194:197], v[68:71]
	v_mfma_f32_16x16x32_bf16 v[64:67], v[210:213], v[194:197], v[64:67]
	v_mfma_f32_16x16x32_bf16 v[112:115], v[206:209], v[174:177], v[112:115]
	v_mfma_f32_16x16x32_bf16 v[104:107], v[216:219], v[174:177], v[104:107]
	v_mfma_f32_16x16x32_bf16 v[96:99], v[206:209], v[182:185], v[96:99]
	v_mfma_f32_16x16x32_bf16 v[88:91], v[216:219], v[182:185], v[88:91]
	v_mfma_f32_16x16x32_bf16 v[80:83], v[206:209], v[190:193], v[80:83]
	v_mfma_f32_16x16x32_bf16 v[72:75], v[216:219], v[190:193], v[72:75]
	v_mfma_f32_16x16x32_bf16 v[68:71], v[206:209], v[198:201], v[68:71]
	v_mfma_f32_16x16x32_bf16 v[64:67], v[216:219], v[198:201], v[64:67]
	s_mov_b32 m0, s17
	v_lshl_add_u64 v[224:225], s[26:27], 0, v[128:129]
	s_barrier
	ds_read_b128 v[170:173], v155 offset:16384
	ds_read_b128 v[174:177], v155 offset:17408
	ds_read_b128 v[178:181], v155 offset:18432
	ds_read_b128 v[182:185], v155 offset:19456
	ds_read_b128 v[186:189], v155 offset:20480
	ds_read_b128 v[190:193], v155 offset:21504
	ds_read_b128 v[194:197], v155 offset:22528
	ds_read_b128 v[198:201], v155 offset:23552
	global_load_lds_dwordx4 v[224:225], off
	v_lshl_add_u64 v[226:227], s[26:27], 0, v[132:133]
	s_mov_b32 m0, s30
	s_nop 0
	global_load_lds_dwordx4 v[226:227], off
	s_barrier
	s_waitcnt lgkmcnt(0)
	s_waitcnt lgkmcnt(0)
	v_mfma_f32_16x16x32_bf16 v[60:63], v[144:147], v[170:173], v[60:63]
	v_mfma_f32_16x16x32_bf16 v[56:59], v[162:165], v[170:173], v[56:59]
	v_mfma_f32_16x16x32_bf16 v[52:55], v[144:147], v[178:181], v[52:55]
	v_mfma_f32_16x16x32_bf16 v[44:47], v[162:165], v[178:181], v[44:47]
	v_mfma_f32_16x16x32_bf16 v[36:39], v[144:147], v[186:189], v[36:39]
	v_mfma_f32_16x16x32_bf16 v[28:31], v[162:165], v[186:189], v[28:31]
	v_mfma_f32_16x16x32_bf16 v[20:23], v[144:147], v[194:197], v[20:23]
	v_mfma_f32_16x16x32_bf16 v[12:15], v[162:165], v[194:197], v[12:15]
	v_mfma_f32_16x16x32_bf16 v[60:63], v[158:161], v[174:177], v[60:63]
	v_mfma_f32_16x16x32_bf16 v[56:59], v[166:169], v[174:177], v[56:59]
	v_mfma_f32_16x16x32_bf16 v[52:55], v[158:161], v[182:185], v[52:55]
	v_mfma_f32_16x16x32_bf16 v[44:47], v[166:169], v[182:185], v[44:47]
	v_mfma_f32_16x16x32_bf16 v[36:39], v[158:161], v[190:193], v[36:39]
	v_mfma_f32_16x16x32_bf16 v[28:31], v[166:169], v[190:193], v[28:31]
	v_mfma_f32_16x16x32_bf16 v[20:23], v[158:161], v[198:201], v[20:23]
	v_mfma_f32_16x16x32_bf16 v[12:15], v[166:169], v[198:201], v[12:15]
	s_barrier
; #define PG8_STAGE(bufoff, gbase, voff) do { _Pragma("unroll") for (int _i = 0; _i < 2; ++_i) \
;         __builtin_amdgcn_global_load_lds((const unsigned*)((const char*)(gbase) + (voff)[_i]), (LAS unsigned*)(lds + (bufoff) + ldsw + _i * 8192), 16, 0, 0); } while (0)
; #define PG8_LDA(dst, b, h) do { _Pragma("unroll") for (int m = 0; m < 4; ++m) _Pragma("unroll") for (int k = 0; k < 2; ++k) dst[m][k] = *(const LAS bf16x8*)(lds + PG8_SA(b, h) + aoff + m * 2048 + k * 1024); } while (0)
; #define PG8_LDB(dst, b, h) do { _Pragma("unroll") for (int n = 0; n < 2; ++n) _Pragma("unroll") for (int k = 0; k < 2; ++k) dst[n][k] = *(const LAS bf16x8*)(lds + PG8_SB(b, h) + boff + n * 2048 + k * 1024); } while (0)
; #define PG8_MMA(ai, bj, At, Bt) do { __builtin_amdgcn_s_setprio(1); _Pragma("unroll") for (int m = 0; m < 4; ++m) _Pragma("unroll") for (int n = 0; n < 2; ++n) _Pragma("unroll") for (int k = 0; k < 2; ++k) \
;         acc[ai][bj][m][n] = __builtin_amdgcn_mfma_f32_16x16x32_bf16(Bt[n][k], At[m][k], acc[ai][bj][m][n], 0, 0, 0); __builtin_amdgcn_s_setprio(0); } while (0)
; #define PG8_WAIT_V(n) asm volatile("s_waitcnt vmcnt(" #n ")" ::: "memory")
; #define PG8_WAIT_L(n) asm volatile("s_waitcnt lgkmcnt(" #n ")" ::: "memory")
; #define PG8_BAR __builtin_amdgcn_s_barrier()
; #define PG8_SCHED __builtin_amdgcn_sched_barrier(0)
; template <class Epi>
; __device__ __forceinline__ void gemm_phase(LAS unsigned char* lds, const Gemm g, const StaticOrder& S, const Epi& E) {
;     ...
;             PG8_STAGE(PG8_SB(0, 1), b2 + hstep, voffB);
;             PG8_WAIT_V(6); PG8_BAR; PG8_MMA(1, 1, At, B1); PG8_BAR;
;             PG8_LDB(B0, 1, 0); PG8_SCHED; PG8_LDA(At, 1, 0); PG8_STAGE(PG8_SA(0, 1), a2 + hstep, voffA);
;             PG8_WAIT_L(8); PG8_BAR; PG8_WAIT_L(0); PG8_MMA(0, 0, At, B0); PG8_BAR; PG8_SCHED;
;             PG8_LDB(B1, 1, 1); PG8_STAGE(PG8_SB(1, 0), b3, voffB);
;             PG8_BAR; PG8_WAIT_L(0); PG8_MMA(0, 1, At, B1); PG8_BAR;
;             PG8_LDA(At, 1, 1); PG8_STAGE(PG8_SA(1, 0), a3, voffA);
;             PG8_BAR; PG8_WAIT_L(0); PG8_MMA(1, 0, At, B0); PG8_BAR; PG8_SCHED;
	s_add_u32 s78, s24, 0x80000
	s_addc_u32 s79, s25, 0
	s_add_i32 s80, s70, s29
	v_lshl_add_u64 v[144:145], s[78:79], 0, v[130:131]
	s_mov_b32 m0, s80
	s_nop 0
	global_load_lds_dwordx4 v[144:145], off
	v_lshl_add_u64 v[144:145], s[78:79], 0, v[134:135]
	s_add_i32 m0, s80, 0x2000
	s_nop 0
	global_load_lds_dwordx4 v[144:145], off
	s_waitcnt vmcnt(6)
	s_barrier
	v_mfma_f32_16x16x32_bf16 v[48:51], v[202:205], v[170:173], v[48:51]
	v_mfma_f32_16x16x32_bf16 v[40:43], v[210:213], v[170:173], v[40:43]
	v_mfma_f32_16x16x32_bf16 v[32:35], v[202:205], v[178:181], v[32:35]
	v_mfma_f32_16x16x32_bf16 v[24:27], v[210:213], v[178:181], v[24:27]
	v_mfma_f32_16x16x32_bf16 v[16:19], v[202:205], v[186:189], v[16:19]
	v_mfma_f32_16x16x32_bf16 v[8:11], v[210:213], v[186:189], v[8:11]
	v_mfma_f32_16x16x32_bf16 v[4:7], v[202:205], v[194:197], v[4:7]
	v_mfma_f32_16x16x32_bf16 v[0:3], v[210:213], v[194:197], v[0:3]
	v_mfma_f32_16x16x32_bf16 v[48:51], v[206:209], v[174:177], v[48:51]
	v_mfma_f32_16x16x32_bf16 v[40:43], v[216:219], v[174:177], v[40:43]
	v_mfma_f32_16x16x32_bf16 v[32:35], v[206:209], v[182:185], v[32:35]
	v_mfma_f32_16x16x32_bf16 v[24:27], v[216:219], v[182:185], v[24:27]
	v_mfma_f32_16x16x32_bf16 v[16:19], v[206:209], v[190:193], v[16:19]
	v_mfma_f32_16x16x32_bf16 v[8:11], v[216:219], v[190:193], v[8:11]
	v_mfma_f32_16x16x32_bf16 v[4:7], v[206:209], v[198:201], v[4:7]
	v_mfma_f32_16x16x32_bf16 v[0:3], v[216:219], v[198:201], v[0:3]
	s_add_i32 s78, 0, 0x18000
	v_add_u32_e32 v157, s78, v152
	s_barrier
	ds_read_b128 v[144:147], v157
	ds_read_b128 v[158:161], v157 offset:1024
	ds_read_b128 v[162:165], v157 offset:2048
	ds_read_b128 v[166:169], v157 offset:3072
	s_add_u32 s26, s26, 0x80000
	s_addc_u32 s27, s27, 0
	s_mov_b32 m0, s31
	v_lshl_add_u64 v[202:203], s[26:27], 0, v[128:129]
	ds_read_b128 v[170:173], v155 offset:32768
	ds_read_b128 v[174:177], v155 offset:33792
	ds_read_b128 v[178:181], v155 offset:34816
	ds_read_b128 v[182:185], v155 offset:35840
	ds_read_b128 v[186:189], v155 offset:36864
	ds_read_b128 v[190:193], v155 offset:37888
	ds_read_b128 v[194:197], v155 offset:38912
	ds_read_b128 v[198:201], v155 offset:39936
	global_load_lds_dwordx4 v[202:203], off
	v_lshl_add_u64 v[202:203], s[26:27], 0, v[132:133]
	s_mov_b32 m0, s33
	s_nop 0
	global_load_lds_dwordx4 v[202:203], off
	s_waitcnt lgkmcnt(8)
	s_barrier
	s_waitcnt lgkmcnt(0)
	s_waitcnt lgkmcnt(0)
	v_mfma_f32_16x16x32_bf16 v[124:127], v[144:147], v[170:173], v[124:127]
	v_mfma_f32_16x16x32_bf16 v[120:123], v[162:165], v[170:173], v[120:123]
	v_mfma_f32_16x16x32_bf16 v[116:119], v[144:147], v[178:181], v[116:119]
	v_mfma_f32_16x16x32_bf16 v[108:111], v[162:165], v[178:181], v[108:111]
	v_mfma_f32_16x16x32_bf16 v[100:103], v[144:147], v[186:189], v[100:103]
	v_mfma_f32_16x16x32_bf16 v[92:95], v[162:165], v[186:189], v[92:95]
	v_mfma_f32_16x16x32_bf16 v[84:87], v[144:147], v[194:197], v[84:87]
	v_mfma_f32_16x16x32_bf16 v[76:79], v[162:165], v[194:197], v[76:79]
	v_mfma_f32_16x16x32_bf16 v[124:127], v[158:161], v[174:177], v[124:127]
	v_mfma_f32_16x16x32_bf16 v[120:123], v[166:169], v[174:177], v[120:123]
	v_mfma_f32_16x16x32_bf16 v[116:119], v[158:161], v[182:185], v[116:119]
	v_mfma_f32_16x16x32_bf16 v[108:111], v[166:169], v[182:185], v[108:111]
	v_mfma_f32_16x16x32_bf16 v[100:103], v[158:161], v[190:193], v[100:103]
	v_mfma_f32_16x16x32_bf16 v[92:95], v[166:169], v[190:193], v[92:95]
	v_mfma_f32_16x16x32_bf16 v[84:87], v[158:161], v[198:201], v[84:87]
	v_mfma_f32_16x16x32_bf16 v[76:79], v[166:169], v[198:201], v[76:79]
	s_barrier
	s_add_i32 s26, 0, 0x1c000
	s_add_i32 s27, s78, s29
	v_add_u32_e32 v157, s26, v152
	v_lshl_add_u64 v[220:221], v[220:221], 0, s[4:5]
	s_mov_b32 m0, s27
	ds_read_b128 v[202:205], v157
	ds_read_b128 v[206:209], v157 offset:1024
	ds_read_b128 v[210:213], v157 offset:2048
	ds_read_b128 v[216:219], v157 offset:3072
	global_load_lds_dwordx4 v[220:221], off
	v_lshl_add_u64 v[220:221], v[222:223], 0, s[4:5]
	s_add_i32 m0, s27, 0x2000
	s_nop 0
	global_load_lds_dwordx4 v[220:221], off
	s_barrier
	s_waitcnt lgkmcnt(0)
	s_waitcnt lgkmcnt(0)
	v_mfma_f32_16x16x32_bf16 v[112:115], v[202:205], v[170:173], v[112:115]
	v_mfma_f32_16x16x32_bf16 v[104:107], v[210:213], v[170:173], v[104:107]
	v_mfma_f32_16x16x32_bf16 v[96:99], v[202:205], v[178:181], v[96:99]
	v_mfma_f32_16x16x32_bf16 v[88:91], v[210:213], v[178:181], v[88:91]
	v_mfma_f32_16x16x32_bf16 v[80:83], v[202:205], v[186:189], v[80:83]
	v_mfma_f32_16x16x32_bf16 v[72:75], v[210:213], v[186:189], v[72:75]
	v_mfma_f32_16x16x32_bf16 v[68:71], v[202:205], v[194:197], v[68:71]
	v_mfma_f32_16x16x32_bf16 v[64:67], v[210:213], v[194:197], v[64:67]
	v_mfma_f32_16x16x32_bf16 v[112:115], v[206:209], v[174:177], v[112:115]
	v_mfma_f32_16x16x32_bf16 v[104:107], v[216:219], v[174:177], v[104:107]
	v_mfma_f32_16x16x32_bf16 v[96:99], v[206:209], v[182:185], v[96:99]
	v_mfma_f32_16x16x32_bf16 v[88:91], v[216:219], v[182:185], v[88:91]
	v_mfma_f32_16x16x32_bf16 v[80:83], v[206:209], v[190:193], v[80:83]
	v_mfma_f32_16x16x32_bf16 v[72:75], v[216:219], v[190:193], v[72:75]
	v_mfma_f32_16x16x32_bf16 v[68:71], v[206:209], v[198:201], v[68:71]
	v_mfma_f32_16x16x32_bf16 v[64:67], v[216:219], v[198:201], v[64:67]
	s_mov_b32 m0, s51
	v_lshl_add_u64 v[220:221], v[224:225], 0, s[4:5]
	s_barrier
	ds_read_b128 v[170:173], v155 offset:49152
	ds_read_b128 v[174:177], v155 offset:50176
	ds_read_b128 v[178:181], v155 offset:51200
	ds_read_b128 v[182:185], v155 offset:52224
	ds_read_b128 v[186:189], v155 offset:53248
	ds_read_b128 v[190:193], v155 offset:54272
	ds_read_b128 v[194:197], v155 offset:55296
	ds_read_b128 v[198:201], v155 offset:56320
	global_load_lds_dwordx4 v[220:221], off
	v_lshl_add_u64 v[220:221], v[226:227], 0, s[4:5]
	s_mov_b32 m0, s54
	s_nop 0
	global_load_lds_dwordx4 v[220:221], off
	s_barrier
; #define PG8_STAGE(bufoff, gbase, voff) do { _Pragma("unroll") for (int _i = 0; _i < 2; ++_i) \
;         __builtin_amdgcn_global_load_lds((const unsigned*)((const char*)(gbase) + (voff)[_i]), (LAS unsigned*)(lds + (bufoff) + ldsw + _i * 8192), 16, 0, 0); } while (0)
; #define PG8_MMA(ai, bj, At, Bt) do { __builtin_amdgcn_s_setprio(1); _Pragma("unroll") for (int m = 0; m < 4; ++m) _Pragma("unroll") for (int n = 0; n < 2; ++n) _Pragma("unroll") for (int k = 0; k < 2; ++k) \
;         acc[ai][bj][m][n] = __builtin_amdgcn_mfma_f32_16x16x32_bf16(Bt[n][k], At[m][k], acc[ai][bj][m][n], 0, 0, 0); __builtin_amdgcn_s_setprio(0); } while (0)
; #define PG8_WAIT_V(n) asm volatile("s_waitcnt vmcnt(" #n ")" ::: "memory")
; #define PG8_WAIT_L(n) asm volatile("s_waitcnt lgkmcnt(" #n ")" ::: "memory")
; #define PG8_BAR __builtin_amdgcn_s_barrier()
; #define PG8_SCHED __builtin_amdgcn_sched_barrier(0)
; template <class Epi>
; __device__ __forceinline__ void gemm_phase(LAS unsigned char* lds, const Gemm g, const StaticOrder& S, const Epi& E) {
;     ...
;             PG8_BAR; PG8_WAIT_L(0); PG8_MMA(1, 0, At, B0); PG8_BAR; PG8_SCHED;
;             PG8_STAGE(PG8_SB(1, 1), b3 + hstep, voffB);
;             PG8_WAIT_V(6); PG8_BAR; PG8_MMA(1, 1, At, B1); PG8_BAR;
;         }
	s_waitcnt lgkmcnt(0)
	s_waitcnt lgkmcnt(0)
	v_mfma_f32_16x16x32_bf16 v[60:63], v[144:147], v[170:173], v[60:63]
	v_mfma_f32_16x16x32_bf16 v[56:59], v[162:165], v[170:173], v[56:59]
	v_mfma_f32_16x16x32_bf16 v[52:55], v[144:147], v[178:181], v[52:55]
	v_mfma_f32_16x16x32_bf16 v[44:47], v[162:165], v[178:181], v[44:47]
	v_mfma_f32_16x16x32_bf16 v[36:39], v[144:147], v[186:189], v[36:39]
	v_mfma_f32_16x16x32_bf16 v[28:31], v[162:165], v[186:189], v[28:31]
	v_mfma_f32_16x16x32_bf16 v[20:23], v[144:147], v[194:197], v[20:23]
	v_mfma_f32_16x16x32_bf16 v[12:15], v[162:165], v[194:197], v[12:15]
	v_mfma_f32_16x16x32_bf16 v[60:63], v[158:161], v[174:177], v[60:63]
	v_mfma_f32_16x16x32_bf16 v[56:59], v[166:169], v[174:177], v[56:59]
	v_mfma_f32_16x16x32_bf16 v[52:55], v[158:161], v[182:185], v[52:55]
	v_mfma_f32_16x16x32_bf16 v[44:47], v[166:169], v[182:185], v[44:47]
	v_mfma_f32_16x16x32_bf16 v[36:39], v[158:161], v[190:193], v[36:39]
	v_mfma_f32_16x16x32_bf16 v[28:31], v[166:169], v[190:193], v[28:31]
	v_mfma_f32_16x16x32_bf16 v[20:23], v[158:161], v[198:201], v[20:23]
	v_mfma_f32_16x16x32_bf16 v[12:15], v[166:169], v[198:201], v[12:15]
	s_barrier
	s_add_u32 s24, s24, 0x80080
	s_addc_u32 s25, s25, 0
	s_add_i32 s26, s26, s29
	v_lshl_add_u64 v[144:145], s[24:25], 0, v[130:131]
	s_mov_b32 m0, s26
	s_nop 0
	global_load_lds_dwordx4 v[144:145], off
	v_lshl_add_u64 v[144:145], s[24:25], 0, v[134:135]
	s_add_i32 m0, s26, 0x2000
	s_nop 0
	global_load_lds_dwordx4 v[144:145], off
	s_waitcnt vmcnt(6)
	s_barrier
	v_mfma_f32_16x16x32_bf16 v[48:51], v[202:205], v[170:173], v[48:51]
	v_mfma_f32_16x16x32_bf16 v[40:43], v[210:213], v[170:173], v[40:43]
	v_mfma_f32_16x16x32_bf16 v[32:35], v[202:205], v[178:181], v[32:35]
	v_mfma_f32_16x16x32_bf16 v[24:27], v[210:213], v[178:181], v[24:27]
	v_mfma_f32_16x16x32_bf16 v[16:19], v[202:205], v[186:189], v[16:19]
	v_mfma_f32_16x16x32_bf16 v[8:11], v[210:213], v[186:189], v[8:11]
	v_mfma_f32_16x16x32_bf16 v[4:7], v[202:205], v[194:197], v[4:7]
	v_mfma_f32_16x16x32_bf16 v[0:3], v[210:213], v[194:197], v[0:3]
	v_mfma_f32_16x16x32_bf16 v[48:51], v[206:209], v[174:177], v[48:51]
	v_mfma_f32_16x16x32_bf16 v[40:43], v[216:219], v[174:177], v[40:43]
	v_mfma_f32_16x16x32_bf16 v[32:35], v[206:209], v[182:185], v[32:35]
	v_mfma_f32_16x16x32_bf16 v[24:27], v[216:219], v[182:185], v[24:27]
	v_mfma_f32_16x16x32_bf16 v[16:19], v[206:209], v[190:193], v[16:19]
	v_mfma_f32_16x16x32_bf16 v[8:11], v[216:219], v[190:193], v[8:11]
	v_mfma_f32_16x16x32_bf16 v[4:7], v[206:209], v[198:201], v[4:7]
	v_mfma_f32_16x16x32_bf16 v[0:3], v[216:219], v[198:201], v[0:3]
	s_add_i32 s77, s77, 2
	s_add_u32 s22, s22, 0x100
	s_addc_u32 s23, s23, 0
	s_add_u32 s75, s75, 0x100
	s_addc_u32 s76, s76, 0
	s_cmp_gt_u32 s77, 29
	s_barrier
	s_cbranch_scc0 .LBB0_136
; #define PG8_WAIT_V(n) asm volatile("s_waitcnt vmcnt(" #n ")" ::: "memory")
; #define PG8_BAR __builtin_amdgcn_s_barrier()
; __device__ __forceinline__ u32x4 pack8(const f32x4 v0, const f32x4 v1) { u32x4 w; w.x = cvt_pk_bf16(v0[0], v0[1]); w.y = cvt_pk_bf16(v0[2], v0[3]); w.z = cvt_pk_bf16(v1[0], v1[1]); w.w = cvt_pk_bf16(v1[2], v1[3]); return w; }
; template <class Epi>
; __device__ __forceinline__ void gemm_phase(LAS unsigned char* lds, const Gemm g, const StaticOrder& S, const Epi& E) {
;     ...
;         if (!has_next) break;
; #pragma unroll
;         for (int a = 0; a < 2; ++a)
; #pragma unroll
;             for (int b = 0; b < 2; ++b)
; #pragma unroll
;                 for (int m = 0; m < 4; ++m)
; #pragma unroll
;                     for (int n = 0; n < 2; ++n) acc[a][b][m][n] = (f32x4){0.f, 0.f, 0.f, 0.f};
;         cur = nxt; cA = nA; cB = nB; ++ui;
;     }
;     PG8_WAIT_V(0);
;     if (wr == 0) PG8_BAR;
;     PG8_BAR;
;     __device__ __forceinline__ void operator()(const AccT& acc, const pg8::Unit& u, int wr, int wc, int fr, int fq) const {
;         const int row0 = u.pm * 256 + wr * 64 + fr, col0 = u.pn * 256 + wc * 32 + 8 * fq;
; #pragma unroll
;         for (int ai = 0; ai < 2; ++ai)
; #pragma unroll
;             for (int m = 0; m < 4; ++m) { bf16_t* rowp = O + (size_t)(row0 + ai * 128 + m * 16) * NPROJ + col0;
; #pragma unroll
;                 for (int bj = 0; bj < 2; ++bj) *(u32x4*)(rowp + bj * 128) = pack8(acc[ai][bj][m][0], acc[ai][bj][m][1]); }
;     }
	v_lshl_or_b32 v146, s72, 8, v153
	v_lshl_add_u32 v157, s16, 8, v151
	v_ashrrev_i32_e32 v147, 31, v146
	v_mov_b64_e32 v[144:145], s[0:1]
	v_mad_i64_i32 v[158:159], s[22:23], v157, s71, v[144:145]
	v_lshlrev_b64 v[146:147], 1, v[146:147]
	v_lshl_add_u64 v[158:159], v[158:159], 0, v[146:147]
	v_cvt_pk_bf16_f32 v124, v124, v125
	v_cvt_pk_bf16_f32 v125, v126, v127
	v_cvt_pk_bf16_f32 v126, v120, v121
	v_cvt_pk_bf16_f32 v127, v122, v123
	global_store_dwordx4 v[158:159], v[124:127], off
	v_cvt_pk_bf16_f32 v112, v112, v113
	v_cvt_pk_bf16_f32 v113, v114, v115
	v_cvt_pk_bf16_f32 v114, v104, v105
	v_or_b32_e32 v104, 16, v157
	v_mad_i64_i32 v[104:105], s[22:23], v104, s71, v[144:145]
	v_cvt_pk_bf16_f32 v115, v106, v107
	global_store_dwordx4 v[158:159], v[112:115], off offset:256
	s_and_b64 vcc, exec, s[2:3]
	s_mov_b32 s72, s8
	v_lshl_add_u64 v[112:113], v[104:105], 0, v[146:147]
	v_cvt_pk_bf16_f32 v104, v116, v117
	v_cvt_pk_bf16_f32 v105, v118, v119
	v_cvt_pk_bf16_f32 v106, v108, v109
	v_cvt_pk_bf16_f32 v107, v110, v111
	global_store_dwordx4 v[112:113], v[104:107], off
	v_cvt_pk_bf16_f32 v96, v96, v97
	v_cvt_pk_bf16_f32 v97, v98, v99
	v_cvt_pk_bf16_f32 v98, v88, v89
	v_or_b32_e32 v88, 32, v157
	v_mad_i64_i32 v[88:89], s[22:23], v88, s71, v[144:145]
	v_cvt_pk_bf16_f32 v99, v90, v91
	global_store_dwordx4 v[112:113], v[96:99], off offset:256
	s_mov_b32 s16, s10
	s_mov_b64 s[24:25], s[20:21]
	v_lshl_add_u64 v[96:97], v[88:89], 0, v[146:147]
	v_cvt_pk_bf16_f32 v88, v100, v101
	v_cvt_pk_bf16_f32 v89, v102, v103
	v_cvt_pk_bf16_f32 v90, v92, v93
	v_cvt_pk_bf16_f32 v91, v94, v95
	global_store_dwordx4 v[96:97], v[88:91], off
	v_cvt_pk_bf16_f32 v80, v80, v81
	v_cvt_pk_bf16_f32 v81, v82, v83
	v_cvt_pk_bf16_f32 v82, v72, v73
	v_or_b32_e32 v72, 48, v157
	v_mad_i64_i32 v[72:73], s[22:23], v72, s71, v[144:145]
	v_cvt_pk_bf16_f32 v83, v74, v75
	global_store_dwordx4 v[96:97], v[80:83], off offset:256
	s_nop 1
	v_lshl_add_u64 v[80:81], v[72:73], 0, v[146:147]
	v_cvt_pk_bf16_f32 v72, v84, v85
	v_cvt_pk_bf16_f32 v73, v86, v87
	v_cvt_pk_bf16_f32 v74, v76, v77
	v_cvt_pk_bf16_f32 v75, v78, v79
	global_store_dwordx4 v[80:81], v[72:75], off
	v_cvt_pk_bf16_f32 v68, v68, v69
	v_cvt_pk_bf16_f32 v69, v70, v71
	v_cvt_pk_bf16_f32 v70, v64, v65
	v_add_u32_e32 v64, 0x80, v157
	v_mad_i64_i32 v[64:65], s[22:23], v64, s71, v[144:145]
	v_lshl_add_u64 v[64:65], v[64:65], 0, v[146:147]
	v_cvt_pk_bf16_f32 v71, v66, v67
	global_store_dwordx4 v[80:81], v[68:71], off offset:256
	v_cvt_pk_bf16_f32 v60, v60, v61
	v_cvt_pk_bf16_f32 v61, v62, v63
	v_cvt_pk_bf16_f32 v62, v56, v57
	v_cvt_pk_bf16_f32 v63, v58, v59
	global_store_dwordx4 v[64:65], v[60:63], off
	v_cvt_pk_bf16_f32 v48, v48, v49
	v_cvt_pk_bf16_f32 v49, v50, v51
	v_cvt_pk_bf16_f32 v50, v40, v41
	v_add_u32_e32 v40, 0x90, v157
	v_mad_i64_i32 v[40:41], s[22:23], v40, s71, v[144:145]
	v_cvt_pk_bf16_f32 v51, v42, v43
	global_store_dwordx4 v[64:65], v[48:51], off offset:256
	s_nop 1
	v_lshl_add_u64 v[48:49], v[40:41], 0, v[146:147]
	v_cvt_pk_bf16_f32 v40, v52, v53
	v_cvt_pk_bf16_f32 v41, v54, v55
	v_cvt_pk_bf16_f32 v42, v44, v45
	v_cvt_pk_bf16_f32 v43, v46, v47
	global_store_dwordx4 v[48:49], v[40:43], off
	v_cvt_pk_bf16_f32 v32, v32, v33
	v_cvt_pk_bf16_f32 v33, v34, v35
	v_cvt_pk_bf16_f32 v34, v24, v25
	v_add_u32_e32 v24, 0xa0, v157
	v_mad_i64_i32 v[24:25], s[22:23], v24, s71, v[144:145]
	v_cvt_pk_bf16_f32 v35, v26, v27
	global_store_dwordx4 v[48:49], v[32:35], off offset:256
	s_nop 1
	v_lshl_add_u64 v[32:33], v[24:25], 0, v[146:147]
	v_cvt_pk_bf16_f32 v24, v36, v37
	v_cvt_pk_bf16_f32 v25, v38, v39
	v_cvt_pk_bf16_f32 v26, v28, v29
	v_cvt_pk_bf16_f32 v27, v30, v31
	global_store_dwordx4 v[32:33], v[24:27], off
	v_cvt_pk_bf16_f32 v16, v16, v17
	v_cvt_pk_bf16_f32 v17, v18, v19
	v_cvt_pk_bf16_f32 v18, v8, v9
	v_add_u32_e32 v8, 0xb0, v157
	v_mad_i64_i32 v[8:9], s[22:23], v8, s71, v[144:145]
	v_cvt_pk_bf16_f32 v19, v10, v11
	global_store_dwordx4 v[32:33], v[16:19], off offset:256
	s_mov_b64 s[22:23], s[18:19]
	s_nop 0
	v_lshl_add_u64 v[16:17], v[8:9], 0, v[146:147]
	v_cvt_pk_bf16_f32 v8, v20, v21
	v_cvt_pk_bf16_f32 v9, v22, v23
	v_cvt_pk_bf16_f32 v10, v12, v13
	v_cvt_pk_bf16_f32 v11, v14, v15
	global_store_dwordx4 v[16:17], v[8:11], off
	v_cvt_pk_bf16_f32 v4, v4, v5
	v_cvt_pk_bf16_f32 v5, v6, v7
	v_cvt_pk_bf16_f32 v6, v0, v1
	v_cvt_pk_bf16_f32 v7, v2, v3
	global_store_dwordx4 v[16:17], v[4:7], off offset:256
	s_cbranch_vccz .LBB0_129
	s_waitcnt vmcnt(0)
	s_cmpk_gt_u32 s28, 0xff
	s_cbranch_scc1 .LBB0_140
	s_barrier

; #define PG8_STAGE(bufoff, gbase, voff) do { _Pragma("unroll") for (int _i = 0; _i < 2; ++_i) \
;         __builtin_amdgcn_global_load_lds((const unsigned*)((const char*)(gbase) + (voff)[_i]), (LAS unsigned*)(lds + (bufoff) + ldsw + _i * 8192), 16, 0, 0); } while (0)
; #define PG8_LDA(dst, b, h) do { _Pragma("unroll") for (int m = 0; m < 4; ++m) _Pragma("unroll") for (int k = 0; k < 2; ++k) dst[m][k] = *(const LAS bf16x8*)(lds + PG8_SA(b, h) + aoff + m * 2048 + k * 1024); } while (0)
; #define PG8_LDB(dst, b, h) do { _Pragma("unroll") for (int n = 0; n < 2; ++n) _Pragma("unroll") for (int k = 0; k < 2; ++k) dst[n][k] = *(const LAS bf16x8*)(lds + PG8_SB(b, h) + boff + n * 2048 + k * 1024); } while (0)
; #define PG8_MMA(ai, bj, At, Bt) do { __builtin_amdgcn_s_setprio(1); _Pragma("unroll") for (int m = 0; m < 4; ++m) _Pragma("unroll") for (int n = 0; n < 2; ++n) _Pragma("unroll") for (int k = 0; k < 2; ++k) \
;         acc[ai][bj][m][n] = __builtin_amdgcn_mfma_f32_16x16x32_bf16(Bt[n][k], At[m][k], acc[ai][bj][m][n], 0, 0, 0); __builtin_amdgcn_s_setprio(0); } while (0)
; #define PG8_WAIT_L(n) asm volatile("s_waitcnt lgkmcnt(" #n ")" ::: "memory")
; #define PG8_BAR __builtin_amdgcn_s_barrier()
; #define PG8_SCHED __builtin_amdgcn_sched_barrier(0)
; template <class Epi>
; __device__ __forceinline__ void gemm_phase(LAS unsigned char* lds, const Gemm g, const StaticOrder& S, const Epi& E) {
;     ...
;             const char* a2 = last ? nA : cA + (size_t)(t + 2) * kstep; const char* b2 = last ? nB : cB + (size_t)(t + 2) * kstep;
;             const char* a3 = a2 + kstep; const char* b3 = b2 + kstep;
;             PG8_LDB(B0, 0, 0); PG8_SCHED; PG8_LDA(At, 0, 0); PG8_STAGE(PG8_SA(1, 1), a1 + hstep, voffA);
;             PG8_WAIT_L(8); PG8_BAR; PG8_WAIT_L(0); PG8_MMA(0, 0, At, B0); PG8_BAR; PG8_SCHED;
;             PG8_LDB(B1, 0, 1); PG8_STAGE(PG8_SB(0, 0), b2, voffB);
;             PG8_BAR; PG8_WAIT_L(0); PG8_MMA(0, 1, At, B1); PG8_BAR;
;             PG8_LDA(At, 0, 1); PG8_STAGE(PG8_SA(0, 0), a2, voffA);
;             PG8_BAR; PG8_WAIT_L(0); PG8_MMA(1, 0, At, B0); PG8_BAR; PG8_SCHED;
.LBB0_739:
	ds_read_b128 v[64:67], v198
	ds_read_b128 v[68:71], v198 offset:1024
	ds_read_b128 v[80:83], v198 offset:2048
	ds_read_b128 v[84:87], v198 offset:3072
	s_add_u32 s40, s34, 0xfffc0080
	s_addc_u32 s41, s35, -1
	s_cmp_eq_u32 s63, 12
	s_cselect_b32 s43, s25, s41
	s_cselect_b32 s42, s59, s40
	s_cselect_b32 s41, s23, s62
	s_cselect_b32 s40, s60, s61
	v_lshl_add_u64 v[202:203], s[34:35], 0, v[172:173]
	s_add_i32 m0, s31, 0xc000
	ds_read_b128 v[144:147], v199
	ds_read_b128 v[148:151], v199 offset:1024
	ds_read_b128 v[152:155], v199 offset:2048
	ds_read_b128 v[156:159], v199 offset:3072
	ds_read_b128 v[160:163], v199 offset:4096
	ds_read_b128 v[180:183], v199 offset:5120
	ds_read_b128 v[184:187], v199 offset:6144
	ds_read_b128 v[188:191], v199 offset:7168
	global_load_lds_dwordx4 v[202:203], off
	v_lshl_add_u64 v[202:203], s[34:35], 0, v[174:175]
	s_add_i32 m0, s31, 0xe000
	s_nop 0
	global_load_lds_dwordx4 v[202:203], off
	s_waitcnt lgkmcnt(8)
	s_barrier
	s_waitcnt lgkmcnt(0)
	s_waitcnt lgkmcnt(0)
	v_mfma_f32_16x16x32_bf16 v[140:143], v[64:67], v[144:147], v[140:143]
	v_mfma_f32_16x16x32_bf16 v[136:139], v[80:83], v[144:147], v[136:139]
	v_mfma_f32_16x16x32_bf16 v[124:127], v[64:67], v[152:155], v[124:127]
	v_mfma_f32_16x16x32_bf16 v[120:123], v[80:83], v[152:155], v[120:123]
	v_mfma_f32_16x16x32_bf16 v[108:111], v[64:67], v[160:163], v[108:111]
	v_mfma_f32_16x16x32_bf16 v[104:107], v[80:83], v[160:163], v[104:107]
	v_mfma_f32_16x16x32_bf16 v[92:95], v[64:67], v[184:187], v[92:95]
	v_mfma_f32_16x16x32_bf16 v[88:91], v[80:83], v[184:187], v[88:91]
	v_mfma_f32_16x16x32_bf16 v[140:143], v[68:71], v[148:151], v[140:143]
	v_mfma_f32_16x16x32_bf16 v[136:139], v[84:87], v[148:151], v[136:139]
	v_mfma_f32_16x16x32_bf16 v[124:127], v[68:71], v[156:159], v[124:127]
	v_mfma_f32_16x16x32_bf16 v[120:123], v[84:87], v[156:159], v[120:123]
	v_mfma_f32_16x16x32_bf16 v[108:111], v[68:71], v[180:183], v[108:111]
	v_mfma_f32_16x16x32_bf16 v[104:107], v[84:87], v[180:183], v[104:107]
	v_mfma_f32_16x16x32_bf16 v[92:95], v[68:71], v[188:191], v[92:95]
	v_mfma_f32_16x16x32_bf16 v[88:91], v[84:87], v[188:191], v[88:91]
	s_barrier
	s_add_i32 s64, s56, s44
	v_lshl_add_u64 v[220:221], s[40:41], 0, v[166:167]
	s_mov_b32 m0, s64
	ds_read_b128 v[202:205], v200
	ds_read_b128 v[206:209], v200 offset:1024
	ds_read_b128 v[210:213], v200 offset:2048
	ds_read_b128 v[216:219], v200 offset:3072
	global_load_lds_dwordx4 v[220:221], off
	v_lshl_add_u64 v[222:223], s[40:41], 0, v[170:171]
	s_add_i32 m0, s64, 0x2000
	s_nop 0
	global_load_lds_dwordx4 v[222:223], off
	s_barrier
	s_waitcnt lgkmcnt(0)
	s_waitcnt lgkmcnt(0)
	v_mfma_f32_16x16x32_bf16 v[132:135], v[202:205], v[144:147], v[132:135]
	v_mfma_f32_16x16x32_bf16 v[128:131], v[210:213], v[144:147], v[128:131]
	v_mfma_f32_16x16x32_bf16 v[116:119], v[202:205], v[152:155], v[116:119]
	v_mfma_f32_16x16x32_bf16 v[112:115], v[210:213], v[152:155], v[112:115]
	v_mfma_f32_16x16x32_bf16 v[100:103], v[202:205], v[160:163], v[100:103]
	v_mfma_f32_16x16x32_bf16 v[96:99], v[210:213], v[160:163], v[96:99]
	v_mfma_f32_16x16x32_bf16 v[76:79], v[202:205], v[184:187], v[76:79]
	v_mfma_f32_16x16x32_bf16 v[72:75], v[210:213], v[184:187], v[72:75]
	v_mfma_f32_16x16x32_bf16 v[132:135], v[206:209], v[148:151], v[132:135]
	v_mfma_f32_16x16x32_bf16 v[128:131], v[216:219], v[148:151], v[128:131]
	v_mfma_f32_16x16x32_bf16 v[116:119], v[206:209], v[156:159], v[116:119]
	v_mfma_f32_16x16x32_bf16 v[112:115], v[216:219], v[156:159], v[112:115]
	v_mfma_f32_16x16x32_bf16 v[100:103], v[206:209], v[180:183], v[100:103]
	v_mfma_f32_16x16x32_bf16 v[96:99], v[216:219], v[180:183], v[96:99]
	v_mfma_f32_16x16x32_bf16 v[76:79], v[206:209], v[188:191], v[76:79]
	v_mfma_f32_16x16x32_bf16 v[72:75], v[216:219], v[188:191], v[72:75]
	s_mov_b32 m0, s31
	v_lshl_add_u64 v[224:225], s[42:43], 0, v[164:165]
	s_barrier
	ds_read_b128 v[144:147], v199 offset:16384
	ds_read_b128 v[148:151], v199 offset:17408
	ds_read_b128 v[152:155], v199 offset:18432
	ds_read_b128 v[156:159], v199 offset:19456
	ds_read_b128 v[160:163], v199 offset:20480
	ds_read_b128 v[180:183], v199 offset:21504
	ds_read_b128 v[184:187], v199 offset:22528
	ds_read_b128 v[188:191], v199 offset:23552
	global_load_lds_dwordx4 v[224:225], off
	v_lshl_add_u64 v[226:227], s[42:43], 0, v[168:169]
	s_mov_b32 m0, s45
	s_nop 0
	global_load_lds_dwordx4 v[226:227], off
	s_barrier
	s_waitcnt lgkmcnt(0)
	s_waitcnt lgkmcnt(0)
	v_mfma_f32_16x16x32_bf16 v[60:63], v[64:67], v[144:147], v[60:63]
	v_mfma_f32_16x16x32_bf16 v[56:59], v[80:83], v[144:147], v[56:59]
	v_mfma_f32_16x16x32_bf16 v[44:47], v[64:67], v[152:155], v[44:47]
	v_mfma_f32_16x16x32_bf16 v[40:43], v[80:83], v[152:155], v[40:43]
	v_mfma_f32_16x16x32_bf16 v[28:31], v[64:67], v[160:163], v[28:31]
	v_mfma_f32_16x16x32_bf16 v[24:27], v[80:83], v[160:163], v[24:27]
	v_mfma_f32_16x16x32_bf16 v[12:15], v[64:67], v[184:187], v[12:15]
	v_mfma_f32_16x16x32_bf16 v[8:11], v[80:83], v[184:187], v[8:11]
	v_mfma_f32_16x16x32_bf16 v[60:63], v[68:71], v[148:151], v[60:63]
	v_mfma_f32_16x16x32_bf16 v[56:59], v[84:87], v[148:151], v[56:59]
	v_mfma_f32_16x16x32_bf16 v[44:47], v[68:71], v[156:159], v[44:47]
	v_mfma_f32_16x16x32_bf16 v[40:43], v[84:87], v[156:159], v[40:43]
	v_mfma_f32_16x16x32_bf16 v[28:31], v[68:71], v[180:183], v[28:31]
	v_mfma_f32_16x16x32_bf16 v[24:27], v[84:87], v[180:183], v[24:27]
	v_mfma_f32_16x16x32_bf16 v[12:15], v[68:71], v[188:191], v[12:15]
	v_mfma_f32_16x16x32_bf16 v[8:11], v[84:87], v[188:191], v[8:11]
	s_barrier
; #define PG8_STAGE(bufoff, gbase, voff) do { _Pragma("unroll") for (int _i = 0; _i < 2; ++_i) \
;         __builtin_amdgcn_global_load_lds((const unsigned*)((const char*)(gbase) + (voff)[_i]), (LAS unsigned*)(lds + (bufoff) + ldsw + _i * 8192), 16, 0, 0); } while (0)
; #define PG8_LDA(dst, b, h) do { _Pragma("unroll") for (int m = 0; m < 4; ++m) _Pragma("unroll") for (int k = 0; k < 2; ++k) dst[m][k] = *(const LAS bf16x8*)(lds + PG8_SA(b, h) + aoff + m * 2048 + k * 1024); } while (0)
; #define PG8_LDB(dst, b, h) do { _Pragma("unroll") for (int n = 0; n < 2; ++n) _Pragma("unroll") for (int k = 0; k < 2; ++k) dst[n][k] = *(const LAS bf16x8*)(lds + PG8_SB(b, h) + boff + n * 2048 + k * 1024); } while (0)
; #define PG8_MMA(ai, bj, At, Bt) do { __builtin_amdgcn_s_setprio(1); _Pragma("unroll") for (int m = 0; m < 4; ++m) _Pragma("unroll") for (int n = 0; n < 2; ++n) _Pragma("unroll") for (int k = 0; k < 2; ++k) \
;         acc[ai][bj][m][n] = __builtin_amdgcn_mfma_f32_16x16x32_bf16(Bt[n][k], At[m][k], acc[ai][bj][m][n], 0, 0, 0); __builtin_amdgcn_s_setprio(0); } while (0)
; #define PG8_WAIT_V(n) asm volatile("s_waitcnt vmcnt(" #n ")" ::: "memory")
; #define PG8_WAIT_L(n) asm volatile("s_waitcnt lgkmcnt(" #n ")" ::: "memory")
; #define PG8_BAR __builtin_amdgcn_s_barrier()
; #define PG8_SCHED __builtin_amdgcn_sched_barrier(0)
; template <class Epi>
; __device__ __forceinline__ void gemm_phase(LAS unsigned char* lds, const Gemm g, const StaticOrder& S, const Epi& E) {
;     ...
;             PG8_STAGE(PG8_SB(0, 1), b2 + hstep, voffB);
;             PG8_WAIT_V(6); PG8_BAR; PG8_MMA(1, 1, At, B1); PG8_BAR;
;             PG8_LDB(B0, 1, 0); PG8_SCHED; PG8_LDA(At, 1, 0); PG8_STAGE(PG8_SA(0, 1), a2 + hstep, voffA);
;             PG8_WAIT_L(8); PG8_BAR; PG8_WAIT_L(0); PG8_MMA(0, 0, At, B0); PG8_BAR; PG8_SCHED;
;             PG8_LDB(B1, 1, 1); PG8_STAGE(PG8_SB(1, 0), b3, voffB);
;             PG8_BAR; PG8_WAIT_L(0); PG8_MMA(0, 1, At, B1); PG8_BAR;
;             PG8_LDA(At, 1, 1); PG8_STAGE(PG8_SA(1, 0), a3, voffA);
;             PG8_BAR; PG8_WAIT_L(0); PG8_MMA(1, 0, At, B0); PG8_BAR; PG8_SCHED;
	s_add_u32 s64, s40, 0x40000
	s_addc_u32 s65, s41, 0
	s_add_i32 s66, s57, s44
	v_lshl_add_u64 v[64:65], s[64:65], 0, v[166:167]
	s_mov_b32 m0, s66
	s_nop 0
	global_load_lds_dwordx4 v[64:65], off
	v_lshl_add_u64 v[64:65], s[64:65], 0, v[170:171]
	s_add_i32 m0, s66, 0x2000
	s_nop 0
	global_load_lds_dwordx4 v[64:65], off
	s_waitcnt vmcnt(6)
	s_barrier
	v_mfma_f32_16x16x32_bf16 v[52:55], v[202:205], v[144:147], v[52:55]
	v_mfma_f32_16x16x32_bf16 v[48:51], v[210:213], v[144:147], v[48:51]
	v_mfma_f32_16x16x32_bf16 v[36:39], v[202:205], v[152:155], v[36:39]
	v_mfma_f32_16x16x32_bf16 v[32:35], v[210:213], v[152:155], v[32:35]
	v_mfma_f32_16x16x32_bf16 v[20:23], v[202:205], v[160:163], v[20:23]
	v_mfma_f32_16x16x32_bf16 v[16:19], v[210:213], v[160:163], v[16:19]
	v_mfma_f32_16x16x32_bf16 v[4:7], v[202:205], v[184:187], v[4:7]
	v_mfma_f32_16x16x32_bf16 v[0:3], v[210:213], v[184:187], v[0:3]
	v_mfma_f32_16x16x32_bf16 v[52:55], v[206:209], v[148:151], v[52:55]
	v_mfma_f32_16x16x32_bf16 v[48:51], v[216:219], v[148:151], v[48:51]
	v_mfma_f32_16x16x32_bf16 v[36:39], v[206:209], v[156:159], v[36:39]
	v_mfma_f32_16x16x32_bf16 v[32:35], v[216:219], v[156:159], v[32:35]
	v_mfma_f32_16x16x32_bf16 v[20:23], v[206:209], v[180:183], v[20:23]
	v_mfma_f32_16x16x32_bf16 v[16:19], v[216:219], v[180:183], v[16:19]
	v_mfma_f32_16x16x32_bf16 v[4:7], v[206:209], v[188:191], v[4:7]
	v_mfma_f32_16x16x32_bf16 v[0:3], v[216:219], v[188:191], v[0:3]
	s_add_i32 s64, 0, 0x18000
	v_add_u32_e32 v84, s64, v196
	s_barrier
	ds_read_b128 v[64:67], v84
	ds_read_b128 v[68:71], v84 offset:1024
	ds_read_b128 v[80:83], v84 offset:2048
	ds_read_b128 v[84:87], v84 offset:3072
	s_add_u32 s42, s42, 0x40000
	s_addc_u32 s43, s43, 0
	s_mov_b32 m0, s46
	v_lshl_add_u64 v[202:203], s[42:43], 0, v[164:165]
	ds_read_b128 v[144:147], v199 offset:32768
	ds_read_b128 v[148:151], v199 offset:33792
	ds_read_b128 v[152:155], v199 offset:34816
	ds_read_b128 v[156:159], v199 offset:35840
	ds_read_b128 v[160:163], v199 offset:36864
	ds_read_b128 v[180:183], v199 offset:37888
	ds_read_b128 v[184:187], v199 offset:38912
	ds_read_b128 v[188:191], v199 offset:39936
	global_load_lds_dwordx4 v[202:203], off
	v_lshl_add_u64 v[202:203], s[42:43], 0, v[168:169]
	s_mov_b32 m0, s47
	s_nop 0
	global_load_lds_dwordx4 v[202:203], off
	s_waitcnt lgkmcnt(8)
	s_barrier
	s_waitcnt lgkmcnt(0)
	s_waitcnt lgkmcnt(0)
	v_mfma_f32_16x16x32_bf16 v[140:143], v[64:67], v[144:147], v[140:143]
	v_mfma_f32_16x16x32_bf16 v[136:139], v[80:83], v[144:147], v[136:139]
	v_mfma_f32_16x16x32_bf16 v[124:127], v[64:67], v[152:155], v[124:127]
	v_mfma_f32_16x16x32_bf16 v[120:123], v[80:83], v[152:155], v[120:123]
	v_mfma_f32_16x16x32_bf16 v[108:111], v[64:67], v[160:163], v[108:111]
	v_mfma_f32_16x16x32_bf16 v[104:107], v[80:83], v[160:163], v[104:107]
	v_mfma_f32_16x16x32_bf16 v[92:95], v[64:67], v[184:187], v[92:95]
	v_mfma_f32_16x16x32_bf16 v[88:91], v[80:83], v[184:187], v[88:91]
	v_mfma_f32_16x16x32_bf16 v[140:143], v[68:71], v[148:151], v[140:143]
	v_mfma_f32_16x16x32_bf16 v[136:139], v[84:87], v[148:151], v[136:139]
	v_mfma_f32_16x16x32_bf16 v[124:127], v[68:71], v[156:159], v[124:127]
	v_mfma_f32_16x16x32_bf16 v[120:123], v[84:87], v[156:159], v[120:123]
	v_mfma_f32_16x16x32_bf16 v[108:111], v[68:71], v[180:183], v[108:111]
	v_mfma_f32_16x16x32_bf16 v[104:107], v[84:87], v[180:183], v[104:107]
	v_mfma_f32_16x16x32_bf16 v[92:95], v[68:71], v[188:191], v[92:95]
	v_mfma_f32_16x16x32_bf16 v[88:91], v[84:87], v[188:191], v[88:91]
	s_barrier
	s_add_i32 s42, 0, 0x1c000
	s_add_i32 s43, s64, s44
	v_add_u32_e32 v201, s42, v196
	v_lshl_add_u64 v[220:221], v[220:221], 0, s[10:11]
	s_mov_b32 m0, s43
	ds_read_b128 v[202:205], v201
	ds_read_b128 v[206:209], v201 offset:1024
	ds_read_b128 v[210:213], v201 offset:2048
	ds_read_b128 v[216:219], v201 offset:3072
	global_load_lds_dwordx4 v[220:221], off
	v_lshl_add_u64 v[220:221], v[222:223], 0, s[10:11]
	s_add_i32 m0, s43, 0x2000
	s_nop 0
	global_load_lds_dwordx4 v[220:221], off
	s_barrier
	s_waitcnt lgkmcnt(0)
	s_waitcnt lgkmcnt(0)
	v_mfma_f32_16x16x32_bf16 v[132:135], v[202:205], v[144:147], v[132:135]
	v_mfma_f32_16x16x32_bf16 v[128:131], v[210:213], v[144:147], v[128:131]
	v_mfma_f32_16x16x32_bf16 v[116:119], v[202:205], v[152:155], v[116:119]
	v_mfma_f32_16x16x32_bf16 v[112:115], v[210:213], v[152:155], v[112:115]
	v_mfma_f32_16x16x32_bf16 v[100:103], v[202:205], v[160:163], v[100:103]
	v_mfma_f32_16x16x32_bf16 v[96:99], v[210:213], v[160:163], v[96:99]
	v_mfma_f32_16x16x32_bf16 v[76:79], v[202:205], v[184:187], v[76:79]
	v_mfma_f32_16x16x32_bf16 v[72:75], v[210:213], v[184:187], v[72:75]
	v_mfma_f32_16x16x32_bf16 v[132:135], v[206:209], v[148:151], v[132:135]
	v_mfma_f32_16x16x32_bf16 v[128:131], v[216:219], v[148:151], v[128:131]
	v_mfma_f32_16x16x32_bf16 v[116:119], v[206:209], v[156:159], v[116:119]
	v_mfma_f32_16x16x32_bf16 v[112:115], v[216:219], v[156:159], v[112:115]
	v_mfma_f32_16x16x32_bf16 v[100:103], v[206:209], v[180:183], v[100:103]
	v_mfma_f32_16x16x32_bf16 v[96:99], v[216:219], v[180:183], v[96:99]
	v_mfma_f32_16x16x32_bf16 v[76:79], v[206:209], v[188:191], v[76:79]
	v_mfma_f32_16x16x32_bf16 v[72:75], v[216:219], v[188:191], v[72:75]
	s_mov_b32 m0, s51
	v_lshl_add_u64 v[220:221], v[224:225], 0, s[10:11]
	s_barrier
	ds_read_b128 v[144:147], v199 offset:49152
	ds_read_b128 v[148:151], v199 offset:50176
	ds_read_b128 v[152:155], v199 offset:51200
	ds_read_b128 v[156:159], v199 offset:52224
	ds_read_b128 v[160:163], v199 offset:53248
	ds_read_b128 v[180:183], v199 offset:54272
	ds_read_b128 v[184:187], v199 offset:55296
	ds_read_b128 v[188:191], v199 offset:56320
	global_load_lds_dwordx4 v[220:221], off
	v_lshl_add_u64 v[220:221], v[226:227], 0, s[10:11]
	s_mov_b32 m0, s54
	s_nop 0
	global_load_lds_dwordx4 v[220:221], off
	s_barrier
; #define PG8_STAGE(bufoff, gbase, voff) do { _Pragma("unroll") for (int _i = 0; _i < 2; ++_i) \
;         __builtin_amdgcn_global_load_lds((const unsigned*)((const char*)(gbase) + (voff)[_i]), (LAS unsigned*)(lds + (bufoff) + ldsw + _i * 8192), 16, 0, 0); } while (0)
; #define PG8_MMA(ai, bj, At, Bt) do { __builtin_amdgcn_s_setprio(1); _Pragma("unroll") for (int m = 0; m < 4; ++m) _Pragma("unroll") for (int n = 0; n < 2; ++n) _Pragma("unroll") for (int k = 0; k < 2; ++k) \
;         acc[ai][bj][m][n] = __builtin_amdgcn_mfma_f32_16x16x32_bf16(Bt[n][k], At[m][k], acc[ai][bj][m][n], 0, 0, 0); __builtin_amdgcn_s_setprio(0); } while (0)
; #define PG8_WAIT_V(n) asm volatile("s_waitcnt vmcnt(" #n ")" ::: "memory")
; #define PG8_WAIT_L(n) asm volatile("s_waitcnt lgkmcnt(" #n ")" ::: "memory")
; #define PG8_BAR __builtin_amdgcn_s_barrier()
; #define PG8_SCHED __builtin_amdgcn_sched_barrier(0)
; template <class Epi>
; __device__ __forceinline__ void gemm_phase(LAS unsigned char* lds, const Gemm g, const StaticOrder& S, const Epi& E) {
;     ...
;             PG8_BAR; PG8_WAIT_L(0); PG8_MMA(1, 0, At, B0); PG8_BAR; PG8_SCHED;
;             PG8_STAGE(PG8_SB(1, 1), b3 + hstep, voffB);
;             PG8_WAIT_V(6); PG8_BAR; PG8_MMA(1, 1, At, B1); PG8_BAR;
;         }
;     __device__ __forceinline__ void operator()(const AccT& acc, const pg8::Unit& u, int wr, int wc, int fr, int fq) const {
;         const int row0 = u.pm * 256 + wr * 64 + fr, col0 = u.pn * 256 + wc * 32 + 8 * fq;
;         f32x4 bv[2][2];
; #pragma unroll
;         for (int bj = 0; bj < 2; ++bj)
; #pragma unroll
;             for (int n = 0; n < 2; ++n) bv[bj][n] = *(const f32x4*)(bias + col0 + bj * 128 + 4 * n);
; #pragma unroll
;         for (int ai = 0; ai < 2; ++ai) { u32x4 gw[4][2];
; #pragma unroll
;             for (int m = 0; m < 4; ++m)
; #pragma unroll
;                 for (int bj = 0; bj < 2; ++bj) gw[m][bj] = *(const u32x4*)(G + (size_t)(row0 + ai * 128 + m * 16) * 1024 + col0 + bj * 128);
	s_waitcnt lgkmcnt(0)
	s_waitcnt lgkmcnt(0)
	v_mfma_f32_16x16x32_bf16 v[60:63], v[64:67], v[144:147], v[60:63]
	v_mfma_f32_16x16x32_bf16 v[56:59], v[80:83], v[144:147], v[56:59]
	v_mfma_f32_16x16x32_bf16 v[44:47], v[64:67], v[152:155], v[44:47]
	v_mfma_f32_16x16x32_bf16 v[40:43], v[80:83], v[152:155], v[40:43]
	v_mfma_f32_16x16x32_bf16 v[28:31], v[64:67], v[160:163], v[28:31]
	v_mfma_f32_16x16x32_bf16 v[24:27], v[80:83], v[160:163], v[24:27]
	v_mfma_f32_16x16x32_bf16 v[12:15], v[64:67], v[184:187], v[12:15]
	v_mfma_f32_16x16x32_bf16 v[8:11], v[80:83], v[184:187], v[8:11]
	v_mfma_f32_16x16x32_bf16 v[60:63], v[68:71], v[148:151], v[60:63]
	v_mfma_f32_16x16x32_bf16 v[56:59], v[84:87], v[148:151], v[56:59]
	v_mfma_f32_16x16x32_bf16 v[44:47], v[68:71], v[156:159], v[44:47]
	v_mfma_f32_16x16x32_bf16 v[40:43], v[84:87], v[156:159], v[40:43]
	v_mfma_f32_16x16x32_bf16 v[28:31], v[68:71], v[180:183], v[28:31]
	v_mfma_f32_16x16x32_bf16 v[24:27], v[84:87], v[180:183], v[24:27]
	v_mfma_f32_16x16x32_bf16 v[12:15], v[68:71], v[188:191], v[12:15]
	v_mfma_f32_16x16x32_bf16 v[8:11], v[84:87], v[188:191], v[8:11]
	s_barrier
	s_add_u32 s40, s40, 0x40080
	s_addc_u32 s41, s41, 0
	s_add_i32 s42, s42, s44
	v_lshl_add_u64 v[64:65], s[40:41], 0, v[166:167]
	s_mov_b32 m0, s42
	s_nop 0
	global_load_lds_dwordx4 v[64:65], off
	v_lshl_add_u64 v[64:65], s[40:41], 0, v[170:171]
	s_add_i32 m0, s42, 0x2000
	s_nop 0
	global_load_lds_dwordx4 v[64:65], off
	s_waitcnt vmcnt(6)
	s_barrier
	v_mfma_f32_16x16x32_bf16 v[52:55], v[202:205], v[144:147], v[52:55]
	v_mfma_f32_16x16x32_bf16 v[48:51], v[210:213], v[144:147], v[48:51]
	v_mfma_f32_16x16x32_bf16 v[36:39], v[202:205], v[152:155], v[36:39]
	v_mfma_f32_16x16x32_bf16 v[32:35], v[210:213], v[152:155], v[32:35]
	v_mfma_f32_16x16x32_bf16 v[20:23], v[202:205], v[160:163], v[20:23]
	v_mfma_f32_16x16x32_bf16 v[16:19], v[210:213], v[160:163], v[16:19]
	v_mfma_f32_16x16x32_bf16 v[4:7], v[202:205], v[184:187], v[4:7]
	v_mfma_f32_16x16x32_bf16 v[0:3], v[210:213], v[184:187], v[0:3]
	v_mfma_f32_16x16x32_bf16 v[52:55], v[206:209], v[148:151], v[52:55]
	v_mfma_f32_16x16x32_bf16 v[48:51], v[216:219], v[148:151], v[48:51]
	v_mfma_f32_16x16x32_bf16 v[36:39], v[206:209], v[156:159], v[36:39]
	v_mfma_f32_16x16x32_bf16 v[32:35], v[216:219], v[156:159], v[32:35]
	v_mfma_f32_16x16x32_bf16 v[20:23], v[206:209], v[180:183], v[20:23]
	v_mfma_f32_16x16x32_bf16 v[16:19], v[216:219], v[180:183], v[16:19]
	v_mfma_f32_16x16x32_bf16 v[4:7], v[206:209], v[188:191], v[4:7]
	v_mfma_f32_16x16x32_bf16 v[0:3], v[216:219], v[188:191], v[0:3]
	s_add_i32 s63, s63, 2
	s_add_u32 s34, s34, 0x100
	s_addc_u32 s35, s35, 0
	s_add_u32 s61, s61, 0x100
	s_addc_u32 s62, s62, 0
	s_cmp_gt_u32 s63, 13
	s_barrier
	s_cbranch_scc0 .LBB0_739
	v_lshl_or_b32 v64, s58, 8, v197
	v_ashrrev_i32_e32 v65, 31, v64
	v_readlane_b32 s60, v245, 18
	v_lshl_add_u32 v144, s30, 8, v195
	v_readlane_b32 s66, v245, 24
	v_readlane_b32 s67, v245, 25
	v_ashrrev_i32_e32 v145, 31, v144
	v_lshlrev_b64 v[180:181], 1, v[64:65]
	v_lshl_add_u64 v[66:67], v[64:65], 2, s[66:67]
	v_lshlrev_b64 v[184:185], 11, v[144:145]
	v_lshl_add_u64 v[182:183], s[6:7], 0, v[180:181]
	global_load_dwordx4 v[84:87], v[66:67], off
	global_load_dwordx4 v[80:83], v[66:67], off offset:16
	global_load_dwordx4 v[68:71], v[66:67], off offset:512
	v_lshl_add_u64 v[64:65], v[182:183], 0, v[184:185]
	global_load_dwordx4 v[202:205], v[64:65], off
	global_load_dwordx4 v[206:209], v[64:65], off offset:256
	s_nop 0
	global_load_dwordx4 v[64:67], v[66:67], off offset:528
	v_or_b32_e32 v146, 16, v144
	v_or_b32_e32 v148, 32, v144
	v_or_b32_e32 v144, 48, v144
	v_ashrrev_i32_e32 v147, 31, v146
	v_ashrrev_i32_e32 v149, 31, v148
	v_ashrrev_i32_e32 v145, 31, v144
	v_lshlrev_b64 v[190:191], 11, v[146:147]
	v_lshlrev_b64 v[188:189], 11, v[148:149]
	v_lshlrev_b64 v[186:187], 11, v[144:145]
	v_lshl_add_u64 v[144:145], s[4:5], 0, v[184:185]
	v_lshl_add_u64 v[146:147], v[182:183], 0, v[190:191]
	v_lshl_add_u64 v[148:149], v[182:183], 0, v[188:189]
	v_lshl_add_u64 v[216:217], v[182:183], 0, v[186:187]
	v_lshl_add_u64 v[218:219], v[144:145], 0, v[180:181]
	global_load_dwordx4 v[210:213], v[146:147], off
	global_load_dwordx4 v[160:163], v[146:147], off offset:256
	global_load_dwordx4 v[156:159], v[148:149], off
	global_load_dwordx4 v[152:155], v[148:149], off offset:256
	s_nop 0
	global_load_dwordx4 v[148:151], v[216:217], off
	global_load_dwordx4 v[144:147], v[216:217], off offset:256
	s_and_b64 vcc, exec, s[2:3]
	s_mov_b32 s58, s22
	s_mov_b32 s30, s24
	s_mov_b64 s[40:41], s[28:29]
	s_mov_b64 s[34:35], s[26:27]
	v_readlane_b32 s61, v245, 19
	v_readlane_b32 s62, v245, 20
	v_readlane_b32 s63, v245, 21
	v_readlane_b32 s64, v245, 22
	v_readlane_b32 s65, v245, 23
	v_readlane_b32 s68, v245, 26
	v_readlane_b32 s69, v245, 27
	v_readlane_b32 s70, v245, 28
	v_readlane_b32 s71, v245, 29
	v_readlane_b32 s72, v245, 30
	v_readlane_b32 s73, v245, 31
	v_readlane_b32 s74, v245, 32
	v_readlane_b32 s75, v245, 33
	s_waitcnt vmcnt(0)
; __device__ __forceinline__ u32x4 pack8(const f32x4 v0, const f32x4 v1) { u32x4 w; w.x = cvt_pk_bf16(v0[0], v0[1]); w.y = cvt_pk_bf16(v0[2], v0[3]); w.z = cvt_pk_bf16(v1[0], v1[1]); w.w = cvt_pk_bf16(v1[2], v1[3]); return w; }
; __device__ __forceinline__ void unpack8(const u32x4 w, f32x4& v0, f32x4& v1) { v0 = (f32x4){bflo(w.x), bfhi(w.x), bflo(w.y), bfhi(w.y)}; v1 = (f32x4){bflo(w.z), bfhi(w.z), bflo(w.w), bfhi(w.w)}; }
; __device__ __forceinline__ f32x4 sig4(const f32x4 v) { return (f32x4){sigmoidf_(v[0]), sigmoidf_(v[1]), sigmoidf_(v[2]), sigmoidf_(v[3])}; }
;     __device__ __forceinline__ void operator()(const AccT& acc, const pg8::Unit& u, int wr, int wc, int fr, int fq) const {
;     ...
;         for (int ai = 0; ai < 2; ++ai) { u32x4 gw[4][2];
; #pragma unroll
;             for (int m = 0; m < 4; ++m)
; #pragma unroll
;                 for (int bj = 0; bj < 2; ++bj) gw[m][bj] = *(const u32x4*)(G + (size_t)(row0 + ai * 128 + m * 16) * 1024 + col0 + bj * 128);
; #pragma unroll
;             for (int m = 0; m < 4; ++m)
; #pragma unroll
;                 for (int bj = 0; bj < 2; ++bj) { f32x4 g0, g1; unpack8(gw[m][bj], g0, g1);
;                     *(u32x4*)(O + (size_t)(row0 + ai * 128 + m * 16) * 1024 + col0 + bj * 128) = pack8(g0 * sig4(acc[ai][bj][m][0] + bv[bj][0]), g1 * sig4(acc[ai][bj][m][1] + bv[bj][1])); } }
	v_pk_add_f32 v[140:141], v[140:141], v[84:85]
	v_pk_add_f32 v[142:143], v[142:143], v[86:87]
	v_mul_f32_e32 v201, 0xbfb8aa3b, v140
	v_mul_f32_e32 v216, 0xbfb8aa3b, v141
	v_pk_add_f32 v[138:139], v[138:139], v[82:83]
	v_pk_add_f32 v[136:137], v[136:137], v[80:81]
	v_mul_f32_e32 v217, 0xbfb8aa3b, v142
	v_mul_f32_e32 v220, 0xbfb8aa3b, v143
	v_exp_f32_e32 v201, v201
	v_exp_f32_e32 v216, v216
	v_pk_add_f32 v[132:133], v[132:133], v[68:69]
	v_mul_f32_e32 v221, 0xbfb8aa3b, v136
	v_mul_f32_e32 v222, 0xbfb8aa3b, v137
	v_mul_f32_e32 v223, 0xbfb8aa3b, v138
	v_mul_f32_e32 v224, 0xbfb8aa3b, v139
	v_exp_f32_e32 v217, v217
	v_exp_f32_e32 v220, v220
	v_pk_add_f32 v[134:135], v[134:135], v[70:71]
	v_pk_add_f32 v[128:129], v[128:129], v[64:65]
	v_pk_add_f32 v[130:131], v[130:131], v[66:67]
	v_mul_f32_e32 v132, 0xbfb8aa3b, v132
	v_exp_f32_e32 v221, v221
	v_exp_f32_e32 v222, v222
	v_exp_f32_e32 v223, v223
	v_exp_f32_e32 v224, v224
	v_mul_f32_e32 v133, 0xbfb8aa3b, v133
	v_mul_f32_e32 v134, 0xbfb8aa3b, v134
	v_mul_f32_e32 v135, 0xbfb8aa3b, v135
	v_mul_f32_e32 v128, 0xbfb8aa3b, v128
	v_mul_f32_e32 v129, 0xbfb8aa3b, v129
	v_mul_f32_e32 v130, 0xbfb8aa3b, v130
	v_mul_f32_e32 v131, 0xbfb8aa3b, v131
	v_exp_f32_e32 v132, v132
	v_exp_f32_e32 v133, v133
	v_exp_f32_e32 v134, v134
	v_exp_f32_e32 v135, v135
	v_exp_f32_e32 v128, v128
	v_exp_f32_e32 v129, v129
	v_exp_f32_e32 v130, v130
	v_exp_f32_e32 v131, v131
	v_pk_add_f32 v[124:125], v[124:125], v[84:85]
	v_lshlrev_b32_e32 v136, 16, v202
	v_and_b32_e32 v137, 0xffff0000, v202
	v_lshlrev_b32_e32 v138, 16, v203
	v_and_b32_e32 v139, 0xffff0000, v203
	v_lshlrev_b32_e32 v140, 16, v204
	v_and_b32_e32 v141, 0xffff0000, v204
	v_lshlrev_b32_e32 v142, 16, v205
	v_and_b32_e32 v143, 0xffff0000, v205
	v_lshlrev_b32_e32 v202, 16, v206
	v_and_b32_e32 v203, 0xffff0000, v206
	v_lshlrev_b32_e32 v204, 16, v207
	v_and_b32_e32 v205, 0xffff0000, v207
	v_lshlrev_b32_e32 v206, 16, v208
	v_and_b32_e32 v207, 0xffff0000, v208
	v_add_f32_e32 v201, 1.0, v201
	v_add_f32_e32 v208, 1.0, v216
	v_mul_f32_e32 v124, 0xbfb8aa3b, v124
	v_mul_f32_e32 v125, 0xbfb8aa3b, v125
	v_pk_add_f32 v[120:121], v[120:121], v[80:81]
	v_pk_add_f32 v[122:123], v[122:123], v[82:83]
	v_add_f32_e32 v225, 1.0, v217
	v_add_f32_e32 v226, 1.0, v220
	v_rcp_f32_e32 v216, v201
	v_rcp_f32_e32 v217, v208
	v_exp_f32_e32 v124, v124
	v_pk_add_f32 v[126:127], v[126:127], v[86:87]
	v_exp_f32_e32 v125, v125
	v_mul_f32_e32 v120, 0xbfb8aa3b, v120
	v_mul_f32_e32 v121, 0xbfb8aa3b, v121
	v_mul_f32_e32 v122, 0xbfb8aa3b, v122
	v_mul_f32_e32 v123, 0xbfb8aa3b, v123
	v_add_f32_e32 v227, 1.0, v221
	v_add_f32_e32 v228, 1.0, v222
	v_add_f32_e32 v223, 1.0, v223
	v_add_f32_e32 v229, 1.0, v224
	v_rcp_f32_e32 v220, v225
	v_rcp_f32_e32 v221, v226
	v_mul_f32_e32 v126, 0xbfb8aa3b, v126
	v_mul_f32_e32 v127, 0xbfb8aa3b, v127
	v_exp_f32_e32 v120, v120
	v_exp_f32_e32 v121, v121
	v_exp_f32_e32 v122, v122
	v_exp_f32_e32 v123, v123
	v_rcp_f32_e32 v222, v227
	v_rcp_f32_e32 v224, v223
	v_rcp_f32_e32 v225, v229
	v_rcp_f32_e32 v223, v228
	v_add_f32_e32 v132, 1.0, v132
	v_add_f32_e32 v133, 1.0, v133
	v_add_f32_e32 v134, 1.0, v134
	v_add_f32_e32 v135, 1.0, v135
	v_add_f32_e32 v128, 1.0, v128
	v_add_f32_e32 v129, 1.0, v129
	v_add_f32_e32 v130, 1.0, v130
	v_add_f32_e32 v131, 1.0, v131
	v_exp_f32_e32 v126, v126
	v_exp_f32_e32 v127, v127
	v_pk_add_f32 v[116:117], v[116:117], v[68:69]
	v_pk_add_f32 v[118:119], v[118:119], v[70:71]
	v_pk_add_f32 v[112:113], v[112:113], v[64:65]
	v_pk_add_f32 v[114:115], v[114:115], v[66:67]
	v_rcp_f32_e32 v132, v132
	v_rcp_f32_e32 v133, v133
	v_rcp_f32_e32 v134, v134
	v_rcp_f32_e32 v135, v135
	v_rcp_f32_e32 v128, v128
	v_rcp_f32_e32 v130, v130
	v_rcp_f32_e32 v131, v131
	v_rcp_f32_e32 v129, v129
	v_mul_f32_e32 v116, 0xbfb8aa3b, v116
	v_mul_f32_e32 v117, 0xbfb8aa3b, v117
	v_mul_f32_e32 v118, 0xbfb8aa3b, v118
	v_mul_f32_e32 v119, 0xbfb8aa3b, v119
	v_mul_f32_e32 v112, 0xbfb8aa3b, v112
	v_mul_f32_e32 v113, 0xbfb8aa3b, v113
	v_mul_f32_e32 v114, 0xbfb8aa3b, v114
	v_mul_f32_e32 v115, 0xbfb8aa3b, v115
	v_pk_mul_f32 v[136:137], v[216:217], v[136:137]
	v_add_f32_e32 v124, 1.0, v124
	v_add_f32_e32 v125, 1.0, v125
	v_exp_f32_e32 v116, v116
	v_exp_f32_e32 v117, v117
	v_exp_f32_e32 v118, v118
	v_exp_f32_e32 v119, v119
	v_exp_f32_e32 v112, v112
	v_exp_f32_e32 v113, v113
	v_exp_f32_e32 v114, v114
	v_exp_f32_e32 v115, v115
	v_pk_add_f32 v[108:109], v[108:109], v[84:85]
	v_pk_mul_f32 v[138:139], v[220:221], v[138:139]
	v_cvt_pk_bf16_f32 v136, v136, v137
	v_rcp_f32_e32 v124, v124
	v_cvt_pk_bf16_f32 v137, v138, v139
	v_rcp_f32_e32 v125, v125
	v_add_f32_e32 v120, 1.0, v120
	v_add_f32_e32 v121, 1.0, v121
	v_add_f32_e32 v122, 1.0, v122
	v_add_f32_e32 v123, 1.0, v123
	v_mul_f32_e32 v108, 0xbfb8aa3b, v108
	v_mul_f32_e32 v109, 0xbfb8aa3b, v109
	v_pk_add_f32 v[104:105], v[104:105], v[80:81]
	v_pk_add_f32 v[106:107], v[106:107], v[82:83]
	v_pk_mul_f32 v[142:143], v[224:225], v[142:143]
	v_pk_mul_f32 v[140:141], v[222:223], v[140:141]
	v_add_f32_e32 v126, 1.0, v126
	v_cvt_pk_bf16_f32 v138, v140, v141
	v_cvt_pk_bf16_f32 v139, v142, v143
	global_store_dwordx4 v[218:219], v[136:139], off
	v_add_f32_e32 v127, 1.0, v127
	v_rcp_f32_e32 v120, v120
	v_lshlrev_b32_e32 v136, 16, v209
	v_and_b32_e32 v137, 0xffff0000, v209
	v_rcp_f32_e32 v122, v122
	v_rcp_f32_e32 v123, v123
	v_rcp_f32_e32 v121, v121
	v_exp_f32_e32 v108, v108
	v_pk_add_f32 v[110:111], v[110:111], v[86:87]
	v_exp_f32_e32 v109, v109
	v_mul_f32_e32 v104, 0xbfb8aa3b, v104
	v_mul_f32_e32 v105, 0xbfb8aa3b, v105
	v_mul_f32_e32 v106, 0xbfb8aa3b, v106
	v_mul_f32_e32 v107, 0xbfb8aa3b, v107
	v_pk_mul_f32 v[134:135], v[134:135], v[204:205]
	v_pk_mul_f32 v[132:133], v[132:133], v[202:203]
; __device__ __forceinline__ u32x4 pack8(const f32x4 v0, const f32x4 v1) { u32x4 w; w.x = cvt_pk_bf16(v0[0], v0[1]); w.y = cvt_pk_bf16(v0[2], v0[3]); w.z = cvt_pk_bf16(v1[0], v1[1]); w.w = cvt_pk_bf16(v1[2], v1[3]); return w; }
; __device__ __forceinline__ void unpack8(const u32x4 w, f32x4& v0, f32x4& v1) { v0 = (f32x4){bflo(w.x), bfhi(w.x), bflo(w.y), bfhi(w.y)}; v1 = (f32x4){bflo(w.z), bfhi(w.z), bflo(w.w), bfhi(w.w)}; }
; __device__ __forceinline__ f32x4 sig4(const f32x4 v) { return (f32x4){sigmoidf_(v[0]), sigmoidf_(v[1]), sigmoidf_(v[2]), sigmoidf_(v[3])}; }
;     __device__ __forceinline__ void operator()(const AccT& acc, const pg8::Unit& u, int wr, int wc, int fr, int fq) const {
;     ...
;         for (int ai = 0; ai < 2; ++ai) { u32x4 gw[4][2];
; #pragma unroll
;             for (int m = 0; m < 4; ++m)
; #pragma unroll
;                 for (int bj = 0; bj < 2; ++bj) gw[m][bj] = *(const u32x4*)(G + (size_t)(row0 + ai * 128 + m * 16) * 1024 + col0 + bj * 128);
; #pragma unroll
;             for (int m = 0; m < 4; ++m)
; #pragma unroll
;                 for (int bj = 0; bj < 2; ++bj) { f32x4 g0, g1; unpack8(gw[m][bj], g0, g1);
;                     *(u32x4*)(O + (size_t)(row0 + ai * 128 + m * 16) * 1024 + col0 + bj * 128) = pack8(g0 * sig4(acc[ai][bj][m][0] + bv[bj][0]), g1 * sig4(acc[ai][bj][m][1] + bv[bj][1])); } }
	v_pk_mul_f32 v[136:137], v[130:131], v[136:137]
	v_pk_mul_f32 v[130:131], v[128:129], v[206:207]
	v_cvt_pk_bf16_f32 v128, v132, v133
	v_cvt_pk_bf16_f32 v129, v134, v135
	v_rcp_f32_e32 v126, v126
	v_rcp_f32_e32 v127, v127
	v_mul_f32_e32 v110, 0xbfb8aa3b, v110
	v_mul_f32_e32 v111, 0xbfb8aa3b, v111
	v_exp_f32_e32 v104, v104
	v_exp_f32_e32 v105, v105
	v_exp_f32_e32 v106, v106
	v_exp_f32_e32 v107, v107
	v_cvt_pk_bf16_f32 v130, v130, v131
	v_cvt_pk_bf16_f32 v131, v136, v137
	global_store_dwordx4 v[218:219], v[128:131], off offset:256
	v_add_f32_e32 v116, 1.0, v116
	v_add_f32_e32 v117, 1.0, v117
	v_lshlrev_b32_e32 v128, 16, v210
	v_and_b32_e32 v129, 0xffff0000, v210
	v_add_f32_e32 v118, 1.0, v118
	v_add_f32_e32 v119, 1.0, v119
	v_add_f32_e32 v112, 1.0, v112
	v_add_f32_e32 v113, 1.0, v113
	v_add_f32_e32 v114, 1.0, v114
	v_add_f32_e32 v115, 1.0, v115
	v_exp_f32_e32 v110, v110
	v_exp_f32_e32 v111, v111
	v_pk_add_f32 v[100:101], v[100:101], v[68:69]
	v_pk_add_f32 v[102:103], v[102:103], v[70:71]
	v_pk_add_f32 v[96:97], v[96:97], v[64:65]
	v_pk_add_f32 v[98:99], v[98:99], v[66:67]
	v_lshlrev_b32_e32 v132, 16, v212
	v_and_b32_e32 v133, 0xffff0000, v212
	v_lshlrev_b32_e32 v134, 16, v213
	v_and_b32_e32 v135, 0xffff0000, v213
	v_pk_mul_f32 v[124:125], v[124:125], v[128:129]
	v_rcp_f32_e32 v116, v116
	v_rcp_f32_e32 v117, v117
	v_rcp_f32_e32 v118, v118
	v_rcp_f32_e32 v119, v119
	v_rcp_f32_e32 v112, v112
	v_rcp_f32_e32 v114, v114
	v_rcp_f32_e32 v115, v115
	v_rcp_f32_e32 v113, v113
	v_mul_f32_e32 v100, 0xbfb8aa3b, v100
	v_mul_f32_e32 v101, 0xbfb8aa3b, v101
	v_mul_f32_e32 v102, 0xbfb8aa3b, v102
	v_mul_f32_e32 v103, 0xbfb8aa3b, v103
	v_mul_f32_e32 v96, 0xbfb8aa3b, v96
	v_mul_f32_e32 v97, 0xbfb8aa3b, v97
	v_mul_f32_e32 v98, 0xbfb8aa3b, v98
	v_mul_f32_e32 v99, 0xbfb8aa3b, v99
	v_lshlrev_b32_e32 v130, 16, v211
	v_and_b32_e32 v131, 0xffff0000, v211
	v_pk_mul_f32 v[128:129], v[122:123], v[134:135]
	v_pk_mul_f32 v[122:123], v[120:121], v[132:133]
	v_cvt_pk_bf16_f32 v120, v124, v125
	v_lshl_add_u64 v[124:125], s[4:5], 0, v[190:191]
	v_add_f32_e32 v108, 1.0, v108
	v_add_f32_e32 v109, 1.0, v109
	v_exp_f32_e32 v100, v100
	v_exp_f32_e32 v101, v101
	v_exp_f32_e32 v102, v102
	v_exp_f32_e32 v103, v103
	v_exp_f32_e32 v96, v96
	v_exp_f32_e32 v97, v97
	v_exp_f32_e32 v98, v98
	v_exp_f32_e32 v99, v99
	v_pk_add_f32 v[92:93], v[92:93], v[84:85]
	v_pk_mul_f32 v[126:127], v[126:127], v[130:131]
	v_lshl_add_u64 v[124:125], v[124:125], 0, v[180:181]
	v_cvt_pk_bf16_f32 v121, v126, v127
	v_cvt_pk_bf16_f32 v122, v122, v123
	v_cvt_pk_bf16_f32 v123, v128, v129
	v_rcp_f32_e32 v108, v108
	v_rcp_f32_e32 v109, v109
	v_add_f32_e32 v104, 1.0, v104
	v_add_f32_e32 v105, 1.0, v105
	v_add_f32_e32 v106, 1.0, v106
	v_add_f32_e32 v107, 1.0, v107
	v_mul_f32_e32 v92, 0xbfb8aa3b, v92
	v_mul_f32_e32 v93, 0xbfb8aa3b, v93
	v_pk_add_f32 v[88:89], v[88:89], v[80:81]
	v_pk_add_f32 v[90:91], v[90:91], v[82:83]
	global_store_dwordx4 v[124:125], v[120:123], off
	v_lshlrev_b32_e32 v126, 16, v162
	v_and_b32_e32 v127, 0xffff0000, v162
	v_lshlrev_b32_e32 v120, 16, v160
	v_and_b32_e32 v121, 0xffff0000, v160
	v_lshlrev_b32_e32 v122, 16, v161
	v_and_b32_e32 v123, 0xffff0000, v161
	v_lshlrev_b32_e32 v128, 16, v163
	v_and_b32_e32 v129, 0xffff0000, v163
	v_add_f32_e32 v110, 1.0, v110
	v_add_f32_e32 v111, 1.0, v111
	v_rcp_f32_e32 v104, v104
	v_rcp_f32_e32 v106, v106
	v_rcp_f32_e32 v107, v107
	v_rcp_f32_e32 v105, v105
	v_exp_f32_e32 v92, v92
	v_pk_add_f32 v[94:95], v[94:95], v[86:87]
	v_exp_f32_e32 v93, v93
	v_mul_f32_e32 v88, 0xbfb8aa3b, v88
	v_mul_f32_e32 v89, 0xbfb8aa3b, v89
	v_mul_f32_e32 v90, 0xbfb8aa3b, v90
	v_mul_f32_e32 v91, 0xbfb8aa3b, v91
	v_pk_mul_f32 v[118:119], v[118:119], v[122:123]
	v_pk_mul_f32 v[116:117], v[116:117], v[120:121]
	v_pk_mul_f32 v[120:121], v[114:115], v[128:129]
	v_pk_mul_f32 v[114:115], v[112:113], v[126:127]
	v_cvt_pk_bf16_f32 v112, v116, v117
	v_cvt_pk_bf16_f32 v113, v118, v119
	v_rcp_f32_e32 v110, v110
	v_rcp_f32_e32 v111, v111
	v_mul_f32_e32 v94, 0xbfb8aa3b, v94
	v_mul_f32_e32 v95, 0xbfb8aa3b, v95
	v_exp_f32_e32 v88, v88
	v_exp_f32_e32 v89, v89
	v_exp_f32_e32 v90, v90
	v_exp_f32_e32 v91, v91
	v_cvt_pk_bf16_f32 v114, v114, v115
	v_cvt_pk_bf16_f32 v115, v120, v121
	global_store_dwordx4 v[124:125], v[112:115], off offset:256
	v_add_f32_e32 v100, 1.0, v100
	v_add_f32_e32 v101, 1.0, v101
	v_lshlrev_b32_e32 v112, 16, v156
	v_and_b32_e32 v113, 0xffff0000, v156
	v_add_f32_e32 v102, 1.0, v102
	v_add_f32_e32 v103, 1.0, v103
	v_add_f32_e32 v96, 1.0, v96
	v_add_f32_e32 v97, 1.0, v97
	v_add_f32_e32 v98, 1.0, v98
	v_add_f32_e32 v99, 1.0, v99
	v_exp_f32_e32 v94, v94
	v_exp_f32_e32 v95, v95
	v_pk_add_f32 v[76:77], v[76:77], v[68:69]
	v_lshlrev_b32_e32 v116, 16, v158
	v_and_b32_e32 v117, 0xffff0000, v158
	v_lshlrev_b32_e32 v118, 16, v159
	v_and_b32_e32 v119, 0xffff0000, v159
	v_pk_mul_f32 v[108:109], v[108:109], v[112:113]
	v_rcp_f32_e32 v100, v100
	v_rcp_f32_e32 v101, v101
	v_rcp_f32_e32 v102, v102
	v_rcp_f32_e32 v103, v103
	v_rcp_f32_e32 v96, v96
	v_rcp_f32_e32 v98, v98
	v_rcp_f32_e32 v99, v99
	v_rcp_f32_e32 v97, v97
	v_mul_f32_e32 v76, 0xbfb8aa3b, v76
	v_mul_f32_e32 v77, 0xbfb8aa3b, v77
	v_pk_add_f32 v[72:73], v[72:73], v[64:65]
	v_pk_add_f32 v[74:75], v[74:75], v[66:67]
	v_lshlrev_b32_e32 v114, 16, v157
	v_and_b32_e32 v115, 0xffff0000, v157
	v_pk_mul_f32 v[112:113], v[106:107], v[118:119]
	v_pk_mul_f32 v[106:107], v[104:105], v[116:117]
	v_cvt_pk_bf16_f32 v104, v108, v109
	v_lshl_add_u64 v[108:109], s[4:5], 0, v[188:189]
	v_add_f32_e32 v92, 1.0, v92
	v_add_f32_e32 v93, 1.0, v93
	v_exp_f32_e32 v76, v76
	v_pk_add_f32 v[78:79], v[78:79], v[70:71]
	v_exp_f32_e32 v77, v77
	v_mul_f32_e32 v72, 0xbfb8aa3b, v72
; __device__ __forceinline__ u32x4 pack8(const f32x4 v0, const f32x4 v1) { u32x4 w; w.x = cvt_pk_bf16(v0[0], v0[1]); w.y = cvt_pk_bf16(v0[2], v0[3]); w.z = cvt_pk_bf16(v1[0], v1[1]); w.w = cvt_pk_bf16(v1[2], v1[3]); return w; }
; __device__ __forceinline__ void unpack8(const u32x4 w, f32x4& v0, f32x4& v1) { v0 = (f32x4){bflo(w.x), bfhi(w.x), bflo(w.y), bfhi(w.y)}; v1 = (f32x4){bflo(w.z), bfhi(w.z), bflo(w.w), bfhi(w.w)}; }
; __device__ __forceinline__ f32x4 sig4(const f32x4 v) { return (f32x4){sigmoidf_(v[0]), sigmoidf_(v[1]), sigmoidf_(v[2]), sigmoidf_(v[3])}; }
;     __device__ __forceinline__ void operator()(const AccT& acc, const pg8::Unit& u, int wr, int wc, int fr, int fq) const {
;     ...
;         for (int ai = 0; ai < 2; ++ai) { u32x4 gw[4][2];
; #pragma unroll
;             for (int m = 0; m < 4; ++m)
; #pragma unroll
;                 for (int bj = 0; bj < 2; ++bj) gw[m][bj] = *(const u32x4*)(G + (size_t)(row0 + ai * 128 + m * 16) * 1024 + col0 + bj * 128);
; #pragma unroll
;             for (int m = 0; m < 4; ++m)
; #pragma unroll
;                 for (int bj = 0; bj < 2; ++bj) { f32x4 g0, g1; unpack8(gw[m][bj], g0, g1);
;                     *(u32x4*)(O + (size_t)(row0 + ai * 128 + m * 16) * 1024 + col0 + bj * 128) = pack8(g0 * sig4(acc[ai][bj][m][0] + bv[bj][0]), g1 * sig4(acc[ai][bj][m][1] + bv[bj][1])); } }
	v_mul_f32_e32 v73, 0xbfb8aa3b, v73
	v_mul_f32_e32 v74, 0xbfb8aa3b, v74
	v_mul_f32_e32 v75, 0xbfb8aa3b, v75
	v_pk_mul_f32 v[110:111], v[110:111], v[114:115]
	v_lshl_add_u64 v[108:109], v[108:109], 0, v[180:181]
	v_cvt_pk_bf16_f32 v105, v110, v111
	v_cvt_pk_bf16_f32 v106, v106, v107
	v_cvt_pk_bf16_f32 v107, v112, v113
	v_rcp_f32_e32 v92, v92
	v_rcp_f32_e32 v93, v93
	v_add_f32_e32 v88, 1.0, v88
	v_add_f32_e32 v89, 1.0, v89
	v_add_f32_e32 v90, 1.0, v90
	v_add_f32_e32 v91, 1.0, v91
	v_mul_f32_e32 v78, 0xbfb8aa3b, v78
	v_mul_f32_e32 v79, 0xbfb8aa3b, v79
	v_exp_f32_e32 v72, v72
	v_exp_f32_e32 v73, v73
	v_exp_f32_e32 v74, v74
	v_exp_f32_e32 v75, v75
	global_store_dwordx4 v[108:109], v[104:107], off
	v_lshlrev_b32_e32 v110, 16, v154
	v_and_b32_e32 v111, 0xffff0000, v154
	v_lshlrev_b32_e32 v104, 16, v152
	v_and_b32_e32 v105, 0xffff0000, v152
	v_lshlrev_b32_e32 v106, 16, v153
	v_and_b32_e32 v107, 0xffff0000, v153
	v_lshlrev_b32_e32 v112, 16, v155
	v_and_b32_e32 v113, 0xffff0000, v155
	v_add_f32_e32 v94, 1.0, v94
	v_add_f32_e32 v95, 1.0, v95
	v_rcp_f32_e32 v88, v88
	v_rcp_f32_e32 v90, v90
	v_rcp_f32_e32 v91, v91
	v_rcp_f32_e32 v89, v89
	v_exp_f32_e32 v78, v78
	v_exp_f32_e32 v79, v79
	v_pk_mul_f32 v[102:103], v[102:103], v[106:107]
	v_pk_mul_f32 v[100:101], v[100:101], v[104:105]
	v_pk_mul_f32 v[104:105], v[98:99], v[112:113]
	v_pk_mul_f32 v[98:99], v[96:97], v[110:111]
	v_cvt_pk_bf16_f32 v96, v100, v101
	v_cvt_pk_bf16_f32 v97, v102, v103
	v_rcp_f32_e32 v94, v94
	v_rcp_f32_e32 v95, v95
	v_cvt_pk_bf16_f32 v98, v98, v99
	v_cvt_pk_bf16_f32 v99, v104, v105
	global_store_dwordx4 v[108:109], v[96:99], off offset:256
	v_add_f32_e32 v76, 1.0, v76
	v_add_f32_e32 v77, 1.0, v77
	v_lshlrev_b32_e32 v96, 16, v148
	v_and_b32_e32 v97, 0xffff0000, v148
	v_lshlrev_b32_e32 v100, 16, v150
	v_and_b32_e32 v101, 0xffff0000, v150
	v_lshlrev_b32_e32 v102, 16, v151
	v_and_b32_e32 v103, 0xffff0000, v151
	v_pk_mul_f32 v[92:93], v[92:93], v[96:97]
	v_rcp_f32_e32 v76, v76
	v_rcp_f32_e32 v77, v77
	v_add_f32_e32 v72, 1.0, v72
	v_add_f32_e32 v73, 1.0, v73
	v_add_f32_e32 v74, 1.0, v74
	v_add_f32_e32 v75, 1.0, v75
	v_lshlrev_b32_e32 v98, 16, v149
	v_and_b32_e32 v99, 0xffff0000, v149
	v_pk_mul_f32 v[96:97], v[90:91], v[102:103]
	v_pk_mul_f32 v[90:91], v[88:89], v[100:101]
	v_cvt_pk_bf16_f32 v88, v92, v93
	v_lshl_add_u64 v[92:93], s[4:5], 0, v[186:187]
	v_add_f32_e32 v78, 1.0, v78
	v_add_f32_e32 v79, 1.0, v79
	v_rcp_f32_e32 v72, v72
	v_rcp_f32_e32 v74, v74
	v_rcp_f32_e32 v75, v75
	v_rcp_f32_e32 v73, v73
	v_pk_mul_f32 v[94:95], v[94:95], v[98:99]
	v_lshl_add_u64 v[92:93], v[92:93], 0, v[180:181]
	v_cvt_pk_bf16_f32 v89, v94, v95
	v_rcp_f32_e32 v78, v78
	v_rcp_f32_e32 v79, v79
	v_cvt_pk_bf16_f32 v90, v90, v91
	v_cvt_pk_bf16_f32 v91, v96, v97
	global_store_dwordx4 v[92:93], v[88:91], off
	v_lshlrev_b32_e32 v94, 16, v146
	v_and_b32_e32 v95, 0xffff0000, v146
	v_lshlrev_b32_e32 v88, 16, v144
	v_and_b32_e32 v89, 0xffff0000, v144
	v_lshlrev_b32_e32 v96, 16, v147
	v_and_b32_e32 v97, 0xffff0000, v147
	v_pk_mul_f32 v[76:77], v[76:77], v[88:89]
	v_lshl_add_u64 v[118:119], v[184:185], 0, s[0:1]
	v_lshlrev_b32_e32 v90, 16, v145
	v_and_b32_e32 v91, 0xffff0000, v145
	v_pk_mul_f32 v[88:89], v[74:75], v[96:97]
	v_pk_mul_f32 v[74:75], v[72:73], v[94:95]
	v_cvt_pk_bf16_f32 v72, v76, v77
	v_lshl_add_u64 v[76:77], v[182:183], 0, v[118:119]
	v_pk_mul_f32 v[78:79], v[78:79], v[90:91]
	v_lshl_add_u64 v[104:105], v[184:185], 0, s[16:17]
	v_cvt_pk_bf16_f32 v73, v78, v79
	v_cvt_pk_bf16_f32 v74, v74, v75
	v_cvt_pk_bf16_f32 v75, v88, v89
	global_load_dwordx4 v[106:109], v[76:77], off
	global_load_dwordx4 v[110:113], v[76:77], off offset:256
	v_lshl_add_u64 v[102:103], v[184:185], 0, s[18:19]
	global_store_dwordx4 v[92:93], v[72:75], off offset:256
	v_lshl_add_u64 v[100:101], v[184:185], 0, s[20:21]
	v_pk_add_f32 v[60:61], v[60:61], v[84:85]
	v_lshl_add_u64 v[72:73], v[182:183], 0, v[104:105]
	global_load_dwordx4 v[114:117], v[72:73], off
	global_load_dwordx4 v[96:99], v[72:73], off offset:256
	v_lshl_add_u64 v[72:73], v[182:183], 0, v[102:103]
	global_load_dwordx4 v[92:95], v[72:73], off
	global_load_dwordx4 v[88:91], v[72:73], off offset:256
	v_lshl_add_u64 v[72:73], v[182:183], 0, v[100:101]
	global_load_dwordx4 v[76:79], v[72:73], off
	s_nop 0
	global_load_dwordx4 v[72:75], v[72:73], off offset:256
	v_mul_f32_e32 v60, 0xbfb8aa3b, v60
	v_pk_add_f32 v[62:63], v[62:63], v[86:87]
	v_mul_f32_e32 v61, 0xbfb8aa3b, v61
	v_pk_add_f32 v[56:57], v[56:57], v[80:81]
	v_pk_add_f32 v[58:59], v[58:59], v[82:83]
	v_exp_f32_e32 v60, v60
	v_exp_f32_e32 v61, v61
	v_mul_f32_e32 v62, 0xbfb8aa3b, v62
	v_mul_f32_e32 v63, 0xbfb8aa3b, v63
	v_mul_f32_e32 v56, 0xbfb8aa3b, v56
	v_mul_f32_e32 v57, 0xbfb8aa3b, v57
	v_mul_f32_e32 v58, 0xbfb8aa3b, v58
	v_mul_f32_e32 v59, 0xbfb8aa3b, v59
	v_exp_f32_e32 v62, v62
	v_exp_f32_e32 v63, v63
	v_exp_f32_e32 v56, v56
	v_exp_f32_e32 v57, v57
	v_exp_f32_e32 v58, v58
	v_exp_f32_e32 v59, v59
	v_pk_add_f32 v[52:53], v[52:53], v[68:69]
	v_pk_add_f32 v[54:55], v[54:55], v[70:71]
	v_pk_add_f32 v[48:49], v[48:49], v[64:65]
	v_pk_add_f32 v[50:51], v[50:51], v[66:67]
	v_mul_f32_e32 v52, 0xbfb8aa3b, v52
	v_mul_f32_e32 v53, 0xbfb8aa3b, v53
	v_mul_f32_e32 v54, 0xbfb8aa3b, v54
	v_mul_f32_e32 v55, 0xbfb8aa3b, v55
	v_mul_f32_e32 v48, 0xbfb8aa3b, v48
	v_mul_f32_e32 v49, 0xbfb8aa3b, v49
	v_mul_f32_e32 v50, 0xbfb8aa3b, v50
	v_mul_f32_e32 v51, 0xbfb8aa3b, v51
	v_add_f32_e32 v60, 1.0, v60
	v_add_f32_e32 v61, 1.0, v61
	v_exp_f32_e32 v52, v52
	v_exp_f32_e32 v53, v53
	v_exp_f32_e32 v54, v54
	v_exp_f32_e32 v55, v55
	v_exp_f32_e32 v48, v48
	v_exp_f32_e32 v49, v49
	v_exp_f32_e32 v50, v50
	v_exp_f32_e32 v51, v51
	v_pk_add_f32 v[44:45], v[44:45], v[84:85]
	v_rcp_f32_e32 v60, v60
	v_rcp_f32_e32 v61, v61
	v_add_f32_e32 v62, 1.0, v62
	v_add_f32_e32 v63, 1.0, v63
	v_add_f32_e32 v56, 1.0, v56
	v_add_f32_e32 v57, 1.0, v57
	v_add_f32_e32 v58, 1.0, v58
	v_add_f32_e32 v59, 1.0, v59
	v_mul_f32_e32 v44, 0xbfb8aa3b, v44
	v_mul_f32_e32 v45, 0xbfb8aa3b, v45
	v_pk_add_f32 v[40:41], v[40:41], v[80:81]
	v_pk_add_f32 v[42:43], v[42:43], v[82:83]
	v_rcp_f32_e32 v62, v62
	v_rcp_f32_e32 v63, v63
	v_rcp_f32_e32 v56, v56
	v_rcp_f32_e32 v58, v58
	v_rcp_f32_e32 v59, v59
	v_rcp_f32_e32 v57, v57
	v_exp_f32_e32 v44, v44
	v_pk_add_f32 v[46:47], v[46:47], v[86:87]
	v_exp_f32_e32 v45, v45
	v_mul_f32_e32 v40, 0xbfb8aa3b, v40
	v_mul_f32_e32 v41, 0xbfb8aa3b, v41
	v_mul_f32_e32 v42, 0xbfb8aa3b, v42
	v_mul_f32_e32 v43, 0xbfb8aa3b, v43
	v_mul_f32_e32 v46, 0xbfb8aa3b, v46
	v_mul_f32_e32 v47, 0xbfb8aa3b, v47
	v_exp_f32_e32 v40, v40
	v_exp_f32_e32 v41, v41
	v_exp_f32_e32 v42, v42
	v_exp_f32_e32 v43, v43
	s_waitcnt vmcnt(0)
; __device__ __forceinline__ u32x4 pack8(const f32x4 v0, const f32x4 v1) { u32x4 w; w.x = cvt_pk_bf16(v0[0], v0[1]); w.y = cvt_pk_bf16(v0[2], v0[3]); w.z = cvt_pk_bf16(v1[0], v1[1]); w.w = cvt_pk_bf16(v1[2], v1[3]); return w; }
; __device__ __forceinline__ void unpack8(const u32x4 w, f32x4& v0, f32x4& v1) { v0 = (f32x4){bflo(w.x), bfhi(w.x), bflo(w.y), bfhi(w.y)}; v1 = (f32x4){bflo(w.z), bfhi(w.z), bflo(w.w), bfhi(w.w)}; }
; __device__ __forceinline__ f32x4 sig4(const f32x4 v) { return (f32x4){sigmoidf_(v[0]), sigmoidf_(v[1]), sigmoidf_(v[2]), sigmoidf_(v[3])}; }
;     __device__ __forceinline__ void operator()(const AccT& acc, const pg8::Unit& u, int wr, int wc, int fr, int fq) const {
;     ...
;         for (int ai = 0; ai < 2; ++ai) { u32x4 gw[4][2];
; #pragma unroll
;             for (int m = 0; m < 4; ++m)
; #pragma unroll
;                 for (int bj = 0; bj < 2; ++bj) gw[m][bj] = *(const u32x4*)(G + (size_t)(row0 + ai * 128 + m * 16) * 1024 + col0 + bj * 128);
; #pragma unroll
;             for (int m = 0; m < 4; ++m)
; #pragma unroll
;                 for (int bj = 0; bj < 2; ++bj) { f32x4 g0, g1; unpack8(gw[m][bj], g0, g1);
;                     *(u32x4*)(O + (size_t)(row0 + ai * 128 + m * 16) * 1024 + col0 + bj * 128) = pack8(g0 * sig4(acc[ai][bj][m][0] + bv[bj][0]), g1 * sig4(acc[ai][bj][m][1] + bv[bj][1])); } }
	v_lshlrev_b32_e32 v120, 16, v106
	v_and_b32_e32 v121, 0xffff0000, v106
	v_add_f32_e32 v52, 1.0, v52
	v_add_f32_e32 v53, 1.0, v53
	v_add_f32_e32 v54, 1.0, v54
	v_add_f32_e32 v55, 1.0, v55
	v_add_f32_e32 v48, 1.0, v48
	v_add_f32_e32 v49, 1.0, v49
	v_add_f32_e32 v50, 1.0, v50
	v_add_f32_e32 v51, 1.0, v51
	v_exp_f32_e32 v46, v46
	v_exp_f32_e32 v47, v47
	v_pk_add_f32 v[36:37], v[36:37], v[68:69]
	v_pk_add_f32 v[38:39], v[38:39], v[70:71]
	v_pk_add_f32 v[32:33], v[32:33], v[64:65]
	v_pk_add_f32 v[34:35], v[34:35], v[66:67]
	v_lshlrev_b32_e32 v106, 16, v107
	v_and_b32_e32 v107, 0xffff0000, v107
	v_lshlrev_b32_e32 v122, 16, v108
	v_and_b32_e32 v123, 0xffff0000, v108
	v_lshlrev_b32_e32 v108, 16, v109
	v_and_b32_e32 v109, 0xffff0000, v109
	v_pk_mul_f32 v[60:61], v[60:61], v[120:121]
	v_rcp_f32_e32 v52, v52
	v_rcp_f32_e32 v53, v53
	v_rcp_f32_e32 v54, v54
	v_rcp_f32_e32 v55, v55
	v_rcp_f32_e32 v48, v48
	v_rcp_f32_e32 v50, v50
	v_rcp_f32_e32 v51, v51
	v_rcp_f32_e32 v49, v49
	v_mul_f32_e32 v36, 0xbfb8aa3b, v36
	v_mul_f32_e32 v37, 0xbfb8aa3b, v37
	v_mul_f32_e32 v38, 0xbfb8aa3b, v38
	v_mul_f32_e32 v39, 0xbfb8aa3b, v39
	v_mul_f32_e32 v32, 0xbfb8aa3b, v32
	v_mul_f32_e32 v33, 0xbfb8aa3b, v33
	v_mul_f32_e32 v34, 0xbfb8aa3b, v34
	v_mul_f32_e32 v35, 0xbfb8aa3b, v35
	v_pk_mul_f32 v[62:63], v[62:63], v[106:107]
	v_pk_mul_f32 v[106:107], v[58:59], v[108:109]
	v_pk_mul_f32 v[58:59], v[56:57], v[122:123]
	v_cvt_pk_bf16_f32 v56, v60, v61
	v_lshl_add_u64 v[60:61], s[4:5], 0, v[118:119]
	v_add_f32_e32 v44, 1.0, v44
	v_add_f32_e32 v45, 1.0, v45
	v_exp_f32_e32 v36, v36
	v_exp_f32_e32 v37, v37
	v_exp_f32_e32 v38, v38
	v_exp_f32_e32 v39, v39
	v_exp_f32_e32 v32, v32
	v_exp_f32_e32 v33, v33
	v_exp_f32_e32 v34, v34
	v_exp_f32_e32 v35, v35
	v_pk_add_f32 v[28:29], v[28:29], v[84:85]
	v_cvt_pk_bf16_f32 v57, v62, v63
	v_cvt_pk_bf16_f32 v58, v58, v59
	v_cvt_pk_bf16_f32 v59, v106, v107
	v_lshl_add_u64 v[60:61], v[60:61], 0, v[180:181]
	v_rcp_f32_e32 v44, v44
	v_rcp_f32_e32 v45, v45
	v_add_f32_e32 v40, 1.0, v40
	v_add_f32_e32 v41, 1.0, v41
	v_add_f32_e32 v42, 1.0, v42
	v_add_f32_e32 v43, 1.0, v43
	v_mul_f32_e32 v28, 0xbfb8aa3b, v28
	v_mul_f32_e32 v29, 0xbfb8aa3b, v29
	v_pk_add_f32 v[24:25], v[24:25], v[80:81]
	v_pk_add_f32 v[26:27], v[26:27], v[82:83]
	global_store_dwordx4 v[60:61], v[56:59], off
	v_lshlrev_b32_e32 v62, 16, v112
	v_and_b32_e32 v63, 0xffff0000, v112
	v_lshlrev_b32_e32 v56, 16, v110
	v_and_b32_e32 v57, 0xffff0000, v110
	v_lshlrev_b32_e32 v58, 16, v111
	v_and_b32_e32 v59, 0xffff0000, v111
	v_lshlrev_b32_e32 v106, 16, v113
	v_and_b32_e32 v107, 0xffff0000, v113
	v_add_f32_e32 v46, 1.0, v46
	v_add_f32_e32 v47, 1.0, v47
	v_rcp_f32_e32 v40, v40
	v_rcp_f32_e32 v42, v42
	v_rcp_f32_e32 v43, v43
	v_rcp_f32_e32 v41, v41
	v_exp_f32_e32 v28, v28
	v_pk_add_f32 v[30:31], v[30:31], v[86:87]
	v_exp_f32_e32 v29, v29
	v_mul_f32_e32 v24, 0xbfb8aa3b, v24
	v_mul_f32_e32 v25, 0xbfb8aa3b, v25
	v_mul_f32_e32 v26, 0xbfb8aa3b, v26
	v_mul_f32_e32 v27, 0xbfb8aa3b, v27
	v_pk_mul_f32 v[54:55], v[54:55], v[58:59]
	v_pk_mul_f32 v[52:53], v[52:53], v[56:57]
	v_pk_mul_f32 v[56:57], v[50:51], v[106:107]
	v_pk_mul_f32 v[50:51], v[48:49], v[62:63]
	v_cvt_pk_bf16_f32 v48, v52, v53
	v_cvt_pk_bf16_f32 v49, v54, v55
	v_rcp_f32_e32 v46, v46
	v_rcp_f32_e32 v47, v47
	v_mul_f32_e32 v30, 0xbfb8aa3b, v30
	v_mul_f32_e32 v31, 0xbfb8aa3b, v31
	v_exp_f32_e32 v24, v24
	v_exp_f32_e32 v25, v25
	v_exp_f32_e32 v26, v26
	v_exp_f32_e32 v27, v27
	v_cvt_pk_bf16_f32 v50, v50, v51
	v_cvt_pk_bf16_f32 v51, v56, v57
	global_store_dwordx4 v[60:61], v[48:51], off offset:256
	v_add_f32_e32 v36, 1.0, v36
	v_add_f32_e32 v37, 1.0, v37
	v_lshlrev_b32_e32 v48, 16, v114
	v_and_b32_e32 v49, 0xffff0000, v114
	v_add_f32_e32 v38, 1.0, v38
	v_add_f32_e32 v39, 1.0, v39
	v_add_f32_e32 v32, 1.0, v32
	v_add_f32_e32 v33, 1.0, v33
	v_add_f32_e32 v34, 1.0, v34
	v_add_f32_e32 v35, 1.0, v35
	v_exp_f32_e32 v30, v30
	v_exp_f32_e32 v31, v31
	v_pk_add_f32 v[20:21], v[20:21], v[68:69]
	v_pk_add_f32 v[22:23], v[22:23], v[70:71]
	v_pk_add_f32 v[16:17], v[16:17], v[64:65]
	v_pk_add_f32 v[18:19], v[18:19], v[66:67]
	v_lshlrev_b32_e32 v52, 16, v116
	v_and_b32_e32 v53, 0xffff0000, v116
	v_lshlrev_b32_e32 v54, 16, v117
	v_and_b32_e32 v55, 0xffff0000, v117
	v_pk_mul_f32 v[44:45], v[44:45], v[48:49]
	v_rcp_f32_e32 v36, v36
	v_rcp_f32_e32 v37, v37
	v_rcp_f32_e32 v38, v38
	v_rcp_f32_e32 v39, v39
	v_rcp_f32_e32 v32, v32
	v_rcp_f32_e32 v34, v34
	v_rcp_f32_e32 v35, v35
	v_rcp_f32_e32 v33, v33
	v_mul_f32_e32 v20, 0xbfb8aa3b, v20
	v_mul_f32_e32 v21, 0xbfb8aa3b, v21
	v_mul_f32_e32 v22, 0xbfb8aa3b, v22
	v_mul_f32_e32 v23, 0xbfb8aa3b, v23
	v_mul_f32_e32 v16, 0xbfb8aa3b, v16
	v_mul_f32_e32 v17, 0xbfb8aa3b, v17
	v_mul_f32_e32 v18, 0xbfb8aa3b, v18
	v_mul_f32_e32 v19, 0xbfb8aa3b, v19
	v_lshlrev_b32_e32 v50, 16, v115
	v_and_b32_e32 v51, 0xffff0000, v115
	v_pk_mul_f32 v[48:49], v[42:43], v[54:55]
	v_pk_mul_f32 v[42:43], v[40:41], v[52:53]
	v_cvt_pk_bf16_f32 v40, v44, v45
	v_lshl_add_u64 v[44:45], s[4:5], 0, v[104:105]
	v_add_f32_e32 v28, 1.0, v28
	v_add_f32_e32 v29, 1.0, v29
	v_exp_f32_e32 v20, v20
	v_exp_f32_e32 v21, v21
	v_exp_f32_e32 v22, v22
	v_exp_f32_e32 v23, v23
	v_exp_f32_e32 v16, v16
	v_exp_f32_e32 v17, v17
	v_exp_f32_e32 v18, v18
	v_exp_f32_e32 v19, v19
	v_pk_add_f32 v[12:13], v[12:13], v[84:85]
	v_pk_mul_f32 v[46:47], v[46:47], v[50:51]
	v_lshl_add_u64 v[44:45], v[44:45], 0, v[180:181]
	v_cvt_pk_bf16_f32 v41, v46, v47
	v_cvt_pk_bf16_f32 v42, v42, v43
	v_cvt_pk_bf16_f32 v43, v48, v49
	v_rcp_f32_e32 v28, v28
	v_rcp_f32_e32 v29, v29
	v_add_f32_e32 v24, 1.0, v24
	v_add_f32_e32 v25, 1.0, v25
	v_add_f32_e32 v26, 1.0, v26
	v_add_f32_e32 v27, 1.0, v27
	v_mul_f32_e32 v12, 0xbfb8aa3b, v12
; __device__ __forceinline__ u32x4 pack8(const f32x4 v0, const f32x4 v1) { u32x4 w; w.x = cvt_pk_bf16(v0[0], v0[1]); w.y = cvt_pk_bf16(v0[2], v0[3]); w.z = cvt_pk_bf16(v1[0], v1[1]); w.w = cvt_pk_bf16(v1[2], v1[3]); return w; }
; __device__ __forceinline__ void unpack8(const u32x4 w, f32x4& v0, f32x4& v1) { v0 = (f32x4){bflo(w.x), bfhi(w.x), bflo(w.y), bfhi(w.y)}; v1 = (f32x4){bflo(w.z), bfhi(w.z), bflo(w.w), bfhi(w.w)}; }
; __device__ __forceinline__ f32x4 sig4(const f32x4 v) { return (f32x4){sigmoidf_(v[0]), sigmoidf_(v[1]), sigmoidf_(v[2]), sigmoidf_(v[3])}; }
;     __device__ __forceinline__ void operator()(const AccT& acc, const pg8::Unit& u, int wr, int wc, int fr, int fq) const {
;     ...
;         for (int ai = 0; ai < 2; ++ai) { u32x4 gw[4][2];
; #pragma unroll
;             for (int m = 0; m < 4; ++m)
; #pragma unroll
;                 for (int bj = 0; bj < 2; ++bj) gw[m][bj] = *(const u32x4*)(G + (size_t)(row0 + ai * 128 + m * 16) * 1024 + col0 + bj * 128);
; #pragma unroll
;             for (int m = 0; m < 4; ++m)
; #pragma unroll
;                 for (int bj = 0; bj < 2; ++bj) { f32x4 g0, g1; unpack8(gw[m][bj], g0, g1);
;                     *(u32x4*)(O + (size_t)(row0 + ai * 128 + m * 16) * 1024 + col0 + bj * 128) = pack8(g0 * sig4(acc[ai][bj][m][0] + bv[bj][0]), g1 * sig4(acc[ai][bj][m][1] + bv[bj][1])); } }
	v_mul_f32_e32 v13, 0xbfb8aa3b, v13
	v_pk_add_f32 v[8:9], v[8:9], v[80:81]
	v_pk_add_f32 v[10:11], v[10:11], v[82:83]
	global_store_dwordx4 v[44:45], v[40:43], off
	v_lshlrev_b32_e32 v46, 16, v98
	v_and_b32_e32 v47, 0xffff0000, v98
	v_lshlrev_b32_e32 v40, 16, v96
	v_and_b32_e32 v41, 0xffff0000, v96
	v_lshlrev_b32_e32 v42, 16, v97
	v_and_b32_e32 v43, 0xffff0000, v97
	v_lshlrev_b32_e32 v48, 16, v99
	v_and_b32_e32 v49, 0xffff0000, v99
	v_add_f32_e32 v30, 1.0, v30
	v_add_f32_e32 v31, 1.0, v31
	v_rcp_f32_e32 v24, v24
	v_rcp_f32_e32 v26, v26
	v_rcp_f32_e32 v27, v27
	v_rcp_f32_e32 v25, v25
	v_exp_f32_e32 v12, v12
	v_pk_add_f32 v[14:15], v[14:15], v[86:87]
	v_exp_f32_e32 v13, v13
	v_mul_f32_e32 v8, 0xbfb8aa3b, v8
	v_mul_f32_e32 v9, 0xbfb8aa3b, v9
	v_mul_f32_e32 v10, 0xbfb8aa3b, v10
	v_mul_f32_e32 v11, 0xbfb8aa3b, v11
	v_pk_mul_f32 v[38:39], v[38:39], v[42:43]
	v_pk_mul_f32 v[36:37], v[36:37], v[40:41]
	v_pk_mul_f32 v[40:41], v[34:35], v[48:49]
	v_pk_mul_f32 v[34:35], v[32:33], v[46:47]
	v_cvt_pk_bf16_f32 v32, v36, v37
	v_cvt_pk_bf16_f32 v33, v38, v39
	v_rcp_f32_e32 v30, v30
	v_rcp_f32_e32 v31, v31
	v_mul_f32_e32 v14, 0xbfb8aa3b, v14
	v_mul_f32_e32 v15, 0xbfb8aa3b, v15
	v_exp_f32_e32 v8, v8
	v_exp_f32_e32 v9, v9
	v_exp_f32_e32 v10, v10
	v_exp_f32_e32 v11, v11
	v_cvt_pk_bf16_f32 v34, v34, v35
	v_cvt_pk_bf16_f32 v35, v40, v41
	global_store_dwordx4 v[44:45], v[32:35], off offset:256
	v_add_f32_e32 v20, 1.0, v20
	v_add_f32_e32 v21, 1.0, v21
	v_lshlrev_b32_e32 v32, 16, v92
	v_and_b32_e32 v33, 0xffff0000, v92
	v_add_f32_e32 v22, 1.0, v22
	v_add_f32_e32 v23, 1.0, v23
	v_add_f32_e32 v16, 1.0, v16
	v_add_f32_e32 v17, 1.0, v17
	v_add_f32_e32 v18, 1.0, v18
	v_add_f32_e32 v19, 1.0, v19
	v_exp_f32_e32 v14, v14
	v_exp_f32_e32 v15, v15
	v_pk_add_f32 v[4:5], v[4:5], v[68:69]
	v_pk_add_f32 v[0:1], v[0:1], v[64:65]
	v_pk_add_f32 v[2:3], v[2:3], v[66:67]
	v_lshlrev_b32_e32 v36, 16, v94
	v_and_b32_e32 v37, 0xffff0000, v94
	v_lshlrev_b32_e32 v38, 16, v95
	v_and_b32_e32 v39, 0xffff0000, v95
	v_pk_mul_f32 v[28:29], v[28:29], v[32:33]
	v_rcp_f32_e32 v20, v20
	v_rcp_f32_e32 v21, v21
	v_rcp_f32_e32 v22, v22
	v_rcp_f32_e32 v23, v23
	v_rcp_f32_e32 v16, v16
	v_rcp_f32_e32 v18, v18
	v_rcp_f32_e32 v19, v19
	v_rcp_f32_e32 v17, v17
	v_mul_f32_e32 v4, 0xbfb8aa3b, v4
	v_pk_add_f32 v[6:7], v[6:7], v[70:71]
	v_mul_f32_e32 v5, 0xbfb8aa3b, v5
	v_mul_f32_e32 v0, 0xbfb8aa3b, v0
	v_mul_f32_e32 v1, 0xbfb8aa3b, v1
	v_mul_f32_e32 v2, 0xbfb8aa3b, v2
	v_mul_f32_e32 v3, 0xbfb8aa3b, v3
	v_lshlrev_b32_e32 v34, 16, v93
	v_and_b32_e32 v35, 0xffff0000, v93
	v_pk_mul_f32 v[32:33], v[26:27], v[38:39]
	v_pk_mul_f32 v[26:27], v[24:25], v[36:37]
	v_cvt_pk_bf16_f32 v24, v28, v29
	v_lshl_add_u64 v[28:29], s[4:5], 0, v[102:103]
	v_add_f32_e32 v12, 1.0, v12
	v_add_f32_e32 v13, 1.0, v13
	v_exp_f32_e32 v4, v4
	v_exp_f32_e32 v5, v5
	v_mul_f32_e32 v6, 0xbfb8aa3b, v6
	v_mul_f32_e32 v7, 0xbfb8aa3b, v7
	v_exp_f32_e32 v0, v0
	v_exp_f32_e32 v1, v1
	v_exp_f32_e32 v2, v2
	v_exp_f32_e32 v3, v3
	v_pk_mul_f32 v[30:31], v[30:31], v[34:35]
	v_lshl_add_u64 v[28:29], v[28:29], 0, v[180:181]
	v_cvt_pk_bf16_f32 v25, v30, v31
	v_cvt_pk_bf16_f32 v26, v26, v27
	v_cvt_pk_bf16_f32 v27, v32, v33
	v_rcp_f32_e32 v12, v12
	v_rcp_f32_e32 v13, v13
	v_add_f32_e32 v8, 1.0, v8
	v_add_f32_e32 v9, 1.0, v9
	v_add_f32_e32 v10, 1.0, v10
	v_add_f32_e32 v11, 1.0, v11
	v_exp_f32_e32 v6, v6
	v_exp_f32_e32 v7, v7
	global_store_dwordx4 v[28:29], v[24:27], off
	v_lshlrev_b32_e32 v30, 16, v90
	v_and_b32_e32 v31, 0xffff0000, v90
	v_lshlrev_b32_e32 v24, 16, v88
	v_and_b32_e32 v25, 0xffff0000, v88
	v_lshlrev_b32_e32 v26, 16, v89
	v_and_b32_e32 v27, 0xffff0000, v89
	v_lshlrev_b32_e32 v32, 16, v91
	v_and_b32_e32 v33, 0xffff0000, v91
	v_add_f32_e32 v14, 1.0, v14
	v_add_f32_e32 v15, 1.0, v15
	v_rcp_f32_e32 v8, v8
	v_rcp_f32_e32 v10, v10
	v_rcp_f32_e32 v11, v11
	v_rcp_f32_e32 v9, v9
	v_pk_mul_f32 v[22:23], v[22:23], v[26:27]
	v_pk_mul_f32 v[20:21], v[20:21], v[24:25]
	v_pk_mul_f32 v[24:25], v[18:19], v[32:33]
	v_pk_mul_f32 v[18:19], v[16:17], v[30:31]
	v_cvt_pk_bf16_f32 v16, v20, v21
	v_cvt_pk_bf16_f32 v17, v22, v23
	v_rcp_f32_e32 v14, v14
	v_rcp_f32_e32 v15, v15
	v_cvt_pk_bf16_f32 v18, v18, v19
	v_cvt_pk_bf16_f32 v19, v24, v25
	global_store_dwordx4 v[28:29], v[16:19], off offset:256
	v_add_f32_e32 v4, 1.0, v4
	v_add_f32_e32 v5, 1.0, v5
	v_lshlrev_b32_e32 v16, 16, v76
	v_and_b32_e32 v17, 0xffff0000, v76
	v_add_f32_e32 v0, 1.0, v0
	v_add_f32_e32 v1, 1.0, v1
	v_add_f32_e32 v2, 1.0, v2
	v_add_f32_e32 v3, 1.0, v3
	v_lshlrev_b32_e32 v20, 16, v78
	v_and_b32_e32 v21, 0xffff0000, v78
	v_lshlrev_b32_e32 v22, 16, v79
	v_and_b32_e32 v23, 0xffff0000, v79
	v_pk_mul_f32 v[12:13], v[12:13], v[16:17]
	v_rcp_f32_e32 v4, v4
	v_rcp_f32_e32 v5, v5
	v_add_f32_e32 v6, 1.0, v6
	v_add_f32_e32 v7, 1.0, v7
	v_rcp_f32_e32 v0, v0
	v_rcp_f32_e32 v2, v2
	v_rcp_f32_e32 v3, v3
	v_rcp_f32_e32 v1, v1
	v_lshlrev_b32_e32 v18, 16, v77
	v_and_b32_e32 v19, 0xffff0000, v77
	v_pk_mul_f32 v[16:17], v[10:11], v[22:23]
	v_pk_mul_f32 v[10:11], v[8:9], v[20:21]
	v_cvt_pk_bf16_f32 v8, v12, v13
	v_lshl_add_u64 v[12:13], s[4:5], 0, v[100:101]
	v_rcp_f32_e32 v6, v6
	v_rcp_f32_e32 v7, v7
	v_pk_mul_f32 v[14:15], v[14:15], v[18:19]
	v_lshl_add_u64 v[12:13], v[12:13], 0, v[180:181]
	v_cvt_pk_bf16_f32 v9, v14, v15
	v_cvt_pk_bf16_f32 v10, v10, v11
	v_cvt_pk_bf16_f32 v11, v16, v17
	global_store_dwordx4 v[12:13], v[8:11], off
	v_lshlrev_b32_e32 v14, 16, v74
	v_and_b32_e32 v15, 0xffff0000, v74
	v_lshlrev_b32_e32 v8, 16, v72
	v_and_b32_e32 v9, 0xffff0000, v72
	v_lshlrev_b32_e32 v16, 16, v75
	v_and_b32_e32 v17, 0xffff0000, v75
	v_lshlrev_b32_e32 v10, 16, v73
	v_and_b32_e32 v11, 0xffff0000, v73
	v_pk_mul_f32 v[4:5], v[4:5], v[8:9]
	v_pk_mul_f32 v[8:9], v[2:3], v[16:17]
	v_pk_mul_f32 v[2:3], v[0:1], v[14:15]
	v_pk_mul_f32 v[6:7], v[6:7], v[10:11]
	v_cvt_pk_bf16_f32 v0, v4, v5
	s_nop 0
	v_cvt_pk_bf16_f32 v1, v6, v7
	v_cvt_pk_bf16_f32 v2, v2, v3
	v_cvt_pk_bf16_f32 v3, v8, v9
	global_store_dwordx4 v[12:13], v[0:3], off offset:256
	s_cbranch_vccz .LBB0_732
	s_waitcnt vmcnt(0)
	s_cmpk_gt_u32 s33, 0xff
	s_cbranch_scc1 .LBB0_743
	s_barrier

; #define PG8_STAGE(bufoff, gbase, voff) do { _Pragma("unroll") for (int _i = 0; _i < 2; ++_i) \
;         __builtin_amdgcn_global_load_lds((const unsigned*)((const char*)(gbase) + (voff)[_i]), (LAS unsigned*)(lds + (bufoff) + ldsw + _i * 8192), 16, 0, 0); } while (0)
; #define PG8_LDA(dst, b, h) do { _Pragma("unroll") for (int m = 0; m < 4; ++m) _Pragma("unroll") for (int k = 0; k < 2; ++k) dst[m][k] = *(const LAS bf16x8*)(lds + PG8_SA(b, h) + aoff + m * 2048 + k * 1024); } while (0)
; #define PG8_LDB(dst, b, h) do { _Pragma("unroll") for (int n = 0; n < 2; ++n) _Pragma("unroll") for (int k = 0; k < 2; ++k) dst[n][k] = *(const LAS bf16x8*)(lds + PG8_SB(b, h) + boff + n * 2048 + k * 1024); } while (0)
; #define PG8_MMA(ai, bj, At, Bt) do { __builtin_amdgcn_s_setprio(1); _Pragma("unroll") for (int m = 0; m < 4; ++m) _Pragma("unroll") for (int n = 0; n < 2; ++n) _Pragma("unroll") for (int k = 0; k < 2; ++k) \
;         acc[ai][bj][m][n] = __builtin_amdgcn_mfma_f32_16x16x32_bf16(Bt[n][k], At[m][k], acc[ai][bj][m][n], 0, 0, 0); __builtin_amdgcn_s_setprio(0); } while (0)
; #define PG8_WAIT_L(n) asm volatile("s_waitcnt lgkmcnt(" #n ")" ::: "memory")
; #define PG8_BAR __builtin_amdgcn_s_barrier()
; #define PG8_SCHED __builtin_amdgcn_sched_barrier(0)
; template <class Epi>
; __device__ __forceinline__ void gemm_phase(LAS unsigned char* lds, const Gemm g, const StaticOrder& S, const Epi& E) {
;     ...
;             const char* a2 = last ? nA : cA + (size_t)(t + 2) * kstep; const char* b2 = last ? nB : cB + (size_t)(t + 2) * kstep;
;             const char* a3 = a2 + kstep; const char* b3 = b2 + kstep;
;             PG8_LDB(B0, 0, 0); PG8_SCHED; PG8_LDA(At, 0, 0); PG8_STAGE(PG8_SA(1, 1), a1 + hstep, voffA);
;             PG8_WAIT_L(8); PG8_BAR; PG8_WAIT_L(0); PG8_MMA(0, 0, At, B0); PG8_BAR; PG8_SCHED;
;             PG8_LDB(B1, 0, 1); PG8_STAGE(PG8_SB(0, 0), b2, voffB);
;             PG8_BAR; PG8_WAIT_L(0); PG8_MMA(0, 1, At, B1); PG8_BAR;
;             PG8_LDA(At, 0, 1); PG8_STAGE(PG8_SA(0, 0), a2, voffA);
;             PG8_BAR; PG8_WAIT_L(0); PG8_MMA(1, 0, At, B0); PG8_BAR; PG8_SCHED;
.LBB0_914:
	ds_read_b128 v[128:131], v186
	ds_read_b128 v[132:135], v186 offset:1024
	ds_read_b128 v[136:139], v186 offset:2048
	ds_read_b128 v[140:143], v186 offset:3072
	s_add_u32 s30, s28, 0xfffc0080
	s_addc_u32 s31, s29, -1
	s_cmp_eq_u32 s67, 12
	s_cselect_b32 s35, s19, s31
	s_cselect_b32 s34, s63, s30
	s_cselect_b32 s31, s21, s66
	s_cselect_b32 s30, s64, s65
	v_lshl_add_u64 v[208:209], s[28:29], 0, v[148:149]
	s_add_i32 m0, s27, 0xc000
	ds_read_b128 v[144:147], v187
	ds_read_b128 v[156:159], v187 offset:1024
	ds_read_b128 v[160:163], v187 offset:2048
	ds_read_b128 v[164:167], v187 offset:3072
	ds_read_b128 v[190:193], v187 offset:4096
	ds_read_b128 v[194:197], v187 offset:5120
	ds_read_b128 v[198:201], v187 offset:6144
	ds_read_b128 v[204:207], v187 offset:7168
	global_load_lds_dwordx4 v[208:209], off
	v_lshl_add_u64 v[208:209], s[28:29], 0, v[150:151]
	s_add_i32 m0, s27, 0xe000
	s_nop 0
	global_load_lds_dwordx4 v[208:209], off
	s_waitcnt lgkmcnt(8)
	s_barrier
	s_waitcnt lgkmcnt(0)
	s_waitcnt lgkmcnt(0)
	v_mfma_f32_16x16x32_bf16 v[124:127], v[128:131], v[144:147], v[124:127]
	v_mfma_f32_16x16x32_bf16 v[120:123], v[136:139], v[144:147], v[120:123]
	v_mfma_f32_16x16x32_bf16 v[108:111], v[128:131], v[160:163], v[108:111]
	v_mfma_f32_16x16x32_bf16 v[104:107], v[136:139], v[160:163], v[104:107]
	v_mfma_f32_16x16x32_bf16 v[92:95], v[128:131], v[190:193], v[92:95]
	v_mfma_f32_16x16x32_bf16 v[88:91], v[136:139], v[190:193], v[88:91]
	v_mfma_f32_16x16x32_bf16 v[76:79], v[128:131], v[198:201], v[76:79]
	v_mfma_f32_16x16x32_bf16 v[72:75], v[136:139], v[198:201], v[72:75]
	v_mfma_f32_16x16x32_bf16 v[124:127], v[132:135], v[156:159], v[124:127]
	v_mfma_f32_16x16x32_bf16 v[120:123], v[140:143], v[156:159], v[120:123]
	v_mfma_f32_16x16x32_bf16 v[108:111], v[132:135], v[164:167], v[108:111]
	v_mfma_f32_16x16x32_bf16 v[104:107], v[140:143], v[164:167], v[104:107]
	v_mfma_f32_16x16x32_bf16 v[92:95], v[132:135], v[194:197], v[92:95]
	v_mfma_f32_16x16x32_bf16 v[88:91], v[140:143], v[194:197], v[88:91]
	v_mfma_f32_16x16x32_bf16 v[76:79], v[132:135], v[204:207], v[76:79]
	v_mfma_f32_16x16x32_bf16 v[72:75], v[140:143], v[204:207], v[72:75]
	s_barrier
	s_add_i32 s69, s58, s49
	v_lshl_add_u64 v[212:213], s[30:31], 0, v[174:175]
	s_mov_b32 m0, s69
	ds_read_b128 v[208:211], v188
	ds_read_b128 v[216:219], v188 offset:1024
	ds_read_b128 v[220:223], v188 offset:2048
	ds_read_b128 v[224:227], v188 offset:3072
	global_load_lds_dwordx4 v[212:213], off
	v_lshl_add_u64 v[228:229], s[30:31], 0, v[178:179]
	s_add_i32 m0, s69, 0x2000
	s_nop 0
	global_load_lds_dwordx4 v[228:229], off
	s_barrier
	s_waitcnt lgkmcnt(0)
	s_waitcnt lgkmcnt(0)
	v_mfma_f32_16x16x32_bf16 v[116:119], v[208:211], v[144:147], v[116:119]
	v_mfma_f32_16x16x32_bf16 v[112:115], v[220:223], v[144:147], v[112:115]
	v_mfma_f32_16x16x32_bf16 v[100:103], v[208:211], v[160:163], v[100:103]
	v_mfma_f32_16x16x32_bf16 v[96:99], v[220:223], v[160:163], v[96:99]
	v_mfma_f32_16x16x32_bf16 v[84:87], v[208:211], v[190:193], v[84:87]
	v_mfma_f32_16x16x32_bf16 v[80:83], v[220:223], v[190:193], v[80:83]
	v_mfma_f32_16x16x32_bf16 v[68:71], v[208:211], v[198:201], v[68:71]
	v_mfma_f32_16x16x32_bf16 v[64:67], v[220:223], v[198:201], v[64:67]
	v_mfma_f32_16x16x32_bf16 v[116:119], v[216:219], v[156:159], v[116:119]
	v_mfma_f32_16x16x32_bf16 v[112:115], v[224:227], v[156:159], v[112:115]
	v_mfma_f32_16x16x32_bf16 v[100:103], v[216:219], v[164:167], v[100:103]
	v_mfma_f32_16x16x32_bf16 v[96:99], v[224:227], v[164:167], v[96:99]
	v_mfma_f32_16x16x32_bf16 v[84:87], v[216:219], v[194:197], v[84:87]
	v_mfma_f32_16x16x32_bf16 v[80:83], v[224:227], v[194:197], v[80:83]
	v_mfma_f32_16x16x32_bf16 v[68:71], v[216:219], v[204:207], v[68:71]
	v_mfma_f32_16x16x32_bf16 v[64:67], v[224:227], v[204:207], v[64:67]
	s_mov_b32 m0, s27
	v_lshl_add_u64 v[230:231], s[34:35], 0, v[172:173]
	s_barrier
	ds_read_b128 v[144:147], v187 offset:16384
	ds_read_b128 v[156:159], v187 offset:17408
	ds_read_b128 v[160:163], v187 offset:18432
	ds_read_b128 v[164:167], v187 offset:19456
	ds_read_b128 v[190:193], v187 offset:20480
	ds_read_b128 v[194:197], v187 offset:21504
	ds_read_b128 v[198:201], v187 offset:22528
	ds_read_b128 v[204:207], v187 offset:23552
	global_load_lds_dwordx4 v[230:231], off
	v_lshl_add_u64 v[232:233], s[34:35], 0, v[176:177]
	s_mov_b32 m0, s50
	s_nop 0
	global_load_lds_dwordx4 v[232:233], off
	s_barrier
	s_waitcnt lgkmcnt(0)
	s_waitcnt lgkmcnt(0)
	v_mfma_f32_16x16x32_bf16 v[60:63], v[128:131], v[144:147], v[60:63]
	v_mfma_f32_16x16x32_bf16 v[56:59], v[136:139], v[144:147], v[56:59]
	v_mfma_f32_16x16x32_bf16 v[44:47], v[128:131], v[160:163], v[44:47]
	v_mfma_f32_16x16x32_bf16 v[40:43], v[136:139], v[160:163], v[40:43]
	v_mfma_f32_16x16x32_bf16 v[28:31], v[128:131], v[190:193], v[28:31]
	v_mfma_f32_16x16x32_bf16 v[24:27], v[136:139], v[190:193], v[24:27]
	v_mfma_f32_16x16x32_bf16 v[12:15], v[128:131], v[198:201], v[12:15]
	v_mfma_f32_16x16x32_bf16 v[8:11], v[136:139], v[198:201], v[8:11]
	v_mfma_f32_16x16x32_bf16 v[60:63], v[132:135], v[156:159], v[60:63]
	v_mfma_f32_16x16x32_bf16 v[56:59], v[140:143], v[156:159], v[56:59]
	v_mfma_f32_16x16x32_bf16 v[44:47], v[132:135], v[164:167], v[44:47]
	v_mfma_f32_16x16x32_bf16 v[40:43], v[140:143], v[164:167], v[40:43]
	v_mfma_f32_16x16x32_bf16 v[28:31], v[132:135], v[194:197], v[28:31]
	v_mfma_f32_16x16x32_bf16 v[24:27], v[140:143], v[194:197], v[24:27]
	v_mfma_f32_16x16x32_bf16 v[12:15], v[132:135], v[204:207], v[12:15]
	v_mfma_f32_16x16x32_bf16 v[8:11], v[140:143], v[204:207], v[8:11]
	s_barrier
; #define PG8_STAGE(bufoff, gbase, voff) do { _Pragma("unroll") for (int _i = 0; _i < 2; ++_i) \
;         __builtin_amdgcn_global_load_lds((const unsigned*)((const char*)(gbase) + (voff)[_i]), (LAS unsigned*)(lds + (bufoff) + ldsw + _i * 8192), 16, 0, 0); } while (0)
; #define PG8_LDA(dst, b, h) do { _Pragma("unroll") for (int m = 0; m < 4; ++m) _Pragma("unroll") for (int k = 0; k < 2; ++k) dst[m][k] = *(const LAS bf16x8*)(lds + PG8_SA(b, h) + aoff + m * 2048 + k * 1024); } while (0)
; #define PG8_LDB(dst, b, h) do { _Pragma("unroll") for (int n = 0; n < 2; ++n) _Pragma("unroll") for (int k = 0; k < 2; ++k) dst[n][k] = *(const LAS bf16x8*)(lds + PG8_SB(b, h) + boff + n * 2048 + k * 1024); } while (0)
; #define PG8_MMA(ai, bj, At, Bt) do { __builtin_amdgcn_s_setprio(1); _Pragma("unroll") for (int m = 0; m < 4; ++m) _Pragma("unroll") for (int n = 0; n < 2; ++n) _Pragma("unroll") for (int k = 0; k < 2; ++k) \
;         acc[ai][bj][m][n] = __builtin_amdgcn_mfma_f32_16x16x32_bf16(Bt[n][k], At[m][k], acc[ai][bj][m][n], 0, 0, 0); __builtin_amdgcn_s_setprio(0); } while (0)
; #define PG8_WAIT_V(n) asm volatile("s_waitcnt vmcnt(" #n ")" ::: "memory")
; #define PG8_WAIT_L(n) asm volatile("s_waitcnt lgkmcnt(" #n ")" ::: "memory")
; #define PG8_BAR __builtin_amdgcn_s_barrier()
; #define PG8_SCHED __builtin_amdgcn_sched_barrier(0)
; template <class Epi>
; __device__ __forceinline__ void gemm_phase(LAS unsigned char* lds, const Gemm g, const StaticOrder& S, const Epi& E) {
;     ...
;             PG8_STAGE(PG8_SB(0, 1), b2 + hstep, voffB);
;             PG8_WAIT_V(6); PG8_BAR; PG8_MMA(1, 1, At, B1); PG8_BAR;
;             PG8_LDB(B0, 1, 0); PG8_SCHED; PG8_LDA(At, 1, 0); PG8_STAGE(PG8_SA(0, 1), a2 + hstep, voffA);
;             PG8_WAIT_L(8); PG8_BAR; PG8_WAIT_L(0); PG8_MMA(0, 0, At, B0); PG8_BAR; PG8_SCHED;
;             PG8_LDB(B1, 1, 1); PG8_STAGE(PG8_SB(1, 0), b3, voffB);
;             PG8_BAR; PG8_WAIT_L(0); PG8_MMA(0, 1, At, B1); PG8_BAR;
;             PG8_LDA(At, 1, 1); PG8_STAGE(PG8_SA(1, 0), a3, voffA);
;             PG8_BAR; PG8_WAIT_L(0); PG8_MMA(1, 0, At, B0); PG8_BAR; PG8_SCHED;
	s_add_u32 s70, s30, 0x40000
	s_addc_u32 s71, s31, 0
	s_add_i32 s69, s59, s49
	v_lshl_add_u64 v[128:129], s[70:71], 0, v[174:175]
	s_mov_b32 m0, s69
	s_nop 0
	global_load_lds_dwordx4 v[128:129], off
	v_lshl_add_u64 v[128:129], s[70:71], 0, v[178:179]
	s_add_i32 m0, s69, 0x2000
	s_nop 0
	global_load_lds_dwordx4 v[128:129], off
	s_waitcnt vmcnt(6)
	s_barrier
	v_mfma_f32_16x16x32_bf16 v[52:55], v[208:211], v[144:147], v[52:55]
	v_mfma_f32_16x16x32_bf16 v[48:51], v[220:223], v[144:147], v[48:51]
	v_mfma_f32_16x16x32_bf16 v[36:39], v[208:211], v[160:163], v[36:39]
	v_mfma_f32_16x16x32_bf16 v[32:35], v[220:223], v[160:163], v[32:35]
	v_mfma_f32_16x16x32_bf16 v[20:23], v[208:211], v[190:193], v[20:23]
	v_mfma_f32_16x16x32_bf16 v[16:19], v[220:223], v[190:193], v[16:19]
	v_mfma_f32_16x16x32_bf16 v[4:7], v[208:211], v[198:201], v[4:7]
	v_mfma_f32_16x16x32_bf16 v[0:3], v[220:223], v[198:201], v[0:3]
	v_mfma_f32_16x16x32_bf16 v[52:55], v[216:219], v[156:159], v[52:55]
	v_mfma_f32_16x16x32_bf16 v[48:51], v[224:227], v[156:159], v[48:51]
	v_mfma_f32_16x16x32_bf16 v[36:39], v[216:219], v[164:167], v[36:39]
	v_mfma_f32_16x16x32_bf16 v[32:35], v[224:227], v[164:167], v[32:35]
	v_mfma_f32_16x16x32_bf16 v[20:23], v[216:219], v[194:197], v[20:23]
	v_mfma_f32_16x16x32_bf16 v[16:19], v[224:227], v[194:197], v[16:19]
	v_mfma_f32_16x16x32_bf16 v[4:7], v[216:219], v[204:207], v[4:7]
	v_mfma_f32_16x16x32_bf16 v[0:3], v[224:227], v[204:207], v[0:3]
	s_add_i32 s69, 0, 0x18000
	v_add_u32_e32 v140, s69, v184
	s_barrier
	ds_read_b128 v[128:131], v140
	ds_read_b128 v[132:135], v140 offset:1024
	ds_read_b128 v[136:139], v140 offset:2048
	ds_read_b128 v[140:143], v140 offset:3072
	s_add_u32 s34, s34, 0x40000
	s_addc_u32 s35, s35, 0
	s_mov_b32 m0, s51
	v_lshl_add_u64 v[208:209], s[34:35], 0, v[172:173]
	ds_read_b128 v[144:147], v187 offset:32768
	ds_read_b128 v[156:159], v187 offset:33792
	ds_read_b128 v[160:163], v187 offset:34816
	ds_read_b128 v[164:167], v187 offset:35840
	ds_read_b128 v[190:193], v187 offset:36864
	ds_read_b128 v[194:197], v187 offset:37888
	ds_read_b128 v[198:201], v187 offset:38912
	ds_read_b128 v[204:207], v187 offset:39936
	global_load_lds_dwordx4 v[208:209], off
	v_lshl_add_u64 v[208:209], s[34:35], 0, v[176:177]
	s_mov_b32 m0, s54
	s_nop 0
	global_load_lds_dwordx4 v[208:209], off
	s_waitcnt lgkmcnt(8)
	s_barrier
	s_waitcnt lgkmcnt(0)
	s_waitcnt lgkmcnt(0)
	v_mfma_f32_16x16x32_bf16 v[124:127], v[128:131], v[144:147], v[124:127]
	v_mfma_f32_16x16x32_bf16 v[120:123], v[136:139], v[144:147], v[120:123]
	v_mfma_f32_16x16x32_bf16 v[108:111], v[128:131], v[160:163], v[108:111]
	v_mfma_f32_16x16x32_bf16 v[104:107], v[136:139], v[160:163], v[104:107]
	v_mfma_f32_16x16x32_bf16 v[92:95], v[128:131], v[190:193], v[92:95]
	v_mfma_f32_16x16x32_bf16 v[88:91], v[136:139], v[190:193], v[88:91]
	v_mfma_f32_16x16x32_bf16 v[76:79], v[128:131], v[198:201], v[76:79]
	v_mfma_f32_16x16x32_bf16 v[72:75], v[136:139], v[198:201], v[72:75]
	v_mfma_f32_16x16x32_bf16 v[124:127], v[132:135], v[156:159], v[124:127]
	v_mfma_f32_16x16x32_bf16 v[120:123], v[140:143], v[156:159], v[120:123]
	v_mfma_f32_16x16x32_bf16 v[108:111], v[132:135], v[164:167], v[108:111]
	v_mfma_f32_16x16x32_bf16 v[104:107], v[140:143], v[164:167], v[104:107]
	v_mfma_f32_16x16x32_bf16 v[92:95], v[132:135], v[194:197], v[92:95]
	v_mfma_f32_16x16x32_bf16 v[88:91], v[140:143], v[194:197], v[88:91]
	v_mfma_f32_16x16x32_bf16 v[76:79], v[132:135], v[204:207], v[76:79]
	v_mfma_f32_16x16x32_bf16 v[72:75], v[140:143], v[204:207], v[72:75]
	s_barrier
	s_add_i32 s34, 0, 0x1c000
	s_add_i32 s35, s69, s49
	v_add_u32_e32 v189, s34, v184
	v_lshl_add_u64 v[212:213], v[212:213], 0, s[10:11]
	s_mov_b32 m0, s35
	ds_read_b128 v[208:211], v189
	ds_read_b128 v[216:219], v189 offset:1024
	ds_read_b128 v[220:223], v189 offset:2048
	ds_read_b128 v[224:227], v189 offset:3072
	global_load_lds_dwordx4 v[212:213], off
	v_lshl_add_u64 v[212:213], v[228:229], 0, s[10:11]
	s_add_i32 m0, s35, 0x2000
	s_nop 0
	global_load_lds_dwordx4 v[212:213], off
	s_barrier
	s_waitcnt lgkmcnt(0)
	s_waitcnt lgkmcnt(0)
	v_mfma_f32_16x16x32_bf16 v[116:119], v[208:211], v[144:147], v[116:119]
	v_mfma_f32_16x16x32_bf16 v[112:115], v[220:223], v[144:147], v[112:115]
	v_mfma_f32_16x16x32_bf16 v[100:103], v[208:211], v[160:163], v[100:103]
	v_mfma_f32_16x16x32_bf16 v[96:99], v[220:223], v[160:163], v[96:99]
	v_mfma_f32_16x16x32_bf16 v[84:87], v[208:211], v[190:193], v[84:87]
	v_mfma_f32_16x16x32_bf16 v[80:83], v[220:223], v[190:193], v[80:83]
	v_mfma_f32_16x16x32_bf16 v[68:71], v[208:211], v[198:201], v[68:71]
	v_mfma_f32_16x16x32_bf16 v[64:67], v[220:223], v[198:201], v[64:67]
	v_mfma_f32_16x16x32_bf16 v[116:119], v[216:219], v[156:159], v[116:119]
	v_mfma_f32_16x16x32_bf16 v[112:115], v[224:227], v[156:159], v[112:115]
	v_mfma_f32_16x16x32_bf16 v[100:103], v[216:219], v[164:167], v[100:103]
	v_mfma_f32_16x16x32_bf16 v[96:99], v[224:227], v[164:167], v[96:99]
	v_mfma_f32_16x16x32_bf16 v[84:87], v[216:219], v[194:197], v[84:87]
	v_mfma_f32_16x16x32_bf16 v[80:83], v[224:227], v[194:197], v[80:83]
	v_mfma_f32_16x16x32_bf16 v[68:71], v[216:219], v[204:207], v[68:71]
	v_mfma_f32_16x16x32_bf16 v[64:67], v[224:227], v[204:207], v[64:67]
	s_mov_b32 m0, s55
	v_lshl_add_u64 v[212:213], v[230:231], 0, s[10:11]
	s_barrier
	ds_read_b128 v[144:147], v187 offset:49152
	ds_read_b128 v[156:159], v187 offset:50176
	ds_read_b128 v[160:163], v187 offset:51200
	ds_read_b128 v[164:167], v187 offset:52224
	ds_read_b128 v[190:193], v187 offset:53248
	ds_read_b128 v[194:197], v187 offset:54272
	ds_read_b128 v[198:201], v187 offset:55296
	ds_read_b128 v[204:207], v187 offset:56320
	global_load_lds_dwordx4 v[212:213], off
	v_lshl_add_u64 v[212:213], v[232:233], 0, s[10:11]
	s_mov_b32 m0, s56
	s_nop 0
	global_load_lds_dwordx4 v[212:213], off
	s_barrier
; #define PG8_STAGE(bufoff, gbase, voff) do { _Pragma("unroll") for (int _i = 0; _i < 2; ++_i) \
;         __builtin_amdgcn_global_load_lds((const unsigned*)((const char*)(gbase) + (voff)[_i]), (LAS unsigned*)(lds + (bufoff) + ldsw + _i * 8192), 16, 0, 0); } while (0)
; #define PG8_MMA(ai, bj, At, Bt) do { __builtin_amdgcn_s_setprio(1); _Pragma("unroll") for (int m = 0; m < 4; ++m) _Pragma("unroll") for (int n = 0; n < 2; ++n) _Pragma("unroll") for (int k = 0; k < 2; ++k) \
;         acc[ai][bj][m][n] = __builtin_amdgcn_mfma_f32_16x16x32_bf16(Bt[n][k], At[m][k], acc[ai][bj][m][n], 0, 0, 0); __builtin_amdgcn_s_setprio(0); } while (0)
; #define PG8_WAIT_V(n) asm volatile("s_waitcnt vmcnt(" #n ")" ::: "memory")
; #define PG8_WAIT_L(n) asm volatile("s_waitcnt lgkmcnt(" #n ")" ::: "memory")
; #define PG8_BAR __builtin_amdgcn_s_barrier()
; #define PG8_SCHED __builtin_amdgcn_sched_barrier(0)
; template <class Epi>
; __device__ __forceinline__ void gemm_phase(LAS unsigned char* lds, const Gemm g, const StaticOrder& S, const Epi& E) {
;     ...
;             PG8_BAR; PG8_WAIT_L(0); PG8_MMA(1, 0, At, B0); PG8_BAR; PG8_SCHED;
;             PG8_STAGE(PG8_SB(1, 1), b3 + hstep, voffB);
;             PG8_WAIT_V(6); PG8_BAR; PG8_MMA(1, 1, At, B1); PG8_BAR;
;         }
;     __device__ __forceinline__ void operator()(const AccT& acc, const pg8::Unit& u, int wr, int wc, int fr, int fq) const {
;         const int row0 = u.pm * 256 + wr * 64 + fr, col0 = u.pn * 256 + wc * 32 + 8 * fq;
; #pragma unroll
;         for (int ai = 0; ai < 2; ++ai) { u32x4 gw[4][2];
; #pragma unroll
;             for (int m = 0; m < 4; ++m)
; #pragma unroll
;                 for (int bj = 0; bj < 2; ++bj) gw[m][bj] = *(const u32x4*)(PROJ + (size_t)(row0 + ai * 128 + m * 16) * NPROJ + C_GA + col0 + bj * 128);
	s_waitcnt lgkmcnt(0)
	s_waitcnt lgkmcnt(0)
	v_mfma_f32_16x16x32_bf16 v[60:63], v[128:131], v[144:147], v[60:63]
	v_mfma_f32_16x16x32_bf16 v[56:59], v[136:139], v[144:147], v[56:59]
	v_mfma_f32_16x16x32_bf16 v[44:47], v[128:131], v[160:163], v[44:47]
	v_mfma_f32_16x16x32_bf16 v[40:43], v[136:139], v[160:163], v[40:43]
	v_mfma_f32_16x16x32_bf16 v[28:31], v[128:131], v[190:193], v[28:31]
	v_mfma_f32_16x16x32_bf16 v[24:27], v[136:139], v[190:193], v[24:27]
	v_mfma_f32_16x16x32_bf16 v[12:15], v[128:131], v[198:201], v[12:15]
	v_mfma_f32_16x16x32_bf16 v[8:11], v[136:139], v[198:201], v[8:11]
	v_mfma_f32_16x16x32_bf16 v[60:63], v[132:135], v[156:159], v[60:63]
	v_mfma_f32_16x16x32_bf16 v[56:59], v[140:143], v[156:159], v[56:59]
	v_mfma_f32_16x16x32_bf16 v[44:47], v[132:135], v[164:167], v[44:47]
	v_mfma_f32_16x16x32_bf16 v[40:43], v[140:143], v[164:167], v[40:43]
	v_mfma_f32_16x16x32_bf16 v[28:31], v[132:135], v[194:197], v[28:31]
	v_mfma_f32_16x16x32_bf16 v[24:27], v[140:143], v[194:197], v[24:27]
	v_mfma_f32_16x16x32_bf16 v[12:15], v[132:135], v[204:207], v[12:15]
	v_mfma_f32_16x16x32_bf16 v[8:11], v[140:143], v[204:207], v[8:11]
	s_barrier
	s_add_u32 s30, s30, 0x40080
	s_addc_u32 s31, s31, 0
	s_add_i32 s34, s34, s49
	v_lshl_add_u64 v[128:129], s[30:31], 0, v[174:175]
	s_mov_b32 m0, s34
	s_nop 0
	global_load_lds_dwordx4 v[128:129], off
	v_lshl_add_u64 v[128:129], s[30:31], 0, v[178:179]
	s_add_i32 m0, s34, 0x2000
	s_nop 0
	global_load_lds_dwordx4 v[128:129], off
	s_waitcnt vmcnt(6)
	s_barrier
	v_mfma_f32_16x16x32_bf16 v[52:55], v[208:211], v[144:147], v[52:55]
	v_mfma_f32_16x16x32_bf16 v[48:51], v[220:223], v[144:147], v[48:51]
	v_mfma_f32_16x16x32_bf16 v[36:39], v[208:211], v[160:163], v[36:39]
	v_mfma_f32_16x16x32_bf16 v[32:35], v[220:223], v[160:163], v[32:35]
	v_mfma_f32_16x16x32_bf16 v[20:23], v[208:211], v[190:193], v[20:23]
	v_mfma_f32_16x16x32_bf16 v[16:19], v[220:223], v[190:193], v[16:19]
	v_mfma_f32_16x16x32_bf16 v[4:7], v[208:211], v[198:201], v[4:7]
	v_mfma_f32_16x16x32_bf16 v[0:3], v[220:223], v[198:201], v[0:3]
	v_mfma_f32_16x16x32_bf16 v[52:55], v[216:219], v[156:159], v[52:55]
	v_mfma_f32_16x16x32_bf16 v[48:51], v[224:227], v[156:159], v[48:51]
	v_mfma_f32_16x16x32_bf16 v[36:39], v[216:219], v[164:167], v[36:39]
	v_mfma_f32_16x16x32_bf16 v[32:35], v[224:227], v[164:167], v[32:35]
	v_mfma_f32_16x16x32_bf16 v[20:23], v[216:219], v[194:197], v[20:23]
	v_mfma_f32_16x16x32_bf16 v[16:19], v[224:227], v[194:197], v[16:19]
	v_mfma_f32_16x16x32_bf16 v[4:7], v[216:219], v[204:207], v[4:7]
	v_mfma_f32_16x16x32_bf16 v[0:3], v[224:227], v[204:207], v[0:3]
	s_add_i32 s67, s67, 2
	s_add_u32 s28, s28, 0x100
	s_addc_u32 s29, s29, 0
	s_add_u32 s65, s65, 0x100
	s_addc_u32 s66, s66, 0
	s_cmp_gt_u32 s67, 13
	s_barrier
	s_cbranch_scc0 .LBB0_914
	v_lshl_or_b32 v128, s62, 8, v185
	v_lshl_add_u32 v158, s26, 8, v183
	v_ashrrev_i32_e32 v129, 31, v128
	v_mov_b64_e32 v[160:161], s[0:1]
	v_mad_i64_i32 v[130:131], s[28:29], v158, s61, v[160:161]
	v_lshlrev_b64 v[156:157], 1, v[128:129]
	v_lshl_add_u64 v[128:129], v[130:131], 0, v[156:157]
	v_add_co_u32_e32 v130, vcc, 0x2000, v128
	v_or_b32_e32 v166, 16, v158
	s_nop 0
	v_addc_co_u32_e32 v131, vcc, 0, v129, vcc
	global_load_dwordx4 v[190:193], v[130:131], off offset:2048
	v_lshl_add_u64 v[128:129], v[128:129], 0, s[16:17]
	global_load_dwordx4 v[194:197], v[128:129], off offset:256
	v_or_b32_e32 v164, 32, v158
	v_or_b32_e32 v162, 48, v158
	v_mad_i64_i32 v[130:131], s[28:29], v166, s61, v[160:161]
	v_mad_i64_i32 v[132:133], s[28:29], v164, s61, v[160:161]
	v_mad_i64_i32 v[134:135], s[28:29], v162, s61, v[160:161]
	v_lshl_add_u64 v[128:129], v[130:131], 0, v[156:157]
	v_lshl_add_u64 v[130:131], v[132:133], 0, v[156:157]
	v_lshl_add_u64 v[132:133], v[134:135], 0, v[156:157]
	v_lshl_add_u64 v[134:135], v[128:129], 0, s[16:17]
	v_add_co_u32_e32 v128, vcc, 0x2000, v128
	v_lshl_add_u64 v[136:137], v[130:131], 0, s[16:17]
	s_nop 0
	v_addc_co_u32_e32 v129, vcc, 0, v129, vcc
	global_load_dwordx4 v[198:201], v[128:129], off offset:2048
	global_load_dwordx4 v[144:147], v[134:135], off offset:256
	v_add_co_u32_e32 v130, vcc, 0x2000, v130
	v_ashrrev_i32_e32 v159, 31, v158
	s_nop 0
	v_addc_co_u32_e32 v131, vcc, 0, v131, vcc
	global_load_dwordx4 v[140:143], v[130:131], off offset:2048
	s_nop 0
	global_load_dwordx4 v[136:139], v[136:137], off offset:256
	v_add_co_u32_e32 v128, vcc, 0x2000, v132
	v_lshlrev_b64 v[204:205], 12, v[158:159]
	v_lshl_add_u64 v[206:207], v[132:133], 0, s[16:17]
	v_addc_co_u32_e32 v129, vcc, 0, v133, vcc
	global_load_dwordx4 v[132:135], v[128:129], off offset:2048
	s_nop 0
	global_load_dwordx4 v[128:131], v[206:207], off offset:256
	v_ashrrev_i32_e32 v167, 31, v166
	v_ashrrev_i32_e32 v165, 31, v164
	v_ashrrev_i32_e32 v163, 31, v162
	s_mov_b32 s62, s20
	s_mov_b32 s26, s18
	s_mov_b64 s[30:31], s[24:25]
	s_waitcnt vmcnt(0)
; __device__ __forceinline__ u32x4 pack8(const f32x4 v0, const f32x4 v1) { u32x4 w; w.x = cvt_pk_bf16(v0[0], v0[1]); w.y = cvt_pk_bf16(v0[2], v0[3]); w.z = cvt_pk_bf16(v1[0], v1[1]); w.w = cvt_pk_bf16(v1[2], v1[3]); return w; }
; __device__ __forceinline__ void unpack8(const u32x4 w, f32x4& v0, f32x4& v1) { v0 = (f32x4){bflo(w.x), bfhi(w.x), bflo(w.y), bfhi(w.y)}; v1 = (f32x4){bflo(w.z), bfhi(w.z), bflo(w.w), bfhi(w.w)}; }
; __device__ __forceinline__ f32x4 sig4(const f32x4 v) { return (f32x4){sigmoidf_(v[0]), sigmoidf_(v[1]), sigmoidf_(v[2]), sigmoidf_(v[3])}; }
;     __device__ __forceinline__ void operator()(const AccT& acc, const pg8::Unit& u, int wr, int wc, int fr, int fq) const {
;     ...
;         for (int ai = 0; ai < 2; ++ai) { u32x4 gw[4][2];
; #pragma unroll
;             for (int m = 0; m < 4; ++m)
; #pragma unroll
;                 for (int bj = 0; bj < 2; ++bj) gw[m][bj] = *(const u32x4*)(PROJ + (size_t)(row0 + ai * 128 + m * 16) * NPROJ + C_GA + col0 + bj * 128);
; #pragma unroll
;             for (int m = 0; m < 4; ++m)
; #pragma unroll
;                 for (int bj = 0; bj < 2; ++bj) { f32x4 g0, g1; unpack8(gw[m][bj], g0, g1);
;                     *(u32x4*)(T + (size_t)(row0 + ai * 128 + m * 16) * D + col0 + bj * 128) = pack8(sig4(g0) * acc[ai][bj][m][0], sig4(g1) * acc[ai][bj][m][1]); } }
;     }
	v_lshlrev_b32_e32 v159, 16, v190
	v_and_b32_e32 v189, 0xffff0000, v190
	v_lshlrev_b32_e32 v190, 16, v191
	v_and_b32_e32 v191, 0xffff0000, v191
	v_lshlrev_b32_e32 v203, 16, v192
	v_and_b32_e32 v192, 0xffff0000, v192
	v_lshlrev_b32_e32 v206, 16, v193
	v_and_b32_e32 v193, 0xffff0000, v193
	v_mul_f32_e32 v159, 0xbfb8aa3b, v159
	v_mul_f32_e32 v189, 0xbfb8aa3b, v189
	v_mul_f32_e32 v190, 0xbfb8aa3b, v190
	v_mul_f32_e32 v191, 0xbfb8aa3b, v191
	v_mul_f32_e32 v203, 0xbfb8aa3b, v203
	v_mul_f32_e32 v192, 0xbfb8aa3b, v192
	v_mul_f32_e32 v206, 0xbfb8aa3b, v206
	v_mul_f32_e32 v193, 0xbfb8aa3b, v193
	v_exp_f32_e32 v159, v159
	v_exp_f32_e32 v189, v189
	v_exp_f32_e32 v190, v190
	v_exp_f32_e32 v191, v191
	v_exp_f32_e32 v203, v203
	v_exp_f32_e32 v192, v192
	v_exp_f32_e32 v206, v206
	v_exp_f32_e32 v193, v193
	v_add_f32_e32 v159, 1.0, v159
	v_add_f32_e32 v189, 1.0, v189
	v_add_f32_e32 v207, 1.0, v190
	v_add_f32_e32 v208, 1.0, v191
	v_add_f32_e32 v203, 1.0, v203
	v_add_f32_e32 v210, 1.0, v192
	v_add_f32_e32 v209, 1.0, v206
	v_add_f32_e32 v211, 1.0, v193
	v_rcp_f32_e32 v190, v159
	v_rcp_f32_e32 v191, v189
	v_rcp_f32_e32 v192, v207
	v_rcp_f32_e32 v193, v208
	v_rcp_f32_e32 v206, v203
	v_rcp_f32_e32 v208, v209
	v_rcp_f32_e32 v209, v211
	v_rcp_f32_e32 v207, v210
	v_pk_mul_f32 v[124:125], v[124:125], v[190:191]
	v_pk_mul_f32 v[126:127], v[126:127], v[192:193]
	v_pk_mul_f32 v[190:191], v[122:123], v[208:209]
	v_pk_mul_f32 v[122:123], v[120:121], v[206:207]
	v_cvt_pk_bf16_f32 v120, v124, v125
	v_lshl_add_u64 v[124:125], s[4:5], 0, v[204:205]
	v_cvt_pk_bf16_f32 v121, v126, v127
	v_lshl_add_u64 v[124:125], v[124:125], 0, v[156:157]
	v_lshlrev_b32_e32 v159, 16, v197
	v_cvt_pk_bf16_f32 v122, v122, v123
	v_cvt_pk_bf16_f32 v123, v190, v191
	global_store_dwordx4 v[124:125], v[120:123], off
	v_lshlrev_b32_e32 v126, 16, v196
	v_and_b32_e32 v127, 0xffff0000, v196
	v_lshlrev_b32_e32 v120, 16, v194
	v_and_b32_e32 v121, 0xffff0000, v194
	v_and_b32_e32 v189, 0xffff0000, v197
	v_mul_f32_e32 v159, 0xbfb8aa3b, v159
	v_lshlrev_b32_e32 v122, 16, v195
	v_and_b32_e32 v123, 0xffff0000, v195
	v_mul_f32_e32 v120, 0xbfb8aa3b, v120
	v_mul_f32_e32 v121, 0xbfb8aa3b, v121
	v_mul_f32_e32 v126, 0xbfb8aa3b, v126
	v_mul_f32_e32 v127, 0xbfb8aa3b, v127
	v_exp_f32_e32 v159, v159
	v_mul_f32_e32 v189, 0xbfb8aa3b, v189
	v_exp_f32_e32 v120, v120
	v_exp_f32_e32 v121, v121
	v_mul_f32_e32 v122, 0xbfb8aa3b, v122
	v_mul_f32_e32 v123, 0xbfb8aa3b, v123
	v_exp_f32_e32 v126, v126
	v_exp_f32_e32 v127, v127
	v_exp_f32_e32 v189, v189
	v_exp_f32_e32 v122, v122
	v_exp_f32_e32 v123, v123
	v_add_f32_e32 v159, 1.0, v159
	v_add_f32_e32 v120, 1.0, v120
	v_add_f32_e32 v121, 1.0, v121
	v_add_f32_e32 v126, 1.0, v126
	v_add_f32_e32 v127, 1.0, v127
	v_rcp_f32_e32 v190, v159
	v_add_f32_e32 v159, 1.0, v189
	v_rcp_f32_e32 v120, v120
	v_rcp_f32_e32 v121, v121
	v_add_f32_e32 v122, 1.0, v122
	v_add_f32_e32 v123, 1.0, v123
	v_rcp_f32_e32 v126, v126
	v_rcp_f32_e32 v191, v159
	v_rcp_f32_e32 v127, v127
	v_rcp_f32_e32 v122, v122
	v_rcp_f32_e32 v123, v123
	v_pk_mul_f32 v[116:117], v[116:117], v[120:121]
	v_pk_mul_f32 v[120:121], v[114:115], v[190:191]
	v_pk_mul_f32 v[114:115], v[112:113], v[126:127]
	v_pk_mul_f32 v[118:119], v[118:119], v[122:123]
	v_cvt_pk_bf16_f32 v112, v116, v117
	v_lshlrev_b32_e32 v116, 16, v199
	v_cvt_pk_bf16_f32 v113, v118, v119
	v_cvt_pk_bf16_f32 v114, v114, v115
	v_cvt_pk_bf16_f32 v115, v120, v121
	global_store_dwordx4 v[124:125], v[112:115], off offset:256
	v_lshlrev_b32_e32 v118, 16, v200
	v_and_b32_e32 v119, 0xffff0000, v200
	v_lshlrev_b32_e32 v114, 16, v198
	v_and_b32_e32 v115, 0xffff0000, v198
	v_mul_f32_e32 v114, 0xbfb8aa3b, v114
	v_lshlrev_b32_e32 v120, 16, v201
	v_and_b32_e32 v121, 0xffff0000, v201
	v_mul_f32_e32 v115, 0xbfb8aa3b, v115
	v_and_b32_e32 v117, 0xffff0000, v199
	v_exp_f32_e32 v114, v114
	v_exp_f32_e32 v115, v115
	v_mul_f32_e32 v118, 0xbfb8aa3b, v118
	v_mul_f32_e32 v119, 0xbfb8aa3b, v119
	v_mul_f32_e32 v120, 0xbfb8aa3b, v120
	v_mul_f32_e32 v121, 0xbfb8aa3b, v121
	v_mul_f32_e32 v116, 0xbfb8aa3b, v116
	v_mul_f32_e32 v117, 0xbfb8aa3b, v117
	v_exp_f32_e32 v118, v118
	v_exp_f32_e32 v119, v119
	v_exp_f32_e32 v120, v120
	v_exp_f32_e32 v121, v121
	v_exp_f32_e32 v116, v116
	v_exp_f32_e32 v117, v117
	v_add_f32_e32 v114, 1.0, v114
	v_add_f32_e32 v115, 1.0, v115
	v_rcp_f32_e32 v114, v114
	v_rcp_f32_e32 v115, v115
	v_add_f32_e32 v118, 1.0, v118
	v_add_f32_e32 v119, 1.0, v119
	v_add_f32_e32 v120, 1.0, v120
	v_add_f32_e32 v121, 1.0, v121
	v_add_f32_e32 v116, 1.0, v116
	v_add_f32_e32 v117, 1.0, v117
	v_rcp_f32_e32 v118, v118
	v_rcp_f32_e32 v120, v120
	v_rcp_f32_e32 v121, v121
	v_rcp_f32_e32 v119, v119
	v_rcp_f32_e32 v116, v116
	v_rcp_f32_e32 v117, v117
	v_lshlrev_b64 v[112:113], 12, v[166:167]
	v_pk_mul_f32 v[108:109], v[108:109], v[114:115]
	v_pk_mul_f32 v[114:115], v[106:107], v[120:121]
	v_pk_mul_f32 v[106:107], v[104:105], v[118:119]
	v_cvt_pk_bf16_f32 v104, v108, v109
	v_lshl_add_u64 v[108:109], s[4:5], 0, v[112:113]
	v_pk_mul_f32 v[110:111], v[110:111], v[116:117]
	v_lshl_add_u64 v[108:109], v[108:109], 0, v[156:157]
	v_cvt_pk_bf16_f32 v105, v110, v111
	v_cvt_pk_bf16_f32 v106, v106, v107
	v_cvt_pk_bf16_f32 v107, v114, v115
	global_store_dwordx4 v[108:109], v[104:107], off
	v_lshlrev_b32_e32 v110, 16, v146
	v_and_b32_e32 v111, 0xffff0000, v146
	v_lshlrev_b32_e32 v104, 16, v144
	v_and_b32_e32 v105, 0xffff0000, v144
	v_lshlrev_b32_e32 v112, 16, v147
	v_and_b32_e32 v113, 0xffff0000, v147
	v_lshlrev_b32_e32 v106, 16, v145
	v_and_b32_e32 v107, 0xffff0000, v145
	v_mul_f32_e32 v104, 0xbfb8aa3b, v104
	v_mul_f32_e32 v105, 0xbfb8aa3b, v105
	v_mul_f32_e32 v110, 0xbfb8aa3b, v110
	v_mul_f32_e32 v111, 0xbfb8aa3b, v111
; __device__ __forceinline__ u32x4 pack8(const f32x4 v0, const f32x4 v1) { u32x4 w; w.x = cvt_pk_bf16(v0[0], v0[1]); w.y = cvt_pk_bf16(v0[2], v0[3]); w.z = cvt_pk_bf16(v1[0], v1[1]); w.w = cvt_pk_bf16(v1[2], v1[3]); return w; }
; __device__ __forceinline__ void unpack8(const u32x4 w, f32x4& v0, f32x4& v1) { v0 = (f32x4){bflo(w.x), bfhi(w.x), bflo(w.y), bfhi(w.y)}; v1 = (f32x4){bflo(w.z), bfhi(w.z), bflo(w.w), bfhi(w.w)}; }
; __device__ __forceinline__ f32x4 sig4(const f32x4 v) { return (f32x4){sigmoidf_(v[0]), sigmoidf_(v[1]), sigmoidf_(v[2]), sigmoidf_(v[3])}; }
;     __device__ __forceinline__ void operator()(const AccT& acc, const pg8::Unit& u, int wr, int wc, int fr, int fq) const {
;     ...
;         for (int ai = 0; ai < 2; ++ai) { u32x4 gw[4][2];
; #pragma unroll
;             for (int m = 0; m < 4; ++m)
; #pragma unroll
;                 for (int bj = 0; bj < 2; ++bj) gw[m][bj] = *(const u32x4*)(PROJ + (size_t)(row0 + ai * 128 + m * 16) * NPROJ + C_GA + col0 + bj * 128);
; #pragma unroll
;             for (int m = 0; m < 4; ++m)
; #pragma unroll
;                 for (int bj = 0; bj < 2; ++bj) { f32x4 g0, g1; unpack8(gw[m][bj], g0, g1);
;                     *(u32x4*)(T + (size_t)(row0 + ai * 128 + m * 16) * D + col0 + bj * 128) = pack8(sig4(g0) * acc[ai][bj][m][0], sig4(g1) * acc[ai][bj][m][1]); } }
;     }
	v_mul_f32_e32 v112, 0xbfb8aa3b, v112
	v_mul_f32_e32 v113, 0xbfb8aa3b, v113
	v_exp_f32_e32 v104, v104
	v_exp_f32_e32 v105, v105
	v_mul_f32_e32 v106, 0xbfb8aa3b, v106
	v_mul_f32_e32 v107, 0xbfb8aa3b, v107
	v_exp_f32_e32 v110, v110
	v_exp_f32_e32 v111, v111
	v_exp_f32_e32 v112, v112
	v_exp_f32_e32 v113, v113
	v_exp_f32_e32 v106, v106
	v_exp_f32_e32 v107, v107
	v_add_f32_e32 v104, 1.0, v104
	v_add_f32_e32 v105, 1.0, v105
	v_add_f32_e32 v110, 1.0, v110
	v_add_f32_e32 v111, 1.0, v111
	v_add_f32_e32 v112, 1.0, v112
	v_add_f32_e32 v113, 1.0, v113
	v_rcp_f32_e32 v104, v104
	v_rcp_f32_e32 v105, v105
	v_add_f32_e32 v106, 1.0, v106
	v_add_f32_e32 v107, 1.0, v107
	v_rcp_f32_e32 v110, v110
	v_rcp_f32_e32 v112, v112
	v_rcp_f32_e32 v113, v113
	v_rcp_f32_e32 v111, v111
	v_rcp_f32_e32 v106, v106
	v_rcp_f32_e32 v107, v107
	v_pk_mul_f32 v[100:101], v[100:101], v[104:105]
	v_pk_mul_f32 v[104:105], v[98:99], v[112:113]
	v_pk_mul_f32 v[98:99], v[96:97], v[110:111]
	v_pk_mul_f32 v[102:103], v[102:103], v[106:107]
	v_cvt_pk_bf16_f32 v96, v100, v101
	v_lshlrev_b32_e32 v100, 16, v141
	v_cvt_pk_bf16_f32 v97, v102, v103
	v_cvt_pk_bf16_f32 v98, v98, v99
	v_cvt_pk_bf16_f32 v99, v104, v105
	global_store_dwordx4 v[108:109], v[96:99], off offset:256
	v_lshlrev_b32_e32 v102, 16, v142
	v_and_b32_e32 v103, 0xffff0000, v142
	v_lshlrev_b32_e32 v98, 16, v140
	v_and_b32_e32 v99, 0xffff0000, v140
	v_mul_f32_e32 v98, 0xbfb8aa3b, v98
	v_lshlrev_b32_e32 v104, 16, v143
	v_and_b32_e32 v105, 0xffff0000, v143
	v_mul_f32_e32 v99, 0xbfb8aa3b, v99
	v_and_b32_e32 v101, 0xffff0000, v141
	v_exp_f32_e32 v98, v98
	v_exp_f32_e32 v99, v99
	v_mul_f32_e32 v102, 0xbfb8aa3b, v102
	v_mul_f32_e32 v103, 0xbfb8aa3b, v103
	v_mul_f32_e32 v104, 0xbfb8aa3b, v104
	v_mul_f32_e32 v105, 0xbfb8aa3b, v105
	v_mul_f32_e32 v100, 0xbfb8aa3b, v100
	v_mul_f32_e32 v101, 0xbfb8aa3b, v101
	v_exp_f32_e32 v102, v102
	v_exp_f32_e32 v103, v103
	v_exp_f32_e32 v104, v104
	v_exp_f32_e32 v105, v105
	v_exp_f32_e32 v100, v100
	v_exp_f32_e32 v101, v101
	v_add_f32_e32 v98, 1.0, v98
	v_add_f32_e32 v99, 1.0, v99
	v_rcp_f32_e32 v98, v98
	v_rcp_f32_e32 v99, v99
	v_add_f32_e32 v102, 1.0, v102
	v_add_f32_e32 v103, 1.0, v103
	v_add_f32_e32 v104, 1.0, v104
	v_add_f32_e32 v105, 1.0, v105
	v_add_f32_e32 v100, 1.0, v100
	v_add_f32_e32 v101, 1.0, v101
	v_rcp_f32_e32 v102, v102
	v_rcp_f32_e32 v104, v104
	v_rcp_f32_e32 v105, v105
	v_rcp_f32_e32 v103, v103
	v_rcp_f32_e32 v100, v100
	v_rcp_f32_e32 v101, v101
	v_lshlrev_b64 v[96:97], 12, v[164:165]
	v_pk_mul_f32 v[92:93], v[92:93], v[98:99]
	v_pk_mul_f32 v[98:99], v[90:91], v[104:105]
	v_pk_mul_f32 v[90:91], v[88:89], v[102:103]
	v_cvt_pk_bf16_f32 v88, v92, v93
	v_lshl_add_u64 v[92:93], s[4:5], 0, v[96:97]
	v_pk_mul_f32 v[94:95], v[94:95], v[100:101]
	v_lshl_add_u64 v[92:93], v[92:93], 0, v[156:157]
	v_cvt_pk_bf16_f32 v89, v94, v95
	v_cvt_pk_bf16_f32 v90, v90, v91
	v_cvt_pk_bf16_f32 v91, v98, v99
	global_store_dwordx4 v[92:93], v[88:91], off
	v_lshlrev_b32_e32 v94, 16, v138
	v_and_b32_e32 v95, 0xffff0000, v138
	v_lshlrev_b32_e32 v88, 16, v136
	v_and_b32_e32 v89, 0xffff0000, v136
	v_lshlrev_b32_e32 v96, 16, v139
	v_and_b32_e32 v97, 0xffff0000, v139
	v_lshlrev_b32_e32 v90, 16, v137
	v_and_b32_e32 v91, 0xffff0000, v137
	v_mul_f32_e32 v88, 0xbfb8aa3b, v88
	v_mul_f32_e32 v89, 0xbfb8aa3b, v89
	v_mul_f32_e32 v94, 0xbfb8aa3b, v94
	v_mul_f32_e32 v95, 0xbfb8aa3b, v95
	v_mul_f32_e32 v96, 0xbfb8aa3b, v96
	v_mul_f32_e32 v97, 0xbfb8aa3b, v97
	v_exp_f32_e32 v88, v88
	v_exp_f32_e32 v89, v89
	v_mul_f32_e32 v90, 0xbfb8aa3b, v90
	v_mul_f32_e32 v91, 0xbfb8aa3b, v91
	v_exp_f32_e32 v94, v94
	v_exp_f32_e32 v95, v95
	v_exp_f32_e32 v96, v96
	v_exp_f32_e32 v97, v97
	v_exp_f32_e32 v90, v90
	v_exp_f32_e32 v91, v91
	v_add_f32_e32 v88, 1.0, v88
	v_add_f32_e32 v89, 1.0, v89
	v_add_f32_e32 v94, 1.0, v94
	v_add_f32_e32 v95, 1.0, v95
	v_add_f32_e32 v96, 1.0, v96
	v_add_f32_e32 v97, 1.0, v97
	v_rcp_f32_e32 v88, v88
	v_rcp_f32_e32 v89, v89
	v_add_f32_e32 v90, 1.0, v90
	v_add_f32_e32 v91, 1.0, v91
	v_rcp_f32_e32 v94, v94
	v_rcp_f32_e32 v96, v96
	v_rcp_f32_e32 v97, v97
	v_rcp_f32_e32 v95, v95
	v_rcp_f32_e32 v90, v90
	v_rcp_f32_e32 v91, v91
	v_pk_mul_f32 v[84:85], v[84:85], v[88:89]
	v_pk_mul_f32 v[88:89], v[82:83], v[96:97]
	v_pk_mul_f32 v[82:83], v[80:81], v[94:95]
	v_pk_mul_f32 v[86:87], v[86:87], v[90:91]
	v_cvt_pk_bf16_f32 v80, v84, v85
	v_lshlrev_b32_e32 v84, 16, v133
	v_cvt_pk_bf16_f32 v81, v86, v87
	v_cvt_pk_bf16_f32 v82, v82, v83
	v_cvt_pk_bf16_f32 v83, v88, v89
	global_store_dwordx4 v[92:93], v[80:83], off offset:256
	v_lshlrev_b32_e32 v86, 16, v134
	v_and_b32_e32 v87, 0xffff0000, v134
	v_lshlrev_b32_e32 v82, 16, v132
	v_and_b32_e32 v83, 0xffff0000, v132
	v_mul_f32_e32 v82, 0xbfb8aa3b, v82
	v_lshlrev_b32_e32 v88, 16, v135
	v_and_b32_e32 v89, 0xffff0000, v135
	v_mul_f32_e32 v83, 0xbfb8aa3b, v83
	v_and_b32_e32 v85, 0xffff0000, v133
	v_exp_f32_e32 v82, v82
	v_exp_f32_e32 v83, v83
	v_mul_f32_e32 v86, 0xbfb8aa3b, v86
	v_mul_f32_e32 v87, 0xbfb8aa3b, v87
	v_mul_f32_e32 v88, 0xbfb8aa3b, v88
	v_mul_f32_e32 v89, 0xbfb8aa3b, v89
	v_mul_f32_e32 v84, 0xbfb8aa3b, v84
	v_mul_f32_e32 v85, 0xbfb8aa3b, v85
	v_exp_f32_e32 v86, v86
	v_exp_f32_e32 v87, v87
	v_exp_f32_e32 v88, v88
	v_exp_f32_e32 v89, v89
	v_exp_f32_e32 v84, v84
	v_exp_f32_e32 v85, v85
	v_add_f32_e32 v82, 1.0, v82
	v_add_f32_e32 v83, 1.0, v83
	v_rcp_f32_e32 v82, v82
	v_rcp_f32_e32 v83, v83
	v_add_f32_e32 v86, 1.0, v86
	v_add_f32_e32 v87, 1.0, v87
	v_add_f32_e32 v88, 1.0, v88
	v_add_f32_e32 v89, 1.0, v89
	v_add_f32_e32 v84, 1.0, v84
	v_add_f32_e32 v85, 1.0, v85
	v_rcp_f32_e32 v86, v86
	v_rcp_f32_e32 v88, v88
	v_rcp_f32_e32 v89, v89
	v_rcp_f32_e32 v87, v87
	v_rcp_f32_e32 v84, v84
; __device__ __forceinline__ u32x4 pack8(const f32x4 v0, const f32x4 v1) { u32x4 w; w.x = cvt_pk_bf16(v0[0], v0[1]); w.y = cvt_pk_bf16(v0[2], v0[3]); w.z = cvt_pk_bf16(v1[0], v1[1]); w.w = cvt_pk_bf16(v1[2], v1[3]); return w; }
; __device__ __forceinline__ void unpack8(const u32x4 w, f32x4& v0, f32x4& v1) { v0 = (f32x4){bflo(w.x), bfhi(w.x), bflo(w.y), bfhi(w.y)}; v1 = (f32x4){bflo(w.z), bfhi(w.z), bflo(w.w), bfhi(w.w)}; }
; __device__ __forceinline__ f32x4 sig4(const f32x4 v) { return (f32x4){sigmoidf_(v[0]), sigmoidf_(v[1]), sigmoidf_(v[2]), sigmoidf_(v[3])}; }
;     __device__ __forceinline__ void operator()(const AccT& acc, const pg8::Unit& u, int wr, int wc, int fr, int fq) const {
;     ...
;         for (int ai = 0; ai < 2; ++ai) { u32x4 gw[4][2];
; #pragma unroll
;             for (int m = 0; m < 4; ++m)
; #pragma unroll
;                 for (int bj = 0; bj < 2; ++bj) gw[m][bj] = *(const u32x4*)(PROJ + (size_t)(row0 + ai * 128 + m * 16) * NPROJ + C_GA + col0 + bj * 128);
; #pragma unroll
;             for (int m = 0; m < 4; ++m)
; #pragma unroll
;                 for (int bj = 0; bj < 2; ++bj) { f32x4 g0, g1; unpack8(gw[m][bj], g0, g1);
;                     *(u32x4*)(T + (size_t)(row0 + ai * 128 + m * 16) * D + col0 + bj * 128) = pack8(sig4(g0) * acc[ai][bj][m][0], sig4(g1) * acc[ai][bj][m][1]); } }
;     }
	v_rcp_f32_e32 v85, v85
	v_lshlrev_b64 v[80:81], 12, v[162:163]
	v_pk_mul_f32 v[76:77], v[76:77], v[82:83]
	v_pk_mul_f32 v[82:83], v[74:75], v[88:89]
	v_pk_mul_f32 v[74:75], v[72:73], v[86:87]
	v_cvt_pk_bf16_f32 v72, v76, v77
	v_lshl_add_u64 v[76:77], s[4:5], 0, v[80:81]
	v_pk_mul_f32 v[78:79], v[78:79], v[84:85]
	v_lshl_add_u64 v[76:77], v[76:77], 0, v[156:157]
	v_cvt_pk_bf16_f32 v73, v78, v79
	v_cvt_pk_bf16_f32 v74, v74, v75
	v_cvt_pk_bf16_f32 v75, v82, v83
	global_store_dwordx4 v[76:77], v[72:75], off
	v_lshlrev_b32_e32 v78, 16, v130
	v_and_b32_e32 v79, 0xffff0000, v130
	v_lshlrev_b32_e32 v72, 16, v128
	v_and_b32_e32 v73, 0xffff0000, v128
	v_mul_f32_e32 v72, 0xbfb8aa3b, v72
	v_lshlrev_b32_e32 v80, 16, v131
	v_and_b32_e32 v81, 0xffff0000, v131
	v_mul_f32_e32 v73, 0xbfb8aa3b, v73
	v_lshlrev_b32_e32 v74, 16, v129
	v_and_b32_e32 v75, 0xffff0000, v129
	v_exp_f32_e32 v72, v72
	v_exp_f32_e32 v73, v73
	v_mul_f32_e32 v78, 0xbfb8aa3b, v78
	v_mul_f32_e32 v79, 0xbfb8aa3b, v79
	v_mul_f32_e32 v80, 0xbfb8aa3b, v80
	v_mul_f32_e32 v81, 0xbfb8aa3b, v81
	v_mul_f32_e32 v74, 0xbfb8aa3b, v74
	v_mul_f32_e32 v75, 0xbfb8aa3b, v75
	v_exp_f32_e32 v78, v78
	v_exp_f32_e32 v79, v79
	v_exp_f32_e32 v80, v80
	v_exp_f32_e32 v81, v81
	v_exp_f32_e32 v74, v74
	v_exp_f32_e32 v75, v75
	v_add_f32_e32 v72, 1.0, v72
	v_add_f32_e32 v73, 1.0, v73
	v_rcp_f32_e32 v72, v72
	v_rcp_f32_e32 v73, v73
	v_add_f32_e32 v78, 1.0, v78
	v_add_f32_e32 v79, 1.0, v79
	v_add_f32_e32 v80, 1.0, v80
	v_add_f32_e32 v81, 1.0, v81
	v_add_f32_e32 v74, 1.0, v74
	v_add_f32_e32 v75, 1.0, v75
	v_rcp_f32_e32 v78, v78
	v_rcp_f32_e32 v80, v80
	v_rcp_f32_e32 v81, v81
	v_rcp_f32_e32 v79, v79
	v_rcp_f32_e32 v74, v74
	v_rcp_f32_e32 v75, v75
	v_pk_mul_f32 v[68:69], v[68:69], v[72:73]
	v_add_u32_e32 v100, 0x80, v158
	v_pk_mul_f32 v[72:73], v[66:67], v[80:81]
	v_pk_mul_f32 v[66:67], v[64:65], v[78:79]
	v_cvt_pk_bf16_f32 v64, v68, v69
	v_mad_i64_i32 v[68:69], s[28:29], v100, s61, v[160:161]
	v_pk_mul_f32 v[70:71], v[70:71], v[74:75]
	v_lshl_add_u64 v[68:69], v[68:69], 0, v[156:157]
	v_cvt_pk_bf16_f32 v65, v70, v71
	v_add_co_u32_e32 v70, vcc, s60, v68
	v_cvt_pk_bf16_f32 v66, v66, v67
	v_cvt_pk_bf16_f32 v67, v72, v73
	global_store_dwordx4 v[76:77], v[64:67], off offset:256
	s_nop 0
	v_addc_co_u32_e32 v71, vcc, 0, v69, vcc
	global_load_dwordx4 v[88:91], v[70:71], off offset:2048
	v_lshl_add_u64 v[64:65], v[68:69], 0, s[16:17]
	global_load_dwordx4 v[92:95], v[64:65], off offset:256
	v_add_u32_e32 v102, 0x90, v158
	v_mad_i64_i32 v[64:65], s[28:29], v102, s61, v[160:161]
	v_lshl_add_u64 v[64:65], v[64:65], 0, v[156:157]
	v_lshl_add_u64 v[66:67], v[64:65], 0, s[16:17]
	v_add_co_u32_e32 v64, vcc, s60, v64
	v_add_u32_e32 v86, 0xa0, v158
	s_nop 0
	v_addc_co_u32_e32 v65, vcc, 0, v65, vcc
	global_load_dwordx4 v[96:99], v[64:65], off offset:2048
	global_load_dwordx4 v[80:83], v[66:67], off offset:256
	v_mad_i64_i32 v[64:65], s[28:29], v86, s61, v[160:161]
	v_lshl_add_u64 v[64:65], v[64:65], 0, v[156:157]
	v_lshl_add_u64 v[66:67], v[64:65], 0, s[16:17]
	v_add_co_u32_e32 v64, vcc, s60, v64
	v_add_u32_e32 v84, 0xb0, v158
	s_nop 0
	v_addc_co_u32_e32 v65, vcc, 0, v65, vcc
	global_load_dwordx4 v[76:79], v[64:65], off offset:2048
	global_load_dwordx4 v[72:75], v[66:67], off offset:256
	v_mad_i64_i32 v[64:65], s[28:29], v84, s61, v[160:161]
	v_lshl_add_u64 v[64:65], v[64:65], 0, v[156:157]
	v_lshl_add_u64 v[66:67], v[64:65], 0, s[16:17]
	v_add_co_u32_e32 v64, vcc, s60, v64
	v_ashrrev_i32_e32 v101, 31, v100
	s_nop 0
	v_addc_co_u32_e32 v65, vcc, 0, v65, vcc
	global_load_dwordx4 v[68:71], v[64:65], off offset:2048
	s_nop 0
	global_load_dwordx4 v[64:67], v[66:67], off offset:256
	v_lshlrev_b64 v[100:101], 12, v[100:101]
	v_ashrrev_i32_e32 v103, 31, v102
	v_ashrrev_i32_e32 v87, 31, v86
	v_ashrrev_i32_e32 v85, 31, v84
	s_and_b64 vcc, exec, s[2:3]
	s_mov_b64 s[28:29], s[22:23]
	s_waitcnt vmcnt(0)
	v_lshlrev_b32_e32 v104, 16, v88
	v_and_b32_e32 v88, 0xffff0000, v88
	v_lshlrev_b32_e32 v105, 16, v89
	v_and_b32_e32 v106, 0xffff0000, v89
	v_mul_f32_e32 v89, 0xbfb8aa3b, v104
	v_mul_f32_e32 v88, 0xbfb8aa3b, v88
	v_lshlrev_b32_e32 v107, 16, v90
	v_exp_f32_e32 v89, v89
	v_and_b32_e32 v108, 0xffff0000, v90
	v_exp_f32_e32 v90, v88
	v_mul_f32_e32 v88, 0xbfb8aa3b, v105
	v_lshlrev_b32_e32 v109, 16, v91
	v_and_b32_e32 v110, 0xffff0000, v91
	v_exp_f32_e32 v91, v88
	v_add_f32_e32 v89, 1.0, v89
	v_rcp_f32_e32 v88, v89
	v_add_f32_e32 v89, 1.0, v90
	v_add_f32_e32 v90, 1.0, v91
	v_mul_f32_e32 v91, 0xbfb8aa3b, v106
	v_mul_f32_e32 v104, 0xbfb8aa3b, v107
	v_mul_f32_e32 v105, 0xbfb8aa3b, v108
	v_mul_f32_e32 v106, 0xbfb8aa3b, v109
	v_mul_f32_e32 v107, 0xbfb8aa3b, v110
	v_exp_f32_e32 v104, v104
	v_exp_f32_e32 v105, v105
	v_exp_f32_e32 v106, v106
	v_exp_f32_e32 v107, v107
	v_exp_f32_e32 v91, v91
	v_rcp_f32_e32 v89, v89
	v_add_f32_e32 v104, 1.0, v104
	v_add_f32_e32 v105, 1.0, v105
	v_add_f32_e32 v106, 1.0, v106
	v_add_f32_e32 v107, 1.0, v107
	v_add_f32_e32 v91, 1.0, v91
	v_rcp_f32_e32 v104, v104
	v_rcp_f32_e32 v106, v106
	v_rcp_f32_e32 v107, v107
	v_rcp_f32_e32 v105, v105
	v_rcp_f32_e32 v90, v90
	v_rcp_f32_e32 v91, v91
	v_pk_mul_f32 v[60:61], v[60:61], v[88:89]
	v_pk_mul_f32 v[88:89], v[58:59], v[106:107]
	v_pk_mul_f32 v[58:59], v[56:57], v[104:105]
	v_cvt_pk_bf16_f32 v56, v60, v61
	v_lshl_add_u64 v[60:61], s[4:5], 0, v[100:101]
	v_pk_mul_f32 v[62:63], v[62:63], v[90:91]
	v_lshl_add_u64 v[60:61], v[60:61], 0, v[156:157]
	v_cvt_pk_bf16_f32 v57, v62, v63
	v_cvt_pk_bf16_f32 v58, v58, v59
	v_cvt_pk_bf16_f32 v59, v88, v89
	global_store_dwordx4 v[60:61], v[56:59], off
	v_lshlrev_b32_e32 v62, 16, v94
	v_and_b32_e32 v63, 0xffff0000, v94
	v_lshlrev_b32_e32 v56, 16, v92
; __device__ __forceinline__ u32x4 pack8(const f32x4 v0, const f32x4 v1) { u32x4 w; w.x = cvt_pk_bf16(v0[0], v0[1]); w.y = cvt_pk_bf16(v0[2], v0[3]); w.z = cvt_pk_bf16(v1[0], v1[1]); w.w = cvt_pk_bf16(v1[2], v1[3]); return w; }
; __device__ __forceinline__ void unpack8(const u32x4 w, f32x4& v0, f32x4& v1) { v0 = (f32x4){bflo(w.x), bfhi(w.x), bflo(w.y), bfhi(w.y)}; v1 = (f32x4){bflo(w.z), bfhi(w.z), bflo(w.w), bfhi(w.w)}; }
; __device__ __forceinline__ f32x4 sig4(const f32x4 v) { return (f32x4){sigmoidf_(v[0]), sigmoidf_(v[1]), sigmoidf_(v[2]), sigmoidf_(v[3])}; }
;     __device__ __forceinline__ void operator()(const AccT& acc, const pg8::Unit& u, int wr, int wc, int fr, int fq) const {
;     ...
;         for (int ai = 0; ai < 2; ++ai) { u32x4 gw[4][2];
; #pragma unroll
;             for (int m = 0; m < 4; ++m)
; #pragma unroll
;                 for (int bj = 0; bj < 2; ++bj) gw[m][bj] = *(const u32x4*)(PROJ + (size_t)(row0 + ai * 128 + m * 16) * NPROJ + C_GA + col0 + bj * 128);
; #pragma unroll
;             for (int m = 0; m < 4; ++m)
; #pragma unroll
;                 for (int bj = 0; bj < 2; ++bj) { f32x4 g0, g1; unpack8(gw[m][bj], g0, g1);
;                     *(u32x4*)(T + (size_t)(row0 + ai * 128 + m * 16) * D + col0 + bj * 128) = pack8(sig4(g0) * acc[ai][bj][m][0], sig4(g1) * acc[ai][bj][m][1]); } }
;     }
	v_and_b32_e32 v57, 0xffff0000, v92
	v_lshlrev_b32_e32 v88, 16, v95
	v_and_b32_e32 v89, 0xffff0000, v95
	v_lshlrev_b32_e32 v58, 16, v93
	v_and_b32_e32 v59, 0xffff0000, v93
	v_mul_f32_e32 v56, 0xbfb8aa3b, v56
	v_mul_f32_e32 v57, 0xbfb8aa3b, v57
	v_mul_f32_e32 v62, 0xbfb8aa3b, v62
	v_mul_f32_e32 v63, 0xbfb8aa3b, v63
	v_mul_f32_e32 v88, 0xbfb8aa3b, v88
	v_mul_f32_e32 v89, 0xbfb8aa3b, v89
	v_exp_f32_e32 v56, v56
	v_exp_f32_e32 v57, v57
	v_mul_f32_e32 v58, 0xbfb8aa3b, v58
	v_mul_f32_e32 v59, 0xbfb8aa3b, v59
	v_exp_f32_e32 v62, v62
	v_exp_f32_e32 v63, v63
	v_exp_f32_e32 v88, v88
	v_exp_f32_e32 v89, v89
	v_exp_f32_e32 v58, v58
	v_exp_f32_e32 v59, v59
	v_add_f32_e32 v56, 1.0, v56
	v_add_f32_e32 v57, 1.0, v57
	v_add_f32_e32 v62, 1.0, v62
	v_add_f32_e32 v63, 1.0, v63
	v_add_f32_e32 v88, 1.0, v88
	v_add_f32_e32 v89, 1.0, v89
	v_rcp_f32_e32 v56, v56
	v_rcp_f32_e32 v57, v57
	v_add_f32_e32 v58, 1.0, v58
	v_add_f32_e32 v59, 1.0, v59
	v_rcp_f32_e32 v62, v62
	v_rcp_f32_e32 v88, v88
	v_rcp_f32_e32 v89, v89
	v_rcp_f32_e32 v63, v63
	v_rcp_f32_e32 v58, v58
	v_rcp_f32_e32 v59, v59
	v_pk_mul_f32 v[52:53], v[52:53], v[56:57]
	v_pk_mul_f32 v[56:57], v[50:51], v[88:89]
	v_pk_mul_f32 v[50:51], v[48:49], v[62:63]
	v_pk_mul_f32 v[54:55], v[54:55], v[58:59]
	v_cvt_pk_bf16_f32 v48, v52, v53
	v_lshlrev_b32_e32 v52, 16, v97
	v_cvt_pk_bf16_f32 v49, v54, v55
	v_cvt_pk_bf16_f32 v50, v50, v51
	v_cvt_pk_bf16_f32 v51, v56, v57
	global_store_dwordx4 v[60:61], v[48:51], off offset:256
	v_lshlrev_b32_e32 v54, 16, v98
	v_and_b32_e32 v55, 0xffff0000, v98
	v_lshlrev_b32_e32 v50, 16, v96
	v_and_b32_e32 v51, 0xffff0000, v96
	v_mul_f32_e32 v50, 0xbfb8aa3b, v50
	v_lshlrev_b32_e32 v56, 16, v99
	v_and_b32_e32 v57, 0xffff0000, v99
	v_mul_f32_e32 v51, 0xbfb8aa3b, v51
	v_and_b32_e32 v53, 0xffff0000, v97
	v_exp_f32_e32 v50, v50
	v_exp_f32_e32 v51, v51
	v_mul_f32_e32 v54, 0xbfb8aa3b, v54
	v_mul_f32_e32 v55, 0xbfb8aa3b, v55
	v_mul_f32_e32 v56, 0xbfb8aa3b, v56
	v_mul_f32_e32 v57, 0xbfb8aa3b, v57
	v_mul_f32_e32 v52, 0xbfb8aa3b, v52
	v_mul_f32_e32 v53, 0xbfb8aa3b, v53
	v_exp_f32_e32 v54, v54
	v_exp_f32_e32 v55, v55
	v_exp_f32_e32 v56, v56
	v_exp_f32_e32 v57, v57
	v_exp_f32_e32 v52, v52
	v_exp_f32_e32 v53, v53
	v_add_f32_e32 v50, 1.0, v50
	v_add_f32_e32 v51, 1.0, v51
	v_rcp_f32_e32 v50, v50
	v_rcp_f32_e32 v51, v51
	v_add_f32_e32 v54, 1.0, v54
	v_add_f32_e32 v55, 1.0, v55
	v_add_f32_e32 v56, 1.0, v56
	v_add_f32_e32 v57, 1.0, v57
	v_add_f32_e32 v52, 1.0, v52
	v_add_f32_e32 v53, 1.0, v53
	v_rcp_f32_e32 v54, v54
	v_rcp_f32_e32 v56, v56
	v_rcp_f32_e32 v57, v57
	v_rcp_f32_e32 v55, v55
	v_rcp_f32_e32 v52, v52
	v_rcp_f32_e32 v53, v53
	v_lshlrev_b64 v[48:49], 12, v[102:103]
	v_pk_mul_f32 v[44:45], v[44:45], v[50:51]
	v_pk_mul_f32 v[50:51], v[42:43], v[56:57]
	v_pk_mul_f32 v[42:43], v[40:41], v[54:55]
	v_cvt_pk_bf16_f32 v40, v44, v45
	v_lshl_add_u64 v[44:45], s[4:5], 0, v[48:49]
	v_pk_mul_f32 v[46:47], v[46:47], v[52:53]
	v_lshl_add_u64 v[44:45], v[44:45], 0, v[156:157]
	v_cvt_pk_bf16_f32 v41, v46, v47
	v_cvt_pk_bf16_f32 v42, v42, v43
	v_cvt_pk_bf16_f32 v43, v50, v51
	global_store_dwordx4 v[44:45], v[40:43], off
	v_lshlrev_b32_e32 v46, 16, v82
	v_and_b32_e32 v47, 0xffff0000, v82
	v_lshlrev_b32_e32 v40, 16, v80
	v_and_b32_e32 v41, 0xffff0000, v80
	v_lshlrev_b32_e32 v48, 16, v83
	v_and_b32_e32 v49, 0xffff0000, v83
	v_lshlrev_b32_e32 v42, 16, v81
	v_and_b32_e32 v43, 0xffff0000, v81
	v_mul_f32_e32 v40, 0xbfb8aa3b, v40
	v_mul_f32_e32 v41, 0xbfb8aa3b, v41
	v_mul_f32_e32 v46, 0xbfb8aa3b, v46
	v_mul_f32_e32 v47, 0xbfb8aa3b, v47
	v_mul_f32_e32 v48, 0xbfb8aa3b, v48
	v_mul_f32_e32 v49, 0xbfb8aa3b, v49
	v_exp_f32_e32 v40, v40
	v_exp_f32_e32 v41, v41
	v_mul_f32_e32 v42, 0xbfb8aa3b, v42
	v_mul_f32_e32 v43, 0xbfb8aa3b, v43
	v_exp_f32_e32 v46, v46
	v_exp_f32_e32 v47, v47
	v_exp_f32_e32 v48, v48
	v_exp_f32_e32 v49, v49
	v_exp_f32_e32 v42, v42
	v_exp_f32_e32 v43, v43
	v_add_f32_e32 v40, 1.0, v40
	v_add_f32_e32 v41, 1.0, v41
	v_add_f32_e32 v46, 1.0, v46
	v_add_f32_e32 v47, 1.0, v47
	v_add_f32_e32 v48, 1.0, v48
	v_add_f32_e32 v49, 1.0, v49
	v_rcp_f32_e32 v40, v40
	v_rcp_f32_e32 v41, v41
	v_add_f32_e32 v42, 1.0, v42
	v_add_f32_e32 v43, 1.0, v43
	v_rcp_f32_e32 v46, v46
	v_rcp_f32_e32 v48, v48
	v_rcp_f32_e32 v49, v49
	v_rcp_f32_e32 v47, v47
	v_rcp_f32_e32 v42, v42
	v_rcp_f32_e32 v43, v43
	v_pk_mul_f32 v[36:37], v[36:37], v[40:41]
	v_pk_mul_f32 v[40:41], v[34:35], v[48:49]
	v_pk_mul_f32 v[34:35], v[32:33], v[46:47]
	v_pk_mul_f32 v[38:39], v[38:39], v[42:43]
	v_cvt_pk_bf16_f32 v32, v36, v37
	v_lshlrev_b32_e32 v36, 16, v77
	v_cvt_pk_bf16_f32 v33, v38, v39
	v_cvt_pk_bf16_f32 v34, v34, v35
	v_cvt_pk_bf16_f32 v35, v40, v41
	global_store_dwordx4 v[44:45], v[32:35], off offset:256
	v_lshlrev_b32_e32 v38, 16, v78
	v_and_b32_e32 v39, 0xffff0000, v78
	v_lshlrev_b32_e32 v34, 16, v76
	v_and_b32_e32 v35, 0xffff0000, v76
	v_mul_f32_e32 v34, 0xbfb8aa3b, v34
	v_lshlrev_b32_e32 v40, 16, v79
	v_and_b32_e32 v41, 0xffff0000, v79
	v_mul_f32_e32 v35, 0xbfb8aa3b, v35
	v_and_b32_e32 v37, 0xffff0000, v77
	v_exp_f32_e32 v34, v34
	v_exp_f32_e32 v35, v35
	v_mul_f32_e32 v38, 0xbfb8aa3b, v38
	v_mul_f32_e32 v39, 0xbfb8aa3b, v39
	v_mul_f32_e32 v40, 0xbfb8aa3b, v40
	v_mul_f32_e32 v41, 0xbfb8aa3b, v41
	v_mul_f32_e32 v36, 0xbfb8aa3b, v36
	v_mul_f32_e32 v37, 0xbfb8aa3b, v37
	v_exp_f32_e32 v38, v38
	v_exp_f32_e32 v39, v39
	v_exp_f32_e32 v40, v40
	v_exp_f32_e32 v41, v41
	v_exp_f32_e32 v36, v36
	v_exp_f32_e32 v37, v37
	v_add_f32_e32 v34, 1.0, v34
	v_add_f32_e32 v35, 1.0, v35
	v_rcp_f32_e32 v34, v34
	v_rcp_f32_e32 v35, v35
	v_add_f32_e32 v38, 1.0, v38
	v_add_f32_e32 v39, 1.0, v39
; __device__ __forceinline__ u32x4 pack8(const f32x4 v0, const f32x4 v1) { u32x4 w; w.x = cvt_pk_bf16(v0[0], v0[1]); w.y = cvt_pk_bf16(v0[2], v0[3]); w.z = cvt_pk_bf16(v1[0], v1[1]); w.w = cvt_pk_bf16(v1[2], v1[3]); return w; }
; __device__ __forceinline__ void unpack8(const u32x4 w, f32x4& v0, f32x4& v1) { v0 = (f32x4){bflo(w.x), bfhi(w.x), bflo(w.y), bfhi(w.y)}; v1 = (f32x4){bflo(w.z), bfhi(w.z), bflo(w.w), bfhi(w.w)}; }
; __device__ __forceinline__ f32x4 sig4(const f32x4 v) { return (f32x4){sigmoidf_(v[0]), sigmoidf_(v[1]), sigmoidf_(v[2]), sigmoidf_(v[3])}; }
;     __device__ __forceinline__ void operator()(const AccT& acc, const pg8::Unit& u, int wr, int wc, int fr, int fq) const {
;     ...
;         for (int ai = 0; ai < 2; ++ai) { u32x4 gw[4][2];
; #pragma unroll
;             for (int m = 0; m < 4; ++m)
; #pragma unroll
;                 for (int bj = 0; bj < 2; ++bj) gw[m][bj] = *(const u32x4*)(PROJ + (size_t)(row0 + ai * 128 + m * 16) * NPROJ + C_GA + col0 + bj * 128);
; #pragma unroll
;             for (int m = 0; m < 4; ++m)
; #pragma unroll
;                 for (int bj = 0; bj < 2; ++bj) { f32x4 g0, g1; unpack8(gw[m][bj], g0, g1);
;                     *(u32x4*)(T + (size_t)(row0 + ai * 128 + m * 16) * D + col0 + bj * 128) = pack8(sig4(g0) * acc[ai][bj][m][0], sig4(g1) * acc[ai][bj][m][1]); } }
;     }
	v_add_f32_e32 v40, 1.0, v40
	v_add_f32_e32 v41, 1.0, v41
	v_add_f32_e32 v36, 1.0, v36
	v_add_f32_e32 v37, 1.0, v37
	v_rcp_f32_e32 v38, v38
	v_rcp_f32_e32 v40, v40
	v_rcp_f32_e32 v41, v41
	v_rcp_f32_e32 v39, v39
	v_rcp_f32_e32 v36, v36
	v_rcp_f32_e32 v37, v37
	v_lshlrev_b64 v[32:33], 12, v[86:87]
	v_pk_mul_f32 v[28:29], v[28:29], v[34:35]
	v_pk_mul_f32 v[34:35], v[26:27], v[40:41]
	v_pk_mul_f32 v[26:27], v[24:25], v[38:39]
	v_cvt_pk_bf16_f32 v24, v28, v29
	v_lshl_add_u64 v[28:29], s[4:5], 0, v[32:33]
	v_pk_mul_f32 v[30:31], v[30:31], v[36:37]
	v_lshl_add_u64 v[28:29], v[28:29], 0, v[156:157]
	v_cvt_pk_bf16_f32 v25, v30, v31
	v_cvt_pk_bf16_f32 v26, v26, v27
	v_cvt_pk_bf16_f32 v27, v34, v35
	global_store_dwordx4 v[28:29], v[24:27], off
	v_lshlrev_b32_e32 v30, 16, v74
	v_and_b32_e32 v31, 0xffff0000, v74
	v_lshlrev_b32_e32 v24, 16, v72
	v_and_b32_e32 v25, 0xffff0000, v72
	v_lshlrev_b32_e32 v32, 16, v75
	v_and_b32_e32 v33, 0xffff0000, v75
	v_lshlrev_b32_e32 v26, 16, v73
	v_and_b32_e32 v27, 0xffff0000, v73
	v_mul_f32_e32 v24, 0xbfb8aa3b, v24
	v_mul_f32_e32 v25, 0xbfb8aa3b, v25
	v_mul_f32_e32 v30, 0xbfb8aa3b, v30
	v_mul_f32_e32 v31, 0xbfb8aa3b, v31
	v_mul_f32_e32 v32, 0xbfb8aa3b, v32
	v_mul_f32_e32 v33, 0xbfb8aa3b, v33
	v_exp_f32_e32 v24, v24
	v_exp_f32_e32 v25, v25
	v_mul_f32_e32 v26, 0xbfb8aa3b, v26
	v_mul_f32_e32 v27, 0xbfb8aa3b, v27
	v_exp_f32_e32 v30, v30
	v_exp_f32_e32 v31, v31
	v_exp_f32_e32 v32, v32
	v_exp_f32_e32 v33, v33
	v_exp_f32_e32 v26, v26
	v_exp_f32_e32 v27, v27
	v_add_f32_e32 v24, 1.0, v24
	v_add_f32_e32 v25, 1.0, v25
	v_add_f32_e32 v30, 1.0, v30
	v_add_f32_e32 v31, 1.0, v31
	v_add_f32_e32 v32, 1.0, v32
	v_add_f32_e32 v33, 1.0, v33
	v_rcp_f32_e32 v24, v24
	v_rcp_f32_e32 v25, v25
	v_add_f32_e32 v26, 1.0, v26
	v_add_f32_e32 v27, 1.0, v27
	v_rcp_f32_e32 v30, v30
	v_rcp_f32_e32 v32, v32
	v_rcp_f32_e32 v33, v33
	v_rcp_f32_e32 v31, v31
	v_rcp_f32_e32 v26, v26
	v_rcp_f32_e32 v27, v27
	v_pk_mul_f32 v[20:21], v[20:21], v[24:25]
	v_pk_mul_f32 v[24:25], v[18:19], v[32:33]
	v_pk_mul_f32 v[18:19], v[16:17], v[30:31]
	v_pk_mul_f32 v[22:23], v[22:23], v[26:27]
	v_cvt_pk_bf16_f32 v16, v20, v21
	v_lshlrev_b32_e32 v20, 16, v69
	v_cvt_pk_bf16_f32 v17, v22, v23
	v_cvt_pk_bf16_f32 v18, v18, v19
	v_cvt_pk_bf16_f32 v19, v24, v25
	global_store_dwordx4 v[28:29], v[16:19], off offset:256
	v_lshlrev_b32_e32 v22, 16, v70
	v_and_b32_e32 v23, 0xffff0000, v70
	v_lshlrev_b32_e32 v18, 16, v68
	v_and_b32_e32 v19, 0xffff0000, v68
	v_mul_f32_e32 v18, 0xbfb8aa3b, v18
	v_lshlrev_b32_e32 v24, 16, v71
	v_and_b32_e32 v25, 0xffff0000, v71
	v_mul_f32_e32 v19, 0xbfb8aa3b, v19
	v_and_b32_e32 v21, 0xffff0000, v69
	v_exp_f32_e32 v18, v18
	v_exp_f32_e32 v19, v19
	v_mul_f32_e32 v22, 0xbfb8aa3b, v22
	v_mul_f32_e32 v23, 0xbfb8aa3b, v23
	v_mul_f32_e32 v24, 0xbfb8aa3b, v24
	v_mul_f32_e32 v25, 0xbfb8aa3b, v25
	v_mul_f32_e32 v20, 0xbfb8aa3b, v20
	v_mul_f32_e32 v21, 0xbfb8aa3b, v21
	v_exp_f32_e32 v22, v22
	v_exp_f32_e32 v23, v23
	v_exp_f32_e32 v24, v24
	v_exp_f32_e32 v25, v25
	v_exp_f32_e32 v20, v20
	v_exp_f32_e32 v21, v21
	v_add_f32_e32 v18, 1.0, v18
	v_add_f32_e32 v19, 1.0, v19
	v_rcp_f32_e32 v18, v18
	v_rcp_f32_e32 v19, v19
	v_add_f32_e32 v22, 1.0, v22
	v_add_f32_e32 v23, 1.0, v23
	v_add_f32_e32 v24, 1.0, v24
	v_add_f32_e32 v25, 1.0, v25
	v_add_f32_e32 v20, 1.0, v20
	v_add_f32_e32 v21, 1.0, v21
	v_rcp_f32_e32 v22, v22
	v_rcp_f32_e32 v24, v24
	v_rcp_f32_e32 v25, v25
	v_rcp_f32_e32 v23, v23
	v_rcp_f32_e32 v20, v20
	v_rcp_f32_e32 v21, v21
	v_lshlrev_b64 v[16:17], 12, v[84:85]
	v_pk_mul_f32 v[12:13], v[12:13], v[18:19]
	v_pk_mul_f32 v[18:19], v[10:11], v[24:25]
	v_pk_mul_f32 v[10:11], v[8:9], v[22:23]
	v_cvt_pk_bf16_f32 v8, v12, v13
	v_lshl_add_u64 v[12:13], s[4:5], 0, v[16:17]
	v_pk_mul_f32 v[14:15], v[14:15], v[20:21]
	v_lshl_add_u64 v[12:13], v[12:13], 0, v[156:157]
	v_cvt_pk_bf16_f32 v9, v14, v15
	v_cvt_pk_bf16_f32 v10, v10, v11
	v_cvt_pk_bf16_f32 v11, v18, v19
	global_store_dwordx4 v[12:13], v[8:11], off
	v_lshlrev_b32_e32 v14, 16, v66
	v_and_b32_e32 v15, 0xffff0000, v66
	v_lshlrev_b32_e32 v8, 16, v64
	v_and_b32_e32 v9, 0xffff0000, v64
	v_lshlrev_b32_e32 v16, 16, v67
	v_and_b32_e32 v17, 0xffff0000, v67
	v_lshlrev_b32_e32 v10, 16, v65
	v_and_b32_e32 v11, 0xffff0000, v65
	v_mul_f32_e32 v8, 0xbfb8aa3b, v8
	v_mul_f32_e32 v9, 0xbfb8aa3b, v9
	v_mul_f32_e32 v14, 0xbfb8aa3b, v14
	v_mul_f32_e32 v15, 0xbfb8aa3b, v15
	v_mul_f32_e32 v16, 0xbfb8aa3b, v16
	v_mul_f32_e32 v17, 0xbfb8aa3b, v17
	v_exp_f32_e32 v8, v8
	v_exp_f32_e32 v9, v9
	v_mul_f32_e32 v10, 0xbfb8aa3b, v10
	v_mul_f32_e32 v11, 0xbfb8aa3b, v11
	v_exp_f32_e32 v14, v14
	v_exp_f32_e32 v15, v15
	v_exp_f32_e32 v16, v16
	v_exp_f32_e32 v17, v17
	v_exp_f32_e32 v10, v10
	v_exp_f32_e32 v11, v11
	v_add_f32_e32 v8, 1.0, v8
	v_add_f32_e32 v9, 1.0, v9
	v_add_f32_e32 v14, 1.0, v14
	v_add_f32_e32 v15, 1.0, v15
	v_add_f32_e32 v16, 1.0, v16
	v_add_f32_e32 v17, 1.0, v17
	v_rcp_f32_e32 v8, v8
	v_rcp_f32_e32 v9, v9
	v_add_f32_e32 v10, 1.0, v10
	v_add_f32_e32 v11, 1.0, v11
	v_rcp_f32_e32 v14, v14
	v_rcp_f32_e32 v16, v16
	v_rcp_f32_e32 v17, v17
	v_rcp_f32_e32 v15, v15
	v_rcp_f32_e32 v10, v10
	v_rcp_f32_e32 v11, v11
	v_pk_mul_f32 v[4:5], v[4:5], v[8:9]
	v_pk_mul_f32 v[8:9], v[2:3], v[16:17]
	v_pk_mul_f32 v[2:3], v[0:1], v[14:15]
	v_pk_mul_f32 v[6:7], v[6:7], v[10:11]
	v_cvt_pk_bf16_f32 v0, v4, v5
	s_nop 0
	v_cvt_pk_bf16_f32 v1, v6, v7
	v_cvt_pk_bf16_f32 v2, v2, v3
	v_cvt_pk_bf16_f32 v3, v8, v9
	global_store_dwordx4 v[12:13], v[0:3], off offset:256
	s_cbranch_vccz .LBB0_907
	s_waitcnt vmcnt(0)
	s_cmpk_gt_u32 s41, 0xff
	s_cbranch_scc1 .LBB0_918
	s_barrier

; #define PG8_STAGE(bufoff, gbase, voff) do { _Pragma("unroll") for (int _i = 0; _i < 2; ++_i) \
;         __builtin_amdgcn_global_load_lds((const unsigned*)((const char*)(gbase) + (voff)[_i]), (LAS unsigned*)(lds + (bufoff) + ldsw + _i * 8192), 16, 0, 0); } while (0)
; #define PG8_LDA(dst, b, h) do { _Pragma("unroll") for (int m = 0; m < 4; ++m) _Pragma("unroll") for (int k = 0; k < 2; ++k) dst[m][k] = *(const LAS bf16x8*)(lds + PG8_SA(b, h) + aoff + m * 2048 + k * 1024); } while (0)
; #define PG8_LDB(dst, b, h) do { _Pragma("unroll") for (int n = 0; n < 2; ++n) _Pragma("unroll") for (int k = 0; k < 2; ++k) dst[n][k] = *(const LAS bf16x8*)(lds + PG8_SB(b, h) + boff + n * 2048 + k * 1024); } while (0)
; #define PG8_MMA(ai, bj, At, Bt) do { __builtin_amdgcn_s_setprio(1); _Pragma("unroll") for (int m = 0; m < 4; ++m) _Pragma("unroll") for (int n = 0; n < 2; ++n) _Pragma("unroll") for (int k = 0; k < 2; ++k) \
;         acc[ai][bj][m][n] = __builtin_amdgcn_mfma_f32_16x16x32_bf16(Bt[n][k], At[m][k], acc[ai][bj][m][n], 0, 0, 0); __builtin_amdgcn_s_setprio(0); } while (0)
; #define PG8_WAIT_V(n) asm volatile("s_waitcnt vmcnt(" #n ")" ::: "memory")
; #define PG8_WAIT_L(n) asm volatile("s_waitcnt lgkmcnt(" #n ")" ::: "memory")
; #define PG8_BAR __builtin_amdgcn_s_barrier()
; #define PG8_SCHED __builtin_amdgcn_sched_barrier(0)
; template <class Epi>
; __device__ __forceinline__ void gemm_phase(LAS unsigned char* lds, const Gemm g, const StaticOrder& S, const Epi& E) {
;     ...
;             PG8_LDB(B0, 0, 0); PG8_SCHED; PG8_LDA(At, 0, 0); PG8_STAGE(PG8_SA(1, 1), a1 + hstep, voffA);
;             PG8_WAIT_L(8); PG8_BAR; PG8_WAIT_L(0); PG8_MMA(0, 0, At, B0); PG8_BAR; PG8_SCHED;
;             PG8_LDB(B1, 0, 1); PG8_STAGE(PG8_SB(0, 0), b2, voffB);
;             PG8_BAR; PG8_WAIT_L(0); PG8_MMA(0, 1, At, B1); PG8_BAR;
;             PG8_LDA(At, 0, 1); PG8_STAGE(PG8_SA(0, 0), a2, voffA);
;             PG8_BAR; PG8_WAIT_L(0); PG8_MMA(1, 0, At, B0); PG8_BAR; PG8_SCHED;
;             PG8_STAGE(PG8_SB(0, 1), b2 + hstep, voffB);
;             PG8_WAIT_V(6); PG8_BAR; PG8_MMA(1, 1, At, B1); PG8_BAR;
.LBB0_930:
	ds_read_b128 v[128:131], v207
	ds_read_b128 v[132:135], v207 offset:1024
	ds_read_b128 v[136:139], v207 offset:2048
	ds_read_b128 v[140:143], v207 offset:3072
	s_add_u32 s28, s26, 0xfffc0080
	s_addc_u32 s29, s27, -1
	s_cmp_eq_u32 s62, 12
	s_cselect_b32 s31, s17, s29
	s_cselect_b32 s30, s58, s28
	s_cselect_b32 s29, s19, s61
	s_cselect_b32 s28, s59, s60
	v_lshl_add_u64 v[192:193], s[26:27], 0, v[180:181]
	s_add_i32 m0, s25, 0xc000
	ds_read_b128 v[144:147], v208
	ds_read_b128 v[148:151], v208 offset:1024
	ds_read_b128 v[152:155], v208 offset:2048
	ds_read_b128 v[156:159], v208 offset:3072
	ds_read_b128 v[160:163], v208 offset:4096
	ds_read_b128 v[164:167], v208 offset:5120
	ds_read_b128 v[168:171], v208 offset:6144
	ds_read_b128 v[188:191], v208 offset:7168
	global_load_lds_dwordx4 v[192:193], off
	v_lshl_add_u64 v[192:193], s[26:27], 0, v[182:183]
	s_add_i32 m0, s25, 0xe000
	s_nop 0
	global_load_lds_dwordx4 v[192:193], off
	s_waitcnt lgkmcnt(8)
	s_barrier
	s_waitcnt lgkmcnt(0)
	s_waitcnt lgkmcnt(0)
	v_mfma_f32_16x16x32_bf16 v[124:127], v[128:131], v[144:147], v[124:127]
	v_mfma_f32_16x16x32_bf16 v[120:123], v[136:139], v[144:147], v[120:123]
	v_mfma_f32_16x16x32_bf16 v[108:111], v[128:131], v[152:155], v[108:111]
	v_mfma_f32_16x16x32_bf16 v[104:107], v[136:139], v[152:155], v[104:107]
	v_mfma_f32_16x16x32_bf16 v[92:95], v[128:131], v[160:163], v[92:95]
	v_mfma_f32_16x16x32_bf16 v[88:91], v[136:139], v[160:163], v[88:91]
	v_mfma_f32_16x16x32_bf16 v[76:79], v[128:131], v[168:171], v[76:79]
	v_mfma_f32_16x16x32_bf16 v[72:75], v[136:139], v[168:171], v[72:75]
	v_mfma_f32_16x16x32_bf16 v[124:127], v[132:135], v[148:151], v[124:127]
	v_mfma_f32_16x16x32_bf16 v[120:123], v[140:143], v[148:151], v[120:123]
	v_mfma_f32_16x16x32_bf16 v[108:111], v[132:135], v[156:159], v[108:111]
	v_mfma_f32_16x16x32_bf16 v[104:107], v[140:143], v[156:159], v[104:107]
	v_mfma_f32_16x16x32_bf16 v[92:95], v[132:135], v[164:167], v[92:95]
	v_mfma_f32_16x16x32_bf16 v[88:91], v[140:143], v[164:167], v[88:91]
	v_mfma_f32_16x16x32_bf16 v[76:79], v[132:135], v[188:191], v[76:79]
	v_mfma_f32_16x16x32_bf16 v[72:75], v[140:143], v[188:191], v[72:75]
	s_barrier
	s_add_i32 s63, s51, s35
	v_lshl_add_u64 v[200:201], s[28:29], 0, v[174:175]
	s_mov_b32 m0, s63
	ds_read_b128 v[192:195], v209
	ds_read_b128 v[196:199], v209 offset:1024
	ds_read_b128 v[210:213], v209 offset:2048
	ds_read_b128 v[216:219], v209 offset:3072
	global_load_lds_dwordx4 v[200:201], off
	v_lshl_add_u64 v[220:221], s[28:29], 0, v[178:179]
	s_add_i32 m0, s63, 0x2000
	s_nop 0
	global_load_lds_dwordx4 v[220:221], off
	s_barrier
	s_waitcnt lgkmcnt(0)
	s_waitcnt lgkmcnt(0)
	v_mfma_f32_16x16x32_bf16 v[116:119], v[192:195], v[144:147], v[116:119]
	v_mfma_f32_16x16x32_bf16 v[112:115], v[210:213], v[144:147], v[112:115]
	v_mfma_f32_16x16x32_bf16 v[100:103], v[192:195], v[152:155], v[100:103]
	v_mfma_f32_16x16x32_bf16 v[96:99], v[210:213], v[152:155], v[96:99]
	v_mfma_f32_16x16x32_bf16 v[84:87], v[192:195], v[160:163], v[84:87]
	v_mfma_f32_16x16x32_bf16 v[80:83], v[210:213], v[160:163], v[80:83]
	v_mfma_f32_16x16x32_bf16 v[68:71], v[192:195], v[168:171], v[68:71]
	v_mfma_f32_16x16x32_bf16 v[64:67], v[210:213], v[168:171], v[64:67]
	v_mfma_f32_16x16x32_bf16 v[116:119], v[196:199], v[148:151], v[116:119]
	v_mfma_f32_16x16x32_bf16 v[112:115], v[216:219], v[148:151], v[112:115]
	v_mfma_f32_16x16x32_bf16 v[100:103], v[196:199], v[156:159], v[100:103]
	v_mfma_f32_16x16x32_bf16 v[96:99], v[216:219], v[156:159], v[96:99]
	v_mfma_f32_16x16x32_bf16 v[84:87], v[196:199], v[164:167], v[84:87]
	v_mfma_f32_16x16x32_bf16 v[80:83], v[216:219], v[164:167], v[80:83]
	v_mfma_f32_16x16x32_bf16 v[68:71], v[196:199], v[188:191], v[68:71]
	v_mfma_f32_16x16x32_bf16 v[64:67], v[216:219], v[188:191], v[64:67]
	s_mov_b32 m0, s25
	v_lshl_add_u64 v[222:223], s[30:31], 0, v[172:173]
	s_barrier
	ds_read_b128 v[144:147], v208 offset:16384
	ds_read_b128 v[148:151], v208 offset:17408
	ds_read_b128 v[152:155], v208 offset:18432
	ds_read_b128 v[156:159], v208 offset:19456
	ds_read_b128 v[160:163], v208 offset:20480
	ds_read_b128 v[164:167], v208 offset:21504
	ds_read_b128 v[168:171], v208 offset:22528
	ds_read_b128 v[188:191], v208 offset:23552
	global_load_lds_dwordx4 v[222:223], off
	v_lshl_add_u64 v[224:225], s[30:31], 0, v[176:177]
	s_mov_b32 m0, s45
	s_nop 0
	global_load_lds_dwordx4 v[224:225], off
	s_barrier
	s_waitcnt lgkmcnt(0)
	s_waitcnt lgkmcnt(0)
	v_mfma_f32_16x16x32_bf16 v[60:63], v[128:131], v[144:147], v[60:63]
	v_mfma_f32_16x16x32_bf16 v[56:59], v[136:139], v[144:147], v[56:59]
	v_mfma_f32_16x16x32_bf16 v[44:47], v[128:131], v[152:155], v[44:47]
	v_mfma_f32_16x16x32_bf16 v[40:43], v[136:139], v[152:155], v[40:43]
	v_mfma_f32_16x16x32_bf16 v[28:31], v[128:131], v[160:163], v[28:31]
	v_mfma_f32_16x16x32_bf16 v[24:27], v[136:139], v[160:163], v[24:27]
	v_mfma_f32_16x16x32_bf16 v[12:15], v[128:131], v[168:171], v[12:15]
	v_mfma_f32_16x16x32_bf16 v[8:11], v[136:139], v[168:171], v[8:11]
	v_mfma_f32_16x16x32_bf16 v[60:63], v[132:135], v[148:151], v[60:63]
	v_mfma_f32_16x16x32_bf16 v[56:59], v[140:143], v[148:151], v[56:59]
	v_mfma_f32_16x16x32_bf16 v[44:47], v[132:135], v[156:159], v[44:47]
	v_mfma_f32_16x16x32_bf16 v[40:43], v[140:143], v[156:159], v[40:43]
	v_mfma_f32_16x16x32_bf16 v[28:31], v[132:135], v[164:167], v[28:31]
	v_mfma_f32_16x16x32_bf16 v[24:27], v[140:143], v[164:167], v[24:27]
	v_mfma_f32_16x16x32_bf16 v[12:15], v[132:135], v[188:191], v[12:15]
	v_mfma_f32_16x16x32_bf16 v[8:11], v[140:143], v[188:191], v[8:11]
	s_barrier
; #define PG8_STAGE(bufoff, gbase, voff) do { _Pragma("unroll") for (int _i = 0; _i < 2; ++_i) \
;         __builtin_amdgcn_global_load_lds((const unsigned*)((const char*)(gbase) + (voff)[_i]), (LAS unsigned*)(lds + (bufoff) + ldsw + _i * 8192), 16, 0, 0); } while (0)
; #define PG8_LDA(dst, b, h) do { _Pragma("unroll") for (int m = 0; m < 4; ++m) _Pragma("unroll") for (int k = 0; k < 2; ++k) dst[m][k] = *(const LAS bf16x8*)(lds + PG8_SA(b, h) + aoff + m * 2048 + k * 1024); } while (0)
; #define PG8_LDB(dst, b, h) do { _Pragma("unroll") for (int n = 0; n < 2; ++n) _Pragma("unroll") for (int k = 0; k < 2; ++k) dst[n][k] = *(const LAS bf16x8*)(lds + PG8_SB(b, h) + boff + n * 2048 + k * 1024); } while (0)
; #define PG8_MMA(ai, bj, At, Bt) do { __builtin_amdgcn_s_setprio(1); _Pragma("unroll") for (int m = 0; m < 4; ++m) _Pragma("unroll") for (int n = 0; n < 2; ++n) _Pragma("unroll") for (int k = 0; k < 2; ++k) \
;         acc[ai][bj][m][n] = __builtin_amdgcn_mfma_f32_16x16x32_bf16(Bt[n][k], At[m][k], acc[ai][bj][m][n], 0, 0, 0); __builtin_amdgcn_s_setprio(0); } while (0)
; #define PG8_WAIT_V(n) asm volatile("s_waitcnt vmcnt(" #n ")" ::: "memory")
; #define PG8_WAIT_L(n) asm volatile("s_waitcnt lgkmcnt(" #n ")" ::: "memory")
; #define PG8_BAR __builtin_amdgcn_s_barrier()
; #define PG8_SCHED __builtin_amdgcn_sched_barrier(0)
; template <class Epi>
; __device__ __forceinline__ void gemm_phase(LAS unsigned char* lds, const Gemm g, const StaticOrder& S, const Epi& E) {
;     ...
;             PG8_WAIT_V(6); PG8_BAR; PG8_MMA(1, 1, At, B1); PG8_BAR;
;             PG8_LDB(B0, 1, 0); PG8_SCHED; PG8_LDA(At, 1, 0); PG8_STAGE(PG8_SA(0, 1), a2 + hstep, voffA);
;             PG8_WAIT_L(8); PG8_BAR; PG8_WAIT_L(0); PG8_MMA(0, 0, At, B0); PG8_BAR; PG8_SCHED;
;             PG8_LDB(B1, 1, 1); PG8_STAGE(PG8_SB(1, 0), b3, voffB);
;             PG8_BAR; PG8_WAIT_L(0); PG8_MMA(0, 1, At, B1); PG8_BAR;
;             PG8_LDA(At, 1, 1); PG8_STAGE(PG8_SA(1, 0), a3, voffA);
;             PG8_BAR; PG8_WAIT_L(0); PG8_MMA(1, 0, At, B0); PG8_BAR; PG8_SCHED;
	s_add_u32 s64, s28, 0x40000
	s_addc_u32 s65, s29, 0
	s_add_i32 s63, s54, s35
	v_lshl_add_u64 v[128:129], s[64:65], 0, v[174:175]
	s_mov_b32 m0, s63
	s_nop 0
	global_load_lds_dwordx4 v[128:129], off
	v_lshl_add_u64 v[128:129], s[64:65], 0, v[178:179]
	s_add_i32 m0, s63, 0x2000
	s_nop 0
	global_load_lds_dwordx4 v[128:129], off
	s_waitcnt vmcnt(6)
	s_barrier
	v_mfma_f32_16x16x32_bf16 v[52:55], v[192:195], v[144:147], v[52:55]
	v_mfma_f32_16x16x32_bf16 v[48:51], v[210:213], v[144:147], v[48:51]
	v_mfma_f32_16x16x32_bf16 v[36:39], v[192:195], v[152:155], v[36:39]
	v_mfma_f32_16x16x32_bf16 v[32:35], v[210:213], v[152:155], v[32:35]
	v_mfma_f32_16x16x32_bf16 v[20:23], v[192:195], v[160:163], v[20:23]
	v_mfma_f32_16x16x32_bf16 v[16:19], v[210:213], v[160:163], v[16:19]
	v_mfma_f32_16x16x32_bf16 v[4:7], v[192:195], v[168:171], v[4:7]
	v_mfma_f32_16x16x32_bf16 v[0:3], v[210:213], v[168:171], v[0:3]
	v_mfma_f32_16x16x32_bf16 v[52:55], v[196:199], v[148:151], v[52:55]
	v_mfma_f32_16x16x32_bf16 v[48:51], v[216:219], v[148:151], v[48:51]
	v_mfma_f32_16x16x32_bf16 v[36:39], v[196:199], v[156:159], v[36:39]
	v_mfma_f32_16x16x32_bf16 v[32:35], v[216:219], v[156:159], v[32:35]
	v_mfma_f32_16x16x32_bf16 v[20:23], v[196:199], v[164:167], v[20:23]
	v_mfma_f32_16x16x32_bf16 v[16:19], v[216:219], v[164:167], v[16:19]
	v_mfma_f32_16x16x32_bf16 v[4:7], v[196:199], v[188:191], v[4:7]
	v_mfma_f32_16x16x32_bf16 v[0:3], v[216:219], v[188:191], v[0:3]
	s_add_i32 s63, 0, 0x18000
	v_add_u32_e32 v140, s63, v205
	s_barrier
	ds_read_b128 v[128:131], v140
	ds_read_b128 v[132:135], v140 offset:1024
	ds_read_b128 v[136:139], v140 offset:2048
	ds_read_b128 v[140:143], v140 offset:3072
	s_add_u32 s30, s30, 0x40000
	s_addc_u32 s31, s31, 0
	s_mov_b32 m0, s46
	v_lshl_add_u64 v[192:193], s[30:31], 0, v[172:173]
	ds_read_b128 v[144:147], v208 offset:32768
	ds_read_b128 v[148:151], v208 offset:33792
	ds_read_b128 v[152:155], v208 offset:34816
	ds_read_b128 v[156:159], v208 offset:35840
	ds_read_b128 v[160:163], v208 offset:36864
	ds_read_b128 v[164:167], v208 offset:37888
	ds_read_b128 v[168:171], v208 offset:38912
	ds_read_b128 v[188:191], v208 offset:39936
	global_load_lds_dwordx4 v[192:193], off
	v_lshl_add_u64 v[192:193], s[30:31], 0, v[176:177]
	s_mov_b32 m0, s47
	s_nop 0
	global_load_lds_dwordx4 v[192:193], off
	s_waitcnt lgkmcnt(8)
	s_barrier
	s_waitcnt lgkmcnt(0)
	s_waitcnt lgkmcnt(0)
	v_mfma_f32_16x16x32_bf16 v[124:127], v[128:131], v[144:147], v[124:127]
	v_mfma_f32_16x16x32_bf16 v[120:123], v[136:139], v[144:147], v[120:123]
	v_mfma_f32_16x16x32_bf16 v[108:111], v[128:131], v[152:155], v[108:111]
	v_mfma_f32_16x16x32_bf16 v[104:107], v[136:139], v[152:155], v[104:107]
	v_mfma_f32_16x16x32_bf16 v[92:95], v[128:131], v[160:163], v[92:95]
	v_mfma_f32_16x16x32_bf16 v[88:91], v[136:139], v[160:163], v[88:91]
	v_mfma_f32_16x16x32_bf16 v[76:79], v[128:131], v[168:171], v[76:79]
	v_mfma_f32_16x16x32_bf16 v[72:75], v[136:139], v[168:171], v[72:75]
	v_mfma_f32_16x16x32_bf16 v[124:127], v[132:135], v[148:151], v[124:127]
	v_mfma_f32_16x16x32_bf16 v[120:123], v[140:143], v[148:151], v[120:123]
	v_mfma_f32_16x16x32_bf16 v[108:111], v[132:135], v[156:159], v[108:111]
	v_mfma_f32_16x16x32_bf16 v[104:107], v[140:143], v[156:159], v[104:107]
	v_mfma_f32_16x16x32_bf16 v[92:95], v[132:135], v[164:167], v[92:95]
	v_mfma_f32_16x16x32_bf16 v[88:91], v[140:143], v[164:167], v[88:91]
	v_mfma_f32_16x16x32_bf16 v[76:79], v[132:135], v[188:191], v[76:79]
	v_mfma_f32_16x16x32_bf16 v[72:75], v[140:143], v[188:191], v[72:75]
	s_barrier
	s_add_i32 s30, 0, 0x1c000
	s_add_i32 s31, s63, s35
	v_add_u32_e32 v216, s30, v205
	v_lshl_add_u64 v[200:201], v[200:201], 0, s[8:9]
	s_mov_b32 m0, s31
	ds_read_b128 v[192:195], v216
	ds_read_b128 v[196:199], v216 offset:1024
	ds_read_b128 v[210:213], v216 offset:2048
	ds_read_b128 v[216:219], v216 offset:3072
	global_load_lds_dwordx4 v[200:201], off
	v_lshl_add_u64 v[200:201], v[220:221], 0, s[8:9]
	s_add_i32 m0, s31, 0x2000
	s_nop 0
	global_load_lds_dwordx4 v[200:201], off
	s_barrier
	s_waitcnt lgkmcnt(0)
	s_waitcnt lgkmcnt(0)
	v_mfma_f32_16x16x32_bf16 v[116:119], v[192:195], v[144:147], v[116:119]
	v_mfma_f32_16x16x32_bf16 v[112:115], v[210:213], v[144:147], v[112:115]
	v_mfma_f32_16x16x32_bf16 v[100:103], v[192:195], v[152:155], v[100:103]
	v_mfma_f32_16x16x32_bf16 v[96:99], v[210:213], v[152:155], v[96:99]
	v_mfma_f32_16x16x32_bf16 v[84:87], v[192:195], v[160:163], v[84:87]
	v_mfma_f32_16x16x32_bf16 v[80:83], v[210:213], v[160:163], v[80:83]
	v_mfma_f32_16x16x32_bf16 v[68:71], v[192:195], v[168:171], v[68:71]
	v_mfma_f32_16x16x32_bf16 v[64:67], v[210:213], v[168:171], v[64:67]
	v_mfma_f32_16x16x32_bf16 v[116:119], v[196:199], v[148:151], v[116:119]
	v_mfma_f32_16x16x32_bf16 v[112:115], v[216:219], v[148:151], v[112:115]
	v_mfma_f32_16x16x32_bf16 v[100:103], v[196:199], v[156:159], v[100:103]
	v_mfma_f32_16x16x32_bf16 v[96:99], v[216:219], v[156:159], v[96:99]
	v_mfma_f32_16x16x32_bf16 v[84:87], v[196:199], v[164:167], v[84:87]
	v_mfma_f32_16x16x32_bf16 v[80:83], v[216:219], v[164:167], v[80:83]
	v_mfma_f32_16x16x32_bf16 v[68:71], v[196:199], v[188:191], v[68:71]
	v_mfma_f32_16x16x32_bf16 v[64:67], v[216:219], v[188:191], v[64:67]
	s_mov_b32 m0, s49
	v_lshl_add_u64 v[200:201], v[222:223], 0, s[8:9]
	s_barrier
	ds_read_b128 v[144:147], v208 offset:49152
	ds_read_b128 v[148:151], v208 offset:50176
	ds_read_b128 v[152:155], v208 offset:51200
	ds_read_b128 v[156:159], v208 offset:52224
	ds_read_b128 v[160:163], v208 offset:53248
	ds_read_b128 v[164:167], v208 offset:54272
	ds_read_b128 v[168:171], v208 offset:55296
	ds_read_b128 v[188:191], v208 offset:56320
	global_load_lds_dwordx4 v[200:201], off
	v_lshl_add_u64 v[200:201], v[224:225], 0, s[8:9]
	s_mov_b32 m0, s50
	s_nop 0
	global_load_lds_dwordx4 v[200:201], off
	s_barrier
; #define PG8_STAGE(bufoff, gbase, voff) do { _Pragma("unroll") for (int _i = 0; _i < 2; ++_i) \
;         __builtin_amdgcn_global_load_lds((const unsigned*)((const char*)(gbase) + (voff)[_i]), (LAS unsigned*)(lds + (bufoff) + ldsw + _i * 8192), 16, 0, 0); } while (0)
; #define PG8_MMA(ai, bj, At, Bt) do { __builtin_amdgcn_s_setprio(1); _Pragma("unroll") for (int m = 0; m < 4; ++m) _Pragma("unroll") for (int n = 0; n < 2; ++n) _Pragma("unroll") for (int k = 0; k < 2; ++k) \
;         acc[ai][bj][m][n] = __builtin_amdgcn_mfma_f32_16x16x32_bf16(Bt[n][k], At[m][k], acc[ai][bj][m][n], 0, 0, 0); __builtin_amdgcn_s_setprio(0); } while (0)
; #define PG8_WAIT_V(n) asm volatile("s_waitcnt vmcnt(" #n ")" ::: "memory")
; #define PG8_WAIT_L(n) asm volatile("s_waitcnt lgkmcnt(" #n ")" ::: "memory")
; #define PG8_BAR __builtin_amdgcn_s_barrier()
; #define PG8_SCHED __builtin_amdgcn_sched_barrier(0)
; template <class Epi>
; __device__ __forceinline__ void gemm_phase(LAS unsigned char* lds, const Gemm g, const StaticOrder& S, const Epi& E) {
;     ...
;             PG8_BAR; PG8_WAIT_L(0); PG8_MMA(1, 0, At, B0); PG8_BAR; PG8_SCHED;
;             PG8_STAGE(PG8_SB(1, 1), b3 + hstep, voffB);
;             PG8_WAIT_V(6); PG8_BAR; PG8_MMA(1, 1, At, B1); PG8_BAR;
;         }
;     __device__ __forceinline__ void operator()(const AccT& acc, const pg8::Unit& u, int wr, int wc, int fr, int fq) const {
;         const int row0 = u.pm * 256 + wr * 64 + fr, col0 = u.pn * 256 + wc * 32 + 8 * fq;
; #pragma unroll
;         for (int ai = 0; ai < 2; ++ai) { u32x4 gw[4][2], tw[4][2];
; #pragma unroll
;             for (int m = 0; m < 4; ++m)
; #pragma unroll
;                 for (int bj = 0; bj < 2; ++bj) { const int r = row0 + ai * 128 + m * 16; gw[m][bj] = *(const u32x4*)(PROJ + (size_t)r * NPROJ + C_GB + col0 + bj * 128); tw[m][bj] = *(const u32x4*)(T + (size_t)r * D + col0 + bj * 128); }
	s_waitcnt lgkmcnt(0)
	s_waitcnt lgkmcnt(0)
	v_mfma_f32_16x16x32_bf16 v[60:63], v[128:131], v[144:147], v[60:63]
	v_mfma_f32_16x16x32_bf16 v[56:59], v[136:139], v[144:147], v[56:59]
	v_mfma_f32_16x16x32_bf16 v[44:47], v[128:131], v[152:155], v[44:47]
	v_mfma_f32_16x16x32_bf16 v[40:43], v[136:139], v[152:155], v[40:43]
	v_mfma_f32_16x16x32_bf16 v[28:31], v[128:131], v[160:163], v[28:31]
	v_mfma_f32_16x16x32_bf16 v[24:27], v[136:139], v[160:163], v[24:27]
	v_mfma_f32_16x16x32_bf16 v[12:15], v[128:131], v[168:171], v[12:15]
	v_mfma_f32_16x16x32_bf16 v[8:11], v[136:139], v[168:171], v[8:11]
	v_mfma_f32_16x16x32_bf16 v[60:63], v[132:135], v[148:151], v[60:63]
	v_mfma_f32_16x16x32_bf16 v[56:59], v[140:143], v[148:151], v[56:59]
	v_mfma_f32_16x16x32_bf16 v[44:47], v[132:135], v[156:159], v[44:47]
	v_mfma_f32_16x16x32_bf16 v[40:43], v[140:143], v[156:159], v[40:43]
	v_mfma_f32_16x16x32_bf16 v[28:31], v[132:135], v[164:167], v[28:31]
	v_mfma_f32_16x16x32_bf16 v[24:27], v[140:143], v[164:167], v[24:27]
	v_mfma_f32_16x16x32_bf16 v[12:15], v[132:135], v[188:191], v[12:15]
	v_mfma_f32_16x16x32_bf16 v[8:11], v[140:143], v[188:191], v[8:11]
	s_barrier
	s_add_u32 s28, s28, 0x40080
	s_addc_u32 s29, s29, 0
	s_add_i32 s30, s30, s35
	v_lshl_add_u64 v[128:129], s[28:29], 0, v[174:175]
	s_mov_b32 m0, s30
	s_nop 0
	global_load_lds_dwordx4 v[128:129], off
	v_lshl_add_u64 v[128:129], s[28:29], 0, v[178:179]
	s_add_i32 m0, s30, 0x2000
	s_nop 0
	global_load_lds_dwordx4 v[128:129], off
	s_waitcnt vmcnt(6)
	s_barrier
	v_mfma_f32_16x16x32_bf16 v[52:55], v[192:195], v[144:147], v[52:55]
	v_mfma_f32_16x16x32_bf16 v[48:51], v[210:213], v[144:147], v[48:51]
	v_mfma_f32_16x16x32_bf16 v[36:39], v[192:195], v[152:155], v[36:39]
	v_mfma_f32_16x16x32_bf16 v[32:35], v[210:213], v[152:155], v[32:35]
	v_mfma_f32_16x16x32_bf16 v[20:23], v[192:195], v[160:163], v[20:23]
	v_mfma_f32_16x16x32_bf16 v[16:19], v[210:213], v[160:163], v[16:19]
	v_mfma_f32_16x16x32_bf16 v[4:7], v[192:195], v[168:171], v[4:7]
	v_mfma_f32_16x16x32_bf16 v[0:3], v[210:213], v[168:171], v[0:3]
	v_mfma_f32_16x16x32_bf16 v[52:55], v[196:199], v[148:151], v[52:55]
	v_mfma_f32_16x16x32_bf16 v[48:51], v[216:219], v[148:151], v[48:51]
	v_mfma_f32_16x16x32_bf16 v[36:39], v[196:199], v[156:159], v[36:39]
	v_mfma_f32_16x16x32_bf16 v[32:35], v[216:219], v[156:159], v[32:35]
	v_mfma_f32_16x16x32_bf16 v[20:23], v[196:199], v[164:167], v[20:23]
	v_mfma_f32_16x16x32_bf16 v[16:19], v[216:219], v[164:167], v[16:19]
	v_mfma_f32_16x16x32_bf16 v[4:7], v[196:199], v[188:191], v[4:7]
	v_mfma_f32_16x16x32_bf16 v[0:3], v[216:219], v[188:191], v[0:3]
	s_add_i32 s62, s62, 2
	s_add_u32 s26, s26, 0x100
	s_addc_u32 s27, s27, 0
	s_add_u32 s60, s60, 0x100
	s_addc_u32 s61, s61, 0
	s_cmp_gt_u32 s62, 13
	s_barrier
	s_cbranch_scc0 .LBB0_930
	v_lshl_or_b32 v128, s57, 8, v206
	v_lshl_add_u32 v192, s24, 8, v204
	v_ashrrev_i32_e32 v129, 31, v128
	v_mov_b64_e32 v[194:195], s[0:1]
	v_lshlrev_b64 v[188:189], 1, v[128:129]
	v_mad_i64_i32 v[128:129], s[26:27], v192, s55, v[194:195]
	v_lshl_add_u64 v[128:129], v[128:129], 0, v[188:189]
	v_add_co_u32_e32 v130, vcc, 0x3000, v128
	v_ashrrev_i32_e32 v193, 31, v192
	s_nop 0
	v_addc_co_u32_e32 v131, vcc, 0, v129, vcc
	global_load_dwordx4 v[216:219], v[130:131], off offset:2048
	v_lshl_add_u64 v[190:191], s[4:5], 0, v[188:189]
	v_lshlrev_b64 v[232:233], 12, v[192:193]
	v_lshl_add_u64 v[132:133], v[190:191], 0, v[232:233]
	global_load_dwordx4 v[210:213], v[132:133], off
	v_lshl_add_u64 v[128:129], v[128:129], 0, s[10:11]
	global_load_dwordx4 v[220:223], v[128:129], off offset:256
	v_or_b32_e32 v130, 16, v192
	v_or_b32_e32 v134, 32, v192
	v_or_b32_e32 v136, 48, v192
	v_ashrrev_i32_e32 v131, 31, v130
	v_mad_i64_i32 v[138:139], s[26:27], v130, s55, v[194:195]
	v_mad_i64_i32 v[140:141], s[26:27], v134, s55, v[194:195]
	v_ashrrev_i32_e32 v135, 31, v134
	v_ashrrev_i32_e32 v137, 31, v136
	v_mad_i64_i32 v[142:143], s[26:27], v136, s55, v[194:195]
	v_lshl_add_u64 v[148:149], v[138:139], 0, v[188:189]
	v_lshlrev_b64 v[200:201], 12, v[130:131]
	v_lshl_add_u64 v[140:141], v[140:141], 0, v[188:189]
	v_lshlrev_b64 v[198:199], 12, v[134:135]
	v_lshl_add_u64 v[134:135], v[142:143], 0, v[188:189]
	v_lshlrev_b64 v[196:197], 12, v[136:137]
	v_lshl_add_u64 v[130:131], v[148:149], 0, s[10:11]
	v_lshl_add_u64 v[142:143], v[190:191], 0, v[200:201]
	v_lshl_add_u64 v[136:137], v[140:141], 0, s[10:11]
	v_lshl_add_u64 v[150:151], v[190:191], 0, v[198:199]
	v_lshl_add_u64 v[156:157], v[134:135], 0, s[10:11]
	v_lshl_add_u64 v[234:235], v[190:191], 0, v[196:197]
	global_load_dwordx4 v[168:171], v[142:143], off
	global_load_dwordx4 v[160:163], v[130:131], off offset:256
	global_load_dwordx4 v[152:155], v[150:151], off
	global_load_dwordx4 v[144:147], v[136:137], off offset:256
	s_nop 0
	global_load_dwordx4 v[136:139], v[234:235], off
	global_load_dwordx4 v[128:131], v[156:157], off offset:256
	global_load_dwordx4 v[224:227], v[132:133], off offset:256
	v_add_co_u32_e32 v148, vcc, s56, v148
	s_mov_b32 s57, s18
	s_nop 0
	v_addc_co_u32_e32 v149, vcc, 0, v149, vcc
	global_load_dwordx4 v[228:231], v[148:149], off offset:2048
	global_load_dwordx4 v[164:167], v[142:143], off offset:256
	v_add_co_u32_e32 v132, vcc, s56, v140
	s_mov_b32 s24, s16
	s_nop 0
	v_addc_co_u32_e32 v133, vcc, 0, v141, vcc
	global_load_dwordx4 v[156:159], v[132:133], off offset:2048
	s_nop 0
	global_load_dwordx4 v[148:151], v[150:151], off offset:256
	v_add_co_u32_e32 v134, vcc, s56, v134
	s_mov_b64 s[28:29], s[22:23]
	s_nop 0
	v_addc_co_u32_e32 v135, vcc, 0, v135, vcc
	global_load_dwordx4 v[140:143], v[134:135], off offset:2048
	s_nop 0
	global_load_dwordx4 v[132:135], v[234:235], off offset:256
	s_waitcnt vmcnt(0)
; __device__ __forceinline__ u32x4 pack8(const f32x4 v0, const f32x4 v1) { u32x4 w; w.x = cvt_pk_bf16(v0[0], v0[1]); w.y = cvt_pk_bf16(v0[2], v0[3]); w.z = cvt_pk_bf16(v1[0], v1[1]); w.w = cvt_pk_bf16(v1[2], v1[3]); return w; }
; __device__ __forceinline__ void unpack8(const u32x4 w, f32x4& v0, f32x4& v1) { v0 = (f32x4){bflo(w.x), bfhi(w.x), bflo(w.y), bfhi(w.y)}; v1 = (f32x4){bflo(w.z), bfhi(w.z), bflo(w.w), bfhi(w.w)}; }
; __device__ __forceinline__ f32x4 sig4(const f32x4 v) { return (f32x4){sigmoidf_(v[0]), sigmoidf_(v[1]), sigmoidf_(v[2]), sigmoidf_(v[3])}; }
;     __device__ __forceinline__ void operator()(const AccT& acc, const pg8::Unit& u, int wr, int wc, int fr, int fq) const {
;         const int row0 = u.pm * 256 + wr * 64 + fr, col0 = u.pn * 256 + wc * 32 + 8 * fq;
; #pragma unroll
;         for (int ai = 0; ai < 2; ++ai) { u32x4 gw[4][2], tw[4][2];
; #pragma unroll
;             for (int m = 0; m < 4; ++m)
; #pragma unroll
;                 for (int bj = 0; bj < 2; ++bj) { const int r = row0 + ai * 128 + m * 16; gw[m][bj] = *(const u32x4*)(PROJ + (size_t)r * NPROJ + C_GB + col0 + bj * 128); tw[m][bj] = *(const u32x4*)(T + (size_t)r * D + col0 + bj * 128); }
; #pragma unroll
;             for (int m = 0; m < 4; ++m)
; #pragma unroll
;                 for (int bj = 0; bj < 2; ++bj) { f32x4 g0, g1, t0, t1; unpack8(gw[m][bj], g0, g1); unpack8(tw[m][bj], t0, t1);
;                     *(u32x4*)(O + (size_t)(row0 + ai * 128 + m * 16) * D + col0 + bj * 128) = pack8(t0 + sig4(g0) * acc[ai][bj][m][0], t1 + sig4(g1) * acc[ai][bj][m][1]); } }
	v_lshlrev_b32_e32 v193, 16, v216
	v_and_b32_e32 v216, 0xffff0000, v216
	v_mul_f32_e32 v193, 0xbfb8aa3b, v193
	v_lshlrev_b32_e32 v238, 16, v217
	v_exp_f32_e32 v193, v193
	v_mul_f32_e32 v216, 0xbfb8aa3b, v216
	v_and_b32_e32 v239, 0xffff0000, v217
	v_exp_f32_e32 v217, v216
	v_mul_f32_e32 v216, 0xbfb8aa3b, v238
	v_lshlrev_b32_e32 v240, 16, v218
	v_and_b32_e32 v241, 0xffff0000, v218
	v_exp_f32_e32 v218, v216
	v_add_f32_e32 v193, 1.0, v193
	v_rcp_f32_e32 v216, v193
	v_add_f32_e32 v193, 1.0, v217
	v_rcp_f32_e32 v217, v193
	v_add_f32_e32 v193, 1.0, v218
	v_mul_f32_e32 v218, 0xbfb8aa3b, v239
	v_lshlrev_b32_e32 v242, 16, v219
	v_and_b32_e32 v243, 0xffff0000, v219
	v_exp_f32_e32 v219, v218
	v_mul_f32_e32 v218, 0xbfb8aa3b, v240
	v_exp_f32_e32 v238, v218
	v_rcp_f32_e32 v218, v193
	v_add_f32_e32 v193, 1.0, v219
	v_rcp_f32_e32 v219, v193
	v_add_f32_e32 v193, 1.0, v238
	v_mul_f32_e32 v239, 0xbfb8aa3b, v242
	v_rcp_f32_e32 v238, v193
	v_mul_f32_e32 v193, 0xbfb8aa3b, v241
	v_exp_f32_e32 v239, v239
	v_mul_f32_e32 v240, 0xbfb8aa3b, v243
	v_exp_f32_e32 v193, v193
	v_exp_f32_e32 v241, v240
	v_add_f32_e32 v239, 1.0, v239
	v_rcp_f32_e32 v240, v239
	v_add_f32_e32 v193, 1.0, v193
	v_add_f32_e32 v239, 1.0, v241
	v_rcp_f32_e32 v241, v239
	v_rcp_f32_e32 v239, v193
	v_lshlrev_b32_e32 v234, 16, v210
	v_and_b32_e32 v235, 0xffff0000, v210
	v_lshlrev_b32_e32 v210, 16, v211
	v_and_b32_e32 v211, 0xffff0000, v211
	v_lshlrev_b32_e32 v236, 16, v212
	v_and_b32_e32 v237, 0xffff0000, v212
	v_lshlrev_b32_e32 v212, 16, v213
	v_and_b32_e32 v213, 0xffff0000, v213
	v_pk_fma_f32 v[126:127], v[126:127], v[218:219], v[210:211]
	v_pk_fma_f32 v[124:125], v[124:125], v[216:217], v[234:235]
	v_pk_fma_f32 v[210:211], v[122:123], v[240:241], v[212:213]
	v_pk_fma_f32 v[122:123], v[120:121], v[238:239], v[236:237]
	v_cvt_pk_bf16_f32 v120, v124, v125
	v_cvt_pk_bf16_f32 v121, v126, v127
	v_lshlrev_b32_e32 v127, 16, v220
	v_and_b32_e32 v193, 0xffff0000, v220
	v_lshlrev_b32_e32 v212, 16, v221
	v_mul_f32_e32 v127, 0xbfb8aa3b, v127
	v_mul_f32_e32 v193, 0xbfb8aa3b, v193
	v_exp_f32_e32 v213, v127
	v_exp_f32_e32 v193, v193
	v_mul_f32_e32 v212, 0xbfb8aa3b, v212
	v_exp_f32_e32 v218, v212
	v_and_b32_e32 v216, 0xffff0000, v221
	v_lshlrev_b32_e32 v217, 16, v222
	v_add_f32_e32 v213, 1.0, v213
	v_add_f32_e32 v193, 1.0, v193
	v_mul_f32_e32 v216, 0xbfb8aa3b, v216
	v_rcp_f32_e32 v212, v213
	v_rcp_f32_e32 v213, v193
	v_add_f32_e32 v193, 1.0, v218
	v_exp_f32_e32 v218, v216
	v_mul_f32_e32 v216, 0xbfb8aa3b, v217
	v_and_b32_e32 v219, 0xffff0000, v222
	v_exp_f32_e32 v222, v216
	v_rcp_f32_e32 v216, v193
	v_add_f32_e32 v193, 1.0, v218
	v_lshlrev_b32_e32 v220, 16, v223
	v_rcp_f32_e32 v217, v193
	v_add_f32_e32 v193, 1.0, v222
	v_and_b32_e32 v221, 0xffff0000, v223
	v_rcp_f32_e32 v218, v193
	v_mul_f32_e32 v193, 0xbfb8aa3b, v219
	v_mul_f32_e32 v219, 0xbfb8aa3b, v220
	v_exp_f32_e32 v219, v219
	v_mul_f32_e32 v220, 0xbfb8aa3b, v221
	v_exp_f32_e32 v193, v193
	v_exp_f32_e32 v221, v220
	v_add_f32_e32 v219, 1.0, v219
	v_rcp_f32_e32 v220, v219
	v_add_f32_e32 v193, 1.0, v193
	v_add_f32_e32 v219, 1.0, v221
	v_rcp_f32_e32 v221, v219
	v_rcp_f32_e32 v219, v193
	v_lshl_add_u64 v[124:125], s[6:7], 0, v[232:233]
	v_lshl_add_u64 v[124:125], v[124:125], 0, v[188:189]
	v_cvt_pk_bf16_f32 v122, v122, v123
	v_cvt_pk_bf16_f32 v123, v210, v211
	global_store_dwordx4 v[124:125], v[120:123], off
	v_lshlrev_b32_e32 v126, 16, v226
	v_and_b32_e32 v127, 0xffff0000, v226
	v_lshlrev_b32_e32 v120, 16, v224
	v_and_b32_e32 v121, 0xffff0000, v224
	v_lshlrev_b32_e32 v210, 16, v227
	v_and_b32_e32 v211, 0xffff0000, v227
	v_lshlrev_b32_e32 v122, 16, v225
	v_and_b32_e32 v123, 0xffff0000, v225
	v_pk_fma_f32 v[116:117], v[116:117], v[212:213], v[120:121]
	v_pk_fma_f32 v[120:121], v[114:115], v[220:221], v[210:211]
	v_pk_fma_f32 v[114:115], v[112:113], v[218:219], v[126:127]
	v_pk_fma_f32 v[118:119], v[118:119], v[216:217], v[122:123]
	v_cvt_pk_bf16_f32 v112, v116, v117
	v_lshlrev_b32_e32 v117, 16, v228
	v_cvt_pk_bf16_f32 v113, v118, v119
	v_cvt_pk_bf16_f32 v114, v114, v115
	v_cvt_pk_bf16_f32 v115, v120, v121
	v_and_b32_e32 v120, 0xffff0000, v228
	v_lshlrev_b32_e32 v121, 16, v229
	v_mul_f32_e32 v117, 0xbfb8aa3b, v117
	v_mul_f32_e32 v120, 0xbfb8aa3b, v120
	global_store_dwordx4 v[124:125], v[112:115], off offset:256
	v_exp_f32_e32 v124, v117
	v_and_b32_e32 v122, 0xffff0000, v229
	v_lshlrev_b32_e32 v112, 16, v168
	v_and_b32_e32 v113, 0xffff0000, v168
	v_exp_f32_e32 v168, v120
	v_mul_f32_e32 v120, 0xbfb8aa3b, v121
	v_lshlrev_b32_e32 v114, 16, v169
	v_and_b32_e32 v115, 0xffff0000, v169
	v_exp_f32_e32 v169, v120
	v_lshlrev_b32_e32 v123, 16, v230
	v_and_b32_e32 v125, 0xffff0000, v230
	v_lshlrev_b32_e32 v126, 16, v231
	v_and_b32_e32 v127, 0xffff0000, v231
	v_mul_f32_e32 v122, 0xbfb8aa3b, v122
	v_add_f32_e32 v124, 1.0, v124
	v_add_f32_e32 v121, 1.0, v168
	v_exp_f32_e32 v168, v122
	v_mul_f32_e32 v122, 0xbfb8aa3b, v123
	v_mul_f32_e32 v125, 0xbfb8aa3b, v125
	v_mul_f32_e32 v126, 0xbfb8aa3b, v126
	v_mul_f32_e32 v127, 0xbfb8aa3b, v127
	v_rcp_f32_e32 v120, v124
	v_add_f32_e32 v124, 1.0, v169
	v_exp_f32_e32 v169, v122
	v_exp_f32_e32 v125, v125
	v_exp_f32_e32 v126, v126
	v_exp_f32_e32 v127, v127
	v_add_f32_e32 v123, 1.0, v168
	v_rcp_f32_e32 v122, v124
	v_rcp_f32_e32 v123, v123
	v_add_f32_e32 v124, 1.0, v169
	v_add_f32_e32 v125, 1.0, v125
	v_add_f32_e32 v126, 1.0, v126
	v_add_f32_e32 v127, 1.0, v127
	v_rcp_f32_e32 v121, v121
	v_rcp_f32_e32 v124, v124
	v_rcp_f32_e32 v126, v126
	v_rcp_f32_e32 v127, v127
	v_rcp_f32_e32 v125, v125
	v_lshlrev_b32_e32 v116, 16, v170
	v_and_b32_e32 v117, 0xffff0000, v170
	v_lshlrev_b32_e32 v118, 16, v171
	v_and_b32_e32 v119, 0xffff0000, v171
; __device__ __forceinline__ u32x4 pack8(const f32x4 v0, const f32x4 v1) { u32x4 w; w.x = cvt_pk_bf16(v0[0], v0[1]); w.y = cvt_pk_bf16(v0[2], v0[3]); w.z = cvt_pk_bf16(v1[0], v1[1]); w.w = cvt_pk_bf16(v1[2], v1[3]); return w; }
; __device__ __forceinline__ void unpack8(const u32x4 w, f32x4& v0, f32x4& v1) { v0 = (f32x4){bflo(w.x), bfhi(w.x), bflo(w.y), bfhi(w.y)}; v1 = (f32x4){bflo(w.z), bfhi(w.z), bflo(w.w), bfhi(w.w)}; }
; __device__ __forceinline__ f32x4 sig4(const f32x4 v) { return (f32x4){sigmoidf_(v[0]), sigmoidf_(v[1]), sigmoidf_(v[2]), sigmoidf_(v[3])}; }
;     __device__ __forceinline__ void operator()(const AccT& acc, const pg8::Unit& u, int wr, int wc, int fr, int fq) const {
;         const int row0 = u.pm * 256 + wr * 64 + fr, col0 = u.pn * 256 + wc * 32 + 8 * fq;
; #pragma unroll
;         for (int ai = 0; ai < 2; ++ai) { u32x4 gw[4][2], tw[4][2];
; #pragma unroll
;             for (int m = 0; m < 4; ++m)
; #pragma unroll
;                 for (int bj = 0; bj < 2; ++bj) { const int r = row0 + ai * 128 + m * 16; gw[m][bj] = *(const u32x4*)(PROJ + (size_t)r * NPROJ + C_GB + col0 + bj * 128); tw[m][bj] = *(const u32x4*)(T + (size_t)r * D + col0 + bj * 128); }
; #pragma unroll
;             for (int m = 0; m < 4; ++m)
; #pragma unroll
;                 for (int bj = 0; bj < 2; ++bj) { f32x4 g0, g1, t0, t1; unpack8(gw[m][bj], g0, g1); unpack8(tw[m][bj], t0, t1);
;                     *(u32x4*)(O + (size_t)(row0 + ai * 128 + m * 16) * D + col0 + bj * 128) = pack8(t0 + sig4(g0) * acc[ai][bj][m][0], t1 + sig4(g1) * acc[ai][bj][m][1]); } }
	v_pk_fma_f32 v[110:111], v[110:111], v[122:123], v[114:115]
	v_pk_fma_f32 v[108:109], v[108:109], v[120:121], v[112:113]
	v_pk_fma_f32 v[112:113], v[106:107], v[126:127], v[118:119]
	v_pk_fma_f32 v[106:107], v[104:105], v[124:125], v[116:117]
	v_cvt_pk_bf16_f32 v104, v108, v109
	v_cvt_pk_bf16_f32 v105, v110, v111
	v_lshlrev_b32_e32 v111, 16, v160
	v_and_b32_e32 v114, 0xffff0000, v160
	v_lshlrev_b32_e32 v115, 16, v161
	v_mul_f32_e32 v111, 0xbfb8aa3b, v111
	v_mul_f32_e32 v114, 0xbfb8aa3b, v114
	v_exp_f32_e32 v118, v111
	v_exp_f32_e32 v122, v114
	v_mul_f32_e32 v114, 0xbfb8aa3b, v115
	v_exp_f32_e32 v123, v114
	v_and_b32_e32 v116, 0xffff0000, v161
	v_lshlrev_b32_e32 v117, 16, v162
	v_and_b32_e32 v119, 0xffff0000, v162
	v_lshlrev_b32_e32 v120, 16, v163
	v_and_b32_e32 v121, 0xffff0000, v163
	v_mul_f32_e32 v116, 0xbfb8aa3b, v116
	v_add_f32_e32 v118, 1.0, v118
	v_add_f32_e32 v115, 1.0, v122
	v_exp_f32_e32 v122, v116
	v_mul_f32_e32 v116, 0xbfb8aa3b, v117
	v_mul_f32_e32 v119, 0xbfb8aa3b, v119
	v_mul_f32_e32 v120, 0xbfb8aa3b, v120
	v_mul_f32_e32 v121, 0xbfb8aa3b, v121
	v_rcp_f32_e32 v114, v118
	v_add_f32_e32 v118, 1.0, v123
	v_exp_f32_e32 v123, v116
	v_exp_f32_e32 v119, v119
	v_exp_f32_e32 v120, v120
	v_exp_f32_e32 v121, v121
	v_rcp_f32_e32 v116, v118
	v_add_f32_e32 v118, 1.0, v123
	v_add_f32_e32 v119, 1.0, v119
	v_add_f32_e32 v120, 1.0, v120
	v_add_f32_e32 v121, 1.0, v121
	v_rcp_f32_e32 v115, v115
	v_add_f32_e32 v117, 1.0, v122
	v_rcp_f32_e32 v118, v118
	v_rcp_f32_e32 v120, v120
	v_rcp_f32_e32 v121, v121
	v_rcp_f32_e32 v119, v119
	v_lshl_add_u64 v[108:109], s[6:7], 0, v[200:201]
	v_rcp_f32_e32 v117, v117
	v_lshl_add_u64 v[108:109], v[108:109], 0, v[188:189]
	v_cvt_pk_bf16_f32 v106, v106, v107
	v_cvt_pk_bf16_f32 v107, v112, v113
	global_store_dwordx4 v[108:109], v[104:107], off
	v_lshlrev_b32_e32 v110, 16, v166
	v_and_b32_e32 v111, 0xffff0000, v166
	v_lshlrev_b32_e32 v104, 16, v164
	v_and_b32_e32 v105, 0xffff0000, v164
	v_lshlrev_b32_e32 v112, 16, v167
	v_and_b32_e32 v113, 0xffff0000, v167
	v_lshlrev_b32_e32 v106, 16, v165
	v_and_b32_e32 v107, 0xffff0000, v165
	v_pk_fma_f32 v[100:101], v[100:101], v[114:115], v[104:105]
	v_pk_fma_f32 v[104:105], v[98:99], v[120:121], v[112:113]
	v_pk_fma_f32 v[98:99], v[96:97], v[118:119], v[110:111]
	v_pk_fma_f32 v[102:103], v[102:103], v[116:117], v[106:107]
	v_cvt_pk_bf16_f32 v96, v100, v101
	v_lshlrev_b32_e32 v101, 16, v156
	v_cvt_pk_bf16_f32 v97, v102, v103
	v_cvt_pk_bf16_f32 v98, v98, v99
	v_cvt_pk_bf16_f32 v99, v104, v105
	v_and_b32_e32 v104, 0xffff0000, v156
	v_lshlrev_b32_e32 v105, 16, v157
	v_mul_f32_e32 v101, 0xbfb8aa3b, v101
	v_mul_f32_e32 v104, 0xbfb8aa3b, v104
	global_store_dwordx4 v[108:109], v[96:99], off offset:256
	v_exp_f32_e32 v108, v101
	v_exp_f32_e32 v112, v104
	v_mul_f32_e32 v104, 0xbfb8aa3b, v105
	v_exp_f32_e32 v113, v104
	v_and_b32_e32 v106, 0xffff0000, v157
	v_lshlrev_b32_e32 v107, 16, v158
	v_and_b32_e32 v109, 0xffff0000, v158
	v_lshlrev_b32_e32 v110, 16, v159
	v_and_b32_e32 v111, 0xffff0000, v159
	v_mul_f32_e32 v106, 0xbfb8aa3b, v106
	v_add_f32_e32 v108, 1.0, v108
	v_add_f32_e32 v105, 1.0, v112
	v_exp_f32_e32 v112, v106
	v_mul_f32_e32 v106, 0xbfb8aa3b, v107
	v_mul_f32_e32 v109, 0xbfb8aa3b, v109
	v_mul_f32_e32 v110, 0xbfb8aa3b, v110
	v_mul_f32_e32 v111, 0xbfb8aa3b, v111
	v_rcp_f32_e32 v104, v108
	v_add_f32_e32 v108, 1.0, v113
	v_exp_f32_e32 v113, v106
	v_exp_f32_e32 v109, v109
	v_exp_f32_e32 v110, v110
	v_exp_f32_e32 v111, v111
	v_add_f32_e32 v107, 1.0, v112
	v_rcp_f32_e32 v106, v108
	v_rcp_f32_e32 v107, v107
	v_add_f32_e32 v108, 1.0, v113
	v_add_f32_e32 v109, 1.0, v109
	v_add_f32_e32 v110, 1.0, v110
	v_add_f32_e32 v111, 1.0, v111
	v_rcp_f32_e32 v105, v105
	v_rcp_f32_e32 v108, v108
	v_rcp_f32_e32 v110, v110
	v_rcp_f32_e32 v111, v111
	v_rcp_f32_e32 v109, v109
	v_lshlrev_b32_e32 v98, 16, v153
	v_and_b32_e32 v99, 0xffff0000, v153
	v_lshlrev_b32_e32 v96, 16, v152
	v_and_b32_e32 v97, 0xffff0000, v152
	v_lshlrev_b32_e32 v100, 16, v154
	v_and_b32_e32 v101, 0xffff0000, v154
	v_lshlrev_b32_e32 v102, 16, v155
	v_and_b32_e32 v103, 0xffff0000, v155
	v_pk_fma_f32 v[94:95], v[94:95], v[106:107], v[98:99]
	v_pk_fma_f32 v[92:93], v[92:93], v[104:105], v[96:97]
	v_pk_fma_f32 v[96:97], v[90:91], v[110:111], v[102:103]
	v_pk_fma_f32 v[90:91], v[88:89], v[108:109], v[100:101]
	v_cvt_pk_bf16_f32 v88, v92, v93
	v_cvt_pk_bf16_f32 v89, v94, v95
	v_lshlrev_b32_e32 v95, 16, v144
	v_and_b32_e32 v98, 0xffff0000, v144
	v_lshlrev_b32_e32 v99, 16, v145
	v_mul_f32_e32 v95, 0xbfb8aa3b, v95
	v_mul_f32_e32 v98, 0xbfb8aa3b, v98
	v_exp_f32_e32 v102, v95
	v_exp_f32_e32 v106, v98
	v_mul_f32_e32 v98, 0xbfb8aa3b, v99
	v_exp_f32_e32 v107, v98
	v_and_b32_e32 v100, 0xffff0000, v145
	v_lshlrev_b32_e32 v101, 16, v146
	v_and_b32_e32 v103, 0xffff0000, v146
	v_lshlrev_b32_e32 v104, 16, v147
	v_and_b32_e32 v105, 0xffff0000, v147
	v_mul_f32_e32 v100, 0xbfb8aa3b, v100
	v_add_f32_e32 v102, 1.0, v102
	v_add_f32_e32 v99, 1.0, v106
	v_exp_f32_e32 v106, v100
	v_mul_f32_e32 v100, 0xbfb8aa3b, v101
	v_mul_f32_e32 v103, 0xbfb8aa3b, v103
	v_mul_f32_e32 v104, 0xbfb8aa3b, v104
	v_mul_f32_e32 v105, 0xbfb8aa3b, v105
	v_rcp_f32_e32 v98, v102
	v_add_f32_e32 v102, 1.0, v107
	v_exp_f32_e32 v107, v100
	v_exp_f32_e32 v103, v103
	v_exp_f32_e32 v104, v104
	v_exp_f32_e32 v105, v105
	v_rcp_f32_e32 v100, v102
	v_add_f32_e32 v102, 1.0, v107
	v_add_f32_e32 v103, 1.0, v103
	v_add_f32_e32 v104, 1.0, v104
	v_add_f32_e32 v105, 1.0, v105
	v_rcp_f32_e32 v99, v99
	v_add_f32_e32 v101, 1.0, v106
	v_rcp_f32_e32 v102, v102
	v_rcp_f32_e32 v104, v104
	v_rcp_f32_e32 v105, v105
	v_rcp_f32_e32 v103, v103
	v_lshl_add_u64 v[92:93], s[6:7], 0, v[198:199]
	v_rcp_f32_e32 v101, v101
; __device__ __forceinline__ u32x4 pack8(const f32x4 v0, const f32x4 v1) { u32x4 w; w.x = cvt_pk_bf16(v0[0], v0[1]); w.y = cvt_pk_bf16(v0[2], v0[3]); w.z = cvt_pk_bf16(v1[0], v1[1]); w.w = cvt_pk_bf16(v1[2], v1[3]); return w; }
; __device__ __forceinline__ void unpack8(const u32x4 w, f32x4& v0, f32x4& v1) { v0 = (f32x4){bflo(w.x), bfhi(w.x), bflo(w.y), bfhi(w.y)}; v1 = (f32x4){bflo(w.z), bfhi(w.z), bflo(w.w), bfhi(w.w)}; }
; __device__ __forceinline__ f32x4 sig4(const f32x4 v) { return (f32x4){sigmoidf_(v[0]), sigmoidf_(v[1]), sigmoidf_(v[2]), sigmoidf_(v[3])}; }
;     __device__ __forceinline__ void operator()(const AccT& acc, const pg8::Unit& u, int wr, int wc, int fr, int fq) const {
;         const int row0 = u.pm * 256 + wr * 64 + fr, col0 = u.pn * 256 + wc * 32 + 8 * fq;
; #pragma unroll
;         for (int ai = 0; ai < 2; ++ai) { u32x4 gw[4][2], tw[4][2];
; #pragma unroll
;             for (int m = 0; m < 4; ++m)
; #pragma unroll
;                 for (int bj = 0; bj < 2; ++bj) { const int r = row0 + ai * 128 + m * 16; gw[m][bj] = *(const u32x4*)(PROJ + (size_t)r * NPROJ + C_GB + col0 + bj * 128); tw[m][bj] = *(const u32x4*)(T + (size_t)r * D + col0 + bj * 128); }
; #pragma unroll
;             for (int m = 0; m < 4; ++m)
; #pragma unroll
;                 for (int bj = 0; bj < 2; ++bj) { f32x4 g0, g1, t0, t1; unpack8(gw[m][bj], g0, g1); unpack8(tw[m][bj], t0, t1);
;                     *(u32x4*)(O + (size_t)(row0 + ai * 128 + m * 16) * D + col0 + bj * 128) = pack8(t0 + sig4(g0) * acc[ai][bj][m][0], t1 + sig4(g1) * acc[ai][bj][m][1]); } }
	v_lshl_add_u64 v[92:93], v[92:93], 0, v[188:189]
	v_cvt_pk_bf16_f32 v90, v90, v91
	v_cvt_pk_bf16_f32 v91, v96, v97
	global_store_dwordx4 v[92:93], v[88:91], off
	v_lshlrev_b32_e32 v94, 16, v150
	v_and_b32_e32 v95, 0xffff0000, v150
	v_lshlrev_b32_e32 v88, 16, v148
	v_and_b32_e32 v89, 0xffff0000, v148
	v_lshlrev_b32_e32 v96, 16, v151
	v_and_b32_e32 v97, 0xffff0000, v151
	v_lshlrev_b32_e32 v90, 16, v149
	v_and_b32_e32 v91, 0xffff0000, v149
	v_pk_fma_f32 v[84:85], v[84:85], v[98:99], v[88:89]
	v_pk_fma_f32 v[88:89], v[82:83], v[104:105], v[96:97]
	v_pk_fma_f32 v[82:83], v[80:81], v[102:103], v[94:95]
	v_pk_fma_f32 v[86:87], v[86:87], v[100:101], v[90:91]
	v_cvt_pk_bf16_f32 v80, v84, v85
	v_lshlrev_b32_e32 v85, 16, v140
	v_cvt_pk_bf16_f32 v81, v86, v87
	v_cvt_pk_bf16_f32 v82, v82, v83
	v_cvt_pk_bf16_f32 v83, v88, v89
	v_and_b32_e32 v88, 0xffff0000, v140
	v_lshlrev_b32_e32 v89, 16, v141
	v_mul_f32_e32 v85, 0xbfb8aa3b, v85
	v_mul_f32_e32 v88, 0xbfb8aa3b, v88
	global_store_dwordx4 v[92:93], v[80:83], off offset:256
	v_exp_f32_e32 v92, v85
	v_exp_f32_e32 v96, v88
	v_mul_f32_e32 v88, 0xbfb8aa3b, v89
	v_exp_f32_e32 v97, v88
	v_and_b32_e32 v90, 0xffff0000, v141
	v_lshlrev_b32_e32 v91, 16, v142
	v_and_b32_e32 v93, 0xffff0000, v142
	v_lshlrev_b32_e32 v94, 16, v143
	v_and_b32_e32 v95, 0xffff0000, v143
	v_mul_f32_e32 v90, 0xbfb8aa3b, v90
	v_add_f32_e32 v92, 1.0, v92
	v_add_f32_e32 v89, 1.0, v96
	v_exp_f32_e32 v96, v90
	v_mul_f32_e32 v90, 0xbfb8aa3b, v91
	v_mul_f32_e32 v93, 0xbfb8aa3b, v93
	v_mul_f32_e32 v94, 0xbfb8aa3b, v94
	v_mul_f32_e32 v95, 0xbfb8aa3b, v95
	v_rcp_f32_e32 v88, v92
	v_add_f32_e32 v92, 1.0, v97
	v_exp_f32_e32 v97, v90
	v_exp_f32_e32 v93, v93
	v_exp_f32_e32 v94, v94
	v_exp_f32_e32 v95, v95
	v_add_f32_e32 v91, 1.0, v96
	v_rcp_f32_e32 v90, v92
	v_rcp_f32_e32 v91, v91
	v_add_f32_e32 v92, 1.0, v97
	v_add_f32_e32 v93, 1.0, v93
	v_add_f32_e32 v94, 1.0, v94
	v_add_f32_e32 v95, 1.0, v95
	v_rcp_f32_e32 v89, v89
	v_rcp_f32_e32 v92, v92
	v_rcp_f32_e32 v94, v94
	v_rcp_f32_e32 v95, v95
	v_rcp_f32_e32 v93, v93
	v_lshlrev_b32_e32 v82, 16, v137
	v_and_b32_e32 v83, 0xffff0000, v137
	v_lshlrev_b32_e32 v80, 16, v136
	v_and_b32_e32 v81, 0xffff0000, v136
	v_lshlrev_b32_e32 v84, 16, v138
	v_and_b32_e32 v85, 0xffff0000, v138
	v_lshlrev_b32_e32 v86, 16, v139
	v_and_b32_e32 v87, 0xffff0000, v139
	v_pk_fma_f32 v[78:79], v[78:79], v[90:91], v[82:83]
	v_pk_fma_f32 v[76:77], v[76:77], v[88:89], v[80:81]
	v_pk_fma_f32 v[80:81], v[74:75], v[94:95], v[86:87]
	v_pk_fma_f32 v[74:75], v[72:73], v[92:93], v[84:85]
	v_cvt_pk_bf16_f32 v72, v76, v77
	v_cvt_pk_bf16_f32 v73, v78, v79
	v_lshlrev_b32_e32 v79, 16, v128
	v_and_b32_e32 v82, 0xffff0000, v128
	v_lshlrev_b32_e32 v83, 16, v129
	v_mul_f32_e32 v79, 0xbfb8aa3b, v79
	v_mul_f32_e32 v82, 0xbfb8aa3b, v82
	v_exp_f32_e32 v86, v79
	v_exp_f32_e32 v90, v82
	v_mul_f32_e32 v82, 0xbfb8aa3b, v83
	v_exp_f32_e32 v91, v82
	v_and_b32_e32 v84, 0xffff0000, v129
	v_lshlrev_b32_e32 v85, 16, v130
	v_and_b32_e32 v87, 0xffff0000, v130
	v_lshlrev_b32_e32 v88, 16, v131
	v_and_b32_e32 v89, 0xffff0000, v131
	v_mul_f32_e32 v84, 0xbfb8aa3b, v84
	v_add_f32_e32 v86, 1.0, v86
	v_add_f32_e32 v83, 1.0, v90
	v_exp_f32_e32 v90, v84
	v_mul_f32_e32 v84, 0xbfb8aa3b, v85
	v_mul_f32_e32 v87, 0xbfb8aa3b, v87
	v_mul_f32_e32 v88, 0xbfb8aa3b, v88
	v_mul_f32_e32 v89, 0xbfb8aa3b, v89
	v_rcp_f32_e32 v82, v86
	v_add_f32_e32 v86, 1.0, v91
	v_exp_f32_e32 v91, v84
	v_exp_f32_e32 v87, v87
	v_exp_f32_e32 v88, v88
	v_exp_f32_e32 v89, v89
	v_rcp_f32_e32 v83, v83
	v_rcp_f32_e32 v84, v86
	v_add_f32_e32 v85, 1.0, v90
	v_add_f32_e32 v86, 1.0, v91
	v_add_f32_e32 v87, 1.0, v87
	v_add_f32_e32 v88, 1.0, v88
	v_add_f32_e32 v89, 1.0, v89
	v_lshl_add_u64 v[76:77], s[6:7], 0, v[196:197]
	v_rcp_f32_e32 v85, v85
	v_rcp_f32_e32 v86, v86
	v_rcp_f32_e32 v88, v88
	v_rcp_f32_e32 v89, v89
	v_rcp_f32_e32 v87, v87
	v_lshl_add_u64 v[76:77], v[76:77], 0, v[188:189]
	v_cvt_pk_bf16_f32 v74, v74, v75
	v_cvt_pk_bf16_f32 v75, v80, v81
	global_store_dwordx4 v[76:77], v[72:75], off
	v_lshlrev_b32_e32 v78, 16, v134
	v_and_b32_e32 v79, 0xffff0000, v134
	v_lshlrev_b32_e32 v72, 16, v132
	v_and_b32_e32 v73, 0xffff0000, v132
	v_lshlrev_b32_e32 v74, 16, v133
	v_and_b32_e32 v75, 0xffff0000, v133
	v_lshlrev_b32_e32 v80, 16, v135
	v_and_b32_e32 v81, 0xffff0000, v135
	v_pk_fma_f32 v[68:69], v[68:69], v[82:83], v[72:73]
	v_pk_fma_f32 v[70:71], v[70:71], v[84:85], v[74:75]
	v_pk_fma_f32 v[72:73], v[66:67], v[88:89], v[80:81]
	v_pk_fma_f32 v[66:67], v[64:65], v[86:87], v[78:79]
	v_cvt_pk_bf16_f32 v64, v68, v69
	v_add_u32_e32 v68, 0x80, v192
	v_cvt_pk_bf16_f32 v65, v70, v71
	v_mad_i64_i32 v[70:71], s[26:27], v68, s55, v[194:195]
	v_lshl_add_u64 v[70:71], v[70:71], 0, v[188:189]
	v_cvt_pk_bf16_f32 v66, v66, v67
	v_cvt_pk_bf16_f32 v67, v72, v73
	v_add_co_u32_e32 v72, vcc, s56, v70
	v_ashrrev_i32_e32 v69, 31, v68
	s_nop 0
	v_addc_co_u32_e32 v73, vcc, 0, v71, vcc
	global_load_dwordx4 v[118:121], v[72:73], off offset:2048
	v_lshlrev_b64 v[134:135], 12, v[68:69]
	v_lshl_add_u64 v[68:69], v[190:191], 0, v[134:135]
	global_load_dwordx4 v[122:125], v[68:69], off
	s_waitcnt vmcnt(0)
; __device__ __forceinline__ u32x4 pack8(const f32x4 v0, const f32x4 v1) { u32x4 w; w.x = cvt_pk_bf16(v0[0], v0[1]); w.y = cvt_pk_bf16(v0[2], v0[3]); w.z = cvt_pk_bf16(v1[0], v1[1]); w.w = cvt_pk_bf16(v1[2], v1[3]); return w; }
; __device__ __forceinline__ void unpack8(const u32x4 w, f32x4& v0, f32x4& v1) { v0 = (f32x4){bflo(w.x), bfhi(w.x), bflo(w.y), bfhi(w.y)}; v1 = (f32x4){bflo(w.z), bfhi(w.z), bflo(w.w), bfhi(w.w)}; }
; __device__ __forceinline__ f32x4 sig4(const f32x4 v) { return (f32x4){sigmoidf_(v[0]), sigmoidf_(v[1]), sigmoidf_(v[2]), sigmoidf_(v[3])}; }
;     __device__ __forceinline__ void operator()(const AccT& acc, const pg8::Unit& u, int wr, int wc, int fr, int fq) const {
;         const int row0 = u.pm * 256 + wr * 64 + fr, col0 = u.pn * 256 + wc * 32 + 8 * fq;
; #pragma unroll
;         for (int ai = 0; ai < 2; ++ai) { u32x4 gw[4][2], tw[4][2];
; #pragma unroll
;             for (int m = 0; m < 4; ++m)
; #pragma unroll
;                 for (int bj = 0; bj < 2; ++bj) { const int r = row0 + ai * 128 + m * 16; gw[m][bj] = *(const u32x4*)(PROJ + (size_t)r * NPROJ + C_GB + col0 + bj * 128); tw[m][bj] = *(const u32x4*)(T + (size_t)r * D + col0 + bj * 128); }
; #pragma unroll
;             for (int m = 0; m < 4; ++m)
; #pragma unroll
;                 for (int bj = 0; bj < 2; ++bj) { f32x4 g0, g1, t0, t1; unpack8(gw[m][bj], g0, g1); unpack8(tw[m][bj], t0, t1);
;                     *(u32x4*)(O + (size_t)(row0 + ai * 128 + m * 16) * D + col0 + bj * 128) = pack8(t0 + sig4(g0) * acc[ai][bj][m][0], t1 + sig4(g1) * acc[ai][bj][m][1]); } }
	v_lshlrev_b32_e32 v138, 16, v119
	global_store_dwordx4 v[76:77], v[64:67], off offset:256
	v_and_b32_e32 v139, 0xffff0000, v119
	v_lshlrev_b32_e32 v136, 16, v118
	v_lshl_add_u64 v[64:65], v[70:71], 0, s[10:11]
	global_load_dwordx4 v[126:129], v[64:65], off offset:256
	global_load_dwordx4 v[130:133], v[68:69], off offset:256
	v_add_u32_e32 v64, 0x90, v192
	v_ashrrev_i32_e32 v65, 31, v64
	v_mad_i64_i32 v[66:67], s[26:27], v64, s55, v[194:195]
	v_lshl_add_u64 v[66:67], v[66:67], 0, v[188:189]
	v_lshlrev_b64 v[116:117], 12, v[64:65]
	v_lshl_add_u64 v[68:69], v[66:67], 0, s[10:11]
	v_lshl_add_u64 v[64:65], v[190:191], 0, v[116:117]
	v_add_co_u32_e32 v66, vcc, s56, v66
	v_and_b32_e32 v137, 0xffff0000, v118
	s_nop 0
	v_addc_co_u32_e32 v67, vcc, 0, v67, vcc
	global_load_dwordx4 v[104:107], v[64:65], off
	global_load_dwordx4 v[100:103], v[68:69], off offset:256
	global_load_dwordx4 v[108:111], v[66:67], off offset:2048
	global_load_dwordx4 v[96:99], v[64:65], off offset:256
	v_add_u32_e32 v64, 0xa0, v192
	v_ashrrev_i32_e32 v65, 31, v64
	v_mad_i64_i32 v[66:67], s[26:27], v64, s55, v[194:195]
	v_lshl_add_u64 v[66:67], v[66:67], 0, v[188:189]
	v_lshlrev_b64 v[114:115], 12, v[64:65]
	v_lshl_add_u64 v[68:69], v[66:67], 0, s[10:11]
	v_lshl_add_u64 v[64:65], v[190:191], 0, v[114:115]
	v_add_co_u32_e32 v66, vcc, s56, v66
	v_lshlrev_b32_e32 v140, 16, v120
	s_nop 0
	v_addc_co_u32_e32 v67, vcc, 0, v67, vcc
	global_load_dwordx4 v[88:91], v[64:65], off
	global_load_dwordx4 v[84:87], v[68:69], off offset:256
	global_load_dwordx4 v[92:95], v[66:67], off offset:2048
	global_load_dwordx4 v[80:83], v[64:65], off offset:256
	v_and_b32_e32 v141, 0xffff0000, v120
	v_lshlrev_b32_e32 v142, 16, v121
	v_and_b32_e32 v143, 0xffff0000, v121
	v_mul_f32_e32 v138, 0xbfb8aa3b, v138
	v_mul_f32_e32 v139, 0xbfb8aa3b, v139
	v_lshlrev_b32_e32 v120, 16, v123
	v_and_b32_e32 v121, 0xffff0000, v123
	v_mul_f32_e32 v123, 0xbfb8aa3b, v136
	v_mul_f32_e32 v137, 0xbfb8aa3b, v137
	v_exp_f32_e32 v138, v138
	v_exp_f32_e32 v139, v139
	v_mul_f32_e32 v140, 0xbfb8aa3b, v140
	v_mul_f32_e32 v141, 0xbfb8aa3b, v141
	v_mul_f32_e32 v142, 0xbfb8aa3b, v142
	v_mul_f32_e32 v143, 0xbfb8aa3b, v143
	v_exp_f32_e32 v136, v123
	v_exp_f32_e32 v137, v137
	v_exp_f32_e32 v140, v140
	v_exp_f32_e32 v141, v141
	v_exp_f32_e32 v142, v142
	v_exp_f32_e32 v143, v143
	v_add_f32_e32 v138, 1.0, v138
	v_add_f32_e32 v139, 1.0, v139
	v_add_u32_e32 v64, 0xb0, v192
	v_add_f32_e32 v136, 1.0, v136
	v_add_f32_e32 v137, 1.0, v137
	v_rcp_f32_e32 v138, v138
	v_rcp_f32_e32 v139, v139
	v_add_f32_e32 v140, 1.0, v140
	v_add_f32_e32 v141, 1.0, v141
	v_add_f32_e32 v142, 1.0, v142
	v_add_f32_e32 v143, 1.0, v143
	v_mad_i64_i32 v[66:67], s[26:27], v64, s55, v[194:195]
	v_rcp_f32_e32 v136, v136
	v_rcp_f32_e32 v137, v137
	v_rcp_f32_e32 v140, v140
	v_rcp_f32_e32 v142, v142
	v_rcp_f32_e32 v143, v143
	v_rcp_f32_e32 v141, v141
	v_ashrrev_i32_e32 v65, 31, v64
	v_lshl_add_u64 v[66:67], v[66:67], 0, v[188:189]
	v_lshl_add_u64 v[68:69], v[66:67], 0, s[10:11]
	v_lshlrev_b64 v[112:113], 12, v[64:65]
	v_add_co_u32_e32 v66, vcc, s56, v66
	v_lshl_add_u64 v[64:65], v[190:191], 0, v[112:113]
	s_nop 0
	v_addc_co_u32_e32 v67, vcc, 0, v67, vcc
	v_lshlrev_b32_e32 v118, 16, v122
	v_and_b32_e32 v119, 0xffff0000, v122
	v_lshlrev_b32_e32 v122, 16, v124
	v_and_b32_e32 v123, 0xffff0000, v124
	v_lshlrev_b32_e32 v124, 16, v125
	v_and_b32_e32 v125, 0xffff0000, v125
	v_pk_fma_f32 v[62:63], v[62:63], v[138:139], v[120:121]
	global_load_dwordx4 v[72:75], v[64:65], off
	s_nop 0
	global_load_dwordx4 v[68:71], v[68:69], off offset:256
	s_nop 0
	global_load_dwordx4 v[76:79], v[66:67], off offset:2048
	s_nop 0
	global_load_dwordx4 v[64:67], v[64:65], off offset:256
	v_pk_fma_f32 v[60:61], v[60:61], v[136:137], v[118:119]
	v_pk_fma_f32 v[118:119], v[58:59], v[142:143], v[124:125]
	v_pk_fma_f32 v[58:59], v[56:57], v[140:141], v[122:123]
	v_cvt_pk_bf16_f32 v56, v60, v61
	v_cvt_pk_bf16_f32 v57, v62, v63
	s_waitcnt vmcnt(0)
	v_lshlrev_b32_e32 v63, 16, v126
	v_and_b32_e32 v120, 0xffff0000, v126
	v_lshlrev_b32_e32 v121, 16, v127
	v_mul_f32_e32 v63, 0xbfb8aa3b, v63
	v_mul_f32_e32 v120, 0xbfb8aa3b, v120
	v_lshlrev_b32_e32 v123, 16, v128
	v_and_b32_e32 v125, 0xffff0000, v128
	v_exp_f32_e32 v124, v63
	v_exp_f32_e32 v128, v120
	v_mul_f32_e32 v120, 0xbfb8aa3b, v121
	v_and_b32_e32 v122, 0xffff0000, v127
	v_lshlrev_b32_e32 v126, 16, v129
	v_and_b32_e32 v127, 0xffff0000, v129
	v_exp_f32_e32 v129, v120
	v_mul_f32_e32 v122, 0xbfb8aa3b, v122
	v_add_f32_e32 v124, 1.0, v124
	v_add_f32_e32 v121, 1.0, v128
	v_exp_f32_e32 v128, v122
	v_mul_f32_e32 v122, 0xbfb8aa3b, v123
	v_mul_f32_e32 v125, 0xbfb8aa3b, v125
	v_mul_f32_e32 v126, 0xbfb8aa3b, v126
	v_mul_f32_e32 v127, 0xbfb8aa3b, v127
	v_rcp_f32_e32 v120, v124
	v_add_f32_e32 v124, 1.0, v129
	v_exp_f32_e32 v129, v122
	v_exp_f32_e32 v125, v125
	v_exp_f32_e32 v126, v126
	v_exp_f32_e32 v127, v127
	v_rcp_f32_e32 v122, v124
	v_add_f32_e32 v124, 1.0, v129
	v_add_f32_e32 v125, 1.0, v125
	v_add_f32_e32 v126, 1.0, v126
	v_add_f32_e32 v127, 1.0, v127
	v_rcp_f32_e32 v121, v121
	v_add_f32_e32 v123, 1.0, v128
	v_rcp_f32_e32 v124, v124
	v_rcp_f32_e32 v126, v126
	v_rcp_f32_e32 v127, v127
	v_rcp_f32_e32 v125, v125
	v_lshl_add_u64 v[60:61], s[6:7], 0, v[134:135]
	v_rcp_f32_e32 v123, v123
	v_lshl_add_u64 v[60:61], v[60:61], 0, v[188:189]
	v_cvt_pk_bf16_f32 v58, v58, v59
	v_cvt_pk_bf16_f32 v59, v118, v119
	global_store_dwordx4 v[60:61], v[56:59], off
	v_lshlrev_b32_e32 v62, 16, v132
	v_and_b32_e32 v63, 0xffff0000, v132
	v_lshlrev_b32_e32 v56, 16, v130
	v_and_b32_e32 v57, 0xffff0000, v130
	v_lshlrev_b32_e32 v118, 16, v133
	v_and_b32_e32 v119, 0xffff0000, v133
	v_lshlrev_b32_e32 v58, 16, v131
; __device__ __forceinline__ u32x4 pack8(const f32x4 v0, const f32x4 v1) { u32x4 w; w.x = cvt_pk_bf16(v0[0], v0[1]); w.y = cvt_pk_bf16(v0[2], v0[3]); w.z = cvt_pk_bf16(v1[0], v1[1]); w.w = cvt_pk_bf16(v1[2], v1[3]); return w; }
; __device__ __forceinline__ void unpack8(const u32x4 w, f32x4& v0, f32x4& v1) { v0 = (f32x4){bflo(w.x), bfhi(w.x), bflo(w.y), bfhi(w.y)}; v1 = (f32x4){bflo(w.z), bfhi(w.z), bflo(w.w), bfhi(w.w)}; }
; __device__ __forceinline__ f32x4 sig4(const f32x4 v) { return (f32x4){sigmoidf_(v[0]), sigmoidf_(v[1]), sigmoidf_(v[2]), sigmoidf_(v[3])}; }
;     __device__ __forceinline__ void operator()(const AccT& acc, const pg8::Unit& u, int wr, int wc, int fr, int fq) const {
;         const int row0 = u.pm * 256 + wr * 64 + fr, col0 = u.pn * 256 + wc * 32 + 8 * fq;
; #pragma unroll
;         for (int ai = 0; ai < 2; ++ai) { u32x4 gw[4][2], tw[4][2];
; #pragma unroll
;             for (int m = 0; m < 4; ++m)
; #pragma unroll
;                 for (int bj = 0; bj < 2; ++bj) { const int r = row0 + ai * 128 + m * 16; gw[m][bj] = *(const u32x4*)(PROJ + (size_t)r * NPROJ + C_GB + col0 + bj * 128); tw[m][bj] = *(const u32x4*)(T + (size_t)r * D + col0 + bj * 128); }
; #pragma unroll
;             for (int m = 0; m < 4; ++m)
; #pragma unroll
;                 for (int bj = 0; bj < 2; ++bj) { f32x4 g0, g1, t0, t1; unpack8(gw[m][bj], g0, g1); unpack8(tw[m][bj], t0, t1);
;                     *(u32x4*)(O + (size_t)(row0 + ai * 128 + m * 16) * D + col0 + bj * 128) = pack8(t0 + sig4(g0) * acc[ai][bj][m][0], t1 + sig4(g1) * acc[ai][bj][m][1]); } }
	v_and_b32_e32 v59, 0xffff0000, v131
	v_pk_fma_f32 v[52:53], v[52:53], v[120:121], v[56:57]
	v_pk_fma_f32 v[56:57], v[50:51], v[126:127], v[118:119]
	v_pk_fma_f32 v[50:51], v[48:49], v[124:125], v[62:63]
	v_pk_fma_f32 v[54:55], v[54:55], v[122:123], v[58:59]
	v_cvt_pk_bf16_f32 v48, v52, v53
	v_lshlrev_b32_e32 v53, 16, v108
	v_cvt_pk_bf16_f32 v49, v54, v55
	v_cvt_pk_bf16_f32 v50, v50, v51
	v_cvt_pk_bf16_f32 v51, v56, v57
	v_and_b32_e32 v56, 0xffff0000, v108
	v_lshlrev_b32_e32 v57, 16, v109
	v_mul_f32_e32 v53, 0xbfb8aa3b, v53
	v_mul_f32_e32 v56, 0xbfb8aa3b, v56
	global_store_dwordx4 v[60:61], v[48:51], off offset:256
	v_exp_f32_e32 v60, v53
	v_and_b32_e32 v58, 0xffff0000, v109
	v_lshlrev_b32_e32 v48, 16, v104
	v_and_b32_e32 v49, 0xffff0000, v104
	v_exp_f32_e32 v104, v56
	v_mul_f32_e32 v56, 0xbfb8aa3b, v57
	v_lshlrev_b32_e32 v50, 16, v105
	v_and_b32_e32 v51, 0xffff0000, v105
	v_exp_f32_e32 v105, v56
	v_lshlrev_b32_e32 v59, 16, v110
	v_and_b32_e32 v61, 0xffff0000, v110
	v_lshlrev_b32_e32 v62, 16, v111
	v_and_b32_e32 v63, 0xffff0000, v111
	v_mul_f32_e32 v58, 0xbfb8aa3b, v58
	v_add_f32_e32 v60, 1.0, v60
	v_add_f32_e32 v57, 1.0, v104
	v_exp_f32_e32 v104, v58
	v_mul_f32_e32 v58, 0xbfb8aa3b, v59
	v_mul_f32_e32 v61, 0xbfb8aa3b, v61
	v_mul_f32_e32 v62, 0xbfb8aa3b, v62
	v_mul_f32_e32 v63, 0xbfb8aa3b, v63
	v_rcp_f32_e32 v56, v60
	v_add_f32_e32 v60, 1.0, v105
	v_exp_f32_e32 v105, v58
	v_exp_f32_e32 v61, v61
	v_exp_f32_e32 v62, v62
	v_exp_f32_e32 v63, v63
	v_add_f32_e32 v59, 1.0, v104
	v_rcp_f32_e32 v58, v60
	v_rcp_f32_e32 v59, v59
	v_add_f32_e32 v60, 1.0, v105
	v_add_f32_e32 v61, 1.0, v61
	v_add_f32_e32 v62, 1.0, v62
	v_add_f32_e32 v63, 1.0, v63
	v_rcp_f32_e32 v57, v57
	v_rcp_f32_e32 v60, v60
	v_rcp_f32_e32 v62, v62
	v_rcp_f32_e32 v63, v63
	v_rcp_f32_e32 v61, v61
	v_lshlrev_b32_e32 v52, 16, v106
	v_and_b32_e32 v53, 0xffff0000, v106
	v_lshlrev_b32_e32 v54, 16, v107
	v_and_b32_e32 v55, 0xffff0000, v107
	v_pk_fma_f32 v[46:47], v[46:47], v[58:59], v[50:51]
	v_pk_fma_f32 v[44:45], v[44:45], v[56:57], v[48:49]
	v_pk_fma_f32 v[48:49], v[42:43], v[62:63], v[54:55]
	v_pk_fma_f32 v[42:43], v[40:41], v[60:61], v[52:53]
	v_cvt_pk_bf16_f32 v40, v44, v45
	v_cvt_pk_bf16_f32 v41, v46, v47
	v_lshlrev_b32_e32 v47, 16, v100
	v_and_b32_e32 v50, 0xffff0000, v100
	v_lshlrev_b32_e32 v51, 16, v101
	v_mul_f32_e32 v47, 0xbfb8aa3b, v47
	v_mul_f32_e32 v50, 0xbfb8aa3b, v50
	v_exp_f32_e32 v54, v47
	v_exp_f32_e32 v58, v50
	v_mul_f32_e32 v50, 0xbfb8aa3b, v51
	v_exp_f32_e32 v59, v50
	v_and_b32_e32 v52, 0xffff0000, v101
	v_lshlrev_b32_e32 v53, 16, v102
	v_and_b32_e32 v55, 0xffff0000, v102
	v_lshlrev_b32_e32 v56, 16, v103
	v_and_b32_e32 v57, 0xffff0000, v103
	v_mul_f32_e32 v52, 0xbfb8aa3b, v52
	v_add_f32_e32 v54, 1.0, v54
	v_add_f32_e32 v51, 1.0, v58
	v_exp_f32_e32 v58, v52
	v_mul_f32_e32 v52, 0xbfb8aa3b, v53
	v_mul_f32_e32 v55, 0xbfb8aa3b, v55
	v_mul_f32_e32 v56, 0xbfb8aa3b, v56
	v_mul_f32_e32 v57, 0xbfb8aa3b, v57
	v_rcp_f32_e32 v50, v54
	v_add_f32_e32 v54, 1.0, v59
	v_exp_f32_e32 v59, v52
	v_exp_f32_e32 v55, v55
	v_exp_f32_e32 v56, v56
	v_exp_f32_e32 v57, v57
	v_rcp_f32_e32 v52, v54
	v_add_f32_e32 v54, 1.0, v59
	v_add_f32_e32 v55, 1.0, v55
	v_add_f32_e32 v56, 1.0, v56
	v_add_f32_e32 v57, 1.0, v57
	v_rcp_f32_e32 v51, v51
	v_add_f32_e32 v53, 1.0, v58
	v_rcp_f32_e32 v54, v54
	v_rcp_f32_e32 v56, v56
	v_rcp_f32_e32 v57, v57
	v_rcp_f32_e32 v55, v55
	v_lshl_add_u64 v[44:45], s[6:7], 0, v[116:117]
	v_rcp_f32_e32 v53, v53
	v_lshl_add_u64 v[44:45], v[44:45], 0, v[188:189]
	v_cvt_pk_bf16_f32 v42, v42, v43
	v_cvt_pk_bf16_f32 v43, v48, v49
	global_store_dwordx4 v[44:45], v[40:43], off
	v_lshlrev_b32_e32 v46, 16, v98
	v_and_b32_e32 v47, 0xffff0000, v98
	v_lshlrev_b32_e32 v40, 16, v96
	v_and_b32_e32 v41, 0xffff0000, v96
	v_lshlrev_b32_e32 v48, 16, v99
	v_and_b32_e32 v49, 0xffff0000, v99
	v_lshlrev_b32_e32 v42, 16, v97
	v_and_b32_e32 v43, 0xffff0000, v97
	v_pk_fma_f32 v[36:37], v[36:37], v[50:51], v[40:41]
	v_pk_fma_f32 v[40:41], v[34:35], v[56:57], v[48:49]
	v_pk_fma_f32 v[34:35], v[32:33], v[54:55], v[46:47]
	v_pk_fma_f32 v[38:39], v[38:39], v[52:53], v[42:43]
	v_cvt_pk_bf16_f32 v32, v36, v37
	v_lshlrev_b32_e32 v37, 16, v92
	v_cvt_pk_bf16_f32 v33, v38, v39
	v_cvt_pk_bf16_f32 v34, v34, v35
	v_cvt_pk_bf16_f32 v35, v40, v41
	v_and_b32_e32 v40, 0xffff0000, v92
	v_lshlrev_b32_e32 v41, 16, v93
	v_mul_f32_e32 v37, 0xbfb8aa3b, v37
	v_mul_f32_e32 v40, 0xbfb8aa3b, v40
	global_store_dwordx4 v[44:45], v[32:35], off offset:256
	v_exp_f32_e32 v44, v37
	v_exp_f32_e32 v48, v40
	v_mul_f32_e32 v40, 0xbfb8aa3b, v41
	v_exp_f32_e32 v49, v40
	v_and_b32_e32 v42, 0xffff0000, v93
	v_lshlrev_b32_e32 v43, 16, v94
	v_and_b32_e32 v45, 0xffff0000, v94
	v_lshlrev_b32_e32 v46, 16, v95
	v_and_b32_e32 v47, 0xffff0000, v95
	v_mul_f32_e32 v42, 0xbfb8aa3b, v42
	v_add_f32_e32 v44, 1.0, v44
	v_add_f32_e32 v41, 1.0, v48
	v_exp_f32_e32 v48, v42
	v_mul_f32_e32 v42, 0xbfb8aa3b, v43
	v_mul_f32_e32 v45, 0xbfb8aa3b, v45
	v_mul_f32_e32 v46, 0xbfb8aa3b, v46
	v_mul_f32_e32 v47, 0xbfb8aa3b, v47
	v_rcp_f32_e32 v40, v44
	v_add_f32_e32 v44, 1.0, v49
	v_exp_f32_e32 v49, v42
	v_exp_f32_e32 v45, v45
	v_exp_f32_e32 v46, v46
	v_exp_f32_e32 v47, v47
	v_add_f32_e32 v43, 1.0, v48
	v_rcp_f32_e32 v42, v44
	v_rcp_f32_e32 v43, v43
	v_add_f32_e32 v44, 1.0, v49
	v_add_f32_e32 v45, 1.0, v45
	v_add_f32_e32 v46, 1.0, v46
	v_add_f32_e32 v47, 1.0, v47
	v_rcp_f32_e32 v41, v41
	v_rcp_f32_e32 v44, v44
	v_rcp_f32_e32 v46, v46
	v_rcp_f32_e32 v47, v47
	v_rcp_f32_e32 v45, v45
	v_lshlrev_b32_e32 v34, 16, v89
	v_and_b32_e32 v35, 0xffff0000, v89
	v_lshlrev_b32_e32 v32, 16, v88
	v_and_b32_e32 v33, 0xffff0000, v88
	v_lshlrev_b32_e32 v36, 16, v90
	v_and_b32_e32 v37, 0xffff0000, v90
; #define PG8_WAIT_V(n) asm volatile("s_waitcnt vmcnt(" #n ")" ::: "memory")
; #define PG8_BAR __builtin_amdgcn_s_barrier()
; __device__ __forceinline__ u32x4 pack8(const f32x4 v0, const f32x4 v1) { u32x4 w; w.x = cvt_pk_bf16(v0[0], v0[1]); w.y = cvt_pk_bf16(v0[2], v0[3]); w.z = cvt_pk_bf16(v1[0], v1[1]); w.w = cvt_pk_bf16(v1[2], v1[3]); return w; }
; __device__ __forceinline__ void unpack8(const u32x4 w, f32x4& v0, f32x4& v1) { v0 = (f32x4){bflo(w.x), bfhi(w.x), bflo(w.y), bfhi(w.y)}; v1 = (f32x4){bflo(w.z), bfhi(w.z), bflo(w.w), bfhi(w.w)}; }
; __device__ __forceinline__ f32x4 sig4(const f32x4 v) { return (f32x4){sigmoidf_(v[0]), sigmoidf_(v[1]), sigmoidf_(v[2]), sigmoidf_(v[3])}; }
; template <class Epi>
; __device__ __forceinline__ void gemm_phase(LAS unsigned char* lds, const Gemm g, const StaticOrder& S, const Epi& E) {
;     ...
;         if (!has_next) break;
; #pragma unroll
;         for (int a = 0; a < 2; ++a)
; #pragma unroll
;             for (int b = 0; b < 2; ++b)
; #pragma unroll
;                 for (int m = 0; m < 4; ++m)
; #pragma unroll
;                     for (int n = 0; n < 2; ++n) acc[a][b][m][n] = (f32x4){0.f, 0.f, 0.f, 0.f};
;         cur = nxt; cA = nA; cB = nB; ++ui;
;     }
;     PG8_WAIT_V(0);
;     if (wr == 0) PG8_BAR;
;     PG8_BAR;
;     __device__ __forceinline__ void operator()(const AccT& acc, const pg8::Unit& u, int wr, int wc, int fr, int fq) const {
;     ...
;             for (int m = 0; m < 4; ++m)
; #pragma unroll
;                 for (int bj = 0; bj < 2; ++bj) { f32x4 g0, g1, t0, t1; unpack8(gw[m][bj], g0, g1); unpack8(tw[m][bj], t0, t1);
;                     *(u32x4*)(O + (size_t)(row0 + ai * 128 + m * 16) * D + col0 + bj * 128) = pack8(t0 + sig4(g0) * acc[ai][bj][m][0], t1 + sig4(g1) * acc[ai][bj][m][1]); } }
	v_lshlrev_b32_e32 v38, 16, v91
	v_and_b32_e32 v39, 0xffff0000, v91
	v_pk_fma_f32 v[30:31], v[30:31], v[42:43], v[34:35]
	v_pk_fma_f32 v[28:29], v[28:29], v[40:41], v[32:33]
	v_pk_fma_f32 v[32:33], v[26:27], v[46:47], v[38:39]
	v_pk_fma_f32 v[26:27], v[24:25], v[44:45], v[36:37]
	v_cvt_pk_bf16_f32 v24, v28, v29
	v_cvt_pk_bf16_f32 v25, v30, v31
	v_lshlrev_b32_e32 v31, 16, v84
	v_and_b32_e32 v34, 0xffff0000, v84
	v_lshlrev_b32_e32 v35, 16, v85
	v_mul_f32_e32 v31, 0xbfb8aa3b, v31
	v_mul_f32_e32 v34, 0xbfb8aa3b, v34
	v_exp_f32_e32 v38, v31
	v_exp_f32_e32 v42, v34
	v_mul_f32_e32 v34, 0xbfb8aa3b, v35
	v_exp_f32_e32 v43, v34
	v_and_b32_e32 v36, 0xffff0000, v85
	v_lshlrev_b32_e32 v37, 16, v86
	v_and_b32_e32 v39, 0xffff0000, v86
	v_lshlrev_b32_e32 v40, 16, v87
	v_and_b32_e32 v41, 0xffff0000, v87
	v_mul_f32_e32 v36, 0xbfb8aa3b, v36
	v_add_f32_e32 v38, 1.0, v38
	v_add_f32_e32 v35, 1.0, v42
	v_exp_f32_e32 v42, v36
	v_mul_f32_e32 v36, 0xbfb8aa3b, v37
	v_mul_f32_e32 v39, 0xbfb8aa3b, v39
	v_mul_f32_e32 v40, 0xbfb8aa3b, v40
	v_mul_f32_e32 v41, 0xbfb8aa3b, v41
	v_rcp_f32_e32 v34, v38
	v_add_f32_e32 v38, 1.0, v43
	v_exp_f32_e32 v43, v36
	v_exp_f32_e32 v39, v39
	v_exp_f32_e32 v40, v40
	v_exp_f32_e32 v41, v41
	v_rcp_f32_e32 v36, v38
	v_add_f32_e32 v38, 1.0, v43
	v_add_f32_e32 v39, 1.0, v39
	v_add_f32_e32 v40, 1.0, v40
	v_add_f32_e32 v41, 1.0, v41
	v_rcp_f32_e32 v35, v35
	v_add_f32_e32 v37, 1.0, v42
	v_rcp_f32_e32 v38, v38
	v_rcp_f32_e32 v40, v40
	v_rcp_f32_e32 v41, v41
	v_rcp_f32_e32 v39, v39
	v_lshl_add_u64 v[28:29], s[6:7], 0, v[114:115]
	v_rcp_f32_e32 v37, v37
	v_lshl_add_u64 v[28:29], v[28:29], 0, v[188:189]
	v_cvt_pk_bf16_f32 v26, v26, v27
	v_cvt_pk_bf16_f32 v27, v32, v33
	global_store_dwordx4 v[28:29], v[24:27], off
	v_lshlrev_b32_e32 v30, 16, v82
	v_and_b32_e32 v31, 0xffff0000, v82
	v_lshlrev_b32_e32 v24, 16, v80
	v_and_b32_e32 v25, 0xffff0000, v80
	v_lshlrev_b32_e32 v32, 16, v83
	v_and_b32_e32 v33, 0xffff0000, v83
	v_lshlrev_b32_e32 v26, 16, v81
	v_and_b32_e32 v27, 0xffff0000, v81
	v_pk_fma_f32 v[20:21], v[20:21], v[34:35], v[24:25]
	v_pk_fma_f32 v[24:25], v[18:19], v[40:41], v[32:33]
	v_pk_fma_f32 v[18:19], v[16:17], v[38:39], v[30:31]
	v_pk_fma_f32 v[22:23], v[22:23], v[36:37], v[26:27]
	v_cvt_pk_bf16_f32 v16, v20, v21
	v_lshlrev_b32_e32 v21, 16, v76
	v_cvt_pk_bf16_f32 v17, v22, v23
	v_cvt_pk_bf16_f32 v18, v18, v19
	v_cvt_pk_bf16_f32 v19, v24, v25
	v_and_b32_e32 v24, 0xffff0000, v76
	v_lshlrev_b32_e32 v25, 16, v77
	v_mul_f32_e32 v21, 0xbfb8aa3b, v21
	v_mul_f32_e32 v24, 0xbfb8aa3b, v24
	global_store_dwordx4 v[28:29], v[16:19], off offset:256
	v_exp_f32_e32 v28, v21
	v_exp_f32_e32 v32, v24
	v_mul_f32_e32 v24, 0xbfb8aa3b, v25
	v_exp_f32_e32 v33, v24
	v_and_b32_e32 v26, 0xffff0000, v77
	v_lshlrev_b32_e32 v27, 16, v78
	v_and_b32_e32 v29, 0xffff0000, v78
	v_lshlrev_b32_e32 v30, 16, v79
	v_and_b32_e32 v31, 0xffff0000, v79
	v_mul_f32_e32 v26, 0xbfb8aa3b, v26
	v_add_f32_e32 v28, 1.0, v28
	v_add_f32_e32 v25, 1.0, v32
	v_exp_f32_e32 v32, v26
	v_mul_f32_e32 v26, 0xbfb8aa3b, v27
	v_mul_f32_e32 v29, 0xbfb8aa3b, v29
	v_mul_f32_e32 v30, 0xbfb8aa3b, v30
	v_mul_f32_e32 v31, 0xbfb8aa3b, v31
	v_rcp_f32_e32 v24, v28
	v_add_f32_e32 v28, 1.0, v33
	v_exp_f32_e32 v33, v26
	v_exp_f32_e32 v29, v29
	v_exp_f32_e32 v30, v30
	v_exp_f32_e32 v31, v31
	v_add_f32_e32 v27, 1.0, v32
	v_rcp_f32_e32 v26, v28
	v_rcp_f32_e32 v27, v27
	v_add_f32_e32 v28, 1.0, v33
	v_add_f32_e32 v29, 1.0, v29
	v_add_f32_e32 v30, 1.0, v30
	v_add_f32_e32 v31, 1.0, v31
	v_rcp_f32_e32 v25, v25
	v_rcp_f32_e32 v28, v28
	v_rcp_f32_e32 v30, v30
	v_rcp_f32_e32 v31, v31
	v_rcp_f32_e32 v29, v29
	v_lshlrev_b32_e32 v18, 16, v73
	v_and_b32_e32 v19, 0xffff0000, v73
	v_lshlrev_b32_e32 v16, 16, v72
	v_and_b32_e32 v17, 0xffff0000, v72
	v_lshlrev_b32_e32 v20, 16, v74
	v_and_b32_e32 v21, 0xffff0000, v74
	v_lshlrev_b32_e32 v22, 16, v75
	v_and_b32_e32 v23, 0xffff0000, v75
	v_pk_fma_f32 v[14:15], v[14:15], v[26:27], v[18:19]
	v_pk_fma_f32 v[12:13], v[12:13], v[24:25], v[16:17]
	v_pk_fma_f32 v[16:17], v[10:11], v[30:31], v[22:23]
	v_pk_fma_f32 v[10:11], v[8:9], v[28:29], v[20:21]
	v_cvt_pk_bf16_f32 v8, v12, v13
	v_cvt_pk_bf16_f32 v9, v14, v15
	v_lshlrev_b32_e32 v15, 16, v68
	v_and_b32_e32 v18, 0xffff0000, v68
	v_lshlrev_b32_e32 v19, 16, v69
	v_mul_f32_e32 v15, 0xbfb8aa3b, v15
	v_mul_f32_e32 v18, 0xbfb8aa3b, v18
	v_exp_f32_e32 v22, v15
	v_exp_f32_e32 v26, v18
	v_mul_f32_e32 v18, 0xbfb8aa3b, v19
	v_exp_f32_e32 v27, v18
	v_and_b32_e32 v20, 0xffff0000, v69
	v_lshlrev_b32_e32 v21, 16, v70
	v_and_b32_e32 v23, 0xffff0000, v70
	v_lshlrev_b32_e32 v24, 16, v71
	v_and_b32_e32 v25, 0xffff0000, v71
	v_mul_f32_e32 v20, 0xbfb8aa3b, v20
	v_add_f32_e32 v22, 1.0, v22
	v_add_f32_e32 v19, 1.0, v26
	v_exp_f32_e32 v26, v20
	v_mul_f32_e32 v20, 0xbfb8aa3b, v21
	v_mul_f32_e32 v23, 0xbfb8aa3b, v23
	v_mul_f32_e32 v24, 0xbfb8aa3b, v24
	v_mul_f32_e32 v25, 0xbfb8aa3b, v25
	v_rcp_f32_e32 v18, v22
	v_add_f32_e32 v22, 1.0, v27
	v_exp_f32_e32 v27, v20
	v_exp_f32_e32 v23, v23
	v_exp_f32_e32 v24, v24
	v_exp_f32_e32 v25, v25
	v_rcp_f32_e32 v20, v22
	v_add_f32_e32 v22, 1.0, v27
	v_add_f32_e32 v23, 1.0, v23
	v_add_f32_e32 v24, 1.0, v24
	v_add_f32_e32 v25, 1.0, v25
	v_rcp_f32_e32 v19, v19
	v_add_f32_e32 v21, 1.0, v26
	v_rcp_f32_e32 v22, v22
	v_rcp_f32_e32 v24, v24
	v_rcp_f32_e32 v25, v25
	v_rcp_f32_e32 v23, v23
	v_lshl_add_u64 v[12:13], s[6:7], 0, v[112:113]
	v_rcp_f32_e32 v21, v21
	v_lshl_add_u64 v[12:13], v[12:13], 0, v[188:189]
	v_cvt_pk_bf16_f32 v10, v10, v11
	v_cvt_pk_bf16_f32 v11, v16, v17
	global_store_dwordx4 v[12:13], v[8:11], off
	v_lshlrev_b32_e32 v14, 16, v66
	v_and_b32_e32 v15, 0xffff0000, v66
	v_lshlrev_b32_e32 v8, 16, v64
	v_and_b32_e32 v9, 0xffff0000, v64
	v_lshlrev_b32_e32 v16, 16, v67
	v_and_b32_e32 v17, 0xffff0000, v67
	v_lshlrev_b32_e32 v10, 16, v65
	v_and_b32_e32 v11, 0xffff0000, v65
	v_pk_fma_f32 v[4:5], v[4:5], v[18:19], v[8:9]
	v_pk_fma_f32 v[8:9], v[2:3], v[24:25], v[16:17]
	v_pk_fma_f32 v[2:3], v[0:1], v[22:23], v[14:15]
	s_and_b64 vcc, exec, s[2:3]
	s_mov_b64 s[26:27], s[20:21]
	v_pk_fma_f32 v[6:7], v[6:7], v[20:21], v[10:11]
	v_cvt_pk_bf16_f32 v0, v4, v5
	s_nop 0
	v_cvt_pk_bf16_f32 v1, v6, v7
	v_cvt_pk_bf16_f32 v2, v2, v3
	v_cvt_pk_bf16_f32 v3, v8, v9
	global_store_dwordx4 v[12:13], v[0:3], off offset:256
	s_cbranch_vccz .LBB0_923
	s_waitcnt vmcnt(0)
	s_cmpk_gt_u32 s34, 0xff
	s_cbranch_scc1 .LBB0_934
	s_barrier

; #define PG8_STAGE(bufoff, gbase, voff) do { _Pragma("unroll") for (int _i = 0; _i < 2; ++_i) \
;         __builtin_amdgcn_global_load_lds((const unsigned*)((const char*)(gbase) + (voff)[_i]), (LAS unsigned*)(lds + (bufoff) + ldsw + _i * 8192), 16, 0, 0); } while (0)
; #define PG8_LDA(dst, b, h) do { _Pragma("unroll") for (int m = 0; m < 4; ++m) _Pragma("unroll") for (int k = 0; k < 2; ++k) dst[m][k] = *(const LAS bf16x8*)(lds + PG8_SA(b, h) + aoff + m * 2048 + k * 1024); } while (0)
; #define PG8_LDB(dst, b, h) do { _Pragma("unroll") for (int n = 0; n < 2; ++n) _Pragma("unroll") for (int k = 0; k < 2; ++k) dst[n][k] = *(const LAS bf16x8*)(lds + PG8_SB(b, h) + boff + n * 2048 + k * 1024); } while (0)
; #define PG8_MMA(ai, bj, At, Bt) do { __builtin_amdgcn_s_setprio(1); _Pragma("unroll") for (int m = 0; m < 4; ++m) _Pragma("unroll") for (int n = 0; n < 2; ++n) _Pragma("unroll") for (int k = 0; k < 2; ++k) \
;         acc[ai][bj][m][n] = __builtin_amdgcn_mfma_f32_16x16x32_bf16(Bt[n][k], At[m][k], acc[ai][bj][m][n], 0, 0, 0); __builtin_amdgcn_s_setprio(0); } while (0)
; #define PG8_WAIT_V(n) asm volatile("s_waitcnt vmcnt(" #n ")" ::: "memory")
; #define PG8_WAIT_L(n) asm volatile("s_waitcnt lgkmcnt(" #n ")" ::: "memory")
; #define PG8_BAR __builtin_amdgcn_s_barrier()
; #define PG8_SCHED __builtin_amdgcn_sched_barrier(0)
; template <class Epi>
; __device__ __forceinline__ void gemm_phase(LAS unsigned char* lds, const Gemm g, const StaticOrder& S, const Epi& E) {
;     ...
;             PG8_LDB(B0, 0, 0); PG8_SCHED; PG8_LDA(At, 0, 0); PG8_STAGE(PG8_SA(1, 1), a1 + hstep, voffA);
;             PG8_WAIT_L(8); PG8_BAR; PG8_WAIT_L(0); PG8_MMA(0, 0, At, B0); PG8_BAR; PG8_SCHED;
;             PG8_LDB(B1, 0, 1); PG8_STAGE(PG8_SB(0, 0), b2, voffB);
;             PG8_BAR; PG8_WAIT_L(0); PG8_MMA(0, 1, At, B1); PG8_BAR;
;             PG8_LDA(At, 0, 1); PG8_STAGE(PG8_SA(0, 0), a2, voffA);
;             PG8_BAR; PG8_WAIT_L(0); PG8_MMA(1, 0, At, B0); PG8_BAR; PG8_SCHED;
;             PG8_STAGE(PG8_SB(0, 1), b2 + hstep, voffB);
;             PG8_WAIT_V(6); PG8_BAR; PG8_MMA(1, 1, At, B1); PG8_BAR;
.LBB0_1005:
	ds_read_b128 v[128:131], v210
	ds_read_b128 v[132:135], v210 offset:1024
	ds_read_b128 v[136:139], v210 offset:2048
	ds_read_b128 v[140:143], v210 offset:3072
	s_add_u32 s30, s28, 0xfff80080
	s_addc_u32 s31, s29, -1
	s_cmp_eq_u32 s65, 28
	s_cselect_b32 s35, s1, s31
	s_cselect_b32 s34, s19, s30
	s_cselect_b32 s31, s21, s64
	s_cselect_b32 s30, s27, s63
	v_lshl_add_u64 v[194:195], s[28:29], 0, v[186:187]
	s_add_i32 m0, s40, 0xc000
	ds_read_b128 v[144:147], v211
	ds_read_b128 v[148:151], v211 offset:1024
	ds_read_b128 v[152:155], v211 offset:2048
	ds_read_b128 v[156:159], v211 offset:3072
	ds_read_b128 v[160:163], v211 offset:4096
	ds_read_b128 v[164:167], v211 offset:5120
	ds_read_b128 v[168:171], v211 offset:6144
	ds_read_b128 v[172:175], v211 offset:7168
	global_load_lds_dwordx4 v[194:195], off
	v_lshl_add_u64 v[194:195], s[28:29], 0, v[188:189]
	s_add_i32 m0, s40, 0xe000
	s_nop 0
	global_load_lds_dwordx4 v[194:195], off
	s_waitcnt lgkmcnt(8)
	s_barrier
	s_waitcnt lgkmcnt(0)
	s_waitcnt lgkmcnt(0)
	v_mfma_f32_16x16x32_bf16 v[124:127], v[128:131], v[144:147], v[124:127]
	v_mfma_f32_16x16x32_bf16 v[120:123], v[136:139], v[144:147], v[120:123]
	v_mfma_f32_16x16x32_bf16 v[108:111], v[128:131], v[152:155], v[108:111]
	v_mfma_f32_16x16x32_bf16 v[104:107], v[136:139], v[152:155], v[104:107]
	v_mfma_f32_16x16x32_bf16 v[92:95], v[128:131], v[160:163], v[92:95]
	v_mfma_f32_16x16x32_bf16 v[88:91], v[136:139], v[160:163], v[88:91]
	v_mfma_f32_16x16x32_bf16 v[76:79], v[128:131], v[168:171], v[76:79]
	v_mfma_f32_16x16x32_bf16 v[72:75], v[136:139], v[168:171], v[72:75]
	v_mfma_f32_16x16x32_bf16 v[124:127], v[132:135], v[148:151], v[124:127]
	v_mfma_f32_16x16x32_bf16 v[120:123], v[140:143], v[148:151], v[120:123]
	v_mfma_f32_16x16x32_bf16 v[108:111], v[132:135], v[156:159], v[108:111]
	v_mfma_f32_16x16x32_bf16 v[104:107], v[140:143], v[156:159], v[104:107]
	v_mfma_f32_16x16x32_bf16 v[92:95], v[132:135], v[164:167], v[92:95]
	v_mfma_f32_16x16x32_bf16 v[88:91], v[140:143], v[164:167], v[88:91]
	v_mfma_f32_16x16x32_bf16 v[76:79], v[132:135], v[172:175], v[76:79]
	v_mfma_f32_16x16x32_bf16 v[72:75], v[140:143], v[172:175], v[72:75]
	s_barrier
	s_add_i32 s66, s51, s33
	v_lshl_add_u64 v[220:221], s[30:31], 0, v[178:179]
	s_mov_b32 m0, s66
	ds_read_b128 v[194:197], v212
	ds_read_b128 v[198:201], v212 offset:1024
	ds_read_b128 v[202:205], v212 offset:2048
	ds_read_b128 v[216:219], v212 offset:3072
	global_load_lds_dwordx4 v[220:221], off
	v_lshl_add_u64 v[222:223], s[30:31], 0, v[182:183]
	s_add_i32 m0, s66, 0x2000
	s_nop 0
	global_load_lds_dwordx4 v[222:223], off
	s_barrier
	s_waitcnt lgkmcnt(0)
	s_waitcnt lgkmcnt(0)
	v_mfma_f32_16x16x32_bf16 v[116:119], v[194:197], v[144:147], v[116:119]
	v_mfma_f32_16x16x32_bf16 v[112:115], v[202:205], v[144:147], v[112:115]
	v_mfma_f32_16x16x32_bf16 v[100:103], v[194:197], v[152:155], v[100:103]
	v_mfma_f32_16x16x32_bf16 v[96:99], v[202:205], v[152:155], v[96:99]
	v_mfma_f32_16x16x32_bf16 v[84:87], v[194:197], v[160:163], v[84:87]
	v_mfma_f32_16x16x32_bf16 v[80:83], v[202:205], v[160:163], v[80:83]
	v_mfma_f32_16x16x32_bf16 v[68:71], v[194:197], v[168:171], v[68:71]
	v_mfma_f32_16x16x32_bf16 v[64:67], v[202:205], v[168:171], v[64:67]
	v_mfma_f32_16x16x32_bf16 v[116:119], v[198:201], v[148:151], v[116:119]
	v_mfma_f32_16x16x32_bf16 v[112:115], v[216:219], v[148:151], v[112:115]
	v_mfma_f32_16x16x32_bf16 v[100:103], v[198:201], v[156:159], v[100:103]
	v_mfma_f32_16x16x32_bf16 v[96:99], v[216:219], v[156:159], v[96:99]
	v_mfma_f32_16x16x32_bf16 v[84:87], v[198:201], v[164:167], v[84:87]
	v_mfma_f32_16x16x32_bf16 v[80:83], v[216:219], v[164:167], v[80:83]
	v_mfma_f32_16x16x32_bf16 v[68:71], v[198:201], v[172:175], v[68:71]
	v_mfma_f32_16x16x32_bf16 v[64:67], v[216:219], v[172:175], v[64:67]
	s_mov_b32 m0, s40
	v_lshl_add_u64 v[224:225], s[34:35], 0, v[176:177]
	s_barrier
	ds_read_b128 v[144:147], v211 offset:16384
	ds_read_b128 v[148:151], v211 offset:17408
	ds_read_b128 v[152:155], v211 offset:18432
	ds_read_b128 v[156:159], v211 offset:19456
	ds_read_b128 v[160:163], v211 offset:20480
	ds_read_b128 v[164:167], v211 offset:21504
	ds_read_b128 v[168:171], v211 offset:22528
	ds_read_b128 v[172:175], v211 offset:23552
	global_load_lds_dwordx4 v[224:225], off
	v_lshl_add_u64 v[226:227], s[34:35], 0, v[180:181]
	s_mov_b32 m0, s41
	s_nop 0
	global_load_lds_dwordx4 v[226:227], off
	s_barrier
	s_waitcnt lgkmcnt(0)
	s_waitcnt lgkmcnt(0)
	v_mfma_f32_16x16x32_bf16 v[60:63], v[128:131], v[144:147], v[60:63]
	v_mfma_f32_16x16x32_bf16 v[56:59], v[136:139], v[144:147], v[56:59]
	v_mfma_f32_16x16x32_bf16 v[44:47], v[128:131], v[152:155], v[44:47]
	v_mfma_f32_16x16x32_bf16 v[40:43], v[136:139], v[152:155], v[40:43]
	v_mfma_f32_16x16x32_bf16 v[28:31], v[128:131], v[160:163], v[28:31]
	v_mfma_f32_16x16x32_bf16 v[24:27], v[136:139], v[160:163], v[24:27]
	v_mfma_f32_16x16x32_bf16 v[12:15], v[128:131], v[168:171], v[12:15]
	v_mfma_f32_16x16x32_bf16 v[8:11], v[136:139], v[168:171], v[8:11]
	v_mfma_f32_16x16x32_bf16 v[60:63], v[132:135], v[148:151], v[60:63]
	v_mfma_f32_16x16x32_bf16 v[56:59], v[140:143], v[148:151], v[56:59]
	v_mfma_f32_16x16x32_bf16 v[44:47], v[132:135], v[156:159], v[44:47]
	v_mfma_f32_16x16x32_bf16 v[40:43], v[140:143], v[156:159], v[40:43]
	v_mfma_f32_16x16x32_bf16 v[28:31], v[132:135], v[164:167], v[28:31]
	v_mfma_f32_16x16x32_bf16 v[24:27], v[140:143], v[164:167], v[24:27]
	v_mfma_f32_16x16x32_bf16 v[12:15], v[132:135], v[172:175], v[12:15]
	v_mfma_f32_16x16x32_bf16 v[8:11], v[140:143], v[172:175], v[8:11]
	s_barrier
; #define PG8_STAGE(bufoff, gbase, voff) do { _Pragma("unroll") for (int _i = 0; _i < 2; ++_i) \
;         __builtin_amdgcn_global_load_lds((const unsigned*)((const char*)(gbase) + (voff)[_i]), (LAS unsigned*)(lds + (bufoff) + ldsw + _i * 8192), 16, 0, 0); } while (0)
; #define PG8_LDA(dst, b, h) do { _Pragma("unroll") for (int m = 0; m < 4; ++m) _Pragma("unroll") for (int k = 0; k < 2; ++k) dst[m][k] = *(const LAS bf16x8*)(lds + PG8_SA(b, h) + aoff + m * 2048 + k * 1024); } while (0)
; #define PG8_LDB(dst, b, h) do { _Pragma("unroll") for (int n = 0; n < 2; ++n) _Pragma("unroll") for (int k = 0; k < 2; ++k) dst[n][k] = *(const LAS bf16x8*)(lds + PG8_SB(b, h) + boff + n * 2048 + k * 1024); } while (0)
; #define PG8_MMA(ai, bj, At, Bt) do { __builtin_amdgcn_s_setprio(1); _Pragma("unroll") for (int m = 0; m < 4; ++m) _Pragma("unroll") for (int n = 0; n < 2; ++n) _Pragma("unroll") for (int k = 0; k < 2; ++k) \
;         acc[ai][bj][m][n] = __builtin_amdgcn_mfma_f32_16x16x32_bf16(Bt[n][k], At[m][k], acc[ai][bj][m][n], 0, 0, 0); __builtin_amdgcn_s_setprio(0); } while (0)
; #define PG8_WAIT_V(n) asm volatile("s_waitcnt vmcnt(" #n ")" ::: "memory")
; #define PG8_WAIT_L(n) asm volatile("s_waitcnt lgkmcnt(" #n ")" ::: "memory")
; #define PG8_BAR __builtin_amdgcn_s_barrier()
; #define PG8_SCHED __builtin_amdgcn_sched_barrier(0)
; template <class Epi>
; __device__ __forceinline__ void gemm_phase(LAS unsigned char* lds, const Gemm g, const StaticOrder& S, const Epi& E) {
;     ...
;             PG8_WAIT_V(6); PG8_BAR; PG8_MMA(1, 1, At, B1); PG8_BAR;
;             PG8_LDB(B0, 1, 0); PG8_SCHED; PG8_LDA(At, 1, 0); PG8_STAGE(PG8_SA(0, 1), a2 + hstep, voffA);
;             PG8_WAIT_L(8); PG8_BAR; PG8_WAIT_L(0); PG8_MMA(0, 0, At, B0); PG8_BAR; PG8_SCHED;
;             PG8_LDB(B1, 1, 1); PG8_STAGE(PG8_SB(1, 0), b3, voffB);
;             PG8_BAR; PG8_WAIT_L(0); PG8_MMA(0, 1, At, B1); PG8_BAR;
;             PG8_LDA(At, 1, 1); PG8_STAGE(PG8_SA(1, 0), a3, voffA);
;             PG8_BAR; PG8_WAIT_L(0); PG8_MMA(1, 0, At, B0); PG8_BAR; PG8_SCHED;
	s_add_u32 s66, s30, 0x80000
	s_addc_u32 s67, s31, 0
	s_add_i32 s69, s54, s33
	v_lshl_add_u64 v[128:129], s[66:67], 0, v[178:179]
	s_mov_b32 m0, s69
	s_nop 0
	global_load_lds_dwordx4 v[128:129], off
	v_lshl_add_u64 v[128:129], s[66:67], 0, v[182:183]
	s_add_i32 m0, s69, 0x2000
	s_nop 0
	global_load_lds_dwordx4 v[128:129], off
	s_waitcnt vmcnt(6)
	s_barrier
	v_mfma_f32_16x16x32_bf16 v[52:55], v[194:197], v[144:147], v[52:55]
	v_mfma_f32_16x16x32_bf16 v[48:51], v[202:205], v[144:147], v[48:51]
	v_mfma_f32_16x16x32_bf16 v[36:39], v[194:197], v[152:155], v[36:39]
	v_mfma_f32_16x16x32_bf16 v[32:35], v[202:205], v[152:155], v[32:35]
	v_mfma_f32_16x16x32_bf16 v[20:23], v[194:197], v[160:163], v[20:23]
	v_mfma_f32_16x16x32_bf16 v[16:19], v[202:205], v[160:163], v[16:19]
	v_mfma_f32_16x16x32_bf16 v[4:7], v[194:197], v[168:171], v[4:7]
	v_mfma_f32_16x16x32_bf16 v[0:3], v[202:205], v[168:171], v[0:3]
	v_mfma_f32_16x16x32_bf16 v[52:55], v[198:201], v[148:151], v[52:55]
	v_mfma_f32_16x16x32_bf16 v[48:51], v[216:219], v[148:151], v[48:51]
	v_mfma_f32_16x16x32_bf16 v[36:39], v[198:201], v[156:159], v[36:39]
	v_mfma_f32_16x16x32_bf16 v[32:35], v[216:219], v[156:159], v[32:35]
	v_mfma_f32_16x16x32_bf16 v[20:23], v[198:201], v[164:167], v[20:23]
	v_mfma_f32_16x16x32_bf16 v[16:19], v[216:219], v[164:167], v[16:19]
	v_mfma_f32_16x16x32_bf16 v[4:7], v[198:201], v[172:175], v[4:7]
	v_mfma_f32_16x16x32_bf16 v[0:3], v[216:219], v[172:175], v[0:3]
	s_add_i32 s66, 0, 0x18000
	v_add_u32_e32 v140, s66, v208
	s_barrier
	ds_read_b128 v[128:131], v140
	ds_read_b128 v[132:135], v140 offset:1024
	ds_read_b128 v[136:139], v140 offset:2048
	ds_read_b128 v[140:143], v140 offset:3072
	s_add_u32 s34, s34, 0x80000
	s_addc_u32 s35, s35, 0
	s_mov_b32 m0, s42
	v_lshl_add_u64 v[194:195], s[34:35], 0, v[176:177]
	ds_read_b128 v[144:147], v211 offset:32768
	ds_read_b128 v[148:151], v211 offset:33792
	ds_read_b128 v[152:155], v211 offset:34816
	ds_read_b128 v[156:159], v211 offset:35840
	ds_read_b128 v[160:163], v211 offset:36864
	ds_read_b128 v[164:167], v211 offset:37888
	ds_read_b128 v[168:171], v211 offset:38912
	ds_read_b128 v[172:175], v211 offset:39936
	global_load_lds_dwordx4 v[194:195], off
	v_lshl_add_u64 v[194:195], s[34:35], 0, v[180:181]
	s_mov_b32 m0, s43
	s_nop 0
	global_load_lds_dwordx4 v[194:195], off
	s_waitcnt lgkmcnt(8)
	s_barrier
	s_waitcnt lgkmcnt(0)
	s_waitcnt lgkmcnt(0)
	v_mfma_f32_16x16x32_bf16 v[124:127], v[128:131], v[144:147], v[124:127]
	v_mfma_f32_16x16x32_bf16 v[120:123], v[136:139], v[144:147], v[120:123]
	v_mfma_f32_16x16x32_bf16 v[108:111], v[128:131], v[152:155], v[108:111]
	v_mfma_f32_16x16x32_bf16 v[104:107], v[136:139], v[152:155], v[104:107]
	v_mfma_f32_16x16x32_bf16 v[92:95], v[128:131], v[160:163], v[92:95]
	v_mfma_f32_16x16x32_bf16 v[88:91], v[136:139], v[160:163], v[88:91]
	v_mfma_f32_16x16x32_bf16 v[76:79], v[128:131], v[168:171], v[76:79]
	v_mfma_f32_16x16x32_bf16 v[72:75], v[136:139], v[168:171], v[72:75]
	v_mfma_f32_16x16x32_bf16 v[124:127], v[132:135], v[148:151], v[124:127]
	v_mfma_f32_16x16x32_bf16 v[120:123], v[140:143], v[148:151], v[120:123]
	v_mfma_f32_16x16x32_bf16 v[108:111], v[132:135], v[156:159], v[108:111]
	v_mfma_f32_16x16x32_bf16 v[104:107], v[140:143], v[156:159], v[104:107]
	v_mfma_f32_16x16x32_bf16 v[92:95], v[132:135], v[164:167], v[92:95]
	v_mfma_f32_16x16x32_bf16 v[88:91], v[140:143], v[164:167], v[88:91]
	v_mfma_f32_16x16x32_bf16 v[76:79], v[132:135], v[172:175], v[76:79]
	v_mfma_f32_16x16x32_bf16 v[72:75], v[140:143], v[172:175], v[72:75]
	s_barrier
	s_add_i32 s34, 0, 0x1c000
	s_add_i32 s35, s66, s33
	v_add_u32_e32 v184, s34, v208
	v_lshl_add_u64 v[220:221], v[220:221], 0, s[10:11]
	s_mov_b32 m0, s35
	ds_read_b128 v[194:197], v184
	ds_read_b128 v[198:201], v184 offset:1024
	ds_read_b128 v[202:205], v184 offset:2048
	ds_read_b128 v[216:219], v184 offset:3072
	global_load_lds_dwordx4 v[220:221], off
	v_lshl_add_u64 v[220:221], v[222:223], 0, s[10:11]
	s_add_i32 m0, s35, 0x2000
	s_nop 0
	global_load_lds_dwordx4 v[220:221], off
	s_barrier
	s_waitcnt lgkmcnt(0)
	s_waitcnt lgkmcnt(0)
	v_mfma_f32_16x16x32_bf16 v[116:119], v[194:197], v[144:147], v[116:119]
	v_mfma_f32_16x16x32_bf16 v[112:115], v[202:205], v[144:147], v[112:115]
	v_mfma_f32_16x16x32_bf16 v[100:103], v[194:197], v[152:155], v[100:103]
	v_mfma_f32_16x16x32_bf16 v[96:99], v[202:205], v[152:155], v[96:99]
	v_mfma_f32_16x16x32_bf16 v[84:87], v[194:197], v[160:163], v[84:87]
	v_mfma_f32_16x16x32_bf16 v[80:83], v[202:205], v[160:163], v[80:83]
	v_mfma_f32_16x16x32_bf16 v[68:71], v[194:197], v[168:171], v[68:71]
	v_mfma_f32_16x16x32_bf16 v[64:67], v[202:205], v[168:171], v[64:67]
	v_mfma_f32_16x16x32_bf16 v[116:119], v[198:201], v[148:151], v[116:119]
	v_mfma_f32_16x16x32_bf16 v[112:115], v[216:219], v[148:151], v[112:115]
	v_mfma_f32_16x16x32_bf16 v[100:103], v[198:201], v[156:159], v[100:103]
	v_mfma_f32_16x16x32_bf16 v[96:99], v[216:219], v[156:159], v[96:99]
	v_mfma_f32_16x16x32_bf16 v[84:87], v[198:201], v[164:167], v[84:87]
	v_mfma_f32_16x16x32_bf16 v[80:83], v[216:219], v[164:167], v[80:83]
	v_mfma_f32_16x16x32_bf16 v[68:71], v[198:201], v[172:175], v[68:71]
	v_mfma_f32_16x16x32_bf16 v[64:67], v[216:219], v[172:175], v[64:67]
	s_mov_b32 m0, s48
	v_lshl_add_u64 v[220:221], v[224:225], 0, s[10:11]
	s_barrier
	ds_read_b128 v[144:147], v211 offset:49152
	ds_read_b128 v[148:151], v211 offset:50176
	ds_read_b128 v[152:155], v211 offset:51200
	ds_read_b128 v[156:159], v211 offset:52224
	ds_read_b128 v[160:163], v211 offset:53248
	ds_read_b128 v[164:167], v211 offset:54272
	ds_read_b128 v[168:171], v211 offset:55296
	ds_read_b128 v[172:175], v211 offset:56320
	global_load_lds_dwordx4 v[220:221], off
	v_lshl_add_u64 v[220:221], v[226:227], 0, s[10:11]
	s_mov_b32 m0, s49
	s_nop 0
	global_load_lds_dwordx4 v[220:221], off
	s_barrier
; #define PG8_STAGE(bufoff, gbase, voff) do { _Pragma("unroll") for (int _i = 0; _i < 2; ++_i) \
;         __builtin_amdgcn_global_load_lds((const unsigned*)((const char*)(gbase) + (voff)[_i]), (LAS unsigned*)(lds + (bufoff) + ldsw + _i * 8192), 16, 0, 0); } while (0)
; #define PG8_MMA(ai, bj, At, Bt) do { __builtin_amdgcn_s_setprio(1); _Pragma("unroll") for (int m = 0; m < 4; ++m) _Pragma("unroll") for (int n = 0; n < 2; ++n) _Pragma("unroll") for (int k = 0; k < 2; ++k) \
;         acc[ai][bj][m][n] = __builtin_amdgcn_mfma_f32_16x16x32_bf16(Bt[n][k], At[m][k], acc[ai][bj][m][n], 0, 0, 0); __builtin_amdgcn_s_setprio(0); } while (0)
; #define PG8_WAIT_V(n) asm volatile("s_waitcnt vmcnt(" #n ")" ::: "memory")
; #define PG8_WAIT_L(n) asm volatile("s_waitcnt lgkmcnt(" #n ")" ::: "memory")
; #define PG8_BAR __builtin_amdgcn_s_barrier()
; template <class Epi>
; __device__ __forceinline__ void gemm_phase(LAS unsigned char* lds, const Gemm g, const StaticOrder& S, const Epi& E) {
;     ...
;             PG8_BAR; PG8_WAIT_L(0); PG8_MMA(1, 0, At, B0); PG8_BAR; PG8_SCHED;
;             PG8_STAGE(PG8_SB(1, 1), b3 + hstep, voffB);
;             PG8_WAIT_V(6); PG8_BAR; PG8_MMA(1, 1, At, B1); PG8_BAR;
;         }
;     __device__ __forceinline__ void operator()(const AccT& acc, const pg8::Unit& u, int wr, int wc, int fr, int fq) const {
;         const int row0 = u.pm * 256 + wr * 64 + fr, col0 = u.pn * 256 + wc * 32 + 8 * fq;
; #pragma unroll
;         for (int ai = 0; ai < 2; ++ai) { f32x4 b0[4][2], b1[4][2];
; #pragma unroll
;             for (int m = 0; m < 4; ++m) { const int r = row0 + ai * 128 + m * 16; const int rc = r < NREAL ? r : NREAL - 1;
; #pragma unroll
;                 for (int bj = 0; bj < 2; ++bj) {
;                     if (mode) unpack8(*(const u32x4*)(X1 + (size_t)rc * D + col0 + bj * 128), b0[m][bj], b1[m][bj]);
;                     else { const float* b2 = (rc < ROW_S ? xp + (size_t)rc * D : xs + (size_t)(rc - ROW_S) * D) + col0 + bj * 128; b0[m][bj] = *(const f32x4*)b2; b1[m][bj] = *(const f32x4*)(b2 + 4); } } }
; #pragma unroll
;             for (int m = 0; m < 4; ++m) { const int r = row0 + ai * 128 + m * 16;
;                 if (r < NREAL) {
; #pragma unroll
;                     for (int bj = 0; bj < 2; ++bj) *(u32x4*)(R + (size_t)r * D + col0 + bj * 128) = pack8(ALPHA * b0[m][bj] + acc[ai][bj][m][0], ALPHA * b1[m][bj] + acc[ai][bj][m][1]); } } }
	s_waitcnt lgkmcnt(0)
	s_waitcnt lgkmcnt(0)
	v_mfma_f32_16x16x32_bf16 v[60:63], v[128:131], v[144:147], v[60:63]
	v_mfma_f32_16x16x32_bf16 v[56:59], v[136:139], v[144:147], v[56:59]
	v_mfma_f32_16x16x32_bf16 v[44:47], v[128:131], v[152:155], v[44:47]
	v_mfma_f32_16x16x32_bf16 v[40:43], v[136:139], v[152:155], v[40:43]
	v_mfma_f32_16x16x32_bf16 v[28:31], v[128:131], v[160:163], v[28:31]
	v_mfma_f32_16x16x32_bf16 v[24:27], v[136:139], v[160:163], v[24:27]
	v_mfma_f32_16x16x32_bf16 v[12:15], v[128:131], v[168:171], v[12:15]
	v_mfma_f32_16x16x32_bf16 v[8:11], v[136:139], v[168:171], v[8:11]
	v_mfma_f32_16x16x32_bf16 v[60:63], v[132:135], v[148:151], v[60:63]
	v_mfma_f32_16x16x32_bf16 v[56:59], v[140:143], v[148:151], v[56:59]
	v_mfma_f32_16x16x32_bf16 v[44:47], v[132:135], v[156:159], v[44:47]
	v_mfma_f32_16x16x32_bf16 v[40:43], v[140:143], v[156:159], v[40:43]
	v_mfma_f32_16x16x32_bf16 v[28:31], v[132:135], v[164:167], v[28:31]
	v_mfma_f32_16x16x32_bf16 v[24:27], v[140:143], v[164:167], v[24:27]
	v_mfma_f32_16x16x32_bf16 v[12:15], v[132:135], v[172:175], v[12:15]
	v_mfma_f32_16x16x32_bf16 v[8:11], v[140:143], v[172:175], v[8:11]
	s_barrier
	s_add_u32 s30, s30, 0x80080
	s_addc_u32 s31, s31, 0
	s_add_i32 s34, s34, s33
	v_lshl_add_u64 v[128:129], s[30:31], 0, v[178:179]
	s_mov_b32 m0, s34
	s_nop 0
	global_load_lds_dwordx4 v[128:129], off
	v_lshl_add_u64 v[128:129], s[30:31], 0, v[182:183]
	s_add_i32 m0, s34, 0x2000
	s_nop 0
	global_load_lds_dwordx4 v[128:129], off
	s_waitcnt vmcnt(6)
	s_barrier
	v_mfma_f32_16x16x32_bf16 v[52:55], v[194:197], v[144:147], v[52:55]
	v_mfma_f32_16x16x32_bf16 v[48:51], v[202:205], v[144:147], v[48:51]
	v_mfma_f32_16x16x32_bf16 v[36:39], v[194:197], v[152:155], v[36:39]
	v_mfma_f32_16x16x32_bf16 v[32:35], v[202:205], v[152:155], v[32:35]
	v_mfma_f32_16x16x32_bf16 v[20:23], v[194:197], v[160:163], v[20:23]
	v_mfma_f32_16x16x32_bf16 v[16:19], v[202:205], v[160:163], v[16:19]
	v_mfma_f32_16x16x32_bf16 v[4:7], v[194:197], v[168:171], v[4:7]
	v_mfma_f32_16x16x32_bf16 v[0:3], v[202:205], v[168:171], v[0:3]
	v_mfma_f32_16x16x32_bf16 v[52:55], v[198:201], v[148:151], v[52:55]
	v_mfma_f32_16x16x32_bf16 v[48:51], v[216:219], v[148:151], v[48:51]
	v_mfma_f32_16x16x32_bf16 v[36:39], v[198:201], v[156:159], v[36:39]
	v_mfma_f32_16x16x32_bf16 v[32:35], v[216:219], v[156:159], v[32:35]
	v_mfma_f32_16x16x32_bf16 v[20:23], v[198:201], v[164:167], v[20:23]
	v_mfma_f32_16x16x32_bf16 v[16:19], v[216:219], v[164:167], v[16:19]
	v_mfma_f32_16x16x32_bf16 v[4:7], v[198:201], v[172:175], v[4:7]
	v_mfma_f32_16x16x32_bf16 v[0:3], v[216:219], v[172:175], v[0:3]
	s_add_i32 s65, s65, 2
	s_add_u32 s28, s28, 0x100
	s_addc_u32 s29, s29, 0
	s_add_u32 s63, s63, 0x100
	s_addc_u32 s64, s64, 0
	s_cmp_gt_u32 s65, 29
	s_barrier
	s_cbranch_scc0 .LBB0_1005
	v_lshl_add_u32 v196, s26, 8, v207
	v_or_b32_e32 v204, 16, v196
	v_min_i32_e32 v128, 0x207f, v204
	v_ashrrev_i32_e32 v129, 31, v128
	v_add_u32_e32 v184, 0xffffe000, v128
	v_lshl_or_b32 v194, s0, 8, v209
	v_lshlrev_b64 v[130:131], 13, v[184:185]
	v_lshlrev_b64 v[128:129], 13, v[128:129]
	v_ashrrev_i32_e32 v195, 31, v194
	v_lshl_add_u64 v[130:131], s[38:39], 0, v[130:131]
	v_lshl_add_u64 v[128:129], s[36:37], 0, v[128:129]
	v_cmp_gt_i32_e32 vcc, s44, v204
	v_lshlrev_b64 v[198:199], 2, v[194:195]
	v_or_b32_e32 v202, 32, v196
	v_cndmask_b32_e32 v129, v131, v129, vcc
	v_cndmask_b32_e32 v128, v130, v128, vcc
	v_lshl_add_u64 v[128:129], v[128:129], 0, v[198:199]
	global_load_dwordx4 v[168:171], v[128:129], off offset:16
	global_load_dwordx4 v[172:175], v[128:129], off
	global_load_dwordx4 v[160:163], v[128:129], off offset:528
	global_load_dwordx4 v[164:167], v[128:129], off offset:512
	v_min_i32_e32 v128, 0x207f, v202
	v_ashrrev_i32_e32 v129, 31, v128
	v_add_u32_e32 v184, 0xffffe000, v128
	v_lshlrev_b64 v[130:131], 13, v[184:185]
	v_lshlrev_b64 v[128:129], 13, v[128:129]
	v_lshl_add_u64 v[130:131], s[38:39], 0, v[130:131]
	v_lshl_add_u64 v[128:129], s[36:37], 0, v[128:129]
	v_cmp_gt_i32_e32 vcc, s44, v202
	v_or_b32_e32 v200, 48, v196
	v_cmp_gt_i32_e64 s[0:1], s55, v196
	v_cndmask_b32_e32 v129, v131, v129, vcc
	v_cndmask_b32_e32 v128, v130, v128, vcc
	v_lshl_add_u64 v[128:129], v[128:129], 0, v[198:199]
	global_load_dwordx4 v[152:155], v[128:129], off offset:16
	global_load_dwordx4 v[156:159], v[128:129], off
	global_load_dwordx4 v[144:147], v[128:129], off offset:528
	global_load_dwordx4 v[148:151], v[128:129], off offset:512
	v_min_i32_e32 v128, 0x207f, v200
	v_ashrrev_i32_e32 v129, 31, v128
	v_add_u32_e32 v184, 0xffffe000, v128
	v_lshlrev_b64 v[130:131], 13, v[184:185]
	v_lshlrev_b64 v[128:129], 13, v[128:129]
	v_lshl_add_u64 v[130:131], s[38:39], 0, v[130:131]
	v_lshl_add_u64 v[128:129], s[36:37], 0, v[128:129]
	v_cmp_gt_i32_e32 vcc, s44, v200
	s_nop 1
	v_cndmask_b32_e32 v129, v131, v129, vcc
	v_cndmask_b32_e32 v128, v130, v128, vcc
	v_lshl_add_u64 v[132:133], v[128:129], 0, v[198:199]
	global_load_dwordx4 v[136:139], v[132:133], off offset:16
	global_load_dwordx4 v[140:143], v[132:133], off
	global_load_dwordx4 v[128:131], v[132:133], off offset:528
	s_nop 0
	global_load_dwordx4 v[132:135], v[132:133], off offset:512
	v_cmp_gt_i32_e32 vcc, s44, v196
	s_and_saveexec_b64 s[26:27], s[0:1]
	s_cbranch_execnz .LBB0_1015
	s_or_b64 exec, exec, s[26:27]
	v_cmp_gt_i32_e64 s[0:1], s55, v204
	s_and_saveexec_b64 s[26:27], s[0:1]
	s_cbranch_execnz .LBB0_1016

; #define PG8_STAGE(bufoff, gbase, voff) do { _Pragma("unroll") for (int _i = 0; _i < 2; ++_i) \
;         __builtin_amdgcn_global_load_lds((const unsigned*)((const char*)(gbase) + (voff)[_i]), (LAS unsigned*)(lds + (bufoff) + ldsw + _i * 8192), 16, 0, 0); } while (0)
; #define PG8_LDA(dst, b, h) do { _Pragma("unroll") for (int m = 0; m < 4; ++m) _Pragma("unroll") for (int k = 0; k < 2; ++k) dst[m][k] = *(const LAS bf16x8*)(lds + PG8_SA(b, h) + aoff + m * 2048 + k * 1024); } while (0)
; #define PG8_LDB(dst, b, h) do { _Pragma("unroll") for (int n = 0; n < 2; ++n) _Pragma("unroll") for (int k = 0; k < 2; ++k) dst[n][k] = *(const LAS bf16x8*)(lds + PG8_SB(b, h) + boff + n * 2048 + k * 1024); } while (0)
; #define PG8_MMA(ai, bj, At, Bt) do { __builtin_amdgcn_s_setprio(1); _Pragma("unroll") for (int m = 0; m < 4; ++m) _Pragma("unroll") for (int n = 0; n < 2; ++n) _Pragma("unroll") for (int k = 0; k < 2; ++k) \
;         acc[ai][bj][m][n] = __builtin_amdgcn_mfma_f32_16x16x32_bf16(Bt[n][k], At[m][k], acc[ai][bj][m][n], 0, 0, 0); __builtin_amdgcn_s_setprio(0); } while (0)
; #define PG8_WAIT_V(n) asm volatile("s_waitcnt vmcnt(" #n ")" ::: "memory")
; #define PG8_WAIT_L(n) asm volatile("s_waitcnt lgkmcnt(" #n ")" ::: "memory")
; #define PG8_BAR __builtin_amdgcn_s_barrier()
; #define PG8_SCHED __builtin_amdgcn_sched_barrier(0)
; template <class Epi>
; __device__ __forceinline__ void gemm_phase(LAS unsigned char* lds, const Gemm g, const StaticOrder& S, const Epi& E) {
;     ...
;             PG8_LDB(B0, 0, 0); PG8_SCHED; PG8_LDA(At, 0, 0); PG8_STAGE(PG8_SA(1, 1), a1 + hstep, voffA);
;             PG8_WAIT_L(8); PG8_BAR; PG8_WAIT_L(0); PG8_MMA(0, 0, At, B0); PG8_BAR; PG8_SCHED;
;             PG8_LDB(B1, 0, 1); PG8_STAGE(PG8_SB(0, 0), b2, voffB);
;             PG8_BAR; PG8_WAIT_L(0); PG8_MMA(0, 1, At, B1); PG8_BAR;
;             PG8_LDA(At, 0, 1); PG8_STAGE(PG8_SA(0, 0), a2, voffA);
;             PG8_BAR; PG8_WAIT_L(0); PG8_MMA(1, 0, At, B0); PG8_BAR; PG8_SCHED;
;             PG8_STAGE(PG8_SB(0, 1), b2 + hstep, voffB);
;             PG8_WAIT_V(6); PG8_BAR; PG8_MMA(1, 1, At, B1); PG8_BAR;
.LBB0_1150:
	ds_read_b128 v[154:157], v150
	ds_read_b128 v[158:161], v150 offset:1024
	ds_read_b128 v[162:165], v150 offset:2048
	ds_read_b128 v[166:169], v150 offset:3072
	s_add_u32 s24, s22, 0xfff80080
	s_addc_u32 s25, s23, -1
	s_cmp_eq_u32 s48, 28
	s_cselect_b32 s27, s11, s25
	s_cselect_b32 s26, s44, s24
	s_cselect_b32 s25, s9, s47
	s_cselect_b32 s24, s45, s46
	v_lshl_add_u64 v[202:203], s[22:23], 0, v[136:137]
	s_add_i32 m0, s21, 0xc000
	ds_read_b128 v[170:173], v151
	ds_read_b128 v[174:177], v151 offset:1024
	ds_read_b128 v[178:181], v151 offset:2048
	ds_read_b128 v[182:185], v151 offset:3072
	ds_read_b128 v[186:189], v151 offset:4096
	ds_read_b128 v[190:193], v151 offset:5120
	ds_read_b128 v[194:197], v151 offset:6144
	ds_read_b128 v[198:201], v151 offset:7168
	global_load_lds_dwordx4 v[202:203], off
	v_lshl_add_u64 v[202:203], s[22:23], 0, v[138:139]
	s_add_i32 m0, s21, 0xe000
	s_nop 0
	global_load_lds_dwordx4 v[202:203], off
	s_waitcnt lgkmcnt(8)
	s_barrier
	s_waitcnt lgkmcnt(0)
	s_waitcnt lgkmcnt(0)
	v_mfma_f32_16x16x32_bf16 v[124:127], v[154:157], v[170:173], v[124:127]
	v_mfma_f32_16x16x32_bf16 v[120:123], v[162:165], v[170:173], v[120:123]
	v_mfma_f32_16x16x32_bf16 v[108:111], v[154:157], v[178:181], v[108:111]
	v_mfma_f32_16x16x32_bf16 v[104:107], v[162:165], v[178:181], v[104:107]
	v_mfma_f32_16x16x32_bf16 v[92:95], v[154:157], v[186:189], v[92:95]
	v_mfma_f32_16x16x32_bf16 v[88:91], v[162:165], v[186:189], v[88:91]
	v_mfma_f32_16x16x32_bf16 v[76:79], v[154:157], v[194:197], v[76:79]
	v_mfma_f32_16x16x32_bf16 v[72:75], v[162:165], v[194:197], v[72:75]
	v_mfma_f32_16x16x32_bf16 v[124:127], v[158:161], v[174:177], v[124:127]
	v_mfma_f32_16x16x32_bf16 v[120:123], v[166:169], v[174:177], v[120:123]
	v_mfma_f32_16x16x32_bf16 v[108:111], v[158:161], v[182:185], v[108:111]
	v_mfma_f32_16x16x32_bf16 v[104:107], v[166:169], v[182:185], v[104:107]
	v_mfma_f32_16x16x32_bf16 v[92:95], v[158:161], v[190:193], v[92:95]
	v_mfma_f32_16x16x32_bf16 v[88:91], v[166:169], v[190:193], v[88:91]
	v_mfma_f32_16x16x32_bf16 v[76:79], v[158:161], v[198:201], v[76:79]
	v_mfma_f32_16x16x32_bf16 v[72:75], v[166:169], v[198:201], v[72:75]
	s_barrier
	s_add_i32 s49, s40, s29
	v_lshl_add_u64 v[220:221], s[24:25], 0, v[130:131]
	s_mov_b32 m0, s49
	ds_read_b128 v[202:205], v153
	ds_read_b128 v[206:209], v153 offset:1024
	ds_read_b128 v[210:213], v153 offset:2048
	ds_read_b128 v[216:219], v153 offset:3072
	global_load_lds_dwordx4 v[220:221], off
	v_lshl_add_u64 v[222:223], s[24:25], 0, v[134:135]
	s_add_i32 m0, s49, 0x2000
	s_nop 0
	global_load_lds_dwordx4 v[222:223], off
	s_barrier
	s_waitcnt lgkmcnt(0)
	s_waitcnt lgkmcnt(0)
	v_mfma_f32_16x16x32_bf16 v[116:119], v[202:205], v[170:173], v[116:119]
	v_mfma_f32_16x16x32_bf16 v[112:115], v[210:213], v[170:173], v[112:115]
	v_mfma_f32_16x16x32_bf16 v[100:103], v[202:205], v[178:181], v[100:103]
	v_mfma_f32_16x16x32_bf16 v[96:99], v[210:213], v[178:181], v[96:99]
	v_mfma_f32_16x16x32_bf16 v[84:87], v[202:205], v[186:189], v[84:87]
	v_mfma_f32_16x16x32_bf16 v[80:83], v[210:213], v[186:189], v[80:83]
	v_mfma_f32_16x16x32_bf16 v[68:71], v[202:205], v[194:197], v[68:71]
	v_mfma_f32_16x16x32_bf16 v[64:67], v[210:213], v[194:197], v[64:67]
	v_mfma_f32_16x16x32_bf16 v[116:119], v[206:209], v[174:177], v[116:119]
	v_mfma_f32_16x16x32_bf16 v[112:115], v[216:219], v[174:177], v[112:115]
	v_mfma_f32_16x16x32_bf16 v[100:103], v[206:209], v[182:185], v[100:103]
	v_mfma_f32_16x16x32_bf16 v[96:99], v[216:219], v[182:185], v[96:99]
	v_mfma_f32_16x16x32_bf16 v[84:87], v[206:209], v[190:193], v[84:87]
	v_mfma_f32_16x16x32_bf16 v[80:83], v[216:219], v[190:193], v[80:83]
	v_mfma_f32_16x16x32_bf16 v[68:71], v[206:209], v[198:201], v[68:71]
	v_mfma_f32_16x16x32_bf16 v[64:67], v[216:219], v[198:201], v[64:67]
	s_mov_b32 m0, s21
	v_lshl_add_u64 v[224:225], s[26:27], 0, v[128:129]
	s_barrier
	ds_read_b128 v[170:173], v151 offset:16384
	ds_read_b128 v[174:177], v151 offset:17408
	ds_read_b128 v[178:181], v151 offset:18432
	ds_read_b128 v[182:185], v151 offset:19456
	ds_read_b128 v[186:189], v151 offset:20480
	ds_read_b128 v[190:193], v151 offset:21504
	ds_read_b128 v[194:197], v151 offset:22528
	ds_read_b128 v[198:201], v151 offset:23552
	global_load_lds_dwordx4 v[224:225], off
	v_lshl_add_u64 v[226:227], s[26:27], 0, v[132:133]
	s_mov_b32 m0, s30
	s_nop 0
	global_load_lds_dwordx4 v[226:227], off
	s_barrier
	s_waitcnt lgkmcnt(0)
	s_waitcnt lgkmcnt(0)
	v_mfma_f32_16x16x32_bf16 v[60:63], v[154:157], v[170:173], v[60:63]
	v_mfma_f32_16x16x32_bf16 v[56:59], v[162:165], v[170:173], v[56:59]
	v_mfma_f32_16x16x32_bf16 v[44:47], v[154:157], v[178:181], v[44:47]
	v_mfma_f32_16x16x32_bf16 v[40:43], v[162:165], v[178:181], v[40:43]
	v_mfma_f32_16x16x32_bf16 v[28:31], v[154:157], v[186:189], v[28:31]
	v_mfma_f32_16x16x32_bf16 v[24:27], v[162:165], v[186:189], v[24:27]
	v_mfma_f32_16x16x32_bf16 v[12:15], v[154:157], v[194:197], v[12:15]
	v_mfma_f32_16x16x32_bf16 v[8:11], v[162:165], v[194:197], v[8:11]
	v_mfma_f32_16x16x32_bf16 v[60:63], v[158:161], v[174:177], v[60:63]
	v_mfma_f32_16x16x32_bf16 v[56:59], v[166:169], v[174:177], v[56:59]
	v_mfma_f32_16x16x32_bf16 v[44:47], v[158:161], v[182:185], v[44:47]
	v_mfma_f32_16x16x32_bf16 v[40:43], v[166:169], v[182:185], v[40:43]
	v_mfma_f32_16x16x32_bf16 v[28:31], v[158:161], v[190:193], v[28:31]
	v_mfma_f32_16x16x32_bf16 v[24:27], v[166:169], v[190:193], v[24:27]
	v_mfma_f32_16x16x32_bf16 v[12:15], v[158:161], v[198:201], v[12:15]
	v_mfma_f32_16x16x32_bf16 v[8:11], v[166:169], v[198:201], v[8:11]
	s_barrier
; #define PG8_STAGE(bufoff, gbase, voff) do { _Pragma("unroll") for (int _i = 0; _i < 2; ++_i) \
;         __builtin_amdgcn_global_load_lds((const unsigned*)((const char*)(gbase) + (voff)[_i]), (LAS unsigned*)(lds + (bufoff) + ldsw + _i * 8192), 16, 0, 0); } while (0)
; #define PG8_LDA(dst, b, h) do { _Pragma("unroll") for (int m = 0; m < 4; ++m) _Pragma("unroll") for (int k = 0; k < 2; ++k) dst[m][k] = *(const LAS bf16x8*)(lds + PG8_SA(b, h) + aoff + m * 2048 + k * 1024); } while (0)
; #define PG8_LDB(dst, b, h) do { _Pragma("unroll") for (int n = 0; n < 2; ++n) _Pragma("unroll") for (int k = 0; k < 2; ++k) dst[n][k] = *(const LAS bf16x8*)(lds + PG8_SB(b, h) + boff + n * 2048 + k * 1024); } while (0)
; #define PG8_MMA(ai, bj, At, Bt) do { __builtin_amdgcn_s_setprio(1); _Pragma("unroll") for (int m = 0; m < 4; ++m) _Pragma("unroll") for (int n = 0; n < 2; ++n) _Pragma("unroll") for (int k = 0; k < 2; ++k) \
;         acc[ai][bj][m][n] = __builtin_amdgcn_mfma_f32_16x16x32_bf16(Bt[n][k], At[m][k], acc[ai][bj][m][n], 0, 0, 0); __builtin_amdgcn_s_setprio(0); } while (0)
; #define PG8_WAIT_V(n) asm volatile("s_waitcnt vmcnt(" #n ")" ::: "memory")
; #define PG8_WAIT_L(n) asm volatile("s_waitcnt lgkmcnt(" #n ")" ::: "memory")
; #define PG8_BAR __builtin_amdgcn_s_barrier()
; #define PG8_SCHED __builtin_amdgcn_sched_barrier(0)
; template <class Epi>
; __device__ __forceinline__ void gemm_phase(LAS unsigned char* lds, const Gemm g, const StaticOrder& S, const Epi& E) {
;     ...
;             PG8_WAIT_V(6); PG8_BAR; PG8_MMA(1, 1, At, B1); PG8_BAR;
;             PG8_LDB(B0, 1, 0); PG8_SCHED; PG8_LDA(At, 1, 0); PG8_STAGE(PG8_SA(0, 1), a2 + hstep, voffA);
;             PG8_WAIT_L(8); PG8_BAR; PG8_WAIT_L(0); PG8_MMA(0, 0, At, B0); PG8_BAR; PG8_SCHED;
;             PG8_LDB(B1, 1, 1); PG8_STAGE(PG8_SB(1, 0), b3, voffB);
;             PG8_BAR; PG8_WAIT_L(0); PG8_MMA(0, 1, At, B1); PG8_BAR;
;             PG8_LDA(At, 1, 1); PG8_STAGE(PG8_SA(1, 0), a3, voffA);
;             PG8_BAR; PG8_WAIT_L(0); PG8_MMA(1, 0, At, B0); PG8_BAR; PG8_SCHED;
	s_add_u32 s50, s24, 0x80000
	s_addc_u32 s51, s25, 0
	s_add_i32 s49, s41, s29
	v_lshl_add_u64 v[154:155], s[50:51], 0, v[130:131]
	s_mov_b32 m0, s49
	s_nop 0
	global_load_lds_dwordx4 v[154:155], off
	v_lshl_add_u64 v[154:155], s[50:51], 0, v[134:135]
	s_add_i32 m0, s49, 0x2000
	s_nop 0
	global_load_lds_dwordx4 v[154:155], off
	s_waitcnt vmcnt(6)
	s_barrier
	v_mfma_f32_16x16x32_bf16 v[52:55], v[202:205], v[170:173], v[52:55]
	v_mfma_f32_16x16x32_bf16 v[48:51], v[210:213], v[170:173], v[48:51]
	v_mfma_f32_16x16x32_bf16 v[36:39], v[202:205], v[178:181], v[36:39]
	v_mfma_f32_16x16x32_bf16 v[32:35], v[210:213], v[178:181], v[32:35]
	v_mfma_f32_16x16x32_bf16 v[20:23], v[202:205], v[186:189], v[20:23]
	v_mfma_f32_16x16x32_bf16 v[16:19], v[210:213], v[186:189], v[16:19]
	v_mfma_f32_16x16x32_bf16 v[4:7], v[202:205], v[194:197], v[4:7]
	v_mfma_f32_16x16x32_bf16 v[0:3], v[210:213], v[194:197], v[0:3]
	v_mfma_f32_16x16x32_bf16 v[52:55], v[206:209], v[174:177], v[52:55]
	v_mfma_f32_16x16x32_bf16 v[48:51], v[216:219], v[174:177], v[48:51]
	v_mfma_f32_16x16x32_bf16 v[36:39], v[206:209], v[182:185], v[36:39]
	v_mfma_f32_16x16x32_bf16 v[32:35], v[216:219], v[182:185], v[32:35]
	v_mfma_f32_16x16x32_bf16 v[20:23], v[206:209], v[190:193], v[20:23]
	v_mfma_f32_16x16x32_bf16 v[16:19], v[216:219], v[190:193], v[16:19]
	v_mfma_f32_16x16x32_bf16 v[4:7], v[206:209], v[198:201], v[4:7]
	v_mfma_f32_16x16x32_bf16 v[0:3], v[216:219], v[198:201], v[0:3]
	s_add_i32 s49, 0, 0x18000
	v_add_u32_e32 v166, s49, v148
	s_barrier
	ds_read_b128 v[154:157], v166
	ds_read_b128 v[158:161], v166 offset:1024
	ds_read_b128 v[162:165], v166 offset:2048
	ds_read_b128 v[166:169], v166 offset:3072
	s_add_u32 s26, s26, 0x80000
	s_addc_u32 s27, s27, 0
	s_mov_b32 m0, s31
	v_lshl_add_u64 v[202:203], s[26:27], 0, v[128:129]
	ds_read_b128 v[170:173], v151 offset:32768
	ds_read_b128 v[174:177], v151 offset:33792
	ds_read_b128 v[178:181], v151 offset:34816
	ds_read_b128 v[182:185], v151 offset:35840
	ds_read_b128 v[186:189], v151 offset:36864
	ds_read_b128 v[190:193], v151 offset:37888
	ds_read_b128 v[194:197], v151 offset:38912
	ds_read_b128 v[198:201], v151 offset:39936
	global_load_lds_dwordx4 v[202:203], off
	v_lshl_add_u64 v[202:203], s[26:27], 0, v[132:133]
	s_mov_b32 m0, s33
	s_nop 0
	global_load_lds_dwordx4 v[202:203], off
	s_waitcnt lgkmcnt(8)
	s_barrier
	s_waitcnt lgkmcnt(0)
	s_waitcnt lgkmcnt(0)
	v_mfma_f32_16x16x32_bf16 v[124:127], v[154:157], v[170:173], v[124:127]
	v_mfma_f32_16x16x32_bf16 v[120:123], v[162:165], v[170:173], v[120:123]
	v_mfma_f32_16x16x32_bf16 v[108:111], v[154:157], v[178:181], v[108:111]
	v_mfma_f32_16x16x32_bf16 v[104:107], v[162:165], v[178:181], v[104:107]
	v_mfma_f32_16x16x32_bf16 v[92:95], v[154:157], v[186:189], v[92:95]
	v_mfma_f32_16x16x32_bf16 v[88:91], v[162:165], v[186:189], v[88:91]
	v_mfma_f32_16x16x32_bf16 v[76:79], v[154:157], v[194:197], v[76:79]
	v_mfma_f32_16x16x32_bf16 v[72:75], v[162:165], v[194:197], v[72:75]
	v_mfma_f32_16x16x32_bf16 v[124:127], v[158:161], v[174:177], v[124:127]
	v_mfma_f32_16x16x32_bf16 v[120:123], v[166:169], v[174:177], v[120:123]
	v_mfma_f32_16x16x32_bf16 v[108:111], v[158:161], v[182:185], v[108:111]
	v_mfma_f32_16x16x32_bf16 v[104:107], v[166:169], v[182:185], v[104:107]
	v_mfma_f32_16x16x32_bf16 v[92:95], v[158:161], v[190:193], v[92:95]
	v_mfma_f32_16x16x32_bf16 v[88:91], v[166:169], v[190:193], v[88:91]
	v_mfma_f32_16x16x32_bf16 v[76:79], v[158:161], v[198:201], v[76:79]
	v_mfma_f32_16x16x32_bf16 v[72:75], v[166:169], v[198:201], v[72:75]
	s_barrier
	s_add_i32 s26, 0, 0x1c000
	s_add_i32 s27, s49, s29
	v_add_u32_e32 v216, s26, v148
	v_lshl_add_u64 v[220:221], v[220:221], 0, s[4:5]
	s_mov_b32 m0, s27
	ds_read_b128 v[202:205], v216
	ds_read_b128 v[206:209], v216 offset:1024
	ds_read_b128 v[210:213], v216 offset:2048
	ds_read_b128 v[216:219], v216 offset:3072
	global_load_lds_dwordx4 v[220:221], off
	v_lshl_add_u64 v[220:221], v[222:223], 0, s[4:5]
	s_add_i32 m0, s27, 0x2000
	s_nop 0
	global_load_lds_dwordx4 v[220:221], off
	s_barrier
	s_waitcnt lgkmcnt(0)
	s_waitcnt lgkmcnt(0)
	v_mfma_f32_16x16x32_bf16 v[116:119], v[202:205], v[170:173], v[116:119]
	v_mfma_f32_16x16x32_bf16 v[112:115], v[210:213], v[170:173], v[112:115]
	v_mfma_f32_16x16x32_bf16 v[100:103], v[202:205], v[178:181], v[100:103]
	v_mfma_f32_16x16x32_bf16 v[96:99], v[210:213], v[178:181], v[96:99]
	v_mfma_f32_16x16x32_bf16 v[84:87], v[202:205], v[186:189], v[84:87]
	v_mfma_f32_16x16x32_bf16 v[80:83], v[210:213], v[186:189], v[80:83]
	v_mfma_f32_16x16x32_bf16 v[68:71], v[202:205], v[194:197], v[68:71]
	v_mfma_f32_16x16x32_bf16 v[64:67], v[210:213], v[194:197], v[64:67]
	v_mfma_f32_16x16x32_bf16 v[116:119], v[206:209], v[174:177], v[116:119]
	v_mfma_f32_16x16x32_bf16 v[112:115], v[216:219], v[174:177], v[112:115]
	v_mfma_f32_16x16x32_bf16 v[100:103], v[206:209], v[182:185], v[100:103]
	v_mfma_f32_16x16x32_bf16 v[96:99], v[216:219], v[182:185], v[96:99]
	v_mfma_f32_16x16x32_bf16 v[84:87], v[206:209], v[190:193], v[84:87]
	v_mfma_f32_16x16x32_bf16 v[80:83], v[216:219], v[190:193], v[80:83]
	v_mfma_f32_16x16x32_bf16 v[68:71], v[206:209], v[198:201], v[68:71]
	v_mfma_f32_16x16x32_bf16 v[64:67], v[216:219], v[198:201], v[64:67]
	s_mov_b32 m0, s37
	v_lshl_add_u64 v[220:221], v[224:225], 0, s[4:5]
	s_barrier
	ds_read_b128 v[170:173], v151 offset:49152
	ds_read_b128 v[174:177], v151 offset:50176
	ds_read_b128 v[178:181], v151 offset:51200
	ds_read_b128 v[182:185], v151 offset:52224
	ds_read_b128 v[186:189], v151 offset:53248
	ds_read_b128 v[190:193], v151 offset:54272
	ds_read_b128 v[194:197], v151 offset:55296
	ds_read_b128 v[198:201], v151 offset:56320
	global_load_lds_dwordx4 v[220:221], off
	v_lshl_add_u64 v[220:221], v[226:227], 0, s[4:5]
	s_mov_b32 m0, s38
	s_nop 0
	global_load_lds_dwordx4 v[220:221], off
	s_barrier
; #define PG8_STAGE(bufoff, gbase, voff) do { _Pragma("unroll") for (int _i = 0; _i < 2; ++_i) \
;         __builtin_amdgcn_global_load_lds((const unsigned*)((const char*)(gbase) + (voff)[_i]), (LAS unsigned*)(lds + (bufoff) + ldsw + _i * 8192), 16, 0, 0); } while (0)
; #define PG8_MMA(ai, bj, At, Bt) do { __builtin_amdgcn_s_setprio(1); _Pragma("unroll") for (int m = 0; m < 4; ++m) _Pragma("unroll") for (int n = 0; n < 2; ++n) _Pragma("unroll") for (int k = 0; k < 2; ++k) \
;         acc[ai][bj][m][n] = __builtin_amdgcn_mfma_f32_16x16x32_bf16(Bt[n][k], At[m][k], acc[ai][bj][m][n], 0, 0, 0); __builtin_amdgcn_s_setprio(0); } while (0)
; #define PG8_WAIT_V(n) asm volatile("s_waitcnt vmcnt(" #n ")" ::: "memory")
; #define PG8_WAIT_L(n) asm volatile("s_waitcnt lgkmcnt(" #n ")" ::: "memory")
; #define PG8_BAR __builtin_amdgcn_s_barrier()
; #define PG8_SCHED __builtin_amdgcn_sched_barrier(0)
; __device__ __forceinline__ u32x4 pack8(const f32x4 v0, const f32x4 v1) { u32x4 w; w.x = cvt_pk_bf16(v0[0], v0[1]); w.y = cvt_pk_bf16(v0[2], v0[3]); w.z = cvt_pk_bf16(v1[0], v1[1]); w.w = cvt_pk_bf16(v1[2], v1[3]); return w; }
; __device__ __forceinline__ f32x4 sig4(const f32x4 v) { return (f32x4){sigmoidf_(v[0]), sigmoidf_(v[1]), sigmoidf_(v[2]), sigmoidf_(v[3])}; }
; template <class Epi>
; __device__ __forceinline__ void gemm_phase(LAS unsigned char* lds, const Gemm g, const StaticOrder& S, const Epi& E) {
;     ...
;             PG8_BAR; PG8_WAIT_L(0); PG8_MMA(1, 0, At, B0); PG8_BAR; PG8_SCHED;
;             PG8_STAGE(PG8_SB(1, 1), b3 + hstep, voffB);
;             PG8_WAIT_V(6); PG8_BAR; PG8_MMA(1, 1, At, B1); PG8_BAR;
;         }
;     __device__ __forceinline__ void operator()(const AccT& acc, const pg8::Unit& u, int wr, int wc, int fr, int fq) const {
;         const int row0 = u.pm * 256 + wr * 64 + fr, col0 = u.pn * 128 + wc * 32 + 8 * fq;
; #pragma unroll
;         for (int ai = 0; ai < 2; ++ai)
; #pragma unroll
;             for (int m = 0; m < 4; ++m) { const int r = row0 + ai * 128 + m * 16;
;                 const f32x4 g0 = acc[ai][0][m][0], g1 = acc[ai][0][m][1];
;                 const f32x4 o0 = g0 * sig4(g0) * acc[ai][1][m][0], o1 = g1 * sig4(g1) * acc[ai][1][m][1];
;                 *(u32x4*)(O + (size_t)r * DFF + col0) = pack8(o0, o1); }
	s_waitcnt lgkmcnt(0)
	s_waitcnt lgkmcnt(0)
	v_mfma_f32_16x16x32_bf16 v[60:63], v[154:157], v[170:173], v[60:63]
	v_mfma_f32_16x16x32_bf16 v[56:59], v[162:165], v[170:173], v[56:59]
	v_mfma_f32_16x16x32_bf16 v[44:47], v[154:157], v[178:181], v[44:47]
	v_mfma_f32_16x16x32_bf16 v[40:43], v[162:165], v[178:181], v[40:43]
	v_mfma_f32_16x16x32_bf16 v[28:31], v[154:157], v[186:189], v[28:31]
	v_mfma_f32_16x16x32_bf16 v[24:27], v[162:165], v[186:189], v[24:27]
	v_mfma_f32_16x16x32_bf16 v[12:15], v[154:157], v[194:197], v[12:15]
	v_mfma_f32_16x16x32_bf16 v[8:11], v[162:165], v[194:197], v[8:11]
	v_mfma_f32_16x16x32_bf16 v[60:63], v[158:161], v[174:177], v[60:63]
	v_mfma_f32_16x16x32_bf16 v[56:59], v[166:169], v[174:177], v[56:59]
	v_mfma_f32_16x16x32_bf16 v[44:47], v[158:161], v[182:185], v[44:47]
	v_mfma_f32_16x16x32_bf16 v[40:43], v[166:169], v[182:185], v[40:43]
	v_mfma_f32_16x16x32_bf16 v[28:31], v[158:161], v[190:193], v[28:31]
	v_mfma_f32_16x16x32_bf16 v[24:27], v[166:169], v[190:193], v[24:27]
	v_mfma_f32_16x16x32_bf16 v[12:15], v[158:161], v[198:201], v[12:15]
	v_mfma_f32_16x16x32_bf16 v[8:11], v[166:169], v[198:201], v[8:11]
	s_barrier
	s_add_u32 s24, s24, 0x80080
	s_addc_u32 s25, s25, 0
	s_add_i32 s26, s26, s29
	v_lshl_add_u64 v[154:155], s[24:25], 0, v[130:131]
	s_mov_b32 m0, s26
	s_nop 0
	global_load_lds_dwordx4 v[154:155], off
	v_lshl_add_u64 v[154:155], s[24:25], 0, v[134:135]
	s_add_i32 m0, s26, 0x2000
	s_nop 0
	global_load_lds_dwordx4 v[154:155], off
	s_waitcnt vmcnt(6)
	s_barrier
	v_mfma_f32_16x16x32_bf16 v[52:55], v[202:205], v[170:173], v[52:55]
	v_mfma_f32_16x16x32_bf16 v[48:51], v[210:213], v[170:173], v[48:51]
	v_mfma_f32_16x16x32_bf16 v[36:39], v[202:205], v[178:181], v[36:39]
	v_mfma_f32_16x16x32_bf16 v[32:35], v[210:213], v[178:181], v[32:35]
	v_mfma_f32_16x16x32_bf16 v[20:23], v[202:205], v[186:189], v[20:23]
	v_mfma_f32_16x16x32_bf16 v[16:19], v[210:213], v[186:189], v[16:19]
	v_mfma_f32_16x16x32_bf16 v[4:7], v[202:205], v[194:197], v[4:7]
	v_mfma_f32_16x16x32_bf16 v[0:3], v[210:213], v[194:197], v[0:3]
	v_mfma_f32_16x16x32_bf16 v[52:55], v[206:209], v[174:177], v[52:55]
	v_mfma_f32_16x16x32_bf16 v[48:51], v[216:219], v[174:177], v[48:51]
	v_mfma_f32_16x16x32_bf16 v[36:39], v[206:209], v[182:185], v[36:39]
	v_mfma_f32_16x16x32_bf16 v[32:35], v[216:219], v[182:185], v[32:35]
	v_mfma_f32_16x16x32_bf16 v[20:23], v[206:209], v[190:193], v[20:23]
	v_mfma_f32_16x16x32_bf16 v[16:19], v[216:219], v[190:193], v[16:19]
	v_mfma_f32_16x16x32_bf16 v[4:7], v[206:209], v[198:201], v[4:7]
	v_mfma_f32_16x16x32_bf16 v[0:3], v[216:219], v[198:201], v[0:3]
	s_add_i32 s48, s48, 2
	s_add_u32 s22, s22, 0x100
	s_addc_u32 s23, s23, 0
	s_add_u32 s46, s46, 0x100
	s_addc_u32 s47, s47, 0
	s_cmp_gt_u32 s48, 29
	s_barrier
	s_cbranch_scc0 .LBB0_1150
	v_mul_f32_e32 v155, 0xbfb8aa3b, v124
	v_exp_f32_e32 v155, v155
	v_mul_f32_e32 v157, 0xbfb8aa3b, v125
	v_exp_f32_e32 v159, v157
	v_lshl_or_b32 v156, s43, 7, v149
	v_add_f32_e32 v155, 1.0, v155
	v_rcp_f32_e32 v158, v155
	v_add_f32_e32 v155, 1.0, v159
	v_mul_f32_e32 v159, 0xbfb8aa3b, v126
	v_exp_f32_e32 v160, v159
	v_mul_f32_e32 v159, 0xbfb8aa3b, v127
	v_exp_f32_e32 v161, v159
	v_rcp_f32_e32 v159, v155
	v_add_f32_e32 v155, 1.0, v160
	v_rcp_f32_e32 v160, v155
	v_add_f32_e32 v155, 1.0, v161
	v_rcp_f32_e32 v161, v155
	v_mul_f32_e32 v155, 0xbfb8aa3b, v120
	v_pk_mul_f32 v[124:125], v[124:125], v[158:159]
	v_exp_f32_e32 v155, v155
	v_mul_f32_e32 v158, 0xbfb8aa3b, v121
	v_exp_f32_e32 v159, v158
	v_pk_mul_f32 v[126:127], v[126:127], v[160:161]
	v_add_f32_e32 v155, 1.0, v155
	v_rcp_f32_e32 v158, v155
	v_add_f32_e32 v155, 1.0, v159
	v_mul_f32_e32 v159, 0xbfb8aa3b, v122
	v_exp_f32_e32 v160, v159
	v_mul_f32_e32 v159, 0xbfb8aa3b, v123
	v_exp_f32_e32 v161, v159
	v_rcp_f32_e32 v159, v155
	v_add_f32_e32 v155, 1.0, v160
	v_rcp_f32_e32 v160, v155
	v_add_f32_e32 v155, 1.0, v161
	v_rcp_f32_e32 v161, v155
	v_pk_mul_f32 v[120:121], v[120:121], v[158:159]
	v_pk_mul_f32 v[118:119], v[126:127], v[118:119]
	v_pk_mul_f32 v[116:117], v[124:125], v[116:117]
	v_pk_mul_f32 v[122:123], v[122:123], v[160:161]
	v_pk_mul_f32 v[112:113], v[120:121], v[112:113]
	v_lshl_add_u32 v154, s20, 8, v147
	v_ashrrev_i32_e32 v157, 31, v156
	v_pk_mul_f32 v[114:115], v[122:123], v[114:115]
	v_cvt_pk_bf16_f32 v116, v116, v117
	v_cvt_pk_bf16_f32 v117, v118, v119
	v_cvt_pk_bf16_f32 v118, v112, v113
	v_mov_b64_e32 v[112:113], s[0:1]
	v_cvt_pk_bf16_f32 v119, v114, v115
	v_mad_i64_i32 v[120:121], s[22:23], v154, s42, v[112:113]
	v_lshlrev_b64 v[114:115], 1, v[156:157]
	v_lshl_add_u64 v[120:121], v[120:121], 0, v[114:115]
	global_store_dwordx4 v[120:121], v[116:119], off
	v_or_b32_e32 v120, 16, v154
	s_and_b64 vcc, exec, s[2:3]
	v_mul_f32_e32 v116, 0xbfb8aa3b, v108
	v_mul_f32_e32 v117, 0xbfb8aa3b, v109
	v_mul_f32_e32 v118, 0xbfb8aa3b, v110
	v_mul_f32_e32 v119, 0xbfb8aa3b, v111
	v_exp_f32_e32 v116, v116
	v_exp_f32_e32 v117, v117
	v_exp_f32_e32 v118, v118
	v_exp_f32_e32 v119, v119
	v_add_f32_e32 v116, 1.0, v116
	v_add_f32_e32 v117, 1.0, v117
	v_add_f32_e32 v118, 1.0, v118
	v_add_f32_e32 v119, 1.0, v119
	v_rcp_f32_e32 v116, v116
	v_rcp_f32_e32 v117, v117
	v_rcp_f32_e32 v118, v118
	v_rcp_f32_e32 v119, v119
	s_mov_b32 s43, s8
	v_pk_mul_f32 v[108:109], v[108:109], v[116:117]
	v_mul_f32_e32 v116, 0xbfb8aa3b, v104
	v_mul_f32_e32 v117, 0xbfb8aa3b, v105
	v_pk_mul_f32 v[110:111], v[110:111], v[118:119]
	v_mul_f32_e32 v118, 0xbfb8aa3b, v106
	v_mul_f32_e32 v119, 0xbfb8aa3b, v107
	v_exp_f32_e32 v116, v116
	v_exp_f32_e32 v117, v117
	v_exp_f32_e32 v118, v118
	v_exp_f32_e32 v119, v119
	v_add_f32_e32 v116, 1.0, v116
	v_add_f32_e32 v117, 1.0, v117
	v_add_f32_e32 v118, 1.0, v118
; __device__ __forceinline__ u32x4 pack8(const f32x4 v0, const f32x4 v1) { u32x4 w; w.x = cvt_pk_bf16(v0[0], v0[1]); w.y = cvt_pk_bf16(v0[2], v0[3]); w.z = cvt_pk_bf16(v1[0], v1[1]); w.w = cvt_pk_bf16(v1[2], v1[3]); return w; }
; __device__ __forceinline__ f32x4 sig4(const f32x4 v) { return (f32x4){sigmoidf_(v[0]), sigmoidf_(v[1]), sigmoidf_(v[2]), sigmoidf_(v[3])}; }
;     __device__ __forceinline__ void operator()(const AccT& acc, const pg8::Unit& u, int wr, int wc, int fr, int fq) const {
;         const int row0 = u.pm * 256 + wr * 64 + fr, col0 = u.pn * 128 + wc * 32 + 8 * fq;
; #pragma unroll
;         for (int ai = 0; ai < 2; ++ai)
; #pragma unroll
;             for (int m = 0; m < 4; ++m) { const int r = row0 + ai * 128 + m * 16;
;                 const f32x4 g0 = acc[ai][0][m][0], g1 = acc[ai][0][m][1];
;                 const f32x4 o0 = g0 * sig4(g0) * acc[ai][1][m][0], o1 = g1 * sig4(g1) * acc[ai][1][m][1];
;                 *(u32x4*)(O + (size_t)r * DFF + col0) = pack8(o0, o1); }
	v_add_f32_e32 v119, 1.0, v119
	v_rcp_f32_e32 v116, v116
	v_rcp_f32_e32 v117, v117
	v_rcp_f32_e32 v118, v118
	v_rcp_f32_e32 v119, v119
	v_pk_mul_f32 v[100:101], v[108:109], v[100:101]
	v_pk_mul_f32 v[104:105], v[104:105], v[116:117]
	v_pk_mul_f32 v[102:103], v[110:111], v[102:103]
	v_pk_mul_f32 v[106:107], v[106:107], v[118:119]
	s_mov_b32 s20, s10
	v_pk_mul_f32 v[106:107], v[106:107], v[98:99]
	v_pk_mul_f32 v[98:99], v[104:105], v[96:97]
	v_cvt_pk_bf16_f32 v96, v100, v101
	v_mad_i64_i32 v[100:101], s[22:23], v120, s42, v[112:113]
	v_cvt_pk_bf16_f32 v97, v102, v103
	v_cvt_pk_bf16_f32 v98, v98, v99
	v_cvt_pk_bf16_f32 v99, v106, v107
	v_lshl_add_u64 v[100:101], v[100:101], 0, v[114:115]
	global_store_dwordx4 v[100:101], v[96:99], off
	v_or_b32_e32 v100, 32, v154
	s_mov_b64 s[24:25], s[18:19]
	v_mul_f32_e32 v96, 0xbfb8aa3b, v92
	v_mul_f32_e32 v97, 0xbfb8aa3b, v93
	v_mul_f32_e32 v98, 0xbfb8aa3b, v94
	v_mul_f32_e32 v99, 0xbfb8aa3b, v95
	v_exp_f32_e32 v96, v96
	v_exp_f32_e32 v97, v97
	v_exp_f32_e32 v98, v98
	v_exp_f32_e32 v99, v99
	v_add_f32_e32 v96, 1.0, v96
	v_add_f32_e32 v97, 1.0, v97
	v_add_f32_e32 v98, 1.0, v98
	v_add_f32_e32 v99, 1.0, v99
	v_rcp_f32_e32 v96, v96
	v_rcp_f32_e32 v97, v97
	v_rcp_f32_e32 v98, v98
	v_rcp_f32_e32 v99, v99
	v_pk_mul_f32 v[92:93], v[92:93], v[96:97]
	v_mul_f32_e32 v96, 0xbfb8aa3b, v88
	v_mul_f32_e32 v97, 0xbfb8aa3b, v89
	v_pk_mul_f32 v[94:95], v[94:95], v[98:99]
	v_mul_f32_e32 v98, 0xbfb8aa3b, v90
	v_mul_f32_e32 v99, 0xbfb8aa3b, v91
	v_exp_f32_e32 v96, v96
	v_exp_f32_e32 v97, v97
	v_exp_f32_e32 v98, v98
	v_exp_f32_e32 v99, v99
	v_add_f32_e32 v96, 1.0, v96
	v_add_f32_e32 v97, 1.0, v97
	v_add_f32_e32 v98, 1.0, v98
	v_add_f32_e32 v99, 1.0, v99
	v_rcp_f32_e32 v96, v96
	v_rcp_f32_e32 v97, v97
	v_rcp_f32_e32 v98, v98
	v_rcp_f32_e32 v99, v99
	v_pk_mul_f32 v[84:85], v[92:93], v[84:85]
	v_pk_mul_f32 v[88:89], v[88:89], v[96:97]
	v_pk_mul_f32 v[86:87], v[94:95], v[86:87]
	v_pk_mul_f32 v[90:91], v[90:91], v[98:99]
	s_nop 0
	v_pk_mul_f32 v[90:91], v[90:91], v[82:83]
	v_pk_mul_f32 v[82:83], v[88:89], v[80:81]
	v_cvt_pk_bf16_f32 v80, v84, v85
	v_mad_i64_i32 v[84:85], s[22:23], v100, s42, v[112:113]
	v_cvt_pk_bf16_f32 v81, v86, v87
	v_cvt_pk_bf16_f32 v82, v82, v83
	v_cvt_pk_bf16_f32 v83, v90, v91
	v_lshl_add_u64 v[84:85], v[84:85], 0, v[114:115]
	global_store_dwordx4 v[84:85], v[80:83], off
	v_or_b32_e32 v84, 48, v154
	s_nop 0
	v_mul_f32_e32 v80, 0xbfb8aa3b, v76
	v_mul_f32_e32 v81, 0xbfb8aa3b, v77
	v_mul_f32_e32 v82, 0xbfb8aa3b, v78
	v_mul_f32_e32 v83, 0xbfb8aa3b, v79
	v_exp_f32_e32 v80, v80
	v_exp_f32_e32 v81, v81
	v_exp_f32_e32 v82, v82
	v_exp_f32_e32 v83, v83
	v_add_f32_e32 v80, 1.0, v80
	v_add_f32_e32 v81, 1.0, v81
	v_add_f32_e32 v82, 1.0, v82
	v_add_f32_e32 v83, 1.0, v83
	v_rcp_f32_e32 v80, v80
	v_rcp_f32_e32 v81, v81
	v_rcp_f32_e32 v82, v82
	v_rcp_f32_e32 v83, v83
	v_pk_mul_f32 v[76:77], v[76:77], v[80:81]
	v_mul_f32_e32 v80, 0xbfb8aa3b, v72
	v_mul_f32_e32 v81, 0xbfb8aa3b, v73
	v_pk_mul_f32 v[78:79], v[78:79], v[82:83]
	v_mul_f32_e32 v82, 0xbfb8aa3b, v74
	v_mul_f32_e32 v83, 0xbfb8aa3b, v75
	v_exp_f32_e32 v80, v80
	v_exp_f32_e32 v81, v81
	v_exp_f32_e32 v82, v82
	v_exp_f32_e32 v83, v83
	v_add_f32_e32 v80, 1.0, v80
	v_add_f32_e32 v81, 1.0, v81
	v_add_f32_e32 v82, 1.0, v82
	v_add_f32_e32 v83, 1.0, v83
	v_rcp_f32_e32 v80, v80
	v_rcp_f32_e32 v81, v81
	v_rcp_f32_e32 v82, v82
	v_rcp_f32_e32 v83, v83
	v_pk_mul_f32 v[68:69], v[76:77], v[68:69]
	v_pk_mul_f32 v[72:73], v[72:73], v[80:81]
	v_pk_mul_f32 v[70:71], v[78:79], v[70:71]
	v_pk_mul_f32 v[74:75], v[74:75], v[82:83]
	s_nop 0
	v_pk_mul_f32 v[74:75], v[74:75], v[66:67]
	v_pk_mul_f32 v[66:67], v[72:73], v[64:65]
	v_cvt_pk_bf16_f32 v64, v68, v69
	v_mad_i64_i32 v[68:69], s[22:23], v84, s42, v[112:113]
	v_cvt_pk_bf16_f32 v65, v70, v71
	v_cvt_pk_bf16_f32 v66, v66, v67
	v_cvt_pk_bf16_f32 v67, v74, v75
	v_lshl_add_u64 v[68:69], v[68:69], 0, v[114:115]
	global_store_dwordx4 v[68:69], v[64:67], off
	v_add_u32_e32 v68, 0x80, v154
	s_nop 0
	v_mul_f32_e32 v64, 0xbfb8aa3b, v60
	v_mul_f32_e32 v65, 0xbfb8aa3b, v61
	v_mul_f32_e32 v66, 0xbfb8aa3b, v62
	v_mul_f32_e32 v67, 0xbfb8aa3b, v63
	v_exp_f32_e32 v64, v64
	v_exp_f32_e32 v65, v65
	v_exp_f32_e32 v66, v66
	v_exp_f32_e32 v67, v67
	v_add_f32_e32 v64, 1.0, v64
	v_add_f32_e32 v65, 1.0, v65
	v_add_f32_e32 v66, 1.0, v66
	v_add_f32_e32 v67, 1.0, v67
	v_rcp_f32_e32 v64, v64
	v_rcp_f32_e32 v65, v65
	v_rcp_f32_e32 v66, v66
	v_rcp_f32_e32 v67, v67
	v_pk_mul_f32 v[60:61], v[60:61], v[64:65]
	v_mul_f32_e32 v64, 0xbfb8aa3b, v56
	v_mul_f32_e32 v65, 0xbfb8aa3b, v57
	v_pk_mul_f32 v[62:63], v[62:63], v[66:67]
	v_mul_f32_e32 v66, 0xbfb8aa3b, v58
	v_mul_f32_e32 v67, 0xbfb8aa3b, v59
	v_exp_f32_e32 v64, v64
	v_exp_f32_e32 v65, v65
	v_exp_f32_e32 v66, v66
	v_exp_f32_e32 v67, v67
	v_add_f32_e32 v64, 1.0, v64
	v_add_f32_e32 v65, 1.0, v65
	v_add_f32_e32 v66, 1.0, v66
	v_add_f32_e32 v67, 1.0, v67
	v_rcp_f32_e32 v64, v64
	v_rcp_f32_e32 v65, v65
	v_rcp_f32_e32 v66, v66
	v_rcp_f32_e32 v67, v67
	v_pk_mul_f32 v[52:53], v[60:61], v[52:53]
	v_pk_mul_f32 v[56:57], v[56:57], v[64:65]
	v_pk_mul_f32 v[54:55], v[62:63], v[54:55]
	v_pk_mul_f32 v[58:59], v[58:59], v[66:67]
	s_nop 0
	v_pk_mul_f32 v[58:59], v[58:59], v[50:51]
; #define PG8_WAIT_V(n) asm volatile("s_waitcnt vmcnt(" #n ")" ::: "memory")
; #define PG8_BAR __builtin_amdgcn_s_barrier()
; __device__ __forceinline__ u32x4 pack8(const f32x4 v0, const f32x4 v1) { u32x4 w; w.x = cvt_pk_bf16(v0[0], v0[1]); w.y = cvt_pk_bf16(v0[2], v0[3]); w.z = cvt_pk_bf16(v1[0], v1[1]); w.w = cvt_pk_bf16(v1[2], v1[3]); return w; }
; __device__ __forceinline__ f32x4 sig4(const f32x4 v) { return (f32x4){sigmoidf_(v[0]), sigmoidf_(v[1]), sigmoidf_(v[2]), sigmoidf_(v[3])}; }
; template <class Epi>
; __device__ __forceinline__ void gemm_phase(LAS unsigned char* lds, const Gemm g, const StaticOrder& S, const Epi& E) {
;     ...
;         if (!has_next) break;
; #pragma unroll
;         for (int a = 0; a < 2; ++a)
; #pragma unroll
;             for (int b = 0; b < 2; ++b)
; #pragma unroll
;                 for (int m = 0; m < 4; ++m)
; #pragma unroll
;                     for (int n = 0; n < 2; ++n) acc[a][b][m][n] = (f32x4){0.f, 0.f, 0.f, 0.f};
;         cur = nxt; cA = nA; cB = nB; ++ui;
;     }
;     PG8_WAIT_V(0);
;     if (wr == 0) PG8_BAR;
;     PG8_BAR;
;     __device__ __forceinline__ void operator()(const AccT& acc, const pg8::Unit& u, int wr, int wc, int fr, int fq) const {
;         const int row0 = u.pm * 256 + wr * 64 + fr, col0 = u.pn * 128 + wc * 32 + 8 * fq;
; #pragma unroll
;         for (int ai = 0; ai < 2; ++ai)
; #pragma unroll
;             for (int m = 0; m < 4; ++m) { const int r = row0 + ai * 128 + m * 16;
;                 const f32x4 g0 = acc[ai][0][m][0], g1 = acc[ai][0][m][1];
;                 const f32x4 o0 = g0 * sig4(g0) * acc[ai][1][m][0], o1 = g1 * sig4(g1) * acc[ai][1][m][1];
;                 *(u32x4*)(O + (size_t)r * DFF + col0) = pack8(o0, o1); }
	v_pk_mul_f32 v[50:51], v[56:57], v[48:49]
	v_cvt_pk_bf16_f32 v48, v52, v53
	v_mad_i64_i32 v[52:53], s[22:23], v68, s42, v[112:113]
	v_cvt_pk_bf16_f32 v49, v54, v55
	v_cvt_pk_bf16_f32 v50, v50, v51
	v_cvt_pk_bf16_f32 v51, v58, v59
	v_lshl_add_u64 v[52:53], v[52:53], 0, v[114:115]
	global_store_dwordx4 v[52:53], v[48:51], off
	v_add_u32_e32 v52, 0x90, v154
	s_nop 0
	v_mul_f32_e32 v48, 0xbfb8aa3b, v44
	v_mul_f32_e32 v49, 0xbfb8aa3b, v45
	v_mul_f32_e32 v50, 0xbfb8aa3b, v46
	v_mul_f32_e32 v51, 0xbfb8aa3b, v47
	v_exp_f32_e32 v48, v48
	v_exp_f32_e32 v49, v49
	v_exp_f32_e32 v50, v50
	v_exp_f32_e32 v51, v51
	v_add_f32_e32 v48, 1.0, v48
	v_add_f32_e32 v49, 1.0, v49
	v_add_f32_e32 v50, 1.0, v50
	v_add_f32_e32 v51, 1.0, v51
	v_rcp_f32_e32 v48, v48
	v_rcp_f32_e32 v49, v49
	v_rcp_f32_e32 v50, v50
	v_rcp_f32_e32 v51, v51
	v_pk_mul_f32 v[44:45], v[44:45], v[48:49]
	v_mul_f32_e32 v48, 0xbfb8aa3b, v40
	v_mul_f32_e32 v49, 0xbfb8aa3b, v41
	v_pk_mul_f32 v[46:47], v[46:47], v[50:51]
	v_mul_f32_e32 v50, 0xbfb8aa3b, v42
	v_mul_f32_e32 v51, 0xbfb8aa3b, v43
	v_exp_f32_e32 v48, v48
	v_exp_f32_e32 v49, v49
	v_exp_f32_e32 v50, v50
	v_exp_f32_e32 v51, v51
	v_add_f32_e32 v48, 1.0, v48
	v_add_f32_e32 v49, 1.0, v49
	v_add_f32_e32 v50, 1.0, v50
	v_add_f32_e32 v51, 1.0, v51
	v_rcp_f32_e32 v48, v48
	v_rcp_f32_e32 v49, v49
	v_rcp_f32_e32 v50, v50
	v_rcp_f32_e32 v51, v51
	v_pk_mul_f32 v[36:37], v[44:45], v[36:37]
	v_pk_mul_f32 v[40:41], v[40:41], v[48:49]
	v_pk_mul_f32 v[38:39], v[46:47], v[38:39]
	v_pk_mul_f32 v[42:43], v[42:43], v[50:51]
	s_nop 0
	v_pk_mul_f32 v[42:43], v[42:43], v[34:35]
	v_pk_mul_f32 v[34:35], v[40:41], v[32:33]
	v_cvt_pk_bf16_f32 v32, v36, v37
	v_mad_i64_i32 v[36:37], s[22:23], v52, s42, v[112:113]
	v_cvt_pk_bf16_f32 v33, v38, v39
	v_cvt_pk_bf16_f32 v34, v34, v35
	v_cvt_pk_bf16_f32 v35, v42, v43
	v_lshl_add_u64 v[36:37], v[36:37], 0, v[114:115]
	global_store_dwordx4 v[36:37], v[32:35], off
	v_add_u32_e32 v36, 0xa0, v154
	s_nop 0
	v_mul_f32_e32 v32, 0xbfb8aa3b, v28
	v_mul_f32_e32 v33, 0xbfb8aa3b, v29
	v_mul_f32_e32 v34, 0xbfb8aa3b, v30
	v_mul_f32_e32 v35, 0xbfb8aa3b, v31
	v_exp_f32_e32 v32, v32
	v_exp_f32_e32 v33, v33
	v_exp_f32_e32 v34, v34
	v_exp_f32_e32 v35, v35
	v_add_f32_e32 v32, 1.0, v32
	v_add_f32_e32 v33, 1.0, v33
	v_add_f32_e32 v34, 1.0, v34
	v_add_f32_e32 v35, 1.0, v35
	v_rcp_f32_e32 v32, v32
	v_rcp_f32_e32 v33, v33
	v_rcp_f32_e32 v34, v34
	v_rcp_f32_e32 v35, v35
	v_pk_mul_f32 v[28:29], v[28:29], v[32:33]
	v_mul_f32_e32 v32, 0xbfb8aa3b, v24
	v_mul_f32_e32 v33, 0xbfb8aa3b, v25
	v_pk_mul_f32 v[30:31], v[30:31], v[34:35]
	v_mul_f32_e32 v34, 0xbfb8aa3b, v26
	v_mul_f32_e32 v35, 0xbfb8aa3b, v27
	v_exp_f32_e32 v32, v32
	v_exp_f32_e32 v33, v33
	v_exp_f32_e32 v34, v34
	v_exp_f32_e32 v35, v35
	v_add_f32_e32 v32, 1.0, v32
	v_add_f32_e32 v33, 1.0, v33
	v_add_f32_e32 v34, 1.0, v34
	v_add_f32_e32 v35, 1.0, v35
	v_rcp_f32_e32 v32, v32
	v_rcp_f32_e32 v33, v33
	v_rcp_f32_e32 v34, v34
	v_rcp_f32_e32 v35, v35
	v_pk_mul_f32 v[20:21], v[28:29], v[20:21]
	v_pk_mul_f32 v[24:25], v[24:25], v[32:33]
	v_pk_mul_f32 v[22:23], v[30:31], v[22:23]
	v_pk_mul_f32 v[26:27], v[26:27], v[34:35]
	s_nop 0
	v_pk_mul_f32 v[26:27], v[26:27], v[18:19]
	v_pk_mul_f32 v[18:19], v[24:25], v[16:17]
	v_cvt_pk_bf16_f32 v16, v20, v21
	v_mad_i64_i32 v[20:21], s[22:23], v36, s42, v[112:113]
	v_cvt_pk_bf16_f32 v17, v22, v23
	v_cvt_pk_bf16_f32 v18, v18, v19
	v_cvt_pk_bf16_f32 v19, v26, v27
	v_lshl_add_u64 v[20:21], v[20:21], 0, v[114:115]
	global_store_dwordx4 v[20:21], v[16:19], off
	v_add_u32_e32 v20, 0xb0, v154
	s_nop 0
	v_mul_f32_e32 v16, 0xbfb8aa3b, v12
	v_mul_f32_e32 v17, 0xbfb8aa3b, v13
	v_mul_f32_e32 v18, 0xbfb8aa3b, v14
	v_mul_f32_e32 v19, 0xbfb8aa3b, v15
	v_exp_f32_e32 v16, v16
	v_exp_f32_e32 v17, v17
	v_exp_f32_e32 v18, v18
	v_exp_f32_e32 v19, v19
	v_add_f32_e32 v16, 1.0, v16
	v_add_f32_e32 v17, 1.0, v17
	v_add_f32_e32 v18, 1.0, v18
	v_add_f32_e32 v19, 1.0, v19
	v_rcp_f32_e32 v16, v16
	v_rcp_f32_e32 v17, v17
	v_rcp_f32_e32 v18, v18
	v_rcp_f32_e32 v19, v19
	v_pk_mul_f32 v[12:13], v[12:13], v[16:17]
	v_mul_f32_e32 v16, 0xbfb8aa3b, v8
	v_mul_f32_e32 v17, 0xbfb8aa3b, v9
	v_pk_mul_f32 v[14:15], v[14:15], v[18:19]
	v_mul_f32_e32 v18, 0xbfb8aa3b, v10
	v_mul_f32_e32 v19, 0xbfb8aa3b, v11
	v_exp_f32_e32 v16, v16
	v_exp_f32_e32 v17, v17
	v_exp_f32_e32 v18, v18
	v_exp_f32_e32 v19, v19
	v_add_f32_e32 v16, 1.0, v16
	v_add_f32_e32 v17, 1.0, v17
	v_add_f32_e32 v18, 1.0, v18
	v_add_f32_e32 v19, 1.0, v19
	v_rcp_f32_e32 v16, v16
	v_rcp_f32_e32 v17, v17
	v_rcp_f32_e32 v18, v18
	v_rcp_f32_e32 v19, v19
	v_pk_mul_f32 v[4:5], v[12:13], v[4:5]
	v_pk_mul_f32 v[8:9], v[8:9], v[16:17]
	v_pk_mul_f32 v[6:7], v[14:15], v[6:7]
	v_pk_mul_f32 v[10:11], v[10:11], v[18:19]
	s_nop 0
	v_pk_mul_f32 v[10:11], v[10:11], v[2:3]
	v_pk_mul_f32 v[2:3], v[8:9], v[0:1]
	v_cvt_pk_bf16_f32 v0, v4, v5
	v_mad_i64_i32 v[4:5], s[22:23], v20, s42, v[112:113]
	v_lshl_add_u64 v[4:5], v[4:5], 0, v[114:115]
	s_mov_b64 s[22:23], s[16:17]
	v_cvt_pk_bf16_f32 v1, v6, v7
	v_cvt_pk_bf16_f32 v2, v2, v3
	v_cvt_pk_bf16_f32 v3, v10, v11
	global_store_dwordx4 v[4:5], v[0:3], off
	s_cbranch_vccz .LBB0_1143
	s_waitcnt vmcnt(0)
	s_cmpk_gt_u32 s28, 0xff
	s_cbranch_scc1 .LBB0_1154
	s_barrier

; #define PG8_STAGE(bufoff, gbase, voff) do { _Pragma("unroll") for (int _i = 0; _i < 2; ++_i) \
;         __builtin_amdgcn_global_load_lds((const unsigned*)((const char*)(gbase) + (voff)[_i]), (LAS unsigned*)(lds + (bufoff) + ldsw + _i * 8192), 16, 0, 0); } while (0)
; #define PG8_LDA(dst, b, h) do { _Pragma("unroll") for (int m = 0; m < 4; ++m) _Pragma("unroll") for (int k = 0; k < 2; ++k) dst[m][k] = *(const LAS bf16x8*)(lds + PG8_SA(b, h) + aoff + m * 2048 + k * 1024); } while (0)
; #define PG8_LDB(dst, b, h) do { _Pragma("unroll") for (int n = 0; n < 2; ++n) _Pragma("unroll") for (int k = 0; k < 2; ++k) dst[n][k] = *(const LAS bf16x8*)(lds + PG8_SB(b, h) + boff + n * 2048 + k * 1024); } while (0)
; #define PG8_MMA(ai, bj, At, Bt) do { __builtin_amdgcn_s_setprio(1); _Pragma("unroll") for (int m = 0; m < 4; ++m) _Pragma("unroll") for (int n = 0; n < 2; ++n) _Pragma("unroll") for (int k = 0; k < 2; ++k) \
;         acc[ai][bj][m][n] = __builtin_amdgcn_mfma_f32_16x16x32_bf16(Bt[n][k], At[m][k], acc[ai][bj][m][n], 0, 0, 0); __builtin_amdgcn_s_setprio(0); } while (0)
; #define PG8_WAIT_V(n) asm volatile("s_waitcnt vmcnt(" #n ")" ::: "memory")
; #define PG8_WAIT_L(n) asm volatile("s_waitcnt lgkmcnt(" #n ")" ::: "memory")
; #define PG8_BAR __builtin_amdgcn_s_barrier()
; #define PG8_SCHED __builtin_amdgcn_sched_barrier(0)
; template <class Epi>
; __device__ __forceinline__ void gemm_phase(LAS unsigned char* lds, const Gemm g, const StaticOrder& S, const Epi& E) {
;     ...
;             PG8_LDB(B0, 0, 0); PG8_SCHED; PG8_LDA(At, 0, 0); PG8_STAGE(PG8_SA(1, 1), a1 + hstep, voffA);
;             PG8_WAIT_L(8); PG8_BAR; PG8_WAIT_L(0); PG8_MMA(0, 0, At, B0); PG8_BAR; PG8_SCHED;
;             PG8_LDB(B1, 0, 1); PG8_STAGE(PG8_SB(0, 0), b2, voffB);
;             PG8_BAR; PG8_WAIT_L(0); PG8_MMA(0, 1, At, B1); PG8_BAR;
;             PG8_LDA(At, 0, 1); PG8_STAGE(PG8_SA(0, 0), a2, voffA);
;             PG8_BAR; PG8_WAIT_L(0); PG8_MMA(1, 0, At, B0); PG8_BAR; PG8_SCHED;
;             PG8_STAGE(PG8_SB(0, 1), b2 + hstep, voffB);
;             PG8_WAIT_V(6); PG8_BAR; PG8_MMA(1, 1, At, B1); PG8_BAR;
.LBB0_1338:
	ds_read_b128 v[128:131], v185
	ds_read_b128 v[132:135], v185 offset:1024
	ds_read_b128 v[136:139], v185 offset:2048
	ds_read_b128 v[140:143], v185 offset:3072
	s_add_u32 s24, s22, 0xffea0080
	s_addc_u32 s25, s23, -1
	s_cmpk_eq_i32 s53, 0x54
	s_cselect_b32 s27, s1, s25
	s_cselect_b32 s26, s0, s24
	s_cselect_b32 s25, s5, s52
	s_cselect_b32 s24, s4, s51
	v_lshl_add_u64 v[200:201], s[22:23], 0, v[162:163]
	s_add_i32 m0, s29, 0xc000
	ds_read_b128 v[144:147], v186
	ds_read_b128 v[148:151], v186 offset:1024
	ds_read_b128 v[170:173], v186 offset:2048
	ds_read_b128 v[174:177], v186 offset:3072
	ds_read_b128 v[178:181], v186 offset:4096
	ds_read_b128 v[188:191], v186 offset:5120
	ds_read_b128 v[192:195], v186 offset:6144
	ds_read_b128 v[196:199], v186 offset:7168
	global_load_lds_dwordx4 v[200:201], off
	v_lshl_add_u64 v[200:201], s[22:23], 0, v[164:165]
	s_add_i32 m0, s29, 0xe000
	s_nop 0
	global_load_lds_dwordx4 v[200:201], off
	s_waitcnt lgkmcnt(8)
	s_barrier
	s_waitcnt lgkmcnt(0)
	s_waitcnt lgkmcnt(0)
	v_mfma_f32_16x16x32_bf16 v[124:127], v[128:131], v[144:147], v[124:127]
	v_mfma_f32_16x16x32_bf16 v[120:123], v[136:139], v[144:147], v[120:123]
	v_mfma_f32_16x16x32_bf16 v[108:111], v[128:131], v[170:173], v[108:111]
	v_mfma_f32_16x16x32_bf16 v[104:107], v[136:139], v[170:173], v[104:107]
	v_mfma_f32_16x16x32_bf16 v[92:95], v[128:131], v[178:181], v[92:95]
	v_mfma_f32_16x16x32_bf16 v[88:91], v[136:139], v[178:181], v[88:91]
	v_mfma_f32_16x16x32_bf16 v[76:79], v[128:131], v[192:195], v[76:79]
	v_mfma_f32_16x16x32_bf16 v[72:75], v[136:139], v[192:195], v[72:75]
	v_mfma_f32_16x16x32_bf16 v[124:127], v[132:135], v[148:151], v[124:127]
	v_mfma_f32_16x16x32_bf16 v[120:123], v[140:143], v[148:151], v[120:123]
	v_mfma_f32_16x16x32_bf16 v[108:111], v[132:135], v[174:177], v[108:111]
	v_mfma_f32_16x16x32_bf16 v[104:107], v[140:143], v[174:177], v[104:107]
	v_mfma_f32_16x16x32_bf16 v[92:95], v[132:135], v[188:191], v[92:95]
	v_mfma_f32_16x16x32_bf16 v[88:91], v[140:143], v[188:191], v[88:91]
	v_mfma_f32_16x16x32_bf16 v[76:79], v[132:135], v[196:199], v[76:79]
	v_mfma_f32_16x16x32_bf16 v[72:75], v[140:143], v[196:199], v[72:75]
	s_barrier
	s_add_i32 s54, s41, s28
	v_lshl_add_u64 v[212:213], s[24:25], 0, v[156:157]
	s_mov_b32 m0, s54
	ds_read_b128 v[200:203], v187
	ds_read_b128 v[204:207], v187 offset:1024
	ds_read_b128 v[208:211], v187 offset:2048
	ds_read_b128 v[216:219], v187 offset:3072
	global_load_lds_dwordx4 v[212:213], off
	v_lshl_add_u64 v[220:221], s[24:25], 0, v[160:161]
	s_add_i32 m0, s54, 0x2000
	s_nop 0
	global_load_lds_dwordx4 v[220:221], off
	s_barrier
	s_waitcnt lgkmcnt(0)
	s_waitcnt lgkmcnt(0)
	v_mfma_f32_16x16x32_bf16 v[116:119], v[200:203], v[144:147], v[116:119]
	v_mfma_f32_16x16x32_bf16 v[112:115], v[208:211], v[144:147], v[112:115]
	v_mfma_f32_16x16x32_bf16 v[100:103], v[200:203], v[170:173], v[100:103]
	v_mfma_f32_16x16x32_bf16 v[96:99], v[208:211], v[170:173], v[96:99]
	v_mfma_f32_16x16x32_bf16 v[84:87], v[200:203], v[178:181], v[84:87]
	v_mfma_f32_16x16x32_bf16 v[80:83], v[208:211], v[178:181], v[80:83]
	v_mfma_f32_16x16x32_bf16 v[68:71], v[200:203], v[192:195], v[68:71]
	v_mfma_f32_16x16x32_bf16 v[64:67], v[208:211], v[192:195], v[64:67]
	v_mfma_f32_16x16x32_bf16 v[116:119], v[204:207], v[148:151], v[116:119]
	v_mfma_f32_16x16x32_bf16 v[112:115], v[216:219], v[148:151], v[112:115]
	v_mfma_f32_16x16x32_bf16 v[100:103], v[204:207], v[174:177], v[100:103]
	v_mfma_f32_16x16x32_bf16 v[96:99], v[216:219], v[174:177], v[96:99]
	v_mfma_f32_16x16x32_bf16 v[84:87], v[204:207], v[188:191], v[84:87]
	v_mfma_f32_16x16x32_bf16 v[80:83], v[216:219], v[188:191], v[80:83]
	v_mfma_f32_16x16x32_bf16 v[68:71], v[204:207], v[196:199], v[68:71]
	v_mfma_f32_16x16x32_bf16 v[64:67], v[216:219], v[196:199], v[64:67]
	s_mov_b32 m0, s29
	v_lshl_add_u64 v[222:223], s[26:27], 0, v[154:155]
	s_barrier
	ds_read_b128 v[144:147], v186 offset:16384
	ds_read_b128 v[148:151], v186 offset:17408
	ds_read_b128 v[170:173], v186 offset:18432
	ds_read_b128 v[174:177], v186 offset:19456
	ds_read_b128 v[178:181], v186 offset:20480
	ds_read_b128 v[188:191], v186 offset:21504
	ds_read_b128 v[192:195], v186 offset:22528
	ds_read_b128 v[196:199], v186 offset:23552
	global_load_lds_dwordx4 v[222:223], off
	v_lshl_add_u64 v[224:225], s[26:27], 0, v[158:159]
	s_mov_b32 m0, s30
	s_nop 0
	global_load_lds_dwordx4 v[224:225], off
	s_barrier
	s_waitcnt lgkmcnt(0)
	s_waitcnt lgkmcnt(0)
	v_mfma_f32_16x16x32_bf16 v[60:63], v[128:131], v[144:147], v[60:63]
	v_mfma_f32_16x16x32_bf16 v[56:59], v[136:139], v[144:147], v[56:59]
	v_mfma_f32_16x16x32_bf16 v[44:47], v[128:131], v[170:173], v[44:47]
	v_mfma_f32_16x16x32_bf16 v[40:43], v[136:139], v[170:173], v[40:43]
	v_mfma_f32_16x16x32_bf16 v[28:31], v[128:131], v[178:181], v[28:31]
	v_mfma_f32_16x16x32_bf16 v[24:27], v[136:139], v[178:181], v[24:27]
	v_mfma_f32_16x16x32_bf16 v[12:15], v[128:131], v[192:195], v[12:15]
	v_mfma_f32_16x16x32_bf16 v[8:11], v[136:139], v[192:195], v[8:11]
	v_mfma_f32_16x16x32_bf16 v[60:63], v[132:135], v[148:151], v[60:63]
	v_mfma_f32_16x16x32_bf16 v[56:59], v[140:143], v[148:151], v[56:59]
	v_mfma_f32_16x16x32_bf16 v[44:47], v[132:135], v[174:177], v[44:47]
	v_mfma_f32_16x16x32_bf16 v[40:43], v[140:143], v[174:177], v[40:43]
	v_mfma_f32_16x16x32_bf16 v[28:31], v[132:135], v[188:191], v[28:31]
	v_mfma_f32_16x16x32_bf16 v[24:27], v[140:143], v[188:191], v[24:27]
	v_mfma_f32_16x16x32_bf16 v[12:15], v[132:135], v[196:199], v[12:15]
	v_mfma_f32_16x16x32_bf16 v[8:11], v[140:143], v[196:199], v[8:11]
	s_barrier
; #define PG8_STAGE(bufoff, gbase, voff) do { _Pragma("unroll") for (int _i = 0; _i < 2; ++_i) \
;         __builtin_amdgcn_global_load_lds((const unsigned*)((const char*)(gbase) + (voff)[_i]), (LAS unsigned*)(lds + (bufoff) + ldsw + _i * 8192), 16, 0, 0); } while (0)
; #define PG8_LDA(dst, b, h) do { _Pragma("unroll") for (int m = 0; m < 4; ++m) _Pragma("unroll") for (int k = 0; k < 2; ++k) dst[m][k] = *(const LAS bf16x8*)(lds + PG8_SA(b, h) + aoff + m * 2048 + k * 1024); } while (0)
; #define PG8_LDB(dst, b, h) do { _Pragma("unroll") for (int n = 0; n < 2; ++n) _Pragma("unroll") for (int k = 0; k < 2; ++k) dst[n][k] = *(const LAS bf16x8*)(lds + PG8_SB(b, h) + boff + n * 2048 + k * 1024); } while (0)
; #define PG8_MMA(ai, bj, At, Bt) do { __builtin_amdgcn_s_setprio(1); _Pragma("unroll") for (int m = 0; m < 4; ++m) _Pragma("unroll") for (int n = 0; n < 2; ++n) _Pragma("unroll") for (int k = 0; k < 2; ++k) \
;         acc[ai][bj][m][n] = __builtin_amdgcn_mfma_f32_16x16x32_bf16(Bt[n][k], At[m][k], acc[ai][bj][m][n], 0, 0, 0); __builtin_amdgcn_s_setprio(0); } while (0)
; #define PG8_WAIT_V(n) asm volatile("s_waitcnt vmcnt(" #n ")" ::: "memory")
; #define PG8_WAIT_L(n) asm volatile("s_waitcnt lgkmcnt(" #n ")" ::: "memory")
; #define PG8_BAR __builtin_amdgcn_s_barrier()
; #define PG8_SCHED __builtin_amdgcn_sched_barrier(0)
; template <class Epi>
; __device__ __forceinline__ void gemm_phase(LAS unsigned char* lds, const Gemm g, const StaticOrder& S, const Epi& E) {
;     ...
;             PG8_WAIT_V(6); PG8_BAR; PG8_MMA(1, 1, At, B1); PG8_BAR;
;             PG8_LDB(B0, 1, 0); PG8_SCHED; PG8_LDA(At, 1, 0); PG8_STAGE(PG8_SA(0, 1), a2 + hstep, voffA);
;             PG8_WAIT_L(8); PG8_BAR; PG8_WAIT_L(0); PG8_MMA(0, 0, At, B0); PG8_BAR; PG8_SCHED;
;             PG8_LDB(B1, 1, 1); PG8_STAGE(PG8_SB(1, 0), b3, voffB);
;             PG8_BAR; PG8_WAIT_L(0); PG8_MMA(0, 1, At, B1); PG8_BAR;
;             PG8_LDA(At, 1, 1); PG8_STAGE(PG8_SA(1, 0), a3, voffA);
;             PG8_BAR; PG8_WAIT_L(0); PG8_MMA(1, 0, At, B0); PG8_BAR; PG8_SCHED;
	s_add_u32 s54, s24, 0x160000
	s_addc_u32 s55, s25, 0
	s_add_i32 s56, s42, s28
	v_lshl_add_u64 v[128:129], s[54:55], 0, v[156:157]
	s_mov_b32 m0, s56
	s_nop 0
	global_load_lds_dwordx4 v[128:129], off
	v_lshl_add_u64 v[128:129], s[54:55], 0, v[160:161]
	s_add_i32 m0, s56, 0x2000
	s_nop 0
	global_load_lds_dwordx4 v[128:129], off
	s_waitcnt vmcnt(6)
	s_barrier
	v_mfma_f32_16x16x32_bf16 v[52:55], v[200:203], v[144:147], v[52:55]
	v_mfma_f32_16x16x32_bf16 v[48:51], v[208:211], v[144:147], v[48:51]
	v_mfma_f32_16x16x32_bf16 v[36:39], v[200:203], v[170:173], v[36:39]
	v_mfma_f32_16x16x32_bf16 v[32:35], v[208:211], v[170:173], v[32:35]
	v_mfma_f32_16x16x32_bf16 v[20:23], v[200:203], v[178:181], v[20:23]
	v_mfma_f32_16x16x32_bf16 v[16:19], v[208:211], v[178:181], v[16:19]
	v_mfma_f32_16x16x32_bf16 v[4:7], v[200:203], v[192:195], v[4:7]
	v_mfma_f32_16x16x32_bf16 v[0:3], v[208:211], v[192:195], v[0:3]
	v_mfma_f32_16x16x32_bf16 v[52:55], v[204:207], v[148:151], v[52:55]
	v_mfma_f32_16x16x32_bf16 v[48:51], v[216:219], v[148:151], v[48:51]
	v_mfma_f32_16x16x32_bf16 v[36:39], v[204:207], v[174:177], v[36:39]
	v_mfma_f32_16x16x32_bf16 v[32:35], v[216:219], v[174:177], v[32:35]
	v_mfma_f32_16x16x32_bf16 v[20:23], v[204:207], v[188:191], v[20:23]
	v_mfma_f32_16x16x32_bf16 v[16:19], v[216:219], v[188:191], v[16:19]
	v_mfma_f32_16x16x32_bf16 v[4:7], v[204:207], v[196:199], v[4:7]
	v_mfma_f32_16x16x32_bf16 v[0:3], v[216:219], v[196:199], v[0:3]
	s_add_i32 s54, 0, 0x18000
	v_add_u32_e32 v140, s54, v183
	s_barrier
	ds_read_b128 v[128:131], v140
	ds_read_b128 v[132:135], v140 offset:1024
	ds_read_b128 v[136:139], v140 offset:2048
	ds_read_b128 v[140:143], v140 offset:3072
	s_add_u32 s26, s26, 0x160000
	s_addc_u32 s27, s27, 0
	s_mov_b32 m0, s31
	v_lshl_add_u64 v[200:201], s[26:27], 0, v[154:155]
	ds_read_b128 v[144:147], v186 offset:32768
	ds_read_b128 v[148:151], v186 offset:33792
	ds_read_b128 v[170:173], v186 offset:34816
	ds_read_b128 v[174:177], v186 offset:35840
	ds_read_b128 v[178:181], v186 offset:36864
	ds_read_b128 v[188:191], v186 offset:37888
	ds_read_b128 v[192:195], v186 offset:38912
	ds_read_b128 v[196:199], v186 offset:39936
	global_load_lds_dwordx4 v[200:201], off
	v_lshl_add_u64 v[200:201], s[26:27], 0, v[158:159]
	s_mov_b32 m0, s33
	s_nop 0
	global_load_lds_dwordx4 v[200:201], off
	s_waitcnt lgkmcnt(8)
	s_barrier
	s_waitcnt lgkmcnt(0)
	s_waitcnt lgkmcnt(0)
	v_mfma_f32_16x16x32_bf16 v[124:127], v[128:131], v[144:147], v[124:127]
	v_mfma_f32_16x16x32_bf16 v[120:123], v[136:139], v[144:147], v[120:123]
	v_mfma_f32_16x16x32_bf16 v[108:111], v[128:131], v[170:173], v[108:111]
	v_mfma_f32_16x16x32_bf16 v[104:107], v[136:139], v[170:173], v[104:107]
	v_mfma_f32_16x16x32_bf16 v[92:95], v[128:131], v[178:181], v[92:95]
	v_mfma_f32_16x16x32_bf16 v[88:91], v[136:139], v[178:181], v[88:91]
	v_mfma_f32_16x16x32_bf16 v[76:79], v[128:131], v[192:195], v[76:79]
	v_mfma_f32_16x16x32_bf16 v[72:75], v[136:139], v[192:195], v[72:75]
	v_mfma_f32_16x16x32_bf16 v[124:127], v[132:135], v[148:151], v[124:127]
	v_mfma_f32_16x16x32_bf16 v[120:123], v[140:143], v[148:151], v[120:123]
	v_mfma_f32_16x16x32_bf16 v[108:111], v[132:135], v[174:177], v[108:111]
	v_mfma_f32_16x16x32_bf16 v[104:107], v[140:143], v[174:177], v[104:107]
	v_mfma_f32_16x16x32_bf16 v[92:95], v[132:135], v[188:191], v[92:95]
	v_mfma_f32_16x16x32_bf16 v[88:91], v[140:143], v[188:191], v[88:91]
	v_mfma_f32_16x16x32_bf16 v[76:79], v[132:135], v[196:199], v[76:79]
	v_mfma_f32_16x16x32_bf16 v[72:75], v[140:143], v[196:199], v[72:75]
	s_barrier
	s_add_i32 s26, 0, 0x1c000
	s_add_i32 s27, s54, s28
	v_add_u32_e32 v216, s26, v183
	v_lshl_add_u64 v[212:213], v[212:213], 0, s[16:17]
	s_mov_b32 m0, s27
	ds_read_b128 v[200:203], v216
	ds_read_b128 v[204:207], v216 offset:1024
	ds_read_b128 v[208:211], v216 offset:2048
	ds_read_b128 v[216:219], v216 offset:3072
	global_load_lds_dwordx4 v[212:213], off
	v_lshl_add_u64 v[212:213], v[220:221], 0, s[16:17]
	s_add_i32 m0, s27, 0x2000
	s_nop 0
	global_load_lds_dwordx4 v[212:213], off
	s_barrier
	s_waitcnt lgkmcnt(0)
	s_waitcnt lgkmcnt(0)
	v_mfma_f32_16x16x32_bf16 v[116:119], v[200:203], v[144:147], v[116:119]
	v_mfma_f32_16x16x32_bf16 v[112:115], v[208:211], v[144:147], v[112:115]
	v_mfma_f32_16x16x32_bf16 v[100:103], v[200:203], v[170:173], v[100:103]
	v_mfma_f32_16x16x32_bf16 v[96:99], v[208:211], v[170:173], v[96:99]
	v_mfma_f32_16x16x32_bf16 v[84:87], v[200:203], v[178:181], v[84:87]
	v_mfma_f32_16x16x32_bf16 v[80:83], v[208:211], v[178:181], v[80:83]
	v_mfma_f32_16x16x32_bf16 v[68:71], v[200:203], v[192:195], v[68:71]
	v_mfma_f32_16x16x32_bf16 v[64:67], v[208:211], v[192:195], v[64:67]
	v_mfma_f32_16x16x32_bf16 v[116:119], v[204:207], v[148:151], v[116:119]
	v_mfma_f32_16x16x32_bf16 v[112:115], v[216:219], v[148:151], v[112:115]
	v_mfma_f32_16x16x32_bf16 v[100:103], v[204:207], v[174:177], v[100:103]
	v_mfma_f32_16x16x32_bf16 v[96:99], v[216:219], v[174:177], v[96:99]
	v_mfma_f32_16x16x32_bf16 v[84:87], v[204:207], v[188:191], v[84:87]
	v_mfma_f32_16x16x32_bf16 v[80:83], v[216:219], v[188:191], v[80:83]
	v_mfma_f32_16x16x32_bf16 v[68:71], v[204:207], v[196:199], v[68:71]
	v_mfma_f32_16x16x32_bf16 v[64:67], v[216:219], v[196:199], v[64:67]
	s_mov_b32 m0, s38
	v_lshl_add_u64 v[212:213], v[222:223], 0, s[16:17]
	s_barrier
; #define PG8_STAGE(bufoff, gbase, voff) do { _Pragma("unroll") for (int _i = 0; _i < 2; ++_i) \
;         __builtin_amdgcn_global_load_lds((const unsigned*)((const char*)(gbase) + (voff)[_i]), (LAS unsigned*)(lds + (bufoff) + ldsw + _i * 8192), 16, 0, 0); } while (0)
; #define PG8_LDA(dst, b, h) do { _Pragma("unroll") for (int m = 0; m < 4; ++m) _Pragma("unroll") for (int k = 0; k < 2; ++k) dst[m][k] = *(const LAS bf16x8*)(lds + PG8_SA(b, h) + aoff + m * 2048 + k * 1024); } while (0)
; #define PG8_LDB(dst, b, h) do { _Pragma("unroll") for (int n = 0; n < 2; ++n) _Pragma("unroll") for (int k = 0; k < 2; ++k) dst[n][k] = *(const LAS bf16x8*)(lds + PG8_SB(b, h) + boff + n * 2048 + k * 1024); } while (0)
; #define PG8_WAIT_V(n) asm volatile("s_waitcnt vmcnt(" #n ")" ::: "memory")
; #define PG8_WAIT_L(n) asm volatile("s_waitcnt lgkmcnt(" #n ")" ::: "memory")
; template <class Epi>
; __device__ __forceinline__ void gemm_phase(LAS unsigned char* lds, const Gemm g, const StaticOrder& S, const Epi& E) {
;     ...
;             PG8_WAIT_L(8); PG8_BAR; PG8_WAIT_L(0); PG8_MMA(0, 0, At, B0); PG8_BAR; PG8_SCHED;
;             PG8_LDB(B1, 1, 1); PG8_STAGE(PG8_SB(1, 0), b3, voffB);
;             PG8_BAR; PG8_WAIT_L(0); PG8_MMA(0, 1, At, B1); PG8_BAR;
;             PG8_LDA(At, 1, 1); PG8_STAGE(PG8_SA(1, 0), a3, voffA);
;             PG8_BAR; PG8_WAIT_L(0); PG8_MMA(1, 0, At, B0); PG8_BAR; PG8_SCHED;
;             PG8_STAGE(PG8_SB(1, 1), b3 + hstep, voffB);
;             PG8_WAIT_V(6); PG8_BAR; PG8_MMA(1, 1, At, B1); PG8_BAR;
;         }
;     __device__ __forceinline__ void operator()(const AccT& acc, const pg8::Unit& u, int wr, int wc, int fr, int fq) const {
;         const int row0 = u.pm * 256 + wr * 64 + fr, col0 = u.pn * 256 + wc * 32 + 8 * fq;
; #pragma unroll
;         for (int ai = 0; ai < 2; ++ai) { f32x4 b0[4][2], b1[4][2];
; #pragma unroll
;             for (int m = 0; m < 4; ++m) { const int r = row0 + ai * 128 + m * 16; const int rc = r < NREAL ? r : NREAL - 1;
; #pragma unroll
;                 for (int bj = 0; bj < 2; ++bj) {
;                     if (mode) unpack8(*(const u32x4*)(X1 + (size_t)rc * D + col0 + bj * 128), b0[m][bj], b1[m][bj]);
;                     else { const float* b2 = (rc < ROW_S ? xp + (size_t)rc * D : xs + (size_t)(rc - ROW_S) * D) + col0 + bj * 128; b0[m][bj] = *(const f32x4*)b2; b1[m][bj] = *(const f32x4*)(b2 + 4); } } }
	ds_read_b128 v[144:147], v186 offset:49152
	ds_read_b128 v[148:151], v186 offset:50176
	ds_read_b128 v[170:173], v186 offset:51200
	ds_read_b128 v[174:177], v186 offset:52224
	ds_read_b128 v[178:181], v186 offset:53248
	ds_read_b128 v[188:191], v186 offset:54272
	ds_read_b128 v[192:195], v186 offset:55296
	ds_read_b128 v[196:199], v186 offset:56320
	global_load_lds_dwordx4 v[212:213], off
	v_lshl_add_u64 v[212:213], v[224:225], 0, s[16:17]
	s_mov_b32 m0, s39
	s_nop 0
	global_load_lds_dwordx4 v[212:213], off
	s_barrier
	s_waitcnt lgkmcnt(0)
	s_waitcnt lgkmcnt(0)
	v_mfma_f32_16x16x32_bf16 v[60:63], v[128:131], v[144:147], v[60:63]
	v_mfma_f32_16x16x32_bf16 v[56:59], v[136:139], v[144:147], v[56:59]
	v_mfma_f32_16x16x32_bf16 v[44:47], v[128:131], v[170:173], v[44:47]
	v_mfma_f32_16x16x32_bf16 v[40:43], v[136:139], v[170:173], v[40:43]
	v_mfma_f32_16x16x32_bf16 v[28:31], v[128:131], v[178:181], v[28:31]
	v_mfma_f32_16x16x32_bf16 v[24:27], v[136:139], v[178:181], v[24:27]
	v_mfma_f32_16x16x32_bf16 v[12:15], v[128:131], v[192:195], v[12:15]
	v_mfma_f32_16x16x32_bf16 v[8:11], v[136:139], v[192:195], v[8:11]
	v_mfma_f32_16x16x32_bf16 v[60:63], v[132:135], v[148:151], v[60:63]
	v_mfma_f32_16x16x32_bf16 v[56:59], v[140:143], v[148:151], v[56:59]
	v_mfma_f32_16x16x32_bf16 v[44:47], v[132:135], v[174:177], v[44:47]
	v_mfma_f32_16x16x32_bf16 v[40:43], v[140:143], v[174:177], v[40:43]
	v_mfma_f32_16x16x32_bf16 v[28:31], v[132:135], v[188:191], v[28:31]
	v_mfma_f32_16x16x32_bf16 v[24:27], v[140:143], v[188:191], v[24:27]
	v_mfma_f32_16x16x32_bf16 v[12:15], v[132:135], v[196:199], v[12:15]
	v_mfma_f32_16x16x32_bf16 v[8:11], v[140:143], v[196:199], v[8:11]
	s_barrier
	s_add_u32 s24, s24, 0x160080
	s_addc_u32 s25, s25, 0
	s_add_i32 s26, s26, s28
	v_lshl_add_u64 v[128:129], s[24:25], 0, v[156:157]
	s_mov_b32 m0, s26
	s_nop 0
	global_load_lds_dwordx4 v[128:129], off
	v_lshl_add_u64 v[128:129], s[24:25], 0, v[160:161]
	s_add_i32 m0, s26, 0x2000
	s_nop 0
	global_load_lds_dwordx4 v[128:129], off
	s_waitcnt vmcnt(6)
	s_barrier
	v_mfma_f32_16x16x32_bf16 v[52:55], v[200:203], v[144:147], v[52:55]
	v_mfma_f32_16x16x32_bf16 v[48:51], v[208:211], v[144:147], v[48:51]
	v_mfma_f32_16x16x32_bf16 v[36:39], v[200:203], v[170:173], v[36:39]
	v_mfma_f32_16x16x32_bf16 v[32:35], v[208:211], v[170:173], v[32:35]
	v_mfma_f32_16x16x32_bf16 v[20:23], v[200:203], v[178:181], v[20:23]
	v_mfma_f32_16x16x32_bf16 v[16:19], v[208:211], v[178:181], v[16:19]
	v_mfma_f32_16x16x32_bf16 v[4:7], v[200:203], v[192:195], v[4:7]
	v_mfma_f32_16x16x32_bf16 v[0:3], v[208:211], v[192:195], v[0:3]
	v_mfma_f32_16x16x32_bf16 v[52:55], v[204:207], v[148:151], v[52:55]
	v_mfma_f32_16x16x32_bf16 v[48:51], v[216:219], v[148:151], v[48:51]
	v_mfma_f32_16x16x32_bf16 v[36:39], v[204:207], v[174:177], v[36:39]
	v_mfma_f32_16x16x32_bf16 v[32:35], v[216:219], v[174:177], v[32:35]
	v_mfma_f32_16x16x32_bf16 v[20:23], v[204:207], v[188:191], v[20:23]
	v_mfma_f32_16x16x32_bf16 v[16:19], v[216:219], v[188:191], v[16:19]
	v_mfma_f32_16x16x32_bf16 v[4:7], v[204:207], v[196:199], v[4:7]
	v_mfma_f32_16x16x32_bf16 v[0:3], v[216:219], v[196:199], v[0:3]
	s_add_i32 s53, s53, 2
	s_add_u32 s22, s22, 0x100
	s_addc_u32 s23, s23, 0
	s_add_u32 s51, s51, 0x100
	s_addc_u32 s52, s52, 0
	s_cmpk_gt_u32 s53, 0x55
	s_barrier
	s_cbranch_scc0 .LBB0_1338
	v_lshl_add_u32 v172, s50, 8, v182
	v_or_b32_e32 v180, 16, v172
	v_lshl_or_b32 v170, s49, 8, v184
	v_min_i32_e32 v128, 0x207f, v180
	v_ashrrev_i32_e32 v171, 31, v170
	v_ashrrev_i32_e32 v129, 31, v128
	v_lshl_add_u64 v[174:175], v[170:171], 1, s[12:13]
	v_lshlrev_b64 v[128:129], 12, v[128:129]
	v_lshl_add_u64 v[128:129], v[174:175], 0, v[128:129]
	v_or_b32_e32 v178, 32, v172
	global_load_dwordx4 v[148:151], v[128:129], off
	global_load_dwordx4 v[144:147], v[128:129], off offset:256
	v_min_i32_e32 v128, 0x207f, v178
	v_ashrrev_i32_e32 v129, 31, v128
	v_lshlrev_b64 v[128:129], 12, v[128:129]
	v_lshl_add_u64 v[128:129], v[174:175], 0, v[128:129]
	v_or_b32_e32 v176, 48, v172
	global_load_dwordx4 v[140:143], v[128:129], off
	global_load_dwordx4 v[136:139], v[128:129], off offset:256
	v_min_i32_e32 v128, 0x207f, v176
	v_ashrrev_i32_e32 v129, 31, v128
	v_lshlrev_b64 v[128:129], 12, v[128:129]
	v_lshl_add_u64 v[128:129], v[174:175], 0, v[128:129]
	global_load_dwordx4 v[132:135], v[128:129], off
	s_nop 0
	global_load_dwordx4 v[128:131], v[128:129], off offset:256
	v_cmp_gt_i32_e32 vcc, s43, v172
	v_ashrrev_i32_e32 v173, 31, v172
	s_and_saveexec_b64 s[22:23], vcc
	s_cbranch_execnz .LBB0_1348
	s_or_b64 exec, exec, s[22:23]
	v_cmp_gt_i32_e32 vcc, s43, v180
	s_and_saveexec_b64 s[22:23], vcc
	s_cbranch_execnz .LBB0_1349
